# GEMM K-loops: redundant s_waitcnt lgkmcnt(0) after the pre-MFMA barrier removed (same wait sits before the barrier)
# speedup vs baseline: 1.0017x; 1.0017x over previous
; #define PG8_STAGE(bufoff, gbase, voff) do { _Pragma("unroll") for (int _i = 0; _i < 2; ++_i) \
;         __builtin_amdgcn_global_load_lds((const unsigned*)((const char*)(gbase) + (voff)[_i]), (PG8_LAS unsigned*)(lds + (bufoff) + ldsw + _i * 8192), 16, 0, 0); } while (0)
; #define PG8_LDA(dst, b, h) do { _Pragma("unroll") for (int m = 0; m < 4; ++m) _Pragma("unroll") for (int k = 0; k < 2; ++k) dst[m][k] = *(const PG8_LAS bf16x8*)(lds + PG8_SA(b, h) + aoff + m * 2048 + k * 1024); } while (0)
; #define PG8_LDB(dst, b, h) do { _Pragma("unroll") for (int n = 0; n < 2; ++n) _Pragma("unroll") for (int k = 0; k < 2; ++k) dst[n][k] = *(const PG8_LAS bf16x8*)(lds + PG8_SB(b, h) + boff + n * 2048 + k * 1024); } while (0)
; #define PG8_MMA(ai, bj, At, Bt) do { __builtin_amdgcn_s_setprio(1); _Pragma("unroll") for (int m = 0; m < 4; ++m) _Pragma("unroll") for (int n = 0; n < 2; ++n) _Pragma("unroll") for (int k = 0; k < 2; ++k) \
;         acc[ai][bj][m][n] = __builtin_amdgcn_mfma_f32_16x16x32_bf16(Bt[n][k], At[m][k], acc[ai][bj][m][n], 0, 0, 0); __builtin_amdgcn_s_setprio(0); } while (0)
; #define PG8_WAIT_V(n) asm volatile("s_waitcnt vmcnt(" #n ")" ::: "memory")
; template <class Epi, class Sched, bool ALIGN_EPI = false, bool SP2 = false>
; __device__ __forceinline__ void gemm_phase(PG8_LAS unsigned char* lds, const Gemm g, const Sched& S, const Epi& E) {
;     ...
;         const char* nA = has_next ? (const char*)g.A + (size_t)nxt.pm * tstep : cA; const char* nB = has_next ? (const char*)g.Bt + (size_t)nxt.pn * tstep : cB;
;         for (int t = 0; t < nt; t += 2) {
;             const bool last = (t == nt - 2);
;             const char* a1 = cA + (size_t)(t + 1) * kstep;
;             const char* a2 = last ? nA : cA + (size_t)(t + 2) * kstep; const char* b2 = last ? nB : cB + (size_t)(t + 2) * kstep;
;             const char* a3 = a2 + kstep; const char* b3 = b2 + kstep;
;             if (last && has_next) S.a_ready(nxt);
;             if constexpr (SP2) {
;             PG8_LDB(B0, 0, 0); PG8_LDB(B1, 0, 1); PG8_SCHED; PG8_LDA(At, 0, 0); PG8_STAGE(PG8_SA(1, 1), a1 + hstep, voffA);
;             PG8_WAIT_V(8); PG8_WAIT_L(0); PG8_BAR; PG8_MMA(0, 0, At, B0); PG8_MMA(0, 1, At, B1); PG8_BAR; PG8_SCHED;
;             PG8_LDA(At, 0, 1); PG8_STAGE(PG8_SB(0, 0), b2, voffB); PG8_STAGE(PG8_SB(0, 1), b2 + hstep, voffB); PG8_STAGE(PG8_SA(0, 0), a2, voffA);
.LBB0_223:
	s_ashr_i32 s15, s14, 31
	s_lshl_b64 s[16:17], s[14:15], 19
	s_add_u32 s16, s36, s16
	s_addc_u32 s17, s37, s17
	s_and_b64 s[18:19], s[4:5], exec
	s_cselect_b32 s15, s17, s21
	s_cselect_b32 s68, s16, s20
	s_ashr_i32 s13, s12, 31
	s_lshl_b64 s[18:19], s[12:13], 19
	s_add_u32 s18, s53, s18
	s_addc_u32 s19, s54, s19
	s_and_b64 s[46:47], s[4:5], exec
	s_cselect_b32 s13, s19, s43
	s_cselect_b32 s69, s18, s42
	s_add_u32 s20, s20, 0x40080
	s_addc_u32 s21, s21, 0
	s_add_u32 s70, s42, 0x100
	s_addc_u32 s71, s43, 0
	s_mov_b32 s72, -2
	ds_read_b128 v[154:157], v150
	ds_read_b128 v[158:161], v150 offset:1024
	ds_read_b128 v[162:165], v150 offset:2048
	ds_read_b128 v[166:169], v150 offset:3072
	ds_read_b128 v[170:173], v151
	ds_read_b128 v[174:177], v151 offset:1024
	ds_read_b128 v[178:181], v151 offset:2048
	ds_read_b128 v[182:185], v151 offset:3072
	s_add_u32 s42, s20, 0xfffc0080
	s_addc_u32 s43, s21, -1
	s_cmp_eq_u32 s72, 12
	s_cselect_b32 s47, s15, s43
	s_cselect_b32 s46, s68, s42
	s_cselect_b32 s43, s13, s71
	s_cselect_b32 s42, s69, s70
	s_add_i32 m0, s35, 0xc000
	ds_read_b128 v[186:189], v152
	ds_read_b128 v[190:193], v152 offset:1024
	ds_read_b128 v[198:201], v152 offset:2048
	ds_read_b128 v[202:205], v152 offset:3072
	ds_read_b128 v[206:209], v152 offset:4096
	ds_read_b128 v[210:213], v152 offset:5120
	ds_read_b128 v[214:217], v152 offset:6144
	ds_read_b128 v[218:221], v152 offset:7168
	global_load_lds_dwordx4 v136, s[20:21]
	s_add_i32 m0, s35, 0xe000
	s_nop 0
	global_load_lds_dwordx4 v138, s[20:21]
	s_waitcnt vmcnt(8)
	s_waitcnt lgkmcnt(0)
	s_barrier
	v_mfma_f32_16x16x32_bf16 v[124:127], v[154:157], v[186:189], 0
	v_mfma_f32_16x16x32_bf16 v[116:119], v[162:165], v[186:189], 0
	v_mfma_f32_16x16x32_bf16 v[108:111], v[154:157], v[198:201], 0
	v_mfma_f32_16x16x32_bf16 v[100:103], v[162:165], v[198:201], 0
	v_mfma_f32_16x16x32_bf16 v[92:95], v[154:157], v[206:209], 0
	v_mfma_f32_16x16x32_bf16 v[84:87], v[162:165], v[206:209], 0
	v_mfma_f32_16x16x32_bf16 v[76:79], v[154:157], v[214:217], 0
	v_mfma_f32_16x16x32_bf16 v[68:71], v[162:165], v[214:217], 0
	v_mfma_f32_16x16x32_bf16 v[124:127], v[158:161], v[190:193], v[124:127]
	v_mfma_f32_16x16x32_bf16 v[116:119], v[166:169], v[190:193], v[116:119]
	v_mfma_f32_16x16x32_bf16 v[108:111], v[158:161], v[202:205], v[108:111]
	v_mfma_f32_16x16x32_bf16 v[100:103], v[166:169], v[202:205], v[100:103]
	v_mfma_f32_16x16x32_bf16 v[92:95], v[158:161], v[210:213], v[92:95]
	v_mfma_f32_16x16x32_bf16 v[84:87], v[166:169], v[210:213], v[84:87]
	v_mfma_f32_16x16x32_bf16 v[76:79], v[158:161], v[218:221], v[76:79]
	v_mfma_f32_16x16x32_bf16 v[68:71], v[166:169], v[218:221], v[68:71]
	v_mfma_f32_16x16x32_bf16 v[120:123], v[170:173], v[186:189], 0
	v_mfma_f32_16x16x32_bf16 v[112:115], v[178:181], v[186:189], 0
	v_mfma_f32_16x16x32_bf16 v[104:107], v[170:173], v[198:201], 0
	v_mfma_f32_16x16x32_bf16 v[96:99], v[178:181], v[198:201], 0
	v_mfma_f32_16x16x32_bf16 v[88:91], v[170:173], v[206:209], 0
	v_mfma_f32_16x16x32_bf16 v[80:83], v[178:181], v[206:209], 0
	v_mfma_f32_16x16x32_bf16 v[72:75], v[170:173], v[214:217], 0
	v_mfma_f32_16x16x32_bf16 v[64:67], v[178:181], v[214:217], 0
	v_mfma_f32_16x16x32_bf16 v[120:123], v[174:177], v[190:193], v[120:123]
	v_mfma_f32_16x16x32_bf16 v[112:115], v[182:185], v[190:193], v[112:115]
	v_mfma_f32_16x16x32_bf16 v[104:107], v[174:177], v[202:205], v[104:107]
	v_mfma_f32_16x16x32_bf16 v[96:99], v[182:185], v[202:205], v[96:99]
	v_mfma_f32_16x16x32_bf16 v[88:91], v[174:177], v[210:213], v[88:91]
	v_mfma_f32_16x16x32_bf16 v[80:83], v[182:185], v[210:213], v[80:83]
	v_mfma_f32_16x16x32_bf16 v[72:75], v[174:177], v[218:221], v[72:75]
	v_mfma_f32_16x16x32_bf16 v[64:67], v[182:185], v[218:221], v[64:67]
	s_barrier
	s_add_i32 s73, s63, s55
	s_add_u32 s98, s42, s8
	s_addc_u32 s99, s43, s9
	s_add_u32 s100, s46, s8
	s_addc_u32 s101, s47, s9
	s_mov_b32 m0, s73
	ds_read_b128 v[186:189], v152 offset:16384
	ds_read_b128 v[190:193], v152 offset:17408
	ds_read_b128 v[198:201], v152 offset:18432
	ds_read_b128 v[202:205], v152 offset:19456
	ds_read_b128 v[206:209], v152 offset:20480
	ds_read_b128 v[210:213], v152 offset:21504
	ds_read_b128 v[214:217], v152 offset:22528
	ds_read_b128 v[218:221], v152 offset:23552
	global_load_lds_dwordx4 v132, s[42:43]
	s_add_i32 m0, s73, 0x2000
	s_add_u32 s74, s42, 0x40000
	s_addc_u32 s75, s43, 0
	s_add_i32 s73, s64, s55
	global_load_lds_dwordx4 v128, s[42:43]
	s_mov_b32 m0, s73
	s_nop 0
	global_load_lds_dwordx4 v132, s[74:75]
	s_add_i32 m0, s73, 0x2000
	s_nop 0
	global_load_lds_dwordx4 v128, s[74:75]
	s_mov_b32 m0, s35
	s_nop 0
	global_load_lds_dwordx4 v134, s[46:47]
	s_mov_b32 m0, s57
	s_nop 0
	global_load_lds_dwordx4 v130, s[46:47]
	s_waitcnt vmcnt(8)
	s_waitcnt lgkmcnt(0)
	s_barrier
; #define PG8_STAGE(bufoff, gbase, voff) do { _Pragma("unroll") for (int _i = 0; _i < 2; ++_i) \
;         __builtin_amdgcn_global_load_lds((const unsigned*)((const char*)(gbase) + (voff)[_i]), (PG8_LAS unsigned*)(lds + (bufoff) + ldsw + _i * 8192), 16, 0, 0); } while (0)
; #define PG8_LDA(dst, b, h) do { _Pragma("unroll") for (int m = 0; m < 4; ++m) _Pragma("unroll") for (int k = 0; k < 2; ++k) dst[m][k] = *(const PG8_LAS bf16x8*)(lds + PG8_SA(b, h) + aoff + m * 2048 + k * 1024); } while (0)
; #define PG8_LDB(dst, b, h) do { _Pragma("unroll") for (int n = 0; n < 2; ++n) _Pragma("unroll") for (int k = 0; k < 2; ++k) dst[n][k] = *(const PG8_LAS bf16x8*)(lds + PG8_SB(b, h) + boff + n * 2048 + k * 1024); } while (0)
; #define PG8_MMA(ai, bj, At, Bt) do { __builtin_amdgcn_s_setprio(1); _Pragma("unroll") for (int m = 0; m < 4; ++m) _Pragma("unroll") for (int n = 0; n < 2; ++n) _Pragma("unroll") for (int k = 0; k < 2; ++k) \
;         acc[ai][bj][m][n] = __builtin_amdgcn_mfma_f32_16x16x32_bf16(Bt[n][k], At[m][k], acc[ai][bj][m][n], 0, 0, 0); __builtin_amdgcn_s_setprio(0); } while (0)
; #define PG8_WAIT_V(n) asm volatile("s_waitcnt vmcnt(" #n ")" ::: "memory")
; #define PG8_WAIT_L(n) asm volatile("s_waitcnt lgkmcnt(" #n ")" ::: "memory")
; #define PG8_BAR __builtin_amdgcn_s_barrier()
; #define PG8_SCHED __builtin_amdgcn_sched_barrier(0)
; template <class Epi, class Sched, bool ALIGN_EPI = false, bool SP2 = false>
; __device__ __forceinline__ void gemm_phase(PG8_LAS unsigned char* lds, const Gemm g, const Sched& S, const Epi& E) {
;     ...
;             PG8_LDA(At, 0, 1); PG8_STAGE(PG8_SB(0, 0), b2, voffB); PG8_STAGE(PG8_SB(0, 1), b2 + hstep, voffB); PG8_STAGE(PG8_SA(0, 0), a2, voffA);
;             PG8_WAIT_V(8); PG8_WAIT_L(0); PG8_BAR; PG8_MMA(1, 0, At, B0); PG8_MMA(1, 1, At, B1); PG8_BAR; PG8_SCHED;
;             PG8_LDB(B0, 1, 0); PG8_LDB(B1, 1, 1); PG8_SCHED; PG8_LDA(At, 1, 0); PG8_STAGE(PG8_SA(0, 1), a2 + hstep, voffA);
;             PG8_WAIT_V(8); PG8_WAIT_L(0); PG8_BAR; PG8_MMA(0, 0, At, B0); PG8_MMA(0, 1, At, B1); PG8_BAR; PG8_SCHED;
	v_mfma_f32_16x16x32_bf16 v[60:63], v[154:157], v[186:189], 0
	v_mfma_f32_16x16x32_bf16 v[52:55], v[162:165], v[186:189], 0
	v_mfma_f32_16x16x32_bf16 v[44:47], v[154:157], v[198:201], 0
	v_mfma_f32_16x16x32_bf16 v[36:39], v[162:165], v[198:201], 0
	v_mfma_f32_16x16x32_bf16 v[28:31], v[154:157], v[206:209], 0
	v_mfma_f32_16x16x32_bf16 v[20:23], v[162:165], v[206:209], 0
	v_mfma_f32_16x16x32_bf16 v[12:15], v[154:157], v[214:217], 0
	v_mfma_f32_16x16x32_bf16 v[4:7], v[162:165], v[214:217], 0
	v_mfma_f32_16x16x32_bf16 v[60:63], v[158:161], v[190:193], v[60:63]
	v_mfma_f32_16x16x32_bf16 v[52:55], v[166:169], v[190:193], v[52:55]
	v_mfma_f32_16x16x32_bf16 v[44:47], v[158:161], v[202:205], v[44:47]
	v_mfma_f32_16x16x32_bf16 v[36:39], v[166:169], v[202:205], v[36:39]
	v_mfma_f32_16x16x32_bf16 v[28:31], v[158:161], v[210:213], v[28:31]
	v_mfma_f32_16x16x32_bf16 v[20:23], v[166:169], v[210:213], v[20:23]
	v_mfma_f32_16x16x32_bf16 v[12:15], v[158:161], v[218:221], v[12:15]
	v_mfma_f32_16x16x32_bf16 v[4:7], v[166:169], v[218:221], v[4:7]
	v_mfma_f32_16x16x32_bf16 v[56:59], v[170:173], v[186:189], 0
	v_mfma_f32_16x16x32_bf16 v[48:51], v[178:181], v[186:189], 0
	v_mfma_f32_16x16x32_bf16 v[40:43], v[170:173], v[198:201], 0
	v_mfma_f32_16x16x32_bf16 v[32:35], v[178:181], v[198:201], 0
	v_mfma_f32_16x16x32_bf16 v[24:27], v[170:173], v[206:209], 0
	v_mfma_f32_16x16x32_bf16 v[16:19], v[178:181], v[206:209], 0
	v_mfma_f32_16x16x32_bf16 v[8:11], v[170:173], v[214:217], 0
	v_mfma_f32_16x16x32_bf16 v[0:3], v[178:181], v[214:217], 0
	v_mfma_f32_16x16x32_bf16 v[56:59], v[174:177], v[190:193], v[56:59]
	v_mfma_f32_16x16x32_bf16 v[48:51], v[182:185], v[190:193], v[48:51]
	v_mfma_f32_16x16x32_bf16 v[40:43], v[174:177], v[202:205], v[40:43]
	v_mfma_f32_16x16x32_bf16 v[32:35], v[182:185], v[202:205], v[32:35]
	v_mfma_f32_16x16x32_bf16 v[24:27], v[174:177], v[210:213], v[24:27]
	v_mfma_f32_16x16x32_bf16 v[16:19], v[182:185], v[210:213], v[16:19]
	v_mfma_f32_16x16x32_bf16 v[8:11], v[174:177], v[218:221], v[8:11]
	v_mfma_f32_16x16x32_bf16 v[0:3], v[182:185], v[218:221], v[0:3]
	s_barrier
	s_add_i32 s73, 0, 0x18000
	v_add_u32_e32 v153, s73, v147
	s_add_i32 s74, 0, 0x1c000
	ds_read_b128 v[154:157], v153
	ds_read_b128 v[158:161], v153 offset:1024
	ds_read_b128 v[162:165], v153 offset:2048
	ds_read_b128 v[166:169], v153 offset:3072
	v_add_u32_e32 v153, s74, v147
	ds_read_b128 v[170:173], v153
	ds_read_b128 v[174:177], v153 offset:1024
	ds_read_b128 v[178:181], v153 offset:2048
	ds_read_b128 v[182:185], v153 offset:3072
	s_add_u32 s46, s46, 0x40000
	s_addc_u32 s47, s47, 0
	s_mov_b32 m0, s58
	ds_read_b128 v[186:189], v152 offset:32768
	ds_read_b128 v[190:193], v152 offset:33792
	ds_read_b128 v[198:201], v152 offset:34816
	ds_read_b128 v[202:205], v152 offset:35840
	ds_read_b128 v[206:209], v152 offset:36864
	ds_read_b128 v[210:213], v152 offset:37888
	ds_read_b128 v[214:217], v152 offset:38912
	ds_read_b128 v[218:221], v152 offset:39936
	global_load_lds_dwordx4 v134, s[46:47]
	s_mov_b32 m0, s59
	s_nop 0
	global_load_lds_dwordx4 v130, s[46:47]
	s_waitcnt vmcnt(8)
	s_waitcnt lgkmcnt(0)
	s_barrier
	v_mfma_f32_16x16x32_bf16 v[124:127], v[154:157], v[186:189], v[124:127]
	v_mfma_f32_16x16x32_bf16 v[116:119], v[162:165], v[186:189], v[116:119]
	v_mfma_f32_16x16x32_bf16 v[108:111], v[154:157], v[198:201], v[108:111]
	v_mfma_f32_16x16x32_bf16 v[100:103], v[162:165], v[198:201], v[100:103]
	v_mfma_f32_16x16x32_bf16 v[92:95], v[154:157], v[206:209], v[92:95]
	v_mfma_f32_16x16x32_bf16 v[84:87], v[162:165], v[206:209], v[84:87]
	v_mfma_f32_16x16x32_bf16 v[76:79], v[154:157], v[214:217], v[76:79]
	v_mfma_f32_16x16x32_bf16 v[68:71], v[162:165], v[214:217], v[68:71]
	v_mfma_f32_16x16x32_bf16 v[124:127], v[158:161], v[190:193], v[124:127]
	v_mfma_f32_16x16x32_bf16 v[116:119], v[166:169], v[190:193], v[116:119]
	v_mfma_f32_16x16x32_bf16 v[108:111], v[158:161], v[202:205], v[108:111]
	v_mfma_f32_16x16x32_bf16 v[100:103], v[166:169], v[202:205], v[100:103]
	v_mfma_f32_16x16x32_bf16 v[92:95], v[158:161], v[210:213], v[92:95]
	v_mfma_f32_16x16x32_bf16 v[84:87], v[166:169], v[210:213], v[84:87]
	v_mfma_f32_16x16x32_bf16 v[76:79], v[158:161], v[218:221], v[76:79]
	v_mfma_f32_16x16x32_bf16 v[68:71], v[166:169], v[218:221], v[68:71]
	v_mfma_f32_16x16x32_bf16 v[120:123], v[170:173], v[186:189], v[120:123]
	v_mfma_f32_16x16x32_bf16 v[112:115], v[178:181], v[186:189], v[112:115]
	v_mfma_f32_16x16x32_bf16 v[104:107], v[170:173], v[198:201], v[104:107]
	v_mfma_f32_16x16x32_bf16 v[96:99], v[178:181], v[198:201], v[96:99]
	v_mfma_f32_16x16x32_bf16 v[88:91], v[170:173], v[206:209], v[88:91]
	v_mfma_f32_16x16x32_bf16 v[80:83], v[178:181], v[206:209], v[80:83]
	v_mfma_f32_16x16x32_bf16 v[72:75], v[170:173], v[214:217], v[72:75]
	v_mfma_f32_16x16x32_bf16 v[64:67], v[178:181], v[214:217], v[64:67]
	v_mfma_f32_16x16x32_bf16 v[120:123], v[174:177], v[190:193], v[120:123]
	v_mfma_f32_16x16x32_bf16 v[112:115], v[182:185], v[190:193], v[112:115]
	v_mfma_f32_16x16x32_bf16 v[104:107], v[174:177], v[202:205], v[104:107]
	v_mfma_f32_16x16x32_bf16 v[96:99], v[182:185], v[202:205], v[96:99]
	v_mfma_f32_16x16x32_bf16 v[88:91], v[174:177], v[210:213], v[88:91]
	v_mfma_f32_16x16x32_bf16 v[80:83], v[182:185], v[210:213], v[80:83]
	v_mfma_f32_16x16x32_bf16 v[72:75], v[174:177], v[218:221], v[72:75]
	v_mfma_f32_16x16x32_bf16 v[64:67], v[182:185], v[218:221], v[64:67]
	s_barrier
; #define PG8_STAGE(bufoff, gbase, voff) do { _Pragma("unroll") for (int _i = 0; _i < 2; ++_i) \
;         __builtin_amdgcn_global_load_lds((const unsigned*)((const char*)(gbase) + (voff)[_i]), (PG8_LAS unsigned*)(lds + (bufoff) + ldsw + _i * 8192), 16, 0, 0); } while (0)
; #define PG8_LDA(dst, b, h) do { _Pragma("unroll") for (int m = 0; m < 4; ++m) _Pragma("unroll") for (int k = 0; k < 2; ++k) dst[m][k] = *(const PG8_LAS bf16x8*)(lds + PG8_SA(b, h) + aoff + m * 2048 + k * 1024); } while (0)
; #define PG8_LDB(dst, b, h) do { _Pragma("unroll") for (int n = 0; n < 2; ++n) _Pragma("unroll") for (int k = 0; k < 2; ++k) dst[n][k] = *(const PG8_LAS bf16x8*)(lds + PG8_SB(b, h) + boff + n * 2048 + k * 1024); } while (0)
; #define PG8_MMA(ai, bj, At, Bt) do { __builtin_amdgcn_s_setprio(1); _Pragma("unroll") for (int m = 0; m < 4; ++m) _Pragma("unroll") for (int n = 0; n < 2; ++n) _Pragma("unroll") for (int k = 0; k < 2; ++k) \
;         acc[ai][bj][m][n] = __builtin_amdgcn_mfma_f32_16x16x32_bf16(Bt[n][k], At[m][k], acc[ai][bj][m][n], 0, 0, 0); __builtin_amdgcn_s_setprio(0); } while (0)
; #define PG8_WAIT_V(n) asm volatile("s_waitcnt vmcnt(" #n ")" ::: "memory")
; template <class Epi, class Sched, bool ALIGN_EPI = false, bool SP2 = false>
; __device__ __forceinline__ void gemm_phase(PG8_LAS unsigned char* lds, const Gemm g, const Sched& S, const Epi& E) {
;     ...
;             PG8_LDB(B0, 0, 0); PG8_LDB(B1, 0, 1); PG8_SCHED; PG8_LDA(At, 0, 0); PG8_STAGE(PG8_SA(1, 1), a1 + hstep, voffA);
;             PG8_WAIT_V(8); PG8_WAIT_L(0); PG8_BAR; PG8_MMA(0, 0, At, B0); PG8_MMA(0, 1, At, B1); PG8_BAR; PG8_SCHED;
;             PG8_LDA(At, 0, 1); PG8_STAGE(PG8_SB(0, 0), b2, voffB); PG8_STAGE(PG8_SB(0, 1), b2 + hstep, voffB); PG8_STAGE(PG8_SA(0, 0), a2, voffA);
;             PG8_WAIT_V(8); PG8_WAIT_L(0); PG8_BAR; PG8_MMA(1, 0, At, B0); PG8_MMA(1, 1, At, B1); PG8_BAR; PG8_SCHED;
;             PG8_LDB(B0, 1, 0); PG8_LDB(B1, 1, 1); PG8_SCHED; PG8_LDA(At, 1, 0); PG8_STAGE(PG8_SA(0, 1), a2 + hstep, voffA);
;             PG8_WAIT_V(8); PG8_WAIT_L(0); PG8_BAR; PG8_MMA(0, 0, At, B0); PG8_MMA(0, 1, At, B1); PG8_BAR; PG8_SCHED;
;             PG8_LDA(At, 1, 1); PG8_STAGE(PG8_SB(1, 0), b3, voffB); PG8_STAGE(PG8_SB(1, 1), b3 + hstep, voffB); PG8_STAGE(PG8_SA(1, 0), a3, voffA);
;             PG8_WAIT_V(8); PG8_WAIT_L(0); PG8_BAR; PG8_MMA(1, 0, At, B0); PG8_MMA(1, 1, At, B1); PG8_BAR; PG8_SCHED;
	s_add_i32 s46, s73, s55
	s_mov_b32 m0, s46
	ds_read_b128 v[186:189], v152 offset:49152
	ds_read_b128 v[190:193], v152 offset:50176
	ds_read_b128 v[198:201], v152 offset:51200
	ds_read_b128 v[202:205], v152 offset:52224
	ds_read_b128 v[206:209], v152 offset:53248
	ds_read_b128 v[210:213], v152 offset:54272
	ds_read_b128 v[214:217], v152 offset:55296
	ds_read_b128 v[218:221], v152 offset:56320
	global_load_lds_dwordx4 v132, s[98:99]
	s_add_i32 m0, s46, 0x2000
	s_add_u32 s42, s42, 0x40080
	s_addc_u32 s43, s43, 0
	s_add_i32 s46, s74, s55
	global_load_lds_dwordx4 v128, s[98:99]
	s_mov_b32 m0, s46
	s_nop 0
	global_load_lds_dwordx4 v132, s[42:43]
	s_add_i32 m0, s46, 0x2000
	s_nop 0
	global_load_lds_dwordx4 v128, s[42:43]
	s_mov_b32 m0, s61
	s_nop 0
	global_load_lds_dwordx4 v134, s[100:101]
	s_mov_b32 m0, s62
	s_nop 0
	global_load_lds_dwordx4 v130, s[100:101]
	s_waitcnt vmcnt(8)
	s_waitcnt lgkmcnt(0)
	s_barrier
	v_mfma_f32_16x16x32_bf16 v[60:63], v[154:157], v[186:189], v[60:63]
	v_mfma_f32_16x16x32_bf16 v[52:55], v[162:165], v[186:189], v[52:55]
	v_mfma_f32_16x16x32_bf16 v[44:47], v[154:157], v[198:201], v[44:47]
	v_mfma_f32_16x16x32_bf16 v[36:39], v[162:165], v[198:201], v[36:39]
	v_mfma_f32_16x16x32_bf16 v[28:31], v[154:157], v[206:209], v[28:31]
	v_mfma_f32_16x16x32_bf16 v[20:23], v[162:165], v[206:209], v[20:23]
	v_mfma_f32_16x16x32_bf16 v[12:15], v[154:157], v[214:217], v[12:15]
	v_mfma_f32_16x16x32_bf16 v[4:7], v[162:165], v[214:217], v[4:7]
	v_mfma_f32_16x16x32_bf16 v[60:63], v[158:161], v[190:193], v[60:63]
	v_mfma_f32_16x16x32_bf16 v[52:55], v[166:169], v[190:193], v[52:55]
	v_mfma_f32_16x16x32_bf16 v[44:47], v[158:161], v[202:205], v[44:47]
	v_mfma_f32_16x16x32_bf16 v[36:39], v[166:169], v[202:205], v[36:39]
	v_mfma_f32_16x16x32_bf16 v[28:31], v[158:161], v[210:213], v[28:31]
	v_mfma_f32_16x16x32_bf16 v[20:23], v[166:169], v[210:213], v[20:23]
	v_mfma_f32_16x16x32_bf16 v[12:15], v[158:161], v[218:221], v[12:15]
	v_mfma_f32_16x16x32_bf16 v[4:7], v[166:169], v[218:221], v[4:7]
	v_mfma_f32_16x16x32_bf16 v[56:59], v[170:173], v[186:189], v[56:59]
	v_mfma_f32_16x16x32_bf16 v[48:51], v[178:181], v[186:189], v[48:51]
	v_mfma_f32_16x16x32_bf16 v[40:43], v[170:173], v[198:201], v[40:43]
	v_mfma_f32_16x16x32_bf16 v[32:35], v[178:181], v[198:201], v[32:35]
	v_mfma_f32_16x16x32_bf16 v[24:27], v[170:173], v[206:209], v[24:27]
	v_mfma_f32_16x16x32_bf16 v[16:19], v[178:181], v[206:209], v[16:19]
	v_mfma_f32_16x16x32_bf16 v[8:11], v[170:173], v[214:217], v[8:11]
	v_mfma_f32_16x16x32_bf16 v[0:3], v[178:181], v[214:217], v[0:3]
	v_mfma_f32_16x16x32_bf16 v[56:59], v[174:177], v[190:193], v[56:59]
	v_mfma_f32_16x16x32_bf16 v[48:51], v[182:185], v[190:193], v[48:51]
	v_mfma_f32_16x16x32_bf16 v[40:43], v[174:177], v[202:205], v[40:43]
	v_mfma_f32_16x16x32_bf16 v[32:35], v[182:185], v[202:205], v[32:35]
	v_mfma_f32_16x16x32_bf16 v[24:27], v[174:177], v[210:213], v[24:27]
	v_mfma_f32_16x16x32_bf16 v[16:19], v[182:185], v[210:213], v[16:19]
	v_mfma_f32_16x16x32_bf16 v[8:11], v[174:177], v[218:221], v[8:11]
	v_mfma_f32_16x16x32_bf16 v[0:3], v[182:185], v[218:221], v[0:3]
	s_barrier
	s_add_i32 s72, s72, 2
	s_add_u32 s20, s20, 0x100
	s_addc_u32 s21, s21, 0
	s_add_u32 s70, s70, 0x100
	s_addc_u32 s71, s71, 0
	s_cmp_gt_u32 s72, 13
.LBB0_224:
	ds_read_b128 v[154:157], v150
	ds_read_b128 v[158:161], v150 offset:1024
	ds_read_b128 v[162:165], v150 offset:2048
	ds_read_b128 v[166:169], v150 offset:3072
	ds_read_b128 v[170:173], v151
	ds_read_b128 v[174:177], v151 offset:1024
	ds_read_b128 v[178:181], v151 offset:2048
	ds_read_b128 v[182:185], v151 offset:3072
	s_add_u32 s42, s20, 0xfffc0080
	s_addc_u32 s43, s21, -1
	s_cmp_eq_u32 s72, 12
	s_cselect_b32 s47, s15, s43
	s_cselect_b32 s46, s68, s42
	s_cselect_b32 s43, s13, s71
	s_cselect_b32 s42, s69, s70
	s_add_i32 m0, s35, 0xc000
	ds_read_b128 v[186:189], v152
	ds_read_b128 v[190:193], v152 offset:1024
	ds_read_b128 v[198:201], v152 offset:2048
	ds_read_b128 v[202:205], v152 offset:3072
	ds_read_b128 v[206:209], v152 offset:4096
	ds_read_b128 v[210:213], v152 offset:5120
	ds_read_b128 v[214:217], v152 offset:6144
	ds_read_b128 v[218:221], v152 offset:7168
	global_load_lds_dwordx4 v136, s[20:21]
	s_add_i32 m0, s35, 0xe000
	s_nop 0
	global_load_lds_dwordx4 v138, s[20:21]
	s_waitcnt vmcnt(8)
	s_waitcnt lgkmcnt(0)
	s_barrier
	v_mfma_f32_16x16x32_bf16 v[124:127], v[154:157], v[186:189], v[124:127]
	v_mfma_f32_16x16x32_bf16 v[116:119], v[162:165], v[186:189], v[116:119]
	v_mfma_f32_16x16x32_bf16 v[108:111], v[154:157], v[198:201], v[108:111]
	v_mfma_f32_16x16x32_bf16 v[100:103], v[162:165], v[198:201], v[100:103]
	v_mfma_f32_16x16x32_bf16 v[92:95], v[154:157], v[206:209], v[92:95]
	v_mfma_f32_16x16x32_bf16 v[84:87], v[162:165], v[206:209], v[84:87]
	v_mfma_f32_16x16x32_bf16 v[76:79], v[154:157], v[214:217], v[76:79]
	v_mfma_f32_16x16x32_bf16 v[68:71], v[162:165], v[214:217], v[68:71]
	v_mfma_f32_16x16x32_bf16 v[124:127], v[158:161], v[190:193], v[124:127]
	v_mfma_f32_16x16x32_bf16 v[116:119], v[166:169], v[190:193], v[116:119]
	v_mfma_f32_16x16x32_bf16 v[108:111], v[158:161], v[202:205], v[108:111]
	v_mfma_f32_16x16x32_bf16 v[100:103], v[166:169], v[202:205], v[100:103]
	v_mfma_f32_16x16x32_bf16 v[92:95], v[158:161], v[210:213], v[92:95]
	v_mfma_f32_16x16x32_bf16 v[84:87], v[166:169], v[210:213], v[84:87]
	v_mfma_f32_16x16x32_bf16 v[76:79], v[158:161], v[218:221], v[76:79]
	v_mfma_f32_16x16x32_bf16 v[68:71], v[166:169], v[218:221], v[68:71]
	v_mfma_f32_16x16x32_bf16 v[120:123], v[170:173], v[186:189], v[120:123]
	v_mfma_f32_16x16x32_bf16 v[112:115], v[178:181], v[186:189], v[112:115]
	v_mfma_f32_16x16x32_bf16 v[104:107], v[170:173], v[198:201], v[104:107]
	v_mfma_f32_16x16x32_bf16 v[96:99], v[178:181], v[198:201], v[96:99]
	v_mfma_f32_16x16x32_bf16 v[88:91], v[170:173], v[206:209], v[88:91]
	v_mfma_f32_16x16x32_bf16 v[80:83], v[178:181], v[206:209], v[80:83]
	v_mfma_f32_16x16x32_bf16 v[72:75], v[170:173], v[214:217], v[72:75]
	v_mfma_f32_16x16x32_bf16 v[64:67], v[178:181], v[214:217], v[64:67]
	v_mfma_f32_16x16x32_bf16 v[120:123], v[174:177], v[190:193], v[120:123]
	v_mfma_f32_16x16x32_bf16 v[112:115], v[182:185], v[190:193], v[112:115]
	v_mfma_f32_16x16x32_bf16 v[104:107], v[174:177], v[202:205], v[104:107]
	v_mfma_f32_16x16x32_bf16 v[96:99], v[182:185], v[202:205], v[96:99]
	v_mfma_f32_16x16x32_bf16 v[88:91], v[174:177], v[210:213], v[88:91]
	v_mfma_f32_16x16x32_bf16 v[80:83], v[182:185], v[210:213], v[80:83]
	v_mfma_f32_16x16x32_bf16 v[72:75], v[174:177], v[218:221], v[72:75]
	v_mfma_f32_16x16x32_bf16 v[64:67], v[182:185], v[218:221], v[64:67]
	s_barrier
; #define PG8_STAGE(bufoff, gbase, voff) do { _Pragma("unroll") for (int _i = 0; _i < 2; ++_i) \
;         __builtin_amdgcn_global_load_lds((const unsigned*)((const char*)(gbase) + (voff)[_i]), (PG8_LAS unsigned*)(lds + (bufoff) + ldsw + _i * 8192), 16, 0, 0); } while (0)
; #define PG8_LDA(dst, b, h) do { _Pragma("unroll") for (int m = 0; m < 4; ++m) _Pragma("unroll") for (int k = 0; k < 2; ++k) dst[m][k] = *(const PG8_LAS bf16x8*)(lds + PG8_SA(b, h) + aoff + m * 2048 + k * 1024); } while (0)
; #define PG8_LDB(dst, b, h) do { _Pragma("unroll") for (int n = 0; n < 2; ++n) _Pragma("unroll") for (int k = 0; k < 2; ++k) dst[n][k] = *(const PG8_LAS bf16x8*)(lds + PG8_SB(b, h) + boff + n * 2048 + k * 1024); } while (0)
; #define PG8_MMA(ai, bj, At, Bt) do { __builtin_amdgcn_s_setprio(1); _Pragma("unroll") for (int m = 0; m < 4; ++m) _Pragma("unroll") for (int n = 0; n < 2; ++n) _Pragma("unroll") for (int k = 0; k < 2; ++k) \
;         acc[ai][bj][m][n] = __builtin_amdgcn_mfma_f32_16x16x32_bf16(Bt[n][k], At[m][k], acc[ai][bj][m][n], 0, 0, 0); __builtin_amdgcn_s_setprio(0); } while (0)
; #define PG8_WAIT_V(n) asm volatile("s_waitcnt vmcnt(" #n ")" ::: "memory")
; #define PG8_WAIT_L(n) asm volatile("s_waitcnt lgkmcnt(" #n ")" ::: "memory")
; #define PG8_BAR __builtin_amdgcn_s_barrier()
; #define PG8_SCHED __builtin_amdgcn_sched_barrier(0)
; template <class Epi, class Sched, bool ALIGN_EPI = false, bool SP2 = false>
; __device__ __forceinline__ void gemm_phase(PG8_LAS unsigned char* lds, const Gemm g, const Sched& S, const Epi& E) {
;     ...
;             PG8_LDA(At, 0, 1); PG8_STAGE(PG8_SB(0, 0), b2, voffB); PG8_STAGE(PG8_SB(0, 1), b2 + hstep, voffB); PG8_STAGE(PG8_SA(0, 0), a2, voffA);
;             PG8_WAIT_V(8); PG8_WAIT_L(0); PG8_BAR; PG8_MMA(1, 0, At, B0); PG8_MMA(1, 1, At, B1); PG8_BAR; PG8_SCHED;
;             PG8_LDB(B0, 1, 0); PG8_LDB(B1, 1, 1); PG8_SCHED; PG8_LDA(At, 1, 0); PG8_STAGE(PG8_SA(0, 1), a2 + hstep, voffA);
	s_add_i32 s73, s63, s55
	s_add_u32 s98, s42, s8
	s_addc_u32 s99, s43, s9
	s_add_u32 s100, s46, s8
	s_addc_u32 s101, s47, s9
	s_mov_b32 m0, s73
	ds_read_b128 v[186:189], v152 offset:16384
	ds_read_b128 v[190:193], v152 offset:17408
	ds_read_b128 v[198:201], v152 offset:18432
	ds_read_b128 v[202:205], v152 offset:19456
	ds_read_b128 v[206:209], v152 offset:20480
	ds_read_b128 v[210:213], v152 offset:21504
	ds_read_b128 v[214:217], v152 offset:22528
	ds_read_b128 v[218:221], v152 offset:23552
	global_load_lds_dwordx4 v132, s[42:43]
	s_add_i32 m0, s73, 0x2000
	s_add_u32 s74, s42, 0x40000
	s_addc_u32 s75, s43, 0
	s_add_i32 s73, s64, s55
	global_load_lds_dwordx4 v128, s[42:43]
	s_mov_b32 m0, s73
	s_nop 0
	global_load_lds_dwordx4 v132, s[74:75]
	s_add_i32 m0, s73, 0x2000
	s_nop 0
	global_load_lds_dwordx4 v128, s[74:75]
	s_mov_b32 m0, s35
	s_nop 0
	global_load_lds_dwordx4 v134, s[46:47]
	s_mov_b32 m0, s57
	s_nop 0
	global_load_lds_dwordx4 v130, s[46:47]
	s_waitcnt vmcnt(8)
	s_waitcnt lgkmcnt(0)
	s_barrier
	v_mfma_f32_16x16x32_bf16 v[60:63], v[154:157], v[186:189], v[60:63]
	v_mfma_f32_16x16x32_bf16 v[52:55], v[162:165], v[186:189], v[52:55]
	v_mfma_f32_16x16x32_bf16 v[44:47], v[154:157], v[198:201], v[44:47]
	v_mfma_f32_16x16x32_bf16 v[36:39], v[162:165], v[198:201], v[36:39]
	v_mfma_f32_16x16x32_bf16 v[28:31], v[154:157], v[206:209], v[28:31]
	v_mfma_f32_16x16x32_bf16 v[20:23], v[162:165], v[206:209], v[20:23]
	v_mfma_f32_16x16x32_bf16 v[12:15], v[154:157], v[214:217], v[12:15]
	v_mfma_f32_16x16x32_bf16 v[4:7], v[162:165], v[214:217], v[4:7]
	v_mfma_f32_16x16x32_bf16 v[60:63], v[158:161], v[190:193], v[60:63]
	v_mfma_f32_16x16x32_bf16 v[52:55], v[166:169], v[190:193], v[52:55]
	v_mfma_f32_16x16x32_bf16 v[44:47], v[158:161], v[202:205], v[44:47]
	v_mfma_f32_16x16x32_bf16 v[36:39], v[166:169], v[202:205], v[36:39]
	v_mfma_f32_16x16x32_bf16 v[28:31], v[158:161], v[210:213], v[28:31]
	v_mfma_f32_16x16x32_bf16 v[20:23], v[166:169], v[210:213], v[20:23]
	v_mfma_f32_16x16x32_bf16 v[12:15], v[158:161], v[218:221], v[12:15]
	v_mfma_f32_16x16x32_bf16 v[4:7], v[166:169], v[218:221], v[4:7]
	v_mfma_f32_16x16x32_bf16 v[56:59], v[170:173], v[186:189], v[56:59]
	v_mfma_f32_16x16x32_bf16 v[48:51], v[178:181], v[186:189], v[48:51]
	v_mfma_f32_16x16x32_bf16 v[40:43], v[170:173], v[198:201], v[40:43]
	v_mfma_f32_16x16x32_bf16 v[32:35], v[178:181], v[198:201], v[32:35]
	v_mfma_f32_16x16x32_bf16 v[24:27], v[170:173], v[206:209], v[24:27]
	v_mfma_f32_16x16x32_bf16 v[16:19], v[178:181], v[206:209], v[16:19]
	v_mfma_f32_16x16x32_bf16 v[8:11], v[170:173], v[214:217], v[8:11]
	v_mfma_f32_16x16x32_bf16 v[0:3], v[178:181], v[214:217], v[0:3]
	v_mfma_f32_16x16x32_bf16 v[56:59], v[174:177], v[190:193], v[56:59]
	v_mfma_f32_16x16x32_bf16 v[48:51], v[182:185], v[190:193], v[48:51]
	v_mfma_f32_16x16x32_bf16 v[40:43], v[174:177], v[202:205], v[40:43]
	v_mfma_f32_16x16x32_bf16 v[32:35], v[182:185], v[202:205], v[32:35]
	v_mfma_f32_16x16x32_bf16 v[24:27], v[174:177], v[210:213], v[24:27]
	v_mfma_f32_16x16x32_bf16 v[16:19], v[182:185], v[210:213], v[16:19]
	v_mfma_f32_16x16x32_bf16 v[8:11], v[174:177], v[218:221], v[8:11]
	v_mfma_f32_16x16x32_bf16 v[0:3], v[182:185], v[218:221], v[0:3]
	s_barrier
	s_add_i32 s73, 0, 0x18000
	v_add_u32_e32 v153, s73, v147
	s_add_i32 s74, 0, 0x1c000
	ds_read_b128 v[154:157], v153
	ds_read_b128 v[158:161], v153 offset:1024
	ds_read_b128 v[162:165], v153 offset:2048
	ds_read_b128 v[166:169], v153 offset:3072
	v_add_u32_e32 v153, s74, v147
	ds_read_b128 v[170:173], v153
	ds_read_b128 v[174:177], v153 offset:1024
	ds_read_b128 v[178:181], v153 offset:2048
	ds_read_b128 v[182:185], v153 offset:3072
	s_add_u32 s46, s46, 0x40000
	s_addc_u32 s47, s47, 0
	s_mov_b32 m0, s58
	ds_read_b128 v[186:189], v152 offset:32768
	ds_read_b128 v[190:193], v152 offset:33792
	ds_read_b128 v[198:201], v152 offset:34816
	ds_read_b128 v[202:205], v152 offset:35840
	ds_read_b128 v[206:209], v152 offset:36864
	ds_read_b128 v[210:213], v152 offset:37888
	ds_read_b128 v[214:217], v152 offset:38912
	ds_read_b128 v[218:221], v152 offset:39936
	global_load_lds_dwordx4 v134, s[46:47]
	s_mov_b32 m0, s59
	s_nop 0
	global_load_lds_dwordx4 v130, s[46:47]
	s_waitcnt vmcnt(8)
	s_waitcnt lgkmcnt(0)
	s_barrier
; #define PG8_STAGE(bufoff, gbase, voff) do { _Pragma("unroll") for (int _i = 0; _i < 2; ++_i) \
;         __builtin_amdgcn_global_load_lds((const unsigned*)((const char*)(gbase) + (voff)[_i]), (PG8_LAS unsigned*)(lds + (bufoff) + ldsw + _i * 8192), 16, 0, 0); } while (0)
; #define PG8_LDA(dst, b, h) do { _Pragma("unroll") for (int m = 0; m < 4; ++m) _Pragma("unroll") for (int k = 0; k < 2; ++k) dst[m][k] = *(const PG8_LAS bf16x8*)(lds + PG8_SA(b, h) + aoff + m * 2048 + k * 1024); } while (0)
; #define PG8_LDB(dst, b, h) do { _Pragma("unroll") for (int n = 0; n < 2; ++n) _Pragma("unroll") for (int k = 0; k < 2; ++k) dst[n][k] = *(const PG8_LAS bf16x8*)(lds + PG8_SB(b, h) + boff + n * 2048 + k * 1024); } while (0)
; #define PG8_MMA(ai, bj, At, Bt) do { __builtin_amdgcn_s_setprio(1); _Pragma("unroll") for (int m = 0; m < 4; ++m) _Pragma("unroll") for (int n = 0; n < 2; ++n) _Pragma("unroll") for (int k = 0; k < 2; ++k) \
;         acc[ai][bj][m][n] = __builtin_amdgcn_mfma_f32_16x16x32_bf16(Bt[n][k], At[m][k], acc[ai][bj][m][n], 0, 0, 0); __builtin_amdgcn_s_setprio(0); } while (0)
; #define PG8_WAIT_V(n) asm volatile("s_waitcnt vmcnt(" #n ")" ::: "memory")
; #define PG8_WAIT_L(n) asm volatile("s_waitcnt lgkmcnt(" #n ")" ::: "memory")
; #define PG8_BAR __builtin_amdgcn_s_barrier()
; #define PG8_SCHED __builtin_amdgcn_sched_barrier(0)
; template <class Epi, class Sched, bool ALIGN_EPI = false, bool SP2 = false>
; __device__ __forceinline__ void gemm_phase(PG8_LAS unsigned char* lds, const Gemm g, const Sched& S, const Epi& E) {
;     ...
;             PG8_LDB(B0, 1, 0); PG8_LDB(B1, 1, 1); PG8_SCHED; PG8_LDA(At, 1, 0); PG8_STAGE(PG8_SA(0, 1), a2 + hstep, voffA);
;             PG8_WAIT_V(8); PG8_WAIT_L(0); PG8_BAR; PG8_MMA(0, 0, At, B0); PG8_MMA(0, 1, At, B1); PG8_BAR; PG8_SCHED;
;             PG8_LDA(At, 1, 1); PG8_STAGE(PG8_SB(1, 0), b3, voffB); PG8_STAGE(PG8_SB(1, 1), b3 + hstep, voffB); PG8_STAGE(PG8_SA(1, 0), a3, voffA);
;             PG8_WAIT_V(8); PG8_WAIT_L(0); PG8_BAR; PG8_MMA(1, 0, At, B0); PG8_MMA(1, 1, At, B1); PG8_BAR; PG8_SCHED;
;     ...
;         if constexpr (ALIGN_EPI) { if (wr == 0) PG8_BAR; }
	v_mfma_f32_16x16x32_bf16 v[124:127], v[154:157], v[186:189], v[124:127]
	v_mfma_f32_16x16x32_bf16 v[116:119], v[162:165], v[186:189], v[116:119]
	v_mfma_f32_16x16x32_bf16 v[108:111], v[154:157], v[198:201], v[108:111]
	v_mfma_f32_16x16x32_bf16 v[100:103], v[162:165], v[198:201], v[100:103]
	v_mfma_f32_16x16x32_bf16 v[92:95], v[154:157], v[206:209], v[92:95]
	v_mfma_f32_16x16x32_bf16 v[84:87], v[162:165], v[206:209], v[84:87]
	v_mfma_f32_16x16x32_bf16 v[76:79], v[154:157], v[214:217], v[76:79]
	v_mfma_f32_16x16x32_bf16 v[68:71], v[162:165], v[214:217], v[68:71]
	v_mfma_f32_16x16x32_bf16 v[124:127], v[158:161], v[190:193], v[124:127]
	v_mfma_f32_16x16x32_bf16 v[116:119], v[166:169], v[190:193], v[116:119]
	v_mfma_f32_16x16x32_bf16 v[108:111], v[158:161], v[202:205], v[108:111]
	v_mfma_f32_16x16x32_bf16 v[100:103], v[166:169], v[202:205], v[100:103]
	v_mfma_f32_16x16x32_bf16 v[92:95], v[158:161], v[210:213], v[92:95]
	v_mfma_f32_16x16x32_bf16 v[84:87], v[166:169], v[210:213], v[84:87]
	v_mfma_f32_16x16x32_bf16 v[76:79], v[158:161], v[218:221], v[76:79]
	v_mfma_f32_16x16x32_bf16 v[68:71], v[166:169], v[218:221], v[68:71]
	v_mfma_f32_16x16x32_bf16 v[120:123], v[170:173], v[186:189], v[120:123]
	v_mfma_f32_16x16x32_bf16 v[112:115], v[178:181], v[186:189], v[112:115]
	v_mfma_f32_16x16x32_bf16 v[104:107], v[170:173], v[198:201], v[104:107]
	v_mfma_f32_16x16x32_bf16 v[96:99], v[178:181], v[198:201], v[96:99]
	v_mfma_f32_16x16x32_bf16 v[88:91], v[170:173], v[206:209], v[88:91]
	v_mfma_f32_16x16x32_bf16 v[80:83], v[178:181], v[206:209], v[80:83]
	v_mfma_f32_16x16x32_bf16 v[72:75], v[170:173], v[214:217], v[72:75]
	v_mfma_f32_16x16x32_bf16 v[64:67], v[178:181], v[214:217], v[64:67]
	v_mfma_f32_16x16x32_bf16 v[120:123], v[174:177], v[190:193], v[120:123]
	v_mfma_f32_16x16x32_bf16 v[112:115], v[182:185], v[190:193], v[112:115]
	v_mfma_f32_16x16x32_bf16 v[104:107], v[174:177], v[202:205], v[104:107]
	v_mfma_f32_16x16x32_bf16 v[96:99], v[182:185], v[202:205], v[96:99]
	v_mfma_f32_16x16x32_bf16 v[88:91], v[174:177], v[210:213], v[88:91]
	v_mfma_f32_16x16x32_bf16 v[80:83], v[182:185], v[210:213], v[80:83]
	v_mfma_f32_16x16x32_bf16 v[72:75], v[174:177], v[218:221], v[72:75]
	v_mfma_f32_16x16x32_bf16 v[64:67], v[182:185], v[218:221], v[64:67]
	s_barrier
	s_add_i32 s46, s73, s55
	s_mov_b32 m0, s46
	ds_read_b128 v[186:189], v152 offset:49152
	ds_read_b128 v[190:193], v152 offset:50176
	ds_read_b128 v[198:201], v152 offset:51200
	ds_read_b128 v[202:205], v152 offset:52224
	ds_read_b128 v[206:209], v152 offset:53248
	ds_read_b128 v[210:213], v152 offset:54272
	ds_read_b128 v[214:217], v152 offset:55296
	ds_read_b128 v[218:221], v152 offset:56320
	global_load_lds_dwordx4 v132, s[98:99]
	s_add_i32 m0, s46, 0x2000
	s_add_u32 s42, s42, 0x40080
	s_addc_u32 s43, s43, 0
	s_add_i32 s46, s74, s55
	global_load_lds_dwordx4 v128, s[98:99]
	s_mov_b32 m0, s46
	s_nop 0
	global_load_lds_dwordx4 v132, s[42:43]
	s_add_i32 m0, s46, 0x2000
	s_nop 0
	global_load_lds_dwordx4 v128, s[42:43]
	s_mov_b32 m0, s61
	s_nop 0
	global_load_lds_dwordx4 v134, s[100:101]
	s_mov_b32 m0, s62
	s_nop 0
	global_load_lds_dwordx4 v130, s[100:101]
	s_waitcnt vmcnt(8)
	s_waitcnt lgkmcnt(0)
	s_barrier
	v_mfma_f32_16x16x32_bf16 v[60:63], v[154:157], v[186:189], v[60:63]
	v_mfma_f32_16x16x32_bf16 v[52:55], v[162:165], v[186:189], v[52:55]
	v_mfma_f32_16x16x32_bf16 v[44:47], v[154:157], v[198:201], v[44:47]
	v_mfma_f32_16x16x32_bf16 v[36:39], v[162:165], v[198:201], v[36:39]
	v_mfma_f32_16x16x32_bf16 v[28:31], v[154:157], v[206:209], v[28:31]
	v_mfma_f32_16x16x32_bf16 v[20:23], v[162:165], v[206:209], v[20:23]
	v_mfma_f32_16x16x32_bf16 v[12:15], v[154:157], v[214:217], v[12:15]
	v_mfma_f32_16x16x32_bf16 v[4:7], v[162:165], v[214:217], v[4:7]
	v_mfma_f32_16x16x32_bf16 v[60:63], v[158:161], v[190:193], v[60:63]
	v_mfma_f32_16x16x32_bf16 v[52:55], v[166:169], v[190:193], v[52:55]
	v_mfma_f32_16x16x32_bf16 v[44:47], v[158:161], v[202:205], v[44:47]
	v_mfma_f32_16x16x32_bf16 v[36:39], v[166:169], v[202:205], v[36:39]
	v_mfma_f32_16x16x32_bf16 v[28:31], v[158:161], v[210:213], v[28:31]
	v_mfma_f32_16x16x32_bf16 v[20:23], v[166:169], v[210:213], v[20:23]
	v_mfma_f32_16x16x32_bf16 v[12:15], v[158:161], v[218:221], v[12:15]
	v_mfma_f32_16x16x32_bf16 v[4:7], v[166:169], v[218:221], v[4:7]
	v_mfma_f32_16x16x32_bf16 v[56:59], v[170:173], v[186:189], v[56:59]
	v_mfma_f32_16x16x32_bf16 v[48:51], v[178:181], v[186:189], v[48:51]
	v_mfma_f32_16x16x32_bf16 v[40:43], v[170:173], v[198:201], v[40:43]
	v_mfma_f32_16x16x32_bf16 v[32:35], v[178:181], v[198:201], v[32:35]
	v_mfma_f32_16x16x32_bf16 v[24:27], v[170:173], v[206:209], v[24:27]
	v_mfma_f32_16x16x32_bf16 v[16:19], v[178:181], v[206:209], v[16:19]
	v_mfma_f32_16x16x32_bf16 v[8:11], v[170:173], v[214:217], v[8:11]
	v_mfma_f32_16x16x32_bf16 v[0:3], v[178:181], v[214:217], v[0:3]
	v_mfma_f32_16x16x32_bf16 v[56:59], v[174:177], v[190:193], v[56:59]
	v_mfma_f32_16x16x32_bf16 v[48:51], v[182:185], v[190:193], v[48:51]
	v_mfma_f32_16x16x32_bf16 v[40:43], v[174:177], v[202:205], v[40:43]
	v_mfma_f32_16x16x32_bf16 v[32:35], v[182:185], v[202:205], v[32:35]
	v_mfma_f32_16x16x32_bf16 v[24:27], v[174:177], v[210:213], v[24:27]
	v_mfma_f32_16x16x32_bf16 v[16:19], v[182:185], v[210:213], v[16:19]
	v_mfma_f32_16x16x32_bf16 v[8:11], v[174:177], v[218:221], v[8:11]
	v_mfma_f32_16x16x32_bf16 v[0:3], v[182:185], v[218:221], v[0:3]
	s_barrier
	s_add_i32 s72, s72, 2
	s_add_u32 s20, s20, 0x100
	s_addc_u32 s21, s21, 0
	s_add_u32 s70, s70, 0x100
	s_addc_u32 s71, s71, 0
	s_cmp_gt_u32 s72, 13
	s_cbranch_scc0 .LBB0_224
	s_and_b64 vcc, exec, s[10:11]
	s_cbranch_vccz .LBB0_227
	s_barrier

; #define PG8_STAGE(bufoff, gbase, voff) do { _Pragma("unroll") for (int _i = 0; _i < 2; ++_i) \
;         __builtin_amdgcn_global_load_lds((const unsigned*)((const char*)(gbase) + (voff)[_i]), (PG8_LAS unsigned*)(lds + (bufoff) + ldsw + _i * 8192), 16, 0, 0); } while (0)
; #define PG8_LDA(dst, b, h) do { _Pragma("unroll") for (int m = 0; m < 4; ++m) _Pragma("unroll") for (int k = 0; k < 2; ++k) dst[m][k] = *(const PG8_LAS bf16x8*)(lds + PG8_SA(b, h) + aoff + m * 2048 + k * 1024); } while (0)
; #define PG8_LDB(dst, b, h) do { _Pragma("unroll") for (int n = 0; n < 2; ++n) _Pragma("unroll") for (int k = 0; k < 2; ++k) dst[n][k] = *(const PG8_LAS bf16x8*)(lds + PG8_SB(b, h) + boff + n * 2048 + k * 1024); } while (0)
; #define PG8_WAIT_V(n) asm volatile("s_waitcnt vmcnt(" #n ")" ::: "memory")
; #define PG8_WAIT_L(n) asm volatile("s_waitcnt lgkmcnt(" #n ")" ::: "memory")
; #define PG8_BAR __builtin_amdgcn_s_barrier()
; #define PG8_SCHED __builtin_amdgcn_sched_barrier(0)
; template <class Epi, class Sched, bool ALIGN_EPI = false, bool SP2 = false>
; __device__ __forceinline__ void gemm_phase(PG8_LAS unsigned char* lds, const Gemm g, const Sched& S, const Epi& E) {
;     ...
;         const char* nA = has_next ? (const char*)g.A + (size_t)nxt.pm * tstep : cA; const char* nB = has_next ? (const char*)g.Bt + (size_t)nxt.pn * tstep : cB;
;         for (int t = 0; t < nt; t += 2) {
;             const bool last = (t == nt - 2);
;             const char* a1 = cA + (size_t)(t + 1) * kstep;
;             const char* a2 = last ? nA : cA + (size_t)(t + 2) * kstep; const char* b2 = last ? nB : cB + (size_t)(t + 2) * kstep;
;             const char* a3 = a2 + kstep; const char* b3 = b2 + kstep;
;             if (last && has_next) S.a_ready(nxt);
;             if constexpr (SP2) {
;             PG8_LDB(B0, 0, 0); PG8_LDB(B1, 0, 1); PG8_SCHED; PG8_LDA(At, 0, 0); PG8_STAGE(PG8_SA(1, 1), a1 + hstep, voffA);
;             PG8_WAIT_V(8); PG8_WAIT_L(0); PG8_BAR; PG8_MMA(0, 0, At, B0); PG8_MMA(0, 1, At, B1); PG8_BAR; PG8_SCHED;
;             PG8_LDA(At, 0, 1); PG8_STAGE(PG8_SB(0, 0), b2, voffB); PG8_STAGE(PG8_SB(0, 1), b2 + hstep, voffB); PG8_STAGE(PG8_SA(0, 0), a2, voffA);
;             PG8_WAIT_V(8); PG8_WAIT_L(0); PG8_BAR; PG8_MMA(1, 0, At, B0); PG8_MMA(1, 1, At, B1); PG8_BAR; PG8_SCHED;
.LBB0_308:
	s_add_u32 s20, s20, 0xb0080
	s_addc_u32 s21, s21, 0
	s_add_u32 s73, s34, 0x100
	s_addc_u32 s74, s35, 0
	s_mov_b32 s75, -2
	s_waitcnt lgkmcnt(0)
	s_waitcnt lgkmcnt(0)
	ds_read_b128 v[96:99], v223
	ds_read_b128 v[108:111], v223 offset:1024
	ds_read_b128 v[120:123], v223 offset:2048
	ds_read_b128 v[128:131], v223 offset:3072
	ds_read_b128 v[144:147], v224
	ds_read_b128 v[148:151], v224 offset:1024
	ds_read_b128 v[152:155], v224 offset:2048
	ds_read_b128 v[156:159], v224 offset:3072
	s_add_u32 s34, s20, 0xfff50080
	s_addc_u32 s35, s21, -1
	s_cmp_eq_u32 s75, 40
	s_cselect_b32 s51, s1, s35
	s_cselect_b32 s50, s0, s34
	s_cselect_b32 s35, s49, s74
	s_cselect_b32 s34, s48, s73
	s_add_i32 m0, s54, 0xc000
	ds_read_b128 v[160:163], v225
	ds_read_b128 v[164:167], v225 offset:1024
	ds_read_b128 v[168:171], v225 offset:2048
	ds_read_b128 v[172:175], v225 offset:3072
	ds_read_b128 v[176:179], v225 offset:4096
	ds_read_b128 v[180:183], v225 offset:5120
	ds_read_b128 v[202:205], v225 offset:6144
	ds_read_b128 v[206:209], v225 offset:7168
	global_load_lds_dwordx4 v192, s[20:21]
	s_add_i32 m0, s54, 0xe000
	s_nop 0
	global_load_lds_dwordx4 v194, s[20:21]
	s_waitcnt vmcnt(8)
	s_waitcnt lgkmcnt(0)
	s_barrier
	v_mfma_f32_16x16x32_bf16 v[140:143], v[96:99], v[160:163], 0
	v_mfma_f32_16x16x32_bf16 v[136:139], v[120:123], v[160:163], 0
	v_mfma_f32_16x16x32_bf16 v[116:119], v[96:99], v[168:171], 0
	v_mfma_f32_16x16x32_bf16 v[112:115], v[120:123], v[168:171], 0
	v_mfma_f32_16x16x32_bf16 v[92:95], v[96:99], v[176:179], 0
	v_mfma_f32_16x16x32_bf16 v[88:91], v[120:123], v[176:179], 0
	v_mfma_f32_16x16x32_bf16 v[76:79], v[96:99], v[202:205], 0
	v_mfma_f32_16x16x32_bf16 v[72:75], v[120:123], v[202:205], 0
	v_mfma_f32_16x16x32_bf16 v[140:143], v[108:111], v[164:167], v[140:143]
	v_mfma_f32_16x16x32_bf16 v[136:139], v[128:131], v[164:167], v[136:139]
	v_mfma_f32_16x16x32_bf16 v[116:119], v[108:111], v[172:175], v[116:119]
	v_mfma_f32_16x16x32_bf16 v[112:115], v[128:131], v[172:175], v[112:115]
	v_mfma_f32_16x16x32_bf16 v[92:95], v[108:111], v[180:183], v[92:95]
	v_mfma_f32_16x16x32_bf16 v[88:91], v[128:131], v[180:183], v[88:91]
	v_mfma_f32_16x16x32_bf16 v[76:79], v[108:111], v[206:209], v[76:79]
	v_mfma_f32_16x16x32_bf16 v[72:75], v[128:131], v[206:209], v[72:75]
	v_mfma_f32_16x16x32_bf16 v[132:135], v[144:147], v[160:163], 0
	v_mfma_f32_16x16x32_bf16 v[124:127], v[152:155], v[160:163], 0
	v_mfma_f32_16x16x32_bf16 v[104:107], v[144:147], v[168:171], 0
	v_mfma_f32_16x16x32_bf16 v[100:103], v[152:155], v[168:171], 0
	v_mfma_f32_16x16x32_bf16 v[84:87], v[144:147], v[176:179], 0
	v_mfma_f32_16x16x32_bf16 v[80:83], v[152:155], v[176:179], 0
	v_mfma_f32_16x16x32_bf16 v[68:71], v[144:147], v[202:205], 0
	v_mfma_f32_16x16x32_bf16 v[64:67], v[152:155], v[202:205], 0
	v_mfma_f32_16x16x32_bf16 v[132:135], v[148:151], v[164:167], v[132:135]
	v_mfma_f32_16x16x32_bf16 v[124:127], v[156:159], v[164:167], v[124:127]
	v_mfma_f32_16x16x32_bf16 v[104:107], v[148:151], v[172:175], v[104:107]
	v_mfma_f32_16x16x32_bf16 v[100:103], v[156:159], v[172:175], v[100:103]
	v_mfma_f32_16x16x32_bf16 v[84:87], v[148:151], v[180:183], v[84:87]
	v_mfma_f32_16x16x32_bf16 v[80:83], v[156:159], v[180:183], v[80:83]
	v_mfma_f32_16x16x32_bf16 v[68:71], v[148:151], v[206:209], v[68:71]
	v_mfma_f32_16x16x32_bf16 v[64:67], v[156:159], v[206:209], v[64:67]
	s_barrier
	s_add_i32 s76, s67, s53
	s_add_u32 s98, s34, s12
	s_addc_u32 s99, s35, s13
	s_add_u32 s100, s50, s12
	s_addc_u32 s101, s51, s13
	s_mov_b32 m0, s76
	ds_read_b128 v[160:163], v225 offset:16384
	ds_read_b128 v[164:167], v225 offset:17408
	ds_read_b128 v[168:171], v225 offset:18432
	ds_read_b128 v[172:175], v225 offset:19456
	ds_read_b128 v[176:179], v225 offset:20480
	ds_read_b128 v[180:183], v225 offset:21504
	ds_read_b128 v[202:205], v225 offset:22528
	ds_read_b128 v[206:209], v225 offset:23552
	global_load_lds_dwordx4 v186, s[34:35]
	s_add_i32 m0, s76, 0x2000
	s_add_u32 s76, s34, 0xb0000
	s_addc_u32 s77, s35, 0
	s_add_i32 s78, s68, s53
	global_load_lds_dwordx4 v190, s[34:35]
	s_mov_b32 m0, s78
	s_nop 0
	global_load_lds_dwordx4 v186, s[76:77]
	s_add_i32 m0, s78, 0x2000
	s_nop 0
	global_load_lds_dwordx4 v190, s[76:77]
	s_mov_b32 m0, s54
	s_nop 0
	global_load_lds_dwordx4 v184, s[50:51]
	s_mov_b32 m0, s55
	s_nop 0
	global_load_lds_dwordx4 v188, s[50:51]
	s_waitcnt vmcnt(8)
	s_waitcnt lgkmcnt(0)
	s_barrier
	v_mfma_f32_16x16x32_bf16 v[60:63], v[96:99], v[160:163], 0
	v_mfma_f32_16x16x32_bf16 v[56:59], v[120:123], v[160:163], 0
	v_mfma_f32_16x16x32_bf16 v[44:47], v[96:99], v[168:171], 0
	v_mfma_f32_16x16x32_bf16 v[40:43], v[120:123], v[168:171], 0
	v_mfma_f32_16x16x32_bf16 v[28:31], v[96:99], v[176:179], 0
	v_mfma_f32_16x16x32_bf16 v[24:27], v[120:123], v[176:179], 0
	v_mfma_f32_16x16x32_bf16 v[12:15], v[96:99], v[202:205], 0
	v_mfma_f32_16x16x32_bf16 v[8:11], v[120:123], v[202:205], 0
	v_mfma_f32_16x16x32_bf16 v[60:63], v[108:111], v[164:167], v[60:63]
	v_mfma_f32_16x16x32_bf16 v[56:59], v[128:131], v[164:167], v[56:59]
	v_mfma_f32_16x16x32_bf16 v[44:47], v[108:111], v[172:175], v[44:47]
	v_mfma_f32_16x16x32_bf16 v[40:43], v[128:131], v[172:175], v[40:43]
	v_mfma_f32_16x16x32_bf16 v[28:31], v[108:111], v[180:183], v[28:31]
	v_mfma_f32_16x16x32_bf16 v[24:27], v[128:131], v[180:183], v[24:27]
	v_mfma_f32_16x16x32_bf16 v[12:15], v[108:111], v[206:209], v[12:15]
	v_mfma_f32_16x16x32_bf16 v[8:11], v[128:131], v[206:209], v[8:11]
	v_mfma_f32_16x16x32_bf16 v[52:55], v[144:147], v[160:163], 0
	v_mfma_f32_16x16x32_bf16 v[48:51], v[152:155], v[160:163], 0
	v_mfma_f32_16x16x32_bf16 v[36:39], v[144:147], v[168:171], 0
	v_mfma_f32_16x16x32_bf16 v[32:35], v[152:155], v[168:171], 0
	v_mfma_f32_16x16x32_bf16 v[20:23], v[144:147], v[176:179], 0
	v_mfma_f32_16x16x32_bf16 v[16:19], v[152:155], v[176:179], 0
	v_mfma_f32_16x16x32_bf16 v[4:7], v[144:147], v[202:205], 0
	v_mfma_f32_16x16x32_bf16 v[0:3], v[152:155], v[202:205], 0
	v_mfma_f32_16x16x32_bf16 v[52:55], v[148:151], v[164:167], v[52:55]
	v_mfma_f32_16x16x32_bf16 v[48:51], v[156:159], v[164:167], v[48:51]
	v_mfma_f32_16x16x32_bf16 v[36:39], v[148:151], v[172:175], v[36:39]
	v_mfma_f32_16x16x32_bf16 v[32:35], v[156:159], v[172:175], v[32:35]
	v_mfma_f32_16x16x32_bf16 v[20:23], v[148:151], v[180:183], v[20:23]
	v_mfma_f32_16x16x32_bf16 v[16:19], v[156:159], v[180:183], v[16:19]
	v_mfma_f32_16x16x32_bf16 v[4:7], v[148:151], v[206:209], v[4:7]
	v_mfma_f32_16x16x32_bf16 v[0:3], v[156:159], v[206:209], v[0:3]
	s_barrier
; #define PG8_STAGE(bufoff, gbase, voff) do { _Pragma("unroll") for (int _i = 0; _i < 2; ++_i) \
;         __builtin_amdgcn_global_load_lds((const unsigned*)((const char*)(gbase) + (voff)[_i]), (PG8_LAS unsigned*)(lds + (bufoff) + ldsw + _i * 8192), 16, 0, 0); } while (0)
; #define PG8_LDA(dst, b, h) do { _Pragma("unroll") for (int m = 0; m < 4; ++m) _Pragma("unroll") for (int k = 0; k < 2; ++k) dst[m][k] = *(const PG8_LAS bf16x8*)(lds + PG8_SA(b, h) + aoff + m * 2048 + k * 1024); } while (0)
; #define PG8_LDB(dst, b, h) do { _Pragma("unroll") for (int n = 0; n < 2; ++n) _Pragma("unroll") for (int k = 0; k < 2; ++k) dst[n][k] = *(const PG8_LAS bf16x8*)(lds + PG8_SB(b, h) + boff + n * 2048 + k * 1024); } while (0)
; #define PG8_MMA(ai, bj, At, Bt) do { __builtin_amdgcn_s_setprio(1); _Pragma("unroll") for (int m = 0; m < 4; ++m) _Pragma("unroll") for (int n = 0; n < 2; ++n) _Pragma("unroll") for (int k = 0; k < 2; ++k) \
;         acc[ai][bj][m][n] = __builtin_amdgcn_mfma_f32_16x16x32_bf16(Bt[n][k], At[m][k], acc[ai][bj][m][n], 0, 0, 0); __builtin_amdgcn_s_setprio(0); } while (0)
; #define PG8_WAIT_V(n) asm volatile("s_waitcnt vmcnt(" #n ")" ::: "memory")
; #define PG8_WAIT_L(n) asm volatile("s_waitcnt lgkmcnt(" #n ")" ::: "memory")
; #define PG8_BAR __builtin_amdgcn_s_barrier()
; #define PG8_SCHED __builtin_amdgcn_sched_barrier(0)
; template <class Epi, class Sched, bool ALIGN_EPI = false, bool SP2 = false>
; __device__ __forceinline__ void gemm_phase(PG8_LAS unsigned char* lds, const Gemm g, const Sched& S, const Epi& E) {
;     ...
;             PG8_LDB(B0, 1, 0); PG8_LDB(B1, 1, 1); PG8_SCHED; PG8_LDA(At, 1, 0); PG8_STAGE(PG8_SA(0, 1), a2 + hstep, voffA);
;             PG8_WAIT_V(8); PG8_WAIT_L(0); PG8_BAR; PG8_MMA(0, 0, At, B0); PG8_MMA(0, 1, At, B1); PG8_BAR; PG8_SCHED;
;             PG8_LDA(At, 1, 1); PG8_STAGE(PG8_SB(1, 0), b3, voffB); PG8_STAGE(PG8_SB(1, 1), b3 + hstep, voffB); PG8_STAGE(PG8_SA(1, 0), a3, voffA);
;             PG8_WAIT_V(8); PG8_WAIT_L(0); PG8_BAR; PG8_MMA(1, 0, At, B0); PG8_MMA(1, 1, At, B1); PG8_BAR; PG8_SCHED;
	s_add_i32 s76, 0, 0x18000
	s_add_i32 s77, 0, 0x1c000
	v_add_u32_e32 v128, s76, v221
	v_add_u32_e32 v156, s77, v221
	ds_read_b128 v[96:99], v128
	ds_read_b128 v[108:111], v128 offset:1024
	ds_read_b128 v[120:123], v128 offset:2048
	ds_read_b128 v[128:131], v128 offset:3072
	ds_read_b128 v[144:147], v156
	ds_read_b128 v[148:151], v156 offset:1024
	ds_read_b128 v[152:155], v156 offset:2048
	ds_read_b128 v[156:159], v156 offset:3072
	s_add_u32 s50, s50, 0xb0000
	s_addc_u32 s51, s51, 0
	s_mov_b32 m0, s56
	ds_read_b128 v[160:163], v225 offset:32768
	ds_read_b128 v[164:167], v225 offset:33792
	ds_read_b128 v[168:171], v225 offset:34816
	ds_read_b128 v[172:175], v225 offset:35840
	ds_read_b128 v[176:179], v225 offset:36864
	ds_read_b128 v[180:183], v225 offset:37888
	ds_read_b128 v[202:205], v225 offset:38912
	ds_read_b128 v[206:209], v225 offset:39936
	global_load_lds_dwordx4 v184, s[50:51]
	s_mov_b32 m0, s57
	s_nop 0
	global_load_lds_dwordx4 v188, s[50:51]
	s_waitcnt vmcnt(8)
	s_waitcnt lgkmcnt(0)
	s_barrier
	v_mfma_f32_16x16x32_bf16 v[140:143], v[96:99], v[160:163], v[140:143]
	v_mfma_f32_16x16x32_bf16 v[136:139], v[120:123], v[160:163], v[136:139]
	v_mfma_f32_16x16x32_bf16 v[116:119], v[96:99], v[168:171], v[116:119]
	v_mfma_f32_16x16x32_bf16 v[112:115], v[120:123], v[168:171], v[112:115]
	v_mfma_f32_16x16x32_bf16 v[92:95], v[96:99], v[176:179], v[92:95]
	v_mfma_f32_16x16x32_bf16 v[88:91], v[120:123], v[176:179], v[88:91]
	v_mfma_f32_16x16x32_bf16 v[76:79], v[96:99], v[202:205], v[76:79]
	v_mfma_f32_16x16x32_bf16 v[72:75], v[120:123], v[202:205], v[72:75]
	v_mfma_f32_16x16x32_bf16 v[140:143], v[108:111], v[164:167], v[140:143]
	v_mfma_f32_16x16x32_bf16 v[136:139], v[128:131], v[164:167], v[136:139]
	v_mfma_f32_16x16x32_bf16 v[116:119], v[108:111], v[172:175], v[116:119]
	v_mfma_f32_16x16x32_bf16 v[112:115], v[128:131], v[172:175], v[112:115]
	v_mfma_f32_16x16x32_bf16 v[92:95], v[108:111], v[180:183], v[92:95]
	v_mfma_f32_16x16x32_bf16 v[88:91], v[128:131], v[180:183], v[88:91]
	v_mfma_f32_16x16x32_bf16 v[76:79], v[108:111], v[206:209], v[76:79]
	v_mfma_f32_16x16x32_bf16 v[72:75], v[128:131], v[206:209], v[72:75]
	v_mfma_f32_16x16x32_bf16 v[132:135], v[144:147], v[160:163], v[132:135]
	v_mfma_f32_16x16x32_bf16 v[124:127], v[152:155], v[160:163], v[124:127]
	v_mfma_f32_16x16x32_bf16 v[104:107], v[144:147], v[168:171], v[104:107]
	v_mfma_f32_16x16x32_bf16 v[100:103], v[152:155], v[168:171], v[100:103]
	v_mfma_f32_16x16x32_bf16 v[84:87], v[144:147], v[176:179], v[84:87]
	v_mfma_f32_16x16x32_bf16 v[80:83], v[152:155], v[176:179], v[80:83]
	v_mfma_f32_16x16x32_bf16 v[68:71], v[144:147], v[202:205], v[68:71]
	v_mfma_f32_16x16x32_bf16 v[64:67], v[152:155], v[202:205], v[64:67]
	v_mfma_f32_16x16x32_bf16 v[132:135], v[148:151], v[164:167], v[132:135]
	v_mfma_f32_16x16x32_bf16 v[124:127], v[156:159], v[164:167], v[124:127]
	v_mfma_f32_16x16x32_bf16 v[104:107], v[148:151], v[172:175], v[104:107]
	v_mfma_f32_16x16x32_bf16 v[100:103], v[156:159], v[172:175], v[100:103]
	v_mfma_f32_16x16x32_bf16 v[84:87], v[148:151], v[180:183], v[84:87]
	v_mfma_f32_16x16x32_bf16 v[80:83], v[156:159], v[180:183], v[80:83]
	v_mfma_f32_16x16x32_bf16 v[68:71], v[148:151], v[206:209], v[68:71]
	v_mfma_f32_16x16x32_bf16 v[64:67], v[156:159], v[206:209], v[64:67]
	s_barrier
	s_add_i32 s50, s76, s53
	s_mov_b32 m0, s50
	ds_read_b128 v[160:163], v225 offset:49152
	ds_read_b128 v[164:167], v225 offset:50176
	ds_read_b128 v[168:171], v225 offset:51200
	ds_read_b128 v[172:175], v225 offset:52224
	ds_read_b128 v[176:179], v225 offset:53248
	ds_read_b128 v[180:183], v225 offset:54272
	ds_read_b128 v[202:205], v225 offset:55296
	ds_read_b128 v[206:209], v225 offset:56320
	global_load_lds_dwordx4 v186, s[98:99]
	s_add_i32 m0, s50, 0x2000
	s_add_u32 s34, s34, 0xb0080
	s_addc_u32 s35, s35, 0
	s_add_i32 s50, s77, s53
	global_load_lds_dwordx4 v190, s[98:99]
	s_mov_b32 m0, s50
	s_nop 0
	global_load_lds_dwordx4 v186, s[34:35]
	s_add_i32 m0, s50, 0x2000
	s_nop 0
	global_load_lds_dwordx4 v190, s[34:35]
	s_mov_b32 m0, s62
	s_nop 0
	global_load_lds_dwordx4 v184, s[100:101]
	s_mov_b32 m0, s63
	s_nop 0
	global_load_lds_dwordx4 v188, s[100:101]
	s_waitcnt vmcnt(8)
	s_waitcnt lgkmcnt(0)
	s_barrier
	v_mfma_f32_16x16x32_bf16 v[60:63], v[96:99], v[160:163], v[60:63]
	v_mfma_f32_16x16x32_bf16 v[56:59], v[120:123], v[160:163], v[56:59]
	v_mfma_f32_16x16x32_bf16 v[44:47], v[96:99], v[168:171], v[44:47]
	v_mfma_f32_16x16x32_bf16 v[40:43], v[120:123], v[168:171], v[40:43]
	v_mfma_f32_16x16x32_bf16 v[28:31], v[96:99], v[176:179], v[28:31]
	v_mfma_f32_16x16x32_bf16 v[24:27], v[120:123], v[176:179], v[24:27]
	v_mfma_f32_16x16x32_bf16 v[12:15], v[96:99], v[202:205], v[12:15]
	v_mfma_f32_16x16x32_bf16 v[8:11], v[120:123], v[202:205], v[8:11]
	v_mfma_f32_16x16x32_bf16 v[60:63], v[108:111], v[164:167], v[60:63]
	v_mfma_f32_16x16x32_bf16 v[56:59], v[128:131], v[164:167], v[56:59]
	v_mfma_f32_16x16x32_bf16 v[44:47], v[108:111], v[172:175], v[44:47]
	v_mfma_f32_16x16x32_bf16 v[40:43], v[128:131], v[172:175], v[40:43]
	v_mfma_f32_16x16x32_bf16 v[28:31], v[108:111], v[180:183], v[28:31]
	v_mfma_f32_16x16x32_bf16 v[24:27], v[128:131], v[180:183], v[24:27]
	v_mfma_f32_16x16x32_bf16 v[12:15], v[108:111], v[206:209], v[12:15]
	v_mfma_f32_16x16x32_bf16 v[8:11], v[128:131], v[206:209], v[8:11]
	v_mfma_f32_16x16x32_bf16 v[52:55], v[144:147], v[160:163], v[52:55]
	v_mfma_f32_16x16x32_bf16 v[48:51], v[152:155], v[160:163], v[48:51]
	v_mfma_f32_16x16x32_bf16 v[36:39], v[144:147], v[168:171], v[36:39]
	v_mfma_f32_16x16x32_bf16 v[32:35], v[152:155], v[168:171], v[32:35]
	v_mfma_f32_16x16x32_bf16 v[20:23], v[144:147], v[176:179], v[20:23]
	v_mfma_f32_16x16x32_bf16 v[16:19], v[152:155], v[176:179], v[16:19]
	v_mfma_f32_16x16x32_bf16 v[4:7], v[144:147], v[202:205], v[4:7]
	v_mfma_f32_16x16x32_bf16 v[0:3], v[152:155], v[202:205], v[0:3]
	v_mfma_f32_16x16x32_bf16 v[52:55], v[148:151], v[164:167], v[52:55]
	v_mfma_f32_16x16x32_bf16 v[48:51], v[156:159], v[164:167], v[48:51]
	v_mfma_f32_16x16x32_bf16 v[36:39], v[148:151], v[172:175], v[36:39]
	v_mfma_f32_16x16x32_bf16 v[32:35], v[156:159], v[172:175], v[32:35]
	v_mfma_f32_16x16x32_bf16 v[20:23], v[148:151], v[180:183], v[20:23]
	v_mfma_f32_16x16x32_bf16 v[16:19], v[156:159], v[180:183], v[16:19]
	v_mfma_f32_16x16x32_bf16 v[4:7], v[148:151], v[206:209], v[4:7]
	v_mfma_f32_16x16x32_bf16 v[0:3], v[156:159], v[206:209], v[0:3]
	s_barrier
	s_add_i32 s75, s75, 2
	s_add_u32 s20, s20, 0x100
	s_addc_u32 s21, s21, 0
	s_add_u32 s73, s73, 0x100
	s_addc_u32 s74, s74, 0
	s_cmp_gt_u32 s75, 41
; #define PG8_STAGE(bufoff, gbase, voff) do { _Pragma("unroll") for (int _i = 0; _i < 2; ++_i) \
;         __builtin_amdgcn_global_load_lds((const unsigned*)((const char*)(gbase) + (voff)[_i]), (PG8_LAS unsigned*)(lds + (bufoff) + ldsw + _i * 8192), 16, 0, 0); } while (0)
; #define PG8_LDA(dst, b, h) do { _Pragma("unroll") for (int m = 0; m < 4; ++m) _Pragma("unroll") for (int k = 0; k < 2; ++k) dst[m][k] = *(const PG8_LAS bf16x8*)(lds + PG8_SA(b, h) + aoff + m * 2048 + k * 1024); } while (0)
; #define PG8_LDB(dst, b, h) do { _Pragma("unroll") for (int n = 0; n < 2; ++n) _Pragma("unroll") for (int k = 0; k < 2; ++k) dst[n][k] = *(const PG8_LAS bf16x8*)(lds + PG8_SB(b, h) + boff + n * 2048 + k * 1024); } while (0)
; #define PG8_MMA(ai, bj, At, Bt) do { __builtin_amdgcn_s_setprio(1); _Pragma("unroll") for (int m = 0; m < 4; ++m) _Pragma("unroll") for (int n = 0; n < 2; ++n) _Pragma("unroll") for (int k = 0; k < 2; ++k) \
;         acc[ai][bj][m][n] = __builtin_amdgcn_mfma_f32_16x16x32_bf16(Bt[n][k], At[m][k], acc[ai][bj][m][n], 0, 0, 0); __builtin_amdgcn_s_setprio(0); } while (0)
; #define PG8_WAIT_V(n) asm volatile("s_waitcnt vmcnt(" #n ")" ::: "memory")
; #define PG8_WAIT_L(n) asm volatile("s_waitcnt lgkmcnt(" #n ")" ::: "memory")
; #define PG8_BAR __builtin_amdgcn_s_barrier()
; #define PG8_SCHED __builtin_amdgcn_sched_barrier(0)
; template <class Epi, class Sched, bool ALIGN_EPI = false, bool SP2 = false>
; __device__ __forceinline__ void gemm_phase(PG8_LAS unsigned char* lds, const Gemm g, const Sched& S, const Epi& E) {
;     ...
;             PG8_LDB(B0, 0, 0); PG8_LDB(B1, 0, 1); PG8_SCHED; PG8_LDA(At, 0, 0); PG8_STAGE(PG8_SA(1, 1), a1 + hstep, voffA);
;             PG8_WAIT_V(8); PG8_WAIT_L(0); PG8_BAR; PG8_MMA(0, 0, At, B0); PG8_MMA(0, 1, At, B1); PG8_BAR; PG8_SCHED;
;             PG8_LDA(At, 0, 1); PG8_STAGE(PG8_SB(0, 0), b2, voffB); PG8_STAGE(PG8_SB(0, 1), b2 + hstep, voffB); PG8_STAGE(PG8_SA(0, 0), a2, voffA);
;             PG8_WAIT_V(8); PG8_WAIT_L(0); PG8_BAR; PG8_MMA(1, 0, At, B0); PG8_MMA(1, 1, At, B1); PG8_BAR; PG8_SCHED;
.LBB0_309:
	ds_read_b128 v[96:99], v223
	ds_read_b128 v[108:111], v223 offset:1024
	ds_read_b128 v[120:123], v223 offset:2048
	ds_read_b128 v[128:131], v223 offset:3072
	ds_read_b128 v[144:147], v224
	ds_read_b128 v[148:151], v224 offset:1024
	ds_read_b128 v[152:155], v224 offset:2048
	ds_read_b128 v[156:159], v224 offset:3072
	s_add_u32 s34, s20, 0xfff50080
	s_addc_u32 s35, s21, -1
	s_cmp_eq_u32 s75, 40
	s_cselect_b32 s51, s1, s35
	s_cselect_b32 s50, s0, s34
	s_cselect_b32 s35, s49, s74
	s_cselect_b32 s34, s48, s73
	s_add_i32 m0, s54, 0xc000
	ds_read_b128 v[160:163], v225
	ds_read_b128 v[164:167], v225 offset:1024
	ds_read_b128 v[168:171], v225 offset:2048
	ds_read_b128 v[172:175], v225 offset:3072
	ds_read_b128 v[176:179], v225 offset:4096
	ds_read_b128 v[180:183], v225 offset:5120
	ds_read_b128 v[202:205], v225 offset:6144
	ds_read_b128 v[206:209], v225 offset:7168
	global_load_lds_dwordx4 v192, s[20:21]
	s_add_i32 m0, s54, 0xe000
	s_nop 0
	global_load_lds_dwordx4 v194, s[20:21]
	s_waitcnt vmcnt(8)
	s_waitcnt lgkmcnt(0)
	s_barrier
	v_mfma_f32_16x16x32_bf16 v[140:143], v[96:99], v[160:163], v[140:143]
	v_mfma_f32_16x16x32_bf16 v[136:139], v[120:123], v[160:163], v[136:139]
	v_mfma_f32_16x16x32_bf16 v[116:119], v[96:99], v[168:171], v[116:119]
	v_mfma_f32_16x16x32_bf16 v[112:115], v[120:123], v[168:171], v[112:115]
	v_mfma_f32_16x16x32_bf16 v[92:95], v[96:99], v[176:179], v[92:95]
	v_mfma_f32_16x16x32_bf16 v[88:91], v[120:123], v[176:179], v[88:91]
	v_mfma_f32_16x16x32_bf16 v[76:79], v[96:99], v[202:205], v[76:79]
	v_mfma_f32_16x16x32_bf16 v[72:75], v[120:123], v[202:205], v[72:75]
	v_mfma_f32_16x16x32_bf16 v[140:143], v[108:111], v[164:167], v[140:143]
	v_mfma_f32_16x16x32_bf16 v[136:139], v[128:131], v[164:167], v[136:139]
	v_mfma_f32_16x16x32_bf16 v[116:119], v[108:111], v[172:175], v[116:119]
	v_mfma_f32_16x16x32_bf16 v[112:115], v[128:131], v[172:175], v[112:115]
	v_mfma_f32_16x16x32_bf16 v[92:95], v[108:111], v[180:183], v[92:95]
	v_mfma_f32_16x16x32_bf16 v[88:91], v[128:131], v[180:183], v[88:91]
	v_mfma_f32_16x16x32_bf16 v[76:79], v[108:111], v[206:209], v[76:79]
	v_mfma_f32_16x16x32_bf16 v[72:75], v[128:131], v[206:209], v[72:75]
	v_mfma_f32_16x16x32_bf16 v[132:135], v[144:147], v[160:163], v[132:135]
	v_mfma_f32_16x16x32_bf16 v[124:127], v[152:155], v[160:163], v[124:127]
	v_mfma_f32_16x16x32_bf16 v[104:107], v[144:147], v[168:171], v[104:107]
	v_mfma_f32_16x16x32_bf16 v[100:103], v[152:155], v[168:171], v[100:103]
	v_mfma_f32_16x16x32_bf16 v[84:87], v[144:147], v[176:179], v[84:87]
	v_mfma_f32_16x16x32_bf16 v[80:83], v[152:155], v[176:179], v[80:83]
	v_mfma_f32_16x16x32_bf16 v[68:71], v[144:147], v[202:205], v[68:71]
	v_mfma_f32_16x16x32_bf16 v[64:67], v[152:155], v[202:205], v[64:67]
	v_mfma_f32_16x16x32_bf16 v[132:135], v[148:151], v[164:167], v[132:135]
	v_mfma_f32_16x16x32_bf16 v[124:127], v[156:159], v[164:167], v[124:127]
	v_mfma_f32_16x16x32_bf16 v[104:107], v[148:151], v[172:175], v[104:107]
	v_mfma_f32_16x16x32_bf16 v[100:103], v[156:159], v[172:175], v[100:103]
	v_mfma_f32_16x16x32_bf16 v[84:87], v[148:151], v[180:183], v[84:87]
	v_mfma_f32_16x16x32_bf16 v[80:83], v[156:159], v[180:183], v[80:83]
	v_mfma_f32_16x16x32_bf16 v[68:71], v[148:151], v[206:209], v[68:71]
	v_mfma_f32_16x16x32_bf16 v[64:67], v[156:159], v[206:209], v[64:67]
	s_barrier
	s_add_i32 s76, s67, s53
	s_add_u32 s98, s34, s12
	s_addc_u32 s99, s35, s13
	s_add_u32 s100, s50, s12
	s_addc_u32 s101, s51, s13
	s_mov_b32 m0, s76
	ds_read_b128 v[160:163], v225 offset:16384
	ds_read_b128 v[164:167], v225 offset:17408
	ds_read_b128 v[168:171], v225 offset:18432
	ds_read_b128 v[172:175], v225 offset:19456
	ds_read_b128 v[176:179], v225 offset:20480
	ds_read_b128 v[180:183], v225 offset:21504
	ds_read_b128 v[202:205], v225 offset:22528
	ds_read_b128 v[206:209], v225 offset:23552
	global_load_lds_dwordx4 v186, s[34:35]
	s_add_i32 m0, s76, 0x2000
	s_add_u32 s76, s34, 0xb0000
	s_addc_u32 s77, s35, 0
	s_add_i32 s78, s68, s53
	global_load_lds_dwordx4 v190, s[34:35]
	s_mov_b32 m0, s78
	s_nop 0
	global_load_lds_dwordx4 v186, s[76:77]
	s_add_i32 m0, s78, 0x2000
	s_nop 0
	global_load_lds_dwordx4 v190, s[76:77]
	s_mov_b32 m0, s54
	s_nop 0
	global_load_lds_dwordx4 v184, s[50:51]
	s_mov_b32 m0, s55
	s_nop 0
	global_load_lds_dwordx4 v188, s[50:51]
	s_waitcnt vmcnt(8)
	s_waitcnt lgkmcnt(0)
	s_barrier
	v_mfma_f32_16x16x32_bf16 v[60:63], v[96:99], v[160:163], v[60:63]
	v_mfma_f32_16x16x32_bf16 v[56:59], v[120:123], v[160:163], v[56:59]
	v_mfma_f32_16x16x32_bf16 v[44:47], v[96:99], v[168:171], v[44:47]
	v_mfma_f32_16x16x32_bf16 v[40:43], v[120:123], v[168:171], v[40:43]
	v_mfma_f32_16x16x32_bf16 v[28:31], v[96:99], v[176:179], v[28:31]
	v_mfma_f32_16x16x32_bf16 v[24:27], v[120:123], v[176:179], v[24:27]
	v_mfma_f32_16x16x32_bf16 v[12:15], v[96:99], v[202:205], v[12:15]
	v_mfma_f32_16x16x32_bf16 v[8:11], v[120:123], v[202:205], v[8:11]
	v_mfma_f32_16x16x32_bf16 v[60:63], v[108:111], v[164:167], v[60:63]
	v_mfma_f32_16x16x32_bf16 v[56:59], v[128:131], v[164:167], v[56:59]
	v_mfma_f32_16x16x32_bf16 v[44:47], v[108:111], v[172:175], v[44:47]
	v_mfma_f32_16x16x32_bf16 v[40:43], v[128:131], v[172:175], v[40:43]
	v_mfma_f32_16x16x32_bf16 v[28:31], v[108:111], v[180:183], v[28:31]
	v_mfma_f32_16x16x32_bf16 v[24:27], v[128:131], v[180:183], v[24:27]
	v_mfma_f32_16x16x32_bf16 v[12:15], v[108:111], v[206:209], v[12:15]
	v_mfma_f32_16x16x32_bf16 v[8:11], v[128:131], v[206:209], v[8:11]
	v_mfma_f32_16x16x32_bf16 v[52:55], v[144:147], v[160:163], v[52:55]
	v_mfma_f32_16x16x32_bf16 v[48:51], v[152:155], v[160:163], v[48:51]
	v_mfma_f32_16x16x32_bf16 v[36:39], v[144:147], v[168:171], v[36:39]
	v_mfma_f32_16x16x32_bf16 v[32:35], v[152:155], v[168:171], v[32:35]
	v_mfma_f32_16x16x32_bf16 v[20:23], v[144:147], v[176:179], v[20:23]
	v_mfma_f32_16x16x32_bf16 v[16:19], v[152:155], v[176:179], v[16:19]
	v_mfma_f32_16x16x32_bf16 v[4:7], v[144:147], v[202:205], v[4:7]
	v_mfma_f32_16x16x32_bf16 v[0:3], v[152:155], v[202:205], v[0:3]
	v_mfma_f32_16x16x32_bf16 v[52:55], v[148:151], v[164:167], v[52:55]
	v_mfma_f32_16x16x32_bf16 v[48:51], v[156:159], v[164:167], v[48:51]
	v_mfma_f32_16x16x32_bf16 v[36:39], v[148:151], v[172:175], v[36:39]
	v_mfma_f32_16x16x32_bf16 v[32:35], v[156:159], v[172:175], v[32:35]
	v_mfma_f32_16x16x32_bf16 v[20:23], v[148:151], v[180:183], v[20:23]
	v_mfma_f32_16x16x32_bf16 v[16:19], v[156:159], v[180:183], v[16:19]
	v_mfma_f32_16x16x32_bf16 v[4:7], v[148:151], v[206:209], v[4:7]
	v_mfma_f32_16x16x32_bf16 v[0:3], v[156:159], v[206:209], v[0:3]
	s_barrier
; #define PG8_STAGE(bufoff, gbase, voff) do { _Pragma("unroll") for (int _i = 0; _i < 2; ++_i) \
;         __builtin_amdgcn_global_load_lds((const unsigned*)((const char*)(gbase) + (voff)[_i]), (PG8_LAS unsigned*)(lds + (bufoff) + ldsw + _i * 8192), 16, 0, 0); } while (0)
; #define PG8_LDA(dst, b, h) do { _Pragma("unroll") for (int m = 0; m < 4; ++m) _Pragma("unroll") for (int k = 0; k < 2; ++k) dst[m][k] = *(const PG8_LAS bf16x8*)(lds + PG8_SA(b, h) + aoff + m * 2048 + k * 1024); } while (0)
; #define PG8_LDB(dst, b, h) do { _Pragma("unroll") for (int n = 0; n < 2; ++n) _Pragma("unroll") for (int k = 0; k < 2; ++k) dst[n][k] = *(const PG8_LAS bf16x8*)(lds + PG8_SB(b, h) + boff + n * 2048 + k * 1024); } while (0)
; #define PG8_MMA(ai, bj, At, Bt) do { __builtin_amdgcn_s_setprio(1); _Pragma("unroll") for (int m = 0; m < 4; ++m) _Pragma("unroll") for (int n = 0; n < 2; ++n) _Pragma("unroll") for (int k = 0; k < 2; ++k) \
;         acc[ai][bj][m][n] = __builtin_amdgcn_mfma_f32_16x16x32_bf16(Bt[n][k], At[m][k], acc[ai][bj][m][n], 0, 0, 0); __builtin_amdgcn_s_setprio(0); } while (0)
; #define PG8_WAIT_V(n) asm volatile("s_waitcnt vmcnt(" #n ")" ::: "memory")
; #define PG8_WAIT_L(n) asm volatile("s_waitcnt lgkmcnt(" #n ")" ::: "memory")
; #define PG8_BAR __builtin_amdgcn_s_barrier()
; #define PG8_SCHED __builtin_amdgcn_sched_barrier(0)
; template <class Epi, class Sched, bool ALIGN_EPI = false, bool SP2 = false>
; __device__ __forceinline__ void gemm_phase(PG8_LAS unsigned char* lds, const Gemm g, const Sched& S, const Epi& E) {
;     ...
;             PG8_LDB(B0, 1, 0); PG8_LDB(B1, 1, 1); PG8_SCHED; PG8_LDA(At, 1, 0); PG8_STAGE(PG8_SA(0, 1), a2 + hstep, voffA);
;             PG8_WAIT_V(8); PG8_WAIT_L(0); PG8_BAR; PG8_MMA(0, 0, At, B0); PG8_MMA(0, 1, At, B1); PG8_BAR; PG8_SCHED;
;             PG8_LDA(At, 1, 1); PG8_STAGE(PG8_SB(1, 0), b3, voffB); PG8_STAGE(PG8_SB(1, 1), b3 + hstep, voffB); PG8_STAGE(PG8_SA(1, 0), a3, voffA);
;             PG8_WAIT_V(8); PG8_WAIT_L(0); PG8_BAR; PG8_MMA(1, 0, At, B0); PG8_MMA(1, 1, At, B1); PG8_BAR; PG8_SCHED;
;     ...
;         if constexpr (ALIGN_EPI) { if (wr == 0) PG8_BAR; }
	s_add_i32 s76, 0, 0x18000
	s_add_i32 s77, 0, 0x1c000
	v_add_u32_e32 v128, s76, v221
	v_add_u32_e32 v156, s77, v221
	ds_read_b128 v[96:99], v128
	ds_read_b128 v[108:111], v128 offset:1024
	ds_read_b128 v[120:123], v128 offset:2048
	ds_read_b128 v[128:131], v128 offset:3072
	ds_read_b128 v[144:147], v156
	ds_read_b128 v[148:151], v156 offset:1024
	ds_read_b128 v[152:155], v156 offset:2048
	ds_read_b128 v[156:159], v156 offset:3072
	s_add_u32 s50, s50, 0xb0000
	s_addc_u32 s51, s51, 0
	s_mov_b32 m0, s56
	ds_read_b128 v[160:163], v225 offset:32768
	ds_read_b128 v[164:167], v225 offset:33792
	ds_read_b128 v[168:171], v225 offset:34816
	ds_read_b128 v[172:175], v225 offset:35840
	ds_read_b128 v[176:179], v225 offset:36864
	ds_read_b128 v[180:183], v225 offset:37888
	ds_read_b128 v[202:205], v225 offset:38912
	ds_read_b128 v[206:209], v225 offset:39936
	global_load_lds_dwordx4 v184, s[50:51]
	s_mov_b32 m0, s57
	s_nop 0
	global_load_lds_dwordx4 v188, s[50:51]
	s_waitcnt vmcnt(8)
	s_waitcnt lgkmcnt(0)
	s_barrier
	v_mfma_f32_16x16x32_bf16 v[140:143], v[96:99], v[160:163], v[140:143]
	v_mfma_f32_16x16x32_bf16 v[136:139], v[120:123], v[160:163], v[136:139]
	v_mfma_f32_16x16x32_bf16 v[116:119], v[96:99], v[168:171], v[116:119]
	v_mfma_f32_16x16x32_bf16 v[112:115], v[120:123], v[168:171], v[112:115]
	v_mfma_f32_16x16x32_bf16 v[92:95], v[96:99], v[176:179], v[92:95]
	v_mfma_f32_16x16x32_bf16 v[88:91], v[120:123], v[176:179], v[88:91]
	v_mfma_f32_16x16x32_bf16 v[76:79], v[96:99], v[202:205], v[76:79]
	v_mfma_f32_16x16x32_bf16 v[72:75], v[120:123], v[202:205], v[72:75]
	v_mfma_f32_16x16x32_bf16 v[140:143], v[108:111], v[164:167], v[140:143]
	v_mfma_f32_16x16x32_bf16 v[136:139], v[128:131], v[164:167], v[136:139]
	v_mfma_f32_16x16x32_bf16 v[116:119], v[108:111], v[172:175], v[116:119]
	v_mfma_f32_16x16x32_bf16 v[112:115], v[128:131], v[172:175], v[112:115]
	v_mfma_f32_16x16x32_bf16 v[92:95], v[108:111], v[180:183], v[92:95]
	v_mfma_f32_16x16x32_bf16 v[88:91], v[128:131], v[180:183], v[88:91]
	v_mfma_f32_16x16x32_bf16 v[76:79], v[108:111], v[206:209], v[76:79]
	v_mfma_f32_16x16x32_bf16 v[72:75], v[128:131], v[206:209], v[72:75]
	v_mfma_f32_16x16x32_bf16 v[132:135], v[144:147], v[160:163], v[132:135]
	v_mfma_f32_16x16x32_bf16 v[124:127], v[152:155], v[160:163], v[124:127]
	v_mfma_f32_16x16x32_bf16 v[104:107], v[144:147], v[168:171], v[104:107]
	v_mfma_f32_16x16x32_bf16 v[100:103], v[152:155], v[168:171], v[100:103]
	v_mfma_f32_16x16x32_bf16 v[84:87], v[144:147], v[176:179], v[84:87]
	v_mfma_f32_16x16x32_bf16 v[80:83], v[152:155], v[176:179], v[80:83]
	v_mfma_f32_16x16x32_bf16 v[68:71], v[144:147], v[202:205], v[68:71]
	v_mfma_f32_16x16x32_bf16 v[64:67], v[152:155], v[202:205], v[64:67]
	v_mfma_f32_16x16x32_bf16 v[132:135], v[148:151], v[164:167], v[132:135]
	v_mfma_f32_16x16x32_bf16 v[124:127], v[156:159], v[164:167], v[124:127]
	v_mfma_f32_16x16x32_bf16 v[104:107], v[148:151], v[172:175], v[104:107]
	v_mfma_f32_16x16x32_bf16 v[100:103], v[156:159], v[172:175], v[100:103]
	v_mfma_f32_16x16x32_bf16 v[84:87], v[148:151], v[180:183], v[84:87]
	v_mfma_f32_16x16x32_bf16 v[80:83], v[156:159], v[180:183], v[80:83]
	v_mfma_f32_16x16x32_bf16 v[68:71], v[148:151], v[206:209], v[68:71]
	v_mfma_f32_16x16x32_bf16 v[64:67], v[156:159], v[206:209], v[64:67]
	s_barrier
	s_add_i32 s50, s76, s53
	s_mov_b32 m0, s50
	ds_read_b128 v[160:163], v225 offset:49152
	ds_read_b128 v[164:167], v225 offset:50176
	ds_read_b128 v[168:171], v225 offset:51200
	ds_read_b128 v[172:175], v225 offset:52224
	ds_read_b128 v[176:179], v225 offset:53248
	ds_read_b128 v[180:183], v225 offset:54272
	ds_read_b128 v[202:205], v225 offset:55296
	ds_read_b128 v[206:209], v225 offset:56320
	global_load_lds_dwordx4 v186, s[98:99]
	s_add_i32 m0, s50, 0x2000
	s_add_u32 s34, s34, 0xb0080
	s_addc_u32 s35, s35, 0
	s_add_i32 s50, s77, s53
	global_load_lds_dwordx4 v190, s[98:99]
	s_mov_b32 m0, s50
	s_nop 0
	global_load_lds_dwordx4 v186, s[34:35]
	s_add_i32 m0, s50, 0x2000
	s_nop 0
	global_load_lds_dwordx4 v190, s[34:35]
	s_mov_b32 m0, s62
	s_nop 0
	global_load_lds_dwordx4 v184, s[100:101]
	s_mov_b32 m0, s63
	s_nop 0
	global_load_lds_dwordx4 v188, s[100:101]
	s_waitcnt vmcnt(8)
	s_waitcnt lgkmcnt(0)
	s_barrier
	v_mfma_f32_16x16x32_bf16 v[60:63], v[96:99], v[160:163], v[60:63]
	v_mfma_f32_16x16x32_bf16 v[56:59], v[120:123], v[160:163], v[56:59]
	v_mfma_f32_16x16x32_bf16 v[44:47], v[96:99], v[168:171], v[44:47]
	v_mfma_f32_16x16x32_bf16 v[40:43], v[120:123], v[168:171], v[40:43]
	v_mfma_f32_16x16x32_bf16 v[28:31], v[96:99], v[176:179], v[28:31]
	v_mfma_f32_16x16x32_bf16 v[24:27], v[120:123], v[176:179], v[24:27]
	v_mfma_f32_16x16x32_bf16 v[12:15], v[96:99], v[202:205], v[12:15]
	v_mfma_f32_16x16x32_bf16 v[8:11], v[120:123], v[202:205], v[8:11]
	v_mfma_f32_16x16x32_bf16 v[60:63], v[108:111], v[164:167], v[60:63]
	v_mfma_f32_16x16x32_bf16 v[56:59], v[128:131], v[164:167], v[56:59]
	v_mfma_f32_16x16x32_bf16 v[44:47], v[108:111], v[172:175], v[44:47]
	v_mfma_f32_16x16x32_bf16 v[40:43], v[128:131], v[172:175], v[40:43]
	v_mfma_f32_16x16x32_bf16 v[28:31], v[108:111], v[180:183], v[28:31]
	v_mfma_f32_16x16x32_bf16 v[24:27], v[128:131], v[180:183], v[24:27]
	v_mfma_f32_16x16x32_bf16 v[12:15], v[108:111], v[206:209], v[12:15]
	v_mfma_f32_16x16x32_bf16 v[8:11], v[128:131], v[206:209], v[8:11]
	v_mfma_f32_16x16x32_bf16 v[52:55], v[144:147], v[160:163], v[52:55]
	v_mfma_f32_16x16x32_bf16 v[48:51], v[152:155], v[160:163], v[48:51]
	v_mfma_f32_16x16x32_bf16 v[36:39], v[144:147], v[168:171], v[36:39]
	v_mfma_f32_16x16x32_bf16 v[32:35], v[152:155], v[168:171], v[32:35]
	v_mfma_f32_16x16x32_bf16 v[20:23], v[144:147], v[176:179], v[20:23]
	v_mfma_f32_16x16x32_bf16 v[16:19], v[152:155], v[176:179], v[16:19]
	v_mfma_f32_16x16x32_bf16 v[4:7], v[144:147], v[202:205], v[4:7]
	v_mfma_f32_16x16x32_bf16 v[0:3], v[152:155], v[202:205], v[0:3]
	v_mfma_f32_16x16x32_bf16 v[52:55], v[148:151], v[164:167], v[52:55]
	v_mfma_f32_16x16x32_bf16 v[48:51], v[156:159], v[164:167], v[48:51]
	v_mfma_f32_16x16x32_bf16 v[36:39], v[148:151], v[172:175], v[36:39]
	v_mfma_f32_16x16x32_bf16 v[32:35], v[156:159], v[172:175], v[32:35]
	v_mfma_f32_16x16x32_bf16 v[20:23], v[148:151], v[180:183], v[20:23]
	v_mfma_f32_16x16x32_bf16 v[16:19], v[156:159], v[180:183], v[16:19]
	v_mfma_f32_16x16x32_bf16 v[4:7], v[148:151], v[206:209], v[4:7]
	v_mfma_f32_16x16x32_bf16 v[0:3], v[156:159], v[206:209], v[0:3]
	s_barrier
	s_add_i32 s75, s75, 2
	s_add_u32 s20, s20, 0x100
	s_addc_u32 s21, s21, 0
	s_add_u32 s73, s73, 0x100
	s_addc_u32 s74, s74, 0
	s_cmp_gt_u32 s75, 41
	s_cbranch_scc0 .LBB0_309
	s_and_b64 vcc, exec, s[14:15]
	s_cbranch_vccz .LBB0_312
	s_barrier

; #define PG8_STAGE(bufoff, gbase, voff) do { _Pragma("unroll") for (int _i = 0; _i < 2; ++_i) \
;         __builtin_amdgcn_global_load_lds((const unsigned*)((const char*)(gbase) + (voff)[_i]), (PG8_LAS unsigned*)(lds + (bufoff) + ldsw + _i * 8192), 16, 0, 0); } while (0)
; #define PG8_LDA(dst, b, h) do { _Pragma("unroll") for (int m = 0; m < 4; ++m) _Pragma("unroll") for (int k = 0; k < 2; ++k) dst[m][k] = *(const PG8_LAS bf16x8*)(lds + PG8_SA(b, h) + aoff + m * 2048 + k * 1024); } while (0)
; #define PG8_LDB(dst, b, h) do { _Pragma("unroll") for (int n = 0; n < 2; ++n) _Pragma("unroll") for (int k = 0; k < 2; ++k) dst[n][k] = *(const PG8_LAS bf16x8*)(lds + PG8_SB(b, h) + boff + n * 2048 + k * 1024); } while (0)
; #define PG8_MMA(ai, bj, At, Bt) do { __builtin_amdgcn_s_setprio(1); _Pragma("unroll") for (int m = 0; m < 4; ++m) _Pragma("unroll") for (int n = 0; n < 2; ++n) _Pragma("unroll") for (int k = 0; k < 2; ++k) \
;         acc[ai][bj][m][n] = __builtin_amdgcn_mfma_f32_16x16x32_bf16(Bt[n][k], At[m][k], acc[ai][bj][m][n], 0, 0, 0); __builtin_amdgcn_s_setprio(0); } while (0)
; #define PG8_WAIT_V(n) asm volatile("s_waitcnt vmcnt(" #n ")" ::: "memory")
; template <class Epi, class Sched, bool ALIGN_EPI = false, bool SP2 = false>
; __device__ __forceinline__ void gemm_phase(PG8_LAS unsigned char* lds, const Gemm g, const Sched& S, const Epi& E) {
;     ...
;         const char* nA = has_next ? (const char*)g.A + (size_t)nxt.pm * tstep : cA; const char* nB = has_next ? (const char*)g.Bt + (size_t)nxt.pn * tstep : cB;
;         for (int t = 0; t < nt; t += 2) {
;             const bool last = (t == nt - 2);
;             const char* a1 = cA + (size_t)(t + 1) * kstep;
;             const char* a2 = last ? nA : cA + (size_t)(t + 2) * kstep; const char* b2 = last ? nB : cB + (size_t)(t + 2) * kstep;
;             const char* a3 = a2 + kstep; const char* b3 = b2 + kstep;
;             if (last && has_next) S.a_ready(nxt);
;             if constexpr (SP2) {
;             PG8_LDB(B0, 0, 0); PG8_LDB(B1, 0, 1); PG8_SCHED; PG8_LDA(At, 0, 0); PG8_STAGE(PG8_SA(1, 1), a1 + hstep, voffA);
;             PG8_WAIT_V(8); PG8_WAIT_L(0); PG8_BAR; PG8_MMA(0, 0, At, B0); PG8_MMA(0, 1, At, B1); PG8_BAR; PG8_SCHED;
;             PG8_LDA(At, 0, 1); PG8_STAGE(PG8_SB(0, 0), b2, voffB); PG8_STAGE(PG8_SB(0, 1), b2 + hstep, voffB); PG8_STAGE(PG8_SA(0, 0), a2, voffA);
.LBB0_413:
	s_ashr_i32 s43, s42, 31
	s_lshl_b64 s[48:49], s[42:43], 19
	s_add_u32 s48, s36, s48
	s_addc_u32 s49, s37, s49
	s_and_b64 s[50:51], s[4:5], exec
	s_cselect_b32 s43, s49, s21
	s_cselect_b32 s78, s48, s20
	s_ashr_i32 s19, s18, 31
	s_lshl_b64 s[50:51], s[18:19], 19
	s_add_u32 s50, s61, s50
	s_addc_u32 s51, s62, s51
	s_and_b64 s[54:55], s[4:5], exec
	s_cselect_b32 s19, s51, s53
	s_cselect_b32 s79, s50, s52
	s_add_u32 s20, s20, 0x40080
	s_addc_u32 s21, s21, 0
	s_add_u32 s80, s52, 0x100
	s_addc_u32 s81, s53, 0
	s_mov_b32 s84, -2
	ds_read_b128 v[146:149], v165
	ds_read_b128 v[150:153], v165 offset:1024
	ds_read_b128 v[154:157], v165 offset:2048
	ds_read_b128 v[168:171], v165 offset:3072
	ds_read_b128 v[172:175], v166
	ds_read_b128 v[176:179], v166 offset:1024
	ds_read_b128 v[180:183], v166 offset:2048
	ds_read_b128 v[184:187], v166 offset:3072
	s_add_u32 s52, s20, 0xfffc0080
	s_addc_u32 s53, s21, -1
	s_cmp_eq_u32 s84, 12
	s_cselect_b32 s55, s43, s53
	s_cselect_b32 s54, s78, s52
	s_cselect_b32 s53, s19, s81
	s_cselect_b32 s52, s79, s80
	s_add_i32 m0, s35, 0xc000
	ds_read_b128 v[188:191], v167
	ds_read_b128 v[192:195], v167 offset:1024
	ds_read_b128 v[198:201], v167 offset:2048
	ds_read_b128 v[202:205], v167 offset:3072
	ds_read_b128 v[206:209], v167 offset:4096
	ds_read_b128 v[210:213], v167 offset:5120
	ds_read_b128 v[214:217], v167 offset:6144
	ds_read_b128 v[218:221], v167 offset:7168
	global_load_lds_dwordx4 v138, s[20:21]
	s_add_i32 m0, s35, 0xe000
	s_nop 0
	global_load_lds_dwordx4 v140, s[20:21]
	s_waitcnt vmcnt(8)
	s_waitcnt lgkmcnt(0)
	s_barrier
	v_mfma_f32_16x16x32_bf16 v[124:127], v[146:149], v[188:191], 0
	v_mfma_f32_16x16x32_bf16 v[120:123], v[154:157], v[188:191], 0
	v_mfma_f32_16x16x32_bf16 v[108:111], v[146:149], v[198:201], 0
	v_mfma_f32_16x16x32_bf16 v[104:107], v[154:157], v[198:201], 0
	v_mfma_f32_16x16x32_bf16 v[92:95], v[146:149], v[206:209], 0
	v_mfma_f32_16x16x32_bf16 v[88:91], v[154:157], v[206:209], 0
	v_mfma_f32_16x16x32_bf16 v[76:79], v[146:149], v[214:217], 0
	v_mfma_f32_16x16x32_bf16 v[72:75], v[154:157], v[214:217], 0
	v_mfma_f32_16x16x32_bf16 v[124:127], v[150:153], v[192:195], v[124:127]
	v_mfma_f32_16x16x32_bf16 v[120:123], v[168:171], v[192:195], v[120:123]
	v_mfma_f32_16x16x32_bf16 v[108:111], v[150:153], v[202:205], v[108:111]
	v_mfma_f32_16x16x32_bf16 v[104:107], v[168:171], v[202:205], v[104:107]
	v_mfma_f32_16x16x32_bf16 v[92:95], v[150:153], v[210:213], v[92:95]
	v_mfma_f32_16x16x32_bf16 v[88:91], v[168:171], v[210:213], v[88:91]
	v_mfma_f32_16x16x32_bf16 v[76:79], v[150:153], v[218:221], v[76:79]
	v_mfma_f32_16x16x32_bf16 v[72:75], v[168:171], v[218:221], v[72:75]
	v_mfma_f32_16x16x32_bf16 v[116:119], v[172:175], v[188:191], 0
	v_mfma_f32_16x16x32_bf16 v[112:115], v[180:183], v[188:191], 0
	v_mfma_f32_16x16x32_bf16 v[100:103], v[172:175], v[198:201], 0
	v_mfma_f32_16x16x32_bf16 v[96:99], v[180:183], v[198:201], 0
	v_mfma_f32_16x16x32_bf16 v[84:87], v[172:175], v[206:209], 0
	v_mfma_f32_16x16x32_bf16 v[80:83], v[180:183], v[206:209], 0
	v_mfma_f32_16x16x32_bf16 v[68:71], v[172:175], v[214:217], 0
	v_mfma_f32_16x16x32_bf16 v[64:67], v[180:183], v[214:217], 0
	v_mfma_f32_16x16x32_bf16 v[116:119], v[176:179], v[192:195], v[116:119]
	v_mfma_f32_16x16x32_bf16 v[112:115], v[184:187], v[192:195], v[112:115]
	v_mfma_f32_16x16x32_bf16 v[100:103], v[176:179], v[202:205], v[100:103]
	v_mfma_f32_16x16x32_bf16 v[96:99], v[184:187], v[202:205], v[96:99]
	v_mfma_f32_16x16x32_bf16 v[84:87], v[176:179], v[210:213], v[84:87]
	v_mfma_f32_16x16x32_bf16 v[80:83], v[184:187], v[210:213], v[80:83]
	v_mfma_f32_16x16x32_bf16 v[68:71], v[176:179], v[218:221], v[68:71]
	v_mfma_f32_16x16x32_bf16 v[64:67], v[184:187], v[218:221], v[64:67]
	s_barrier
	s_add_i32 s85, s72, s63
	s_add_u32 s98, s52, s8
	s_addc_u32 s99, s53, s9
	s_add_u32 s100, s54, s8
	s_addc_u32 s101, s55, s9
	s_mov_b32 m0, s85
	ds_read_b128 v[188:191], v167 offset:16384
	ds_read_b128 v[192:195], v167 offset:17408
	ds_read_b128 v[198:201], v167 offset:18432
	ds_read_b128 v[202:205], v167 offset:19456
	ds_read_b128 v[206:209], v167 offset:20480
	ds_read_b128 v[210:213], v167 offset:21504
	ds_read_b128 v[214:217], v167 offset:22528
	ds_read_b128 v[218:221], v167 offset:23552
	global_load_lds_dwordx4 v132, s[52:53]
	s_add_i32 m0, s85, 0x2000
	s_add_u32 s86, s52, 0x40000
	s_addc_u32 s87, s53, 0
	s_add_i32 s85, s73, s63
	global_load_lds_dwordx4 v128, s[52:53]
	s_mov_b32 m0, s85
	s_nop 0
	global_load_lds_dwordx4 v132, s[86:87]
	s_add_i32 m0, s85, 0x2000
	s_nop 0
	global_load_lds_dwordx4 v128, s[86:87]
	s_mov_b32 m0, s35
	s_nop 0
	global_load_lds_dwordx4 v134, s[54:55]
	s_mov_b32 m0, s65
	s_nop 0
	global_load_lds_dwordx4 v130, s[54:55]
	s_waitcnt vmcnt(8)
	s_waitcnt lgkmcnt(0)
	s_barrier
; #define PG8_STAGE(bufoff, gbase, voff) do { _Pragma("unroll") for (int _i = 0; _i < 2; ++_i) \
;         __builtin_amdgcn_global_load_lds((const unsigned*)((const char*)(gbase) + (voff)[_i]), (PG8_LAS unsigned*)(lds + (bufoff) + ldsw + _i * 8192), 16, 0, 0); } while (0)
; #define PG8_LDA(dst, b, h) do { _Pragma("unroll") for (int m = 0; m < 4; ++m) _Pragma("unroll") for (int k = 0; k < 2; ++k) dst[m][k] = *(const PG8_LAS bf16x8*)(lds + PG8_SA(b, h) + aoff + m * 2048 + k * 1024); } while (0)
; #define PG8_LDB(dst, b, h) do { _Pragma("unroll") for (int n = 0; n < 2; ++n) _Pragma("unroll") for (int k = 0; k < 2; ++k) dst[n][k] = *(const PG8_LAS bf16x8*)(lds + PG8_SB(b, h) + boff + n * 2048 + k * 1024); } while (0)
; #define PG8_MMA(ai, bj, At, Bt) do { __builtin_amdgcn_s_setprio(1); _Pragma("unroll") for (int m = 0; m < 4; ++m) _Pragma("unroll") for (int n = 0; n < 2; ++n) _Pragma("unroll") for (int k = 0; k < 2; ++k) \
;         acc[ai][bj][m][n] = __builtin_amdgcn_mfma_f32_16x16x32_bf16(Bt[n][k], At[m][k], acc[ai][bj][m][n], 0, 0, 0); __builtin_amdgcn_s_setprio(0); } while (0)
; #define PG8_WAIT_V(n) asm volatile("s_waitcnt vmcnt(" #n ")" ::: "memory")
; #define PG8_WAIT_L(n) asm volatile("s_waitcnt lgkmcnt(" #n ")" ::: "memory")
; #define PG8_BAR __builtin_amdgcn_s_barrier()
; #define PG8_SCHED __builtin_amdgcn_sched_barrier(0)
; template <class Epi, class Sched, bool ALIGN_EPI = false, bool SP2 = false>
; __device__ __forceinline__ void gemm_phase(PG8_LAS unsigned char* lds, const Gemm g, const Sched& S, const Epi& E) {
;     ...
;             PG8_LDA(At, 0, 1); PG8_STAGE(PG8_SB(0, 0), b2, voffB); PG8_STAGE(PG8_SB(0, 1), b2 + hstep, voffB); PG8_STAGE(PG8_SA(0, 0), a2, voffA);
;             PG8_WAIT_V(8); PG8_WAIT_L(0); PG8_BAR; PG8_MMA(1, 0, At, B0); PG8_MMA(1, 1, At, B1); PG8_BAR; PG8_SCHED;
;             PG8_LDB(B0, 1, 0); PG8_LDB(B1, 1, 1); PG8_SCHED; PG8_LDA(At, 1, 0); PG8_STAGE(PG8_SA(0, 1), a2 + hstep, voffA);
;             PG8_WAIT_V(8); PG8_WAIT_L(0); PG8_BAR; PG8_MMA(0, 0, At, B0); PG8_MMA(0, 1, At, B1); PG8_BAR; PG8_SCHED;
	v_mfma_f32_16x16x32_bf16 v[60:63], v[146:149], v[188:191], 0
	v_mfma_f32_16x16x32_bf16 v[56:59], v[154:157], v[188:191], 0
	v_mfma_f32_16x16x32_bf16 v[44:47], v[146:149], v[198:201], 0
	v_mfma_f32_16x16x32_bf16 v[40:43], v[154:157], v[198:201], 0
	v_mfma_f32_16x16x32_bf16 v[28:31], v[146:149], v[206:209], 0
	v_mfma_f32_16x16x32_bf16 v[24:27], v[154:157], v[206:209], 0
	v_mfma_f32_16x16x32_bf16 v[12:15], v[146:149], v[214:217], 0
	v_mfma_f32_16x16x32_bf16 v[8:11], v[154:157], v[214:217], 0
	v_mfma_f32_16x16x32_bf16 v[60:63], v[150:153], v[192:195], v[60:63]
	v_mfma_f32_16x16x32_bf16 v[56:59], v[168:171], v[192:195], v[56:59]
	v_mfma_f32_16x16x32_bf16 v[44:47], v[150:153], v[202:205], v[44:47]
	v_mfma_f32_16x16x32_bf16 v[40:43], v[168:171], v[202:205], v[40:43]
	v_mfma_f32_16x16x32_bf16 v[28:31], v[150:153], v[210:213], v[28:31]
	v_mfma_f32_16x16x32_bf16 v[24:27], v[168:171], v[210:213], v[24:27]
	v_mfma_f32_16x16x32_bf16 v[12:15], v[150:153], v[218:221], v[12:15]
	v_mfma_f32_16x16x32_bf16 v[8:11], v[168:171], v[218:221], v[8:11]
	v_mfma_f32_16x16x32_bf16 v[52:55], v[172:175], v[188:191], 0
	v_mfma_f32_16x16x32_bf16 v[48:51], v[180:183], v[188:191], 0
	v_mfma_f32_16x16x32_bf16 v[36:39], v[172:175], v[198:201], 0
	v_mfma_f32_16x16x32_bf16 v[32:35], v[180:183], v[198:201], 0
	v_mfma_f32_16x16x32_bf16 v[20:23], v[172:175], v[206:209], 0
	v_mfma_f32_16x16x32_bf16 v[16:19], v[180:183], v[206:209], 0
	v_mfma_f32_16x16x32_bf16 v[4:7], v[172:175], v[214:217], 0
	v_mfma_f32_16x16x32_bf16 v[0:3], v[180:183], v[214:217], 0
	v_mfma_f32_16x16x32_bf16 v[52:55], v[176:179], v[192:195], v[52:55]
	v_mfma_f32_16x16x32_bf16 v[48:51], v[184:187], v[192:195], v[48:51]
	v_mfma_f32_16x16x32_bf16 v[36:39], v[176:179], v[202:205], v[36:39]
	v_mfma_f32_16x16x32_bf16 v[32:35], v[184:187], v[202:205], v[32:35]
	v_mfma_f32_16x16x32_bf16 v[20:23], v[176:179], v[210:213], v[20:23]
	v_mfma_f32_16x16x32_bf16 v[16:19], v[184:187], v[210:213], v[16:19]
	v_mfma_f32_16x16x32_bf16 v[4:7], v[176:179], v[218:221], v[4:7]
	v_mfma_f32_16x16x32_bf16 v[0:3], v[184:187], v[218:221], v[0:3]
	s_barrier
	s_add_i32 s85, 0, 0x18000
	v_add_u32_e32 v136, s85, v161
	s_add_i32 s86, 0, 0x1c000
	ds_read_b128 v[146:149], v136
	ds_read_b128 v[150:153], v136 offset:1024
	ds_read_b128 v[154:157], v136 offset:2048
	ds_read_b128 v[168:171], v136 offset:3072
	v_add_u32_e32 v136, s86, v161
	ds_read_b128 v[172:175], v136
	ds_read_b128 v[176:179], v136 offset:1024
	ds_read_b128 v[180:183], v136 offset:2048
	ds_read_b128 v[184:187], v136 offset:3072
	s_add_u32 s54, s54, 0x40000
	s_addc_u32 s55, s55, 0
	s_mov_b32 m0, s66
	ds_read_b128 v[188:191], v167 offset:32768
	ds_read_b128 v[192:195], v167 offset:33792
	ds_read_b128 v[198:201], v167 offset:34816
	ds_read_b128 v[202:205], v167 offset:35840
	ds_read_b128 v[206:209], v167 offset:36864
	ds_read_b128 v[210:213], v167 offset:37888
	ds_read_b128 v[214:217], v167 offset:38912
	ds_read_b128 v[218:221], v167 offset:39936
	global_load_lds_dwordx4 v134, s[54:55]
	s_mov_b32 m0, s67
	s_nop 0
	global_load_lds_dwordx4 v130, s[54:55]
	s_waitcnt vmcnt(8)
	s_waitcnt lgkmcnt(0)
	s_barrier
	v_mfma_f32_16x16x32_bf16 v[124:127], v[146:149], v[188:191], v[124:127]
	v_mfma_f32_16x16x32_bf16 v[120:123], v[154:157], v[188:191], v[120:123]
	v_mfma_f32_16x16x32_bf16 v[108:111], v[146:149], v[198:201], v[108:111]
	v_mfma_f32_16x16x32_bf16 v[104:107], v[154:157], v[198:201], v[104:107]
	v_mfma_f32_16x16x32_bf16 v[92:95], v[146:149], v[206:209], v[92:95]
	v_mfma_f32_16x16x32_bf16 v[88:91], v[154:157], v[206:209], v[88:91]
	v_mfma_f32_16x16x32_bf16 v[76:79], v[146:149], v[214:217], v[76:79]
	v_mfma_f32_16x16x32_bf16 v[72:75], v[154:157], v[214:217], v[72:75]
	v_mfma_f32_16x16x32_bf16 v[124:127], v[150:153], v[192:195], v[124:127]
	v_mfma_f32_16x16x32_bf16 v[120:123], v[168:171], v[192:195], v[120:123]
	v_mfma_f32_16x16x32_bf16 v[108:111], v[150:153], v[202:205], v[108:111]
	v_mfma_f32_16x16x32_bf16 v[104:107], v[168:171], v[202:205], v[104:107]
	v_mfma_f32_16x16x32_bf16 v[92:95], v[150:153], v[210:213], v[92:95]
	v_mfma_f32_16x16x32_bf16 v[88:91], v[168:171], v[210:213], v[88:91]
	v_mfma_f32_16x16x32_bf16 v[76:79], v[150:153], v[218:221], v[76:79]
	v_mfma_f32_16x16x32_bf16 v[72:75], v[168:171], v[218:221], v[72:75]
	v_mfma_f32_16x16x32_bf16 v[116:119], v[172:175], v[188:191], v[116:119]
	v_mfma_f32_16x16x32_bf16 v[112:115], v[180:183], v[188:191], v[112:115]
	v_mfma_f32_16x16x32_bf16 v[100:103], v[172:175], v[198:201], v[100:103]
	v_mfma_f32_16x16x32_bf16 v[96:99], v[180:183], v[198:201], v[96:99]
	v_mfma_f32_16x16x32_bf16 v[84:87], v[172:175], v[206:209], v[84:87]
	v_mfma_f32_16x16x32_bf16 v[80:83], v[180:183], v[206:209], v[80:83]
	v_mfma_f32_16x16x32_bf16 v[68:71], v[172:175], v[214:217], v[68:71]
	v_mfma_f32_16x16x32_bf16 v[64:67], v[180:183], v[214:217], v[64:67]
	v_mfma_f32_16x16x32_bf16 v[116:119], v[176:179], v[192:195], v[116:119]
	v_mfma_f32_16x16x32_bf16 v[112:115], v[184:187], v[192:195], v[112:115]
	v_mfma_f32_16x16x32_bf16 v[100:103], v[176:179], v[202:205], v[100:103]
	v_mfma_f32_16x16x32_bf16 v[96:99], v[184:187], v[202:205], v[96:99]
	v_mfma_f32_16x16x32_bf16 v[84:87], v[176:179], v[210:213], v[84:87]
	v_mfma_f32_16x16x32_bf16 v[80:83], v[184:187], v[210:213], v[80:83]
	v_mfma_f32_16x16x32_bf16 v[68:71], v[176:179], v[218:221], v[68:71]
	v_mfma_f32_16x16x32_bf16 v[64:67], v[184:187], v[218:221], v[64:67]
	s_barrier
; #define PG8_STAGE(bufoff, gbase, voff) do { _Pragma("unroll") for (int _i = 0; _i < 2; ++_i) \
;         __builtin_amdgcn_global_load_lds((const unsigned*)((const char*)(gbase) + (voff)[_i]), (PG8_LAS unsigned*)(lds + (bufoff) + ldsw + _i * 8192), 16, 0, 0); } while (0)
; #define PG8_LDA(dst, b, h) do { _Pragma("unroll") for (int m = 0; m < 4; ++m) _Pragma("unroll") for (int k = 0; k < 2; ++k) dst[m][k] = *(const PG8_LAS bf16x8*)(lds + PG8_SA(b, h) + aoff + m * 2048 + k * 1024); } while (0)
; #define PG8_LDB(dst, b, h) do { _Pragma("unroll") for (int n = 0; n < 2; ++n) _Pragma("unroll") for (int k = 0; k < 2; ++k) dst[n][k] = *(const PG8_LAS bf16x8*)(lds + PG8_SB(b, h) + boff + n * 2048 + k * 1024); } while (0)
; template <class Epi, class Sched, bool ALIGN_EPI = false, bool SP2 = false>
; __device__ __forceinline__ void gemm_phase(PG8_LAS unsigned char* lds, const Gemm g, const Sched& S, const Epi& E) {
;     ...
;         for (int t = 0; t < nt; t += 2) {
;             const bool last = (t == nt - 2);
;             const char* a1 = cA + (size_t)(t + 1) * kstep;
;             const char* a2 = last ? nA : cA + (size_t)(t + 2) * kstep; const char* b2 = last ? nB : cB + (size_t)(t + 2) * kstep;
;             const char* a3 = a2 + kstep; const char* b3 = b2 + kstep;
;             if (last && has_next) S.a_ready(nxt);
;             if constexpr (SP2) {
;             PG8_LDB(B0, 0, 0); PG8_LDB(B1, 0, 1); PG8_SCHED; PG8_LDA(At, 0, 0); PG8_STAGE(PG8_SA(1, 1), a1 + hstep, voffA);
;             PG8_WAIT_V(8); PG8_WAIT_L(0); PG8_BAR; PG8_MMA(0, 0, At, B0); PG8_MMA(0, 1, At, B1); PG8_BAR; PG8_SCHED;
;             PG8_LDA(At, 0, 1); PG8_STAGE(PG8_SB(0, 0), b2, voffB); PG8_STAGE(PG8_SB(0, 1), b2 + hstep, voffB); PG8_STAGE(PG8_SA(0, 0), a2, voffA);
;             PG8_WAIT_V(8); PG8_WAIT_L(0); PG8_BAR; PG8_MMA(1, 0, At, B0); PG8_MMA(1, 1, At, B1); PG8_BAR; PG8_SCHED;
;             PG8_LDB(B0, 1, 0); PG8_LDB(B1, 1, 1); PG8_SCHED; PG8_LDA(At, 1, 0); PG8_STAGE(PG8_SA(0, 1), a2 + hstep, voffA);
;             PG8_WAIT_V(8); PG8_WAIT_L(0); PG8_BAR; PG8_MMA(0, 0, At, B0); PG8_MMA(0, 1, At, B1); PG8_BAR; PG8_SCHED;
;             PG8_LDA(At, 1, 1); PG8_STAGE(PG8_SB(1, 0), b3, voffB); PG8_STAGE(PG8_SB(1, 1), b3 + hstep, voffB); PG8_STAGE(PG8_SA(1, 0), a3, voffA);
;             PG8_WAIT_V(8); PG8_WAIT_L(0); PG8_BAR; PG8_MMA(1, 0, At, B0); PG8_MMA(1, 1, At, B1); PG8_BAR; PG8_SCHED;
	s_add_i32 s54, s85, s63
	s_mov_b32 m0, s54
	ds_read_b128 v[188:191], v167 offset:49152
	ds_read_b128 v[192:195], v167 offset:50176
	ds_read_b128 v[198:201], v167 offset:51200
	ds_read_b128 v[202:205], v167 offset:52224
	ds_read_b128 v[206:209], v167 offset:53248
	ds_read_b128 v[210:213], v167 offset:54272
	ds_read_b128 v[214:217], v167 offset:55296
	ds_read_b128 v[218:221], v167 offset:56320
	global_load_lds_dwordx4 v132, s[98:99]
	s_add_i32 m0, s54, 0x2000
	s_add_u32 s52, s52, 0x40080
	s_addc_u32 s53, s53, 0
	s_add_i32 s54, s86, s63
	global_load_lds_dwordx4 v128, s[98:99]
	s_mov_b32 m0, s54
	s_nop 0
	global_load_lds_dwordx4 v132, s[52:53]
	s_add_i32 m0, s54, 0x2000
	s_nop 0
	global_load_lds_dwordx4 v128, s[52:53]
	s_mov_b32 m0, s69
	s_nop 0
	global_load_lds_dwordx4 v134, s[100:101]
	s_mov_b32 m0, s70
	s_nop 0
	global_load_lds_dwordx4 v130, s[100:101]
	s_waitcnt vmcnt(8)
	s_waitcnt lgkmcnt(0)
	s_barrier
	v_mfma_f32_16x16x32_bf16 v[60:63], v[146:149], v[188:191], v[60:63]
	v_mfma_f32_16x16x32_bf16 v[56:59], v[154:157], v[188:191], v[56:59]
	v_mfma_f32_16x16x32_bf16 v[44:47], v[146:149], v[198:201], v[44:47]
	v_mfma_f32_16x16x32_bf16 v[40:43], v[154:157], v[198:201], v[40:43]
	v_mfma_f32_16x16x32_bf16 v[28:31], v[146:149], v[206:209], v[28:31]
	v_mfma_f32_16x16x32_bf16 v[24:27], v[154:157], v[206:209], v[24:27]
	v_mfma_f32_16x16x32_bf16 v[12:15], v[146:149], v[214:217], v[12:15]
	v_mfma_f32_16x16x32_bf16 v[8:11], v[154:157], v[214:217], v[8:11]
	v_mfma_f32_16x16x32_bf16 v[60:63], v[150:153], v[192:195], v[60:63]
	v_mfma_f32_16x16x32_bf16 v[56:59], v[168:171], v[192:195], v[56:59]
	v_mfma_f32_16x16x32_bf16 v[44:47], v[150:153], v[202:205], v[44:47]
	v_mfma_f32_16x16x32_bf16 v[40:43], v[168:171], v[202:205], v[40:43]
	v_mfma_f32_16x16x32_bf16 v[28:31], v[150:153], v[210:213], v[28:31]
	v_mfma_f32_16x16x32_bf16 v[24:27], v[168:171], v[210:213], v[24:27]
	v_mfma_f32_16x16x32_bf16 v[12:15], v[150:153], v[218:221], v[12:15]
	v_mfma_f32_16x16x32_bf16 v[8:11], v[168:171], v[218:221], v[8:11]
	v_mfma_f32_16x16x32_bf16 v[52:55], v[172:175], v[188:191], v[52:55]
	v_mfma_f32_16x16x32_bf16 v[48:51], v[180:183], v[188:191], v[48:51]
	v_mfma_f32_16x16x32_bf16 v[36:39], v[172:175], v[198:201], v[36:39]
	v_mfma_f32_16x16x32_bf16 v[32:35], v[180:183], v[198:201], v[32:35]
	v_mfma_f32_16x16x32_bf16 v[20:23], v[172:175], v[206:209], v[20:23]
	v_mfma_f32_16x16x32_bf16 v[16:19], v[180:183], v[206:209], v[16:19]
	v_mfma_f32_16x16x32_bf16 v[4:7], v[172:175], v[214:217], v[4:7]
	v_mfma_f32_16x16x32_bf16 v[0:3], v[180:183], v[214:217], v[0:3]
	v_mfma_f32_16x16x32_bf16 v[52:55], v[176:179], v[192:195], v[52:55]
	v_mfma_f32_16x16x32_bf16 v[48:51], v[184:187], v[192:195], v[48:51]
	v_mfma_f32_16x16x32_bf16 v[36:39], v[176:179], v[202:205], v[36:39]
	v_mfma_f32_16x16x32_bf16 v[32:35], v[184:187], v[202:205], v[32:35]
	v_mfma_f32_16x16x32_bf16 v[20:23], v[176:179], v[210:213], v[20:23]
	v_mfma_f32_16x16x32_bf16 v[16:19], v[184:187], v[210:213], v[16:19]
	v_mfma_f32_16x16x32_bf16 v[4:7], v[176:179], v[218:221], v[4:7]
	v_mfma_f32_16x16x32_bf16 v[0:3], v[184:187], v[218:221], v[0:3]
	s_barrier
	s_add_i32 s84, s84, 2
	s_add_u32 s20, s20, 0x100
	s_addc_u32 s21, s21, 0
	s_add_u32 s80, s80, 0x100
	s_addc_u32 s81, s81, 0
	s_cmp_gt_u32 s84, 13
.LBB0_414:
	ds_read_b128 v[146:149], v165
	ds_read_b128 v[150:153], v165 offset:1024
	ds_read_b128 v[154:157], v165 offset:2048
	ds_read_b128 v[168:171], v165 offset:3072
	ds_read_b128 v[172:175], v166
	ds_read_b128 v[176:179], v166 offset:1024
	ds_read_b128 v[180:183], v166 offset:2048
	ds_read_b128 v[184:187], v166 offset:3072
	s_add_u32 s52, s20, 0xfffc0080
	s_addc_u32 s53, s21, -1
	s_cmp_eq_u32 s84, 12
	s_cselect_b32 s55, s43, s53
	s_cselect_b32 s54, s78, s52
	s_cselect_b32 s53, s19, s81
	s_cselect_b32 s52, s79, s80
	s_add_i32 m0, s35, 0xc000
	ds_read_b128 v[188:191], v167
	ds_read_b128 v[192:195], v167 offset:1024
	ds_read_b128 v[198:201], v167 offset:2048
	ds_read_b128 v[202:205], v167 offset:3072
	ds_read_b128 v[206:209], v167 offset:4096
	ds_read_b128 v[210:213], v167 offset:5120
	ds_read_b128 v[214:217], v167 offset:6144
	ds_read_b128 v[218:221], v167 offset:7168
	global_load_lds_dwordx4 v138, s[20:21]
	s_add_i32 m0, s35, 0xe000
	s_nop 0
	global_load_lds_dwordx4 v140, s[20:21]
	s_waitcnt vmcnt(8)
	s_waitcnt lgkmcnt(0)
	s_barrier
	v_mfma_f32_16x16x32_bf16 v[124:127], v[146:149], v[188:191], v[124:127]
	v_mfma_f32_16x16x32_bf16 v[120:123], v[154:157], v[188:191], v[120:123]
	v_mfma_f32_16x16x32_bf16 v[108:111], v[146:149], v[198:201], v[108:111]
	v_mfma_f32_16x16x32_bf16 v[104:107], v[154:157], v[198:201], v[104:107]
	v_mfma_f32_16x16x32_bf16 v[92:95], v[146:149], v[206:209], v[92:95]
	v_mfma_f32_16x16x32_bf16 v[88:91], v[154:157], v[206:209], v[88:91]
	v_mfma_f32_16x16x32_bf16 v[76:79], v[146:149], v[214:217], v[76:79]
	v_mfma_f32_16x16x32_bf16 v[72:75], v[154:157], v[214:217], v[72:75]
	v_mfma_f32_16x16x32_bf16 v[124:127], v[150:153], v[192:195], v[124:127]
	v_mfma_f32_16x16x32_bf16 v[120:123], v[168:171], v[192:195], v[120:123]
	v_mfma_f32_16x16x32_bf16 v[108:111], v[150:153], v[202:205], v[108:111]
	v_mfma_f32_16x16x32_bf16 v[104:107], v[168:171], v[202:205], v[104:107]
	v_mfma_f32_16x16x32_bf16 v[92:95], v[150:153], v[210:213], v[92:95]
	v_mfma_f32_16x16x32_bf16 v[88:91], v[168:171], v[210:213], v[88:91]
	v_mfma_f32_16x16x32_bf16 v[76:79], v[150:153], v[218:221], v[76:79]
	v_mfma_f32_16x16x32_bf16 v[72:75], v[168:171], v[218:221], v[72:75]
	v_mfma_f32_16x16x32_bf16 v[116:119], v[172:175], v[188:191], v[116:119]
	v_mfma_f32_16x16x32_bf16 v[112:115], v[180:183], v[188:191], v[112:115]
	v_mfma_f32_16x16x32_bf16 v[100:103], v[172:175], v[198:201], v[100:103]
	v_mfma_f32_16x16x32_bf16 v[96:99], v[180:183], v[198:201], v[96:99]
	v_mfma_f32_16x16x32_bf16 v[84:87], v[172:175], v[206:209], v[84:87]
	v_mfma_f32_16x16x32_bf16 v[80:83], v[180:183], v[206:209], v[80:83]
	v_mfma_f32_16x16x32_bf16 v[68:71], v[172:175], v[214:217], v[68:71]
	v_mfma_f32_16x16x32_bf16 v[64:67], v[180:183], v[214:217], v[64:67]
	v_mfma_f32_16x16x32_bf16 v[116:119], v[176:179], v[192:195], v[116:119]
	v_mfma_f32_16x16x32_bf16 v[112:115], v[184:187], v[192:195], v[112:115]
	v_mfma_f32_16x16x32_bf16 v[100:103], v[176:179], v[202:205], v[100:103]
	v_mfma_f32_16x16x32_bf16 v[96:99], v[184:187], v[202:205], v[96:99]
	v_mfma_f32_16x16x32_bf16 v[84:87], v[176:179], v[210:213], v[84:87]
	v_mfma_f32_16x16x32_bf16 v[80:83], v[184:187], v[210:213], v[80:83]
	v_mfma_f32_16x16x32_bf16 v[68:71], v[176:179], v[218:221], v[68:71]
	v_mfma_f32_16x16x32_bf16 v[64:67], v[184:187], v[218:221], v[64:67]
	s_barrier
; #define PG8_STAGE(bufoff, gbase, voff) do { _Pragma("unroll") for (int _i = 0; _i < 2; ++_i) \
;         __builtin_amdgcn_global_load_lds((const unsigned*)((const char*)(gbase) + (voff)[_i]), (PG8_LAS unsigned*)(lds + (bufoff) + ldsw + _i * 8192), 16, 0, 0); } while (0)
; #define PG8_LDA(dst, b, h) do { _Pragma("unroll") for (int m = 0; m < 4; ++m) _Pragma("unroll") for (int k = 0; k < 2; ++k) dst[m][k] = *(const PG8_LAS bf16x8*)(lds + PG8_SA(b, h) + aoff + m * 2048 + k * 1024); } while (0)
; #define PG8_LDB(dst, b, h) do { _Pragma("unroll") for (int n = 0; n < 2; ++n) _Pragma("unroll") for (int k = 0; k < 2; ++k) dst[n][k] = *(const PG8_LAS bf16x8*)(lds + PG8_SB(b, h) + boff + n * 2048 + k * 1024); } while (0)
; #define PG8_MMA(ai, bj, At, Bt) do { __builtin_amdgcn_s_setprio(1); _Pragma("unroll") for (int m = 0; m < 4; ++m) _Pragma("unroll") for (int n = 0; n < 2; ++n) _Pragma("unroll") for (int k = 0; k < 2; ++k) \
;         acc[ai][bj][m][n] = __builtin_amdgcn_mfma_f32_16x16x32_bf16(Bt[n][k], At[m][k], acc[ai][bj][m][n], 0, 0, 0); __builtin_amdgcn_s_setprio(0); } while (0)
; #define PG8_WAIT_V(n) asm volatile("s_waitcnt vmcnt(" #n ")" ::: "memory")
; #define PG8_WAIT_L(n) asm volatile("s_waitcnt lgkmcnt(" #n ")" ::: "memory")
; #define PG8_BAR __builtin_amdgcn_s_barrier()
; #define PG8_SCHED __builtin_amdgcn_sched_barrier(0)
; template <class Epi, class Sched, bool ALIGN_EPI = false, bool SP2 = false>
; __device__ __forceinline__ void gemm_phase(PG8_LAS unsigned char* lds, const Gemm g, const Sched& S, const Epi& E) {
;     ...
;             PG8_LDA(At, 0, 1); PG8_STAGE(PG8_SB(0, 0), b2, voffB); PG8_STAGE(PG8_SB(0, 1), b2 + hstep, voffB); PG8_STAGE(PG8_SA(0, 0), a2, voffA);
;             PG8_WAIT_V(8); PG8_WAIT_L(0); PG8_BAR; PG8_MMA(1, 0, At, B0); PG8_MMA(1, 1, At, B1); PG8_BAR; PG8_SCHED;
;             PG8_LDB(B0, 1, 0); PG8_LDB(B1, 1, 1); PG8_SCHED; PG8_LDA(At, 1, 0); PG8_STAGE(PG8_SA(0, 1), a2 + hstep, voffA);
	s_add_i32 s85, s72, s63
	s_add_u32 s98, s52, s8
	s_addc_u32 s99, s53, s9
	s_add_u32 s100, s54, s8
	s_addc_u32 s101, s55, s9
	s_mov_b32 m0, s85
	ds_read_b128 v[188:191], v167 offset:16384
	ds_read_b128 v[192:195], v167 offset:17408
	ds_read_b128 v[198:201], v167 offset:18432
	ds_read_b128 v[202:205], v167 offset:19456
	ds_read_b128 v[206:209], v167 offset:20480
	ds_read_b128 v[210:213], v167 offset:21504
	ds_read_b128 v[214:217], v167 offset:22528
	ds_read_b128 v[218:221], v167 offset:23552
	global_load_lds_dwordx4 v132, s[52:53]
	s_add_i32 m0, s85, 0x2000
	s_add_u32 s86, s52, 0x40000
	s_addc_u32 s87, s53, 0
	s_add_i32 s85, s73, s63
	global_load_lds_dwordx4 v128, s[52:53]
	s_mov_b32 m0, s85
	s_nop 0
	global_load_lds_dwordx4 v132, s[86:87]
	s_add_i32 m0, s85, 0x2000
	s_nop 0
	global_load_lds_dwordx4 v128, s[86:87]
	s_mov_b32 m0, s35
	s_nop 0
	global_load_lds_dwordx4 v134, s[54:55]
	s_mov_b32 m0, s65
	s_nop 0
	global_load_lds_dwordx4 v130, s[54:55]
	s_waitcnt vmcnt(8)
	s_waitcnt lgkmcnt(0)
	s_barrier
	v_mfma_f32_16x16x32_bf16 v[60:63], v[146:149], v[188:191], v[60:63]
	v_mfma_f32_16x16x32_bf16 v[56:59], v[154:157], v[188:191], v[56:59]
	v_mfma_f32_16x16x32_bf16 v[44:47], v[146:149], v[198:201], v[44:47]
	v_mfma_f32_16x16x32_bf16 v[40:43], v[154:157], v[198:201], v[40:43]
	v_mfma_f32_16x16x32_bf16 v[28:31], v[146:149], v[206:209], v[28:31]
	v_mfma_f32_16x16x32_bf16 v[24:27], v[154:157], v[206:209], v[24:27]
	v_mfma_f32_16x16x32_bf16 v[12:15], v[146:149], v[214:217], v[12:15]
	v_mfma_f32_16x16x32_bf16 v[8:11], v[154:157], v[214:217], v[8:11]
	v_mfma_f32_16x16x32_bf16 v[60:63], v[150:153], v[192:195], v[60:63]
	v_mfma_f32_16x16x32_bf16 v[56:59], v[168:171], v[192:195], v[56:59]
	v_mfma_f32_16x16x32_bf16 v[44:47], v[150:153], v[202:205], v[44:47]
	v_mfma_f32_16x16x32_bf16 v[40:43], v[168:171], v[202:205], v[40:43]
	v_mfma_f32_16x16x32_bf16 v[28:31], v[150:153], v[210:213], v[28:31]
	v_mfma_f32_16x16x32_bf16 v[24:27], v[168:171], v[210:213], v[24:27]
	v_mfma_f32_16x16x32_bf16 v[12:15], v[150:153], v[218:221], v[12:15]
	v_mfma_f32_16x16x32_bf16 v[8:11], v[168:171], v[218:221], v[8:11]
	v_mfma_f32_16x16x32_bf16 v[52:55], v[172:175], v[188:191], v[52:55]
	v_mfma_f32_16x16x32_bf16 v[48:51], v[180:183], v[188:191], v[48:51]
	v_mfma_f32_16x16x32_bf16 v[36:39], v[172:175], v[198:201], v[36:39]
	v_mfma_f32_16x16x32_bf16 v[32:35], v[180:183], v[198:201], v[32:35]
	v_mfma_f32_16x16x32_bf16 v[20:23], v[172:175], v[206:209], v[20:23]
	v_mfma_f32_16x16x32_bf16 v[16:19], v[180:183], v[206:209], v[16:19]
	v_mfma_f32_16x16x32_bf16 v[4:7], v[172:175], v[214:217], v[4:7]
	v_mfma_f32_16x16x32_bf16 v[0:3], v[180:183], v[214:217], v[0:3]
	v_mfma_f32_16x16x32_bf16 v[52:55], v[176:179], v[192:195], v[52:55]
	v_mfma_f32_16x16x32_bf16 v[48:51], v[184:187], v[192:195], v[48:51]
	v_mfma_f32_16x16x32_bf16 v[36:39], v[176:179], v[202:205], v[36:39]
	v_mfma_f32_16x16x32_bf16 v[32:35], v[184:187], v[202:205], v[32:35]
	v_mfma_f32_16x16x32_bf16 v[20:23], v[176:179], v[210:213], v[20:23]
	v_mfma_f32_16x16x32_bf16 v[16:19], v[184:187], v[210:213], v[16:19]
	v_mfma_f32_16x16x32_bf16 v[4:7], v[176:179], v[218:221], v[4:7]
	v_mfma_f32_16x16x32_bf16 v[0:3], v[184:187], v[218:221], v[0:3]
	s_barrier
	s_add_i32 s85, 0, 0x18000
	v_add_u32_e32 v136, s85, v161
	s_add_i32 s86, 0, 0x1c000
	ds_read_b128 v[146:149], v136
	ds_read_b128 v[150:153], v136 offset:1024
	ds_read_b128 v[154:157], v136 offset:2048
	ds_read_b128 v[168:171], v136 offset:3072
	v_add_u32_e32 v136, s86, v161
	ds_read_b128 v[172:175], v136
	ds_read_b128 v[176:179], v136 offset:1024
	ds_read_b128 v[180:183], v136 offset:2048
	ds_read_b128 v[184:187], v136 offset:3072
	s_add_u32 s54, s54, 0x40000
	s_addc_u32 s55, s55, 0
	s_mov_b32 m0, s66
	ds_read_b128 v[188:191], v167 offset:32768
	ds_read_b128 v[192:195], v167 offset:33792
	ds_read_b128 v[198:201], v167 offset:34816
	ds_read_b128 v[202:205], v167 offset:35840
	ds_read_b128 v[206:209], v167 offset:36864
	ds_read_b128 v[210:213], v167 offset:37888
	ds_read_b128 v[214:217], v167 offset:38912
	ds_read_b128 v[218:221], v167 offset:39936
	global_load_lds_dwordx4 v134, s[54:55]
	s_mov_b32 m0, s67
	s_nop 0
	global_load_lds_dwordx4 v130, s[54:55]
	s_waitcnt vmcnt(8)
	s_waitcnt lgkmcnt(0)
	s_barrier
; #define PG8_STAGE(bufoff, gbase, voff) do { _Pragma("unroll") for (int _i = 0; _i < 2; ++_i) \
;         __builtin_amdgcn_global_load_lds((const unsigned*)((const char*)(gbase) + (voff)[_i]), (PG8_LAS unsigned*)(lds + (bufoff) + ldsw + _i * 8192), 16, 0, 0); } while (0)
; #define PG8_LDA(dst, b, h) do { _Pragma("unroll") for (int m = 0; m < 4; ++m) _Pragma("unroll") for (int k = 0; k < 2; ++k) dst[m][k] = *(const PG8_LAS bf16x8*)(lds + PG8_SA(b, h) + aoff + m * 2048 + k * 1024); } while (0)
; #define PG8_MMA(ai, bj, At, Bt) do { __builtin_amdgcn_s_setprio(1); _Pragma("unroll") for (int m = 0; m < 4; ++m) _Pragma("unroll") for (int n = 0; n < 2; ++n) _Pragma("unroll") for (int k = 0; k < 2; ++k) \
;         acc[ai][bj][m][n] = __builtin_amdgcn_mfma_f32_16x16x32_bf16(Bt[n][k], At[m][k], acc[ai][bj][m][n], 0, 0, 0); __builtin_amdgcn_s_setprio(0); } while (0)
; #define PG8_WAIT_V(n) asm volatile("s_waitcnt vmcnt(" #n ")" ::: "memory")
; #define PG8_WAIT_L(n) asm volatile("s_waitcnt lgkmcnt(" #n ")" ::: "memory")
; #define PG8_BAR __builtin_amdgcn_s_barrier()
; #define PG8_SCHED __builtin_amdgcn_sched_barrier(0)
; template <class Epi, class Sched, bool ALIGN_EPI = false, bool SP2 = false>
; __device__ __forceinline__ void gemm_phase(PG8_LAS unsigned char* lds, const Gemm g, const Sched& S, const Epi& E) {
;     ...
;             PG8_WAIT_V(8); PG8_WAIT_L(0); PG8_BAR; PG8_MMA(0, 0, At, B0); PG8_MMA(0, 1, At, B1); PG8_BAR; PG8_SCHED;
;             PG8_LDA(At, 1, 1); PG8_STAGE(PG8_SB(1, 0), b3, voffB); PG8_STAGE(PG8_SB(1, 1), b3 + hstep, voffB); PG8_STAGE(PG8_SA(1, 0), a3, voffA);
;             PG8_WAIT_V(8); PG8_WAIT_L(0); PG8_BAR; PG8_MMA(1, 0, At, B0); PG8_MMA(1, 1, At, B1); PG8_BAR; PG8_SCHED;
;     ...
;         if constexpr (ALIGN_EPI) { if (wr == 0) PG8_BAR; }
	v_mfma_f32_16x16x32_bf16 v[124:127], v[146:149], v[188:191], v[124:127]
	v_mfma_f32_16x16x32_bf16 v[120:123], v[154:157], v[188:191], v[120:123]
	v_mfma_f32_16x16x32_bf16 v[108:111], v[146:149], v[198:201], v[108:111]
	v_mfma_f32_16x16x32_bf16 v[104:107], v[154:157], v[198:201], v[104:107]
	v_mfma_f32_16x16x32_bf16 v[92:95], v[146:149], v[206:209], v[92:95]
	v_mfma_f32_16x16x32_bf16 v[88:91], v[154:157], v[206:209], v[88:91]
	v_mfma_f32_16x16x32_bf16 v[76:79], v[146:149], v[214:217], v[76:79]
	v_mfma_f32_16x16x32_bf16 v[72:75], v[154:157], v[214:217], v[72:75]
	v_mfma_f32_16x16x32_bf16 v[124:127], v[150:153], v[192:195], v[124:127]
	v_mfma_f32_16x16x32_bf16 v[120:123], v[168:171], v[192:195], v[120:123]
	v_mfma_f32_16x16x32_bf16 v[108:111], v[150:153], v[202:205], v[108:111]
	v_mfma_f32_16x16x32_bf16 v[104:107], v[168:171], v[202:205], v[104:107]
	v_mfma_f32_16x16x32_bf16 v[92:95], v[150:153], v[210:213], v[92:95]
	v_mfma_f32_16x16x32_bf16 v[88:91], v[168:171], v[210:213], v[88:91]
	v_mfma_f32_16x16x32_bf16 v[76:79], v[150:153], v[218:221], v[76:79]
	v_mfma_f32_16x16x32_bf16 v[72:75], v[168:171], v[218:221], v[72:75]
	v_mfma_f32_16x16x32_bf16 v[116:119], v[172:175], v[188:191], v[116:119]
	v_mfma_f32_16x16x32_bf16 v[112:115], v[180:183], v[188:191], v[112:115]
	v_mfma_f32_16x16x32_bf16 v[100:103], v[172:175], v[198:201], v[100:103]
	v_mfma_f32_16x16x32_bf16 v[96:99], v[180:183], v[198:201], v[96:99]
	v_mfma_f32_16x16x32_bf16 v[84:87], v[172:175], v[206:209], v[84:87]
	v_mfma_f32_16x16x32_bf16 v[80:83], v[180:183], v[206:209], v[80:83]
	v_mfma_f32_16x16x32_bf16 v[68:71], v[172:175], v[214:217], v[68:71]
	v_mfma_f32_16x16x32_bf16 v[64:67], v[180:183], v[214:217], v[64:67]
	v_mfma_f32_16x16x32_bf16 v[116:119], v[176:179], v[192:195], v[116:119]
	v_mfma_f32_16x16x32_bf16 v[112:115], v[184:187], v[192:195], v[112:115]
	v_mfma_f32_16x16x32_bf16 v[100:103], v[176:179], v[202:205], v[100:103]
	v_mfma_f32_16x16x32_bf16 v[96:99], v[184:187], v[202:205], v[96:99]
	v_mfma_f32_16x16x32_bf16 v[84:87], v[176:179], v[210:213], v[84:87]
	v_mfma_f32_16x16x32_bf16 v[80:83], v[184:187], v[210:213], v[80:83]
	v_mfma_f32_16x16x32_bf16 v[68:71], v[176:179], v[218:221], v[68:71]
	v_mfma_f32_16x16x32_bf16 v[64:67], v[184:187], v[218:221], v[64:67]
	s_barrier
	s_add_i32 s54, s85, s63
	s_mov_b32 m0, s54
	ds_read_b128 v[188:191], v167 offset:49152
	ds_read_b128 v[192:195], v167 offset:50176
	ds_read_b128 v[198:201], v167 offset:51200
	ds_read_b128 v[202:205], v167 offset:52224
	ds_read_b128 v[206:209], v167 offset:53248
	ds_read_b128 v[210:213], v167 offset:54272
	ds_read_b128 v[214:217], v167 offset:55296
	ds_read_b128 v[218:221], v167 offset:56320
	global_load_lds_dwordx4 v132, s[98:99]
	s_add_i32 m0, s54, 0x2000
	s_add_u32 s52, s52, 0x40080
	s_addc_u32 s53, s53, 0
	s_add_i32 s54, s86, s63
	global_load_lds_dwordx4 v128, s[98:99]
	s_mov_b32 m0, s54
	s_nop 0
	global_load_lds_dwordx4 v132, s[52:53]
	s_add_i32 m0, s54, 0x2000
	s_nop 0
	global_load_lds_dwordx4 v128, s[52:53]
	s_mov_b32 m0, s69
	s_nop 0
	global_load_lds_dwordx4 v134, s[100:101]
	s_mov_b32 m0, s70
	s_nop 0
	global_load_lds_dwordx4 v130, s[100:101]
	s_waitcnt vmcnt(8)
	s_waitcnt lgkmcnt(0)
	s_barrier
	v_mfma_f32_16x16x32_bf16 v[60:63], v[146:149], v[188:191], v[60:63]
	v_mfma_f32_16x16x32_bf16 v[56:59], v[154:157], v[188:191], v[56:59]
	v_mfma_f32_16x16x32_bf16 v[44:47], v[146:149], v[198:201], v[44:47]
	v_mfma_f32_16x16x32_bf16 v[40:43], v[154:157], v[198:201], v[40:43]
	v_mfma_f32_16x16x32_bf16 v[28:31], v[146:149], v[206:209], v[28:31]
	v_mfma_f32_16x16x32_bf16 v[24:27], v[154:157], v[206:209], v[24:27]
	v_mfma_f32_16x16x32_bf16 v[12:15], v[146:149], v[214:217], v[12:15]
	v_mfma_f32_16x16x32_bf16 v[8:11], v[154:157], v[214:217], v[8:11]
	v_mfma_f32_16x16x32_bf16 v[60:63], v[150:153], v[192:195], v[60:63]
	v_mfma_f32_16x16x32_bf16 v[56:59], v[168:171], v[192:195], v[56:59]
	v_mfma_f32_16x16x32_bf16 v[44:47], v[150:153], v[202:205], v[44:47]
	v_mfma_f32_16x16x32_bf16 v[40:43], v[168:171], v[202:205], v[40:43]
	v_mfma_f32_16x16x32_bf16 v[28:31], v[150:153], v[210:213], v[28:31]
	v_mfma_f32_16x16x32_bf16 v[24:27], v[168:171], v[210:213], v[24:27]
	v_mfma_f32_16x16x32_bf16 v[12:15], v[150:153], v[218:221], v[12:15]
	v_mfma_f32_16x16x32_bf16 v[8:11], v[168:171], v[218:221], v[8:11]
	v_mfma_f32_16x16x32_bf16 v[52:55], v[172:175], v[188:191], v[52:55]
	v_mfma_f32_16x16x32_bf16 v[48:51], v[180:183], v[188:191], v[48:51]
	v_mfma_f32_16x16x32_bf16 v[36:39], v[172:175], v[198:201], v[36:39]
	v_mfma_f32_16x16x32_bf16 v[32:35], v[180:183], v[198:201], v[32:35]
	v_mfma_f32_16x16x32_bf16 v[20:23], v[172:175], v[206:209], v[20:23]
	v_mfma_f32_16x16x32_bf16 v[16:19], v[180:183], v[206:209], v[16:19]
	v_mfma_f32_16x16x32_bf16 v[4:7], v[172:175], v[214:217], v[4:7]
	v_mfma_f32_16x16x32_bf16 v[0:3], v[180:183], v[214:217], v[0:3]
	v_mfma_f32_16x16x32_bf16 v[52:55], v[176:179], v[192:195], v[52:55]
	v_mfma_f32_16x16x32_bf16 v[48:51], v[184:187], v[192:195], v[48:51]
	v_mfma_f32_16x16x32_bf16 v[36:39], v[176:179], v[202:205], v[36:39]
	v_mfma_f32_16x16x32_bf16 v[32:35], v[184:187], v[202:205], v[32:35]
	v_mfma_f32_16x16x32_bf16 v[20:23], v[176:179], v[210:213], v[20:23]
	v_mfma_f32_16x16x32_bf16 v[16:19], v[184:187], v[210:213], v[16:19]
	v_mfma_f32_16x16x32_bf16 v[4:7], v[176:179], v[218:221], v[4:7]
	v_mfma_f32_16x16x32_bf16 v[0:3], v[184:187], v[218:221], v[0:3]
	s_barrier
	s_add_i32 s84, s84, 2
	s_add_u32 s20, s20, 0x100
	s_addc_u32 s21, s21, 0
	s_add_u32 s80, s80, 0x100
	s_addc_u32 s81, s81, 0
	s_cmp_gt_u32 s84, 13
	s_cbranch_scc0 .LBB0_414
	s_and_b64 vcc, exec, s[10:11]
	s_cbranch_vccz .LBB0_417
	s_barrier

; #define PG8_STAGE(bufoff, gbase, voff) do { _Pragma("unroll") for (int _i = 0; _i < 2; ++_i) \
;         __builtin_amdgcn_global_load_lds((const unsigned*)((const char*)(gbase) + (voff)[_i]), (PG8_LAS unsigned*)(lds + (bufoff) + ldsw + _i * 8192), 16, 0, 0); } while (0)
; #define PG8_LDA(dst, b, h) do { _Pragma("unroll") for (int m = 0; m < 4; ++m) _Pragma("unroll") for (int k = 0; k < 2; ++k) dst[m][k] = *(const PG8_LAS bf16x8*)(lds + PG8_SA(b, h) + aoff + m * 2048 + k * 1024); } while (0)
; #define PG8_LDB(dst, b, h) do { _Pragma("unroll") for (int n = 0; n < 2; ++n) _Pragma("unroll") for (int k = 0; k < 2; ++k) dst[n][k] = *(const PG8_LAS bf16x8*)(lds + PG8_SB(b, h) + boff + n * 2048 + k * 1024); } while (0)
; #define PG8_WAIT_V(n) asm volatile("s_waitcnt vmcnt(" #n ")" ::: "memory")
; #define PG8_WAIT_L(n) asm volatile("s_waitcnt lgkmcnt(" #n ")" ::: "memory")
; template <class Epi, class Sched, bool ALIGN_EPI = false, bool SP2 = false>
; __device__ __forceinline__ void gemm_phase(PG8_LAS unsigned char* lds, const Gemm g, const Sched& S, const Epi& E) {
;     ...
;         const bool has_next = S.next(ui + 1, nxt);
;         const char* nA = has_next ? (const char*)g.A + (size_t)nxt.pm * tstep : cA; const char* nB = has_next ? (const char*)g.Bt + (size_t)nxt.pn * tstep : cB;
;         for (int t = 0; t < nt; t += 2) {
;             const bool last = (t == nt - 2);
;             const char* a1 = cA + (size_t)(t + 1) * kstep;
;             const char* a2 = last ? nA : cA + (size_t)(t + 2) * kstep; const char* b2 = last ? nB : cB + (size_t)(t + 2) * kstep;
;             const char* a3 = a2 + kstep; const char* b3 = b2 + kstep;
;             if (last && has_next) S.a_ready(nxt);
;             if constexpr (SP2) {
;             PG8_LDB(B0, 0, 0); PG8_LDB(B1, 0, 1); PG8_SCHED; PG8_LDA(At, 0, 0); PG8_STAGE(PG8_SA(1, 1), a1 + hstep, voffA);
;             PG8_WAIT_V(8); PG8_WAIT_L(0); PG8_BAR; PG8_MMA(0, 0, At, B0); PG8_MMA(0, 1, At, B1); PG8_BAR; PG8_SCHED;
;             PG8_LDA(At, 0, 1); PG8_STAGE(PG8_SB(0, 0), b2, voffB); PG8_STAGE(PG8_SB(0, 1), b2 + hstep, voffB); PG8_STAGE(PG8_SA(0, 0), a2, voffA);
;             PG8_WAIT_V(8); PG8_WAIT_L(0); PG8_BAR; PG8_MMA(1, 0, At, B0); PG8_MMA(1, 1, At, B1); PG8_BAR; PG8_SCHED;
;             PG8_LDB(B0, 1, 0); PG8_LDB(B1, 1, 1); PG8_SCHED; PG8_LDA(At, 1, 0); PG8_STAGE(PG8_SA(0, 1), a2 + hstep, voffA);
.LBB0_623:
	s_ashr_i32 s17, s16, 31
	s_lshl_b64 s[18:19], s[16:17], 18
	s_add_u32 s18, s0, s18
	s_addc_u32 s19, s1, s19
	s_and_b64 s[38:39], s[4:5], exec
	s_cselect_b32 s17, s19, s21
	s_cselect_b32 s63, s18, s20
	s_ashr_i32 s15, s14, 31
	s_lshl_b64 s[38:39], s[14:15], 18
	s_add_u32 s38, s33, s38
	s_addc_u32 s39, s50, s39
	s_and_b64 s[48:49], s[4:5], exec
	s_cselect_b32 s15, s39, s47
	s_cselect_b32 s64, s38, s46
	s_add_u32 s20, s20, 0x20080
	s_addc_u32 s21, s21, 0
	s_add_u32 s65, s46, 0x100
	s_addc_u32 s66, s47, 0
	s_mov_b32 s67, -2
	ds_read_b128 v[112:115], v167
	ds_read_b128 v[116:119], v167 offset:1024
	ds_read_b128 v[152:155], v167 offset:2048
	ds_read_b128 v[156:159], v167 offset:3072
	ds_read_b128 v[160:163], v168
	ds_read_b128 v[170:173], v168 offset:1024
	ds_read_b128 v[174:177], v168 offset:2048
	ds_read_b128 v[178:181], v168 offset:3072
	s_add_u32 s46, s20, 0xfffe0080
	s_addc_u32 s47, s21, -1
	s_cmp_eq_u32 s67, 4
	s_cselect_b32 s49, s17, s47
	s_cselect_b32 s48, s63, s46
	s_cselect_b32 s47, s15, s66
	s_cselect_b32 s46, s64, s65
	s_add_i32 m0, s35, 0xc000
	ds_read_b128 v[182:185], v169
	ds_read_b128 v[186:189], v169 offset:1024
	ds_read_b128 v[190:193], v169 offset:2048
	ds_read_b128 v[198:201], v169 offset:3072
	ds_read_b128 v[202:205], v169 offset:4096
	ds_read_b128 v[206:209], v169 offset:5120
	ds_read_b128 v[210:213], v169 offset:6144
	ds_read_b128 v[214:217], v169 offset:7168
	global_load_lds_dwordx4 v144, s[20:21]
	s_add_i32 m0, s35, 0xe000
	s_nop 0
	global_load_lds_dwordx4 v146, s[20:21]
	s_waitcnt vmcnt(8)
	s_waitcnt lgkmcnt(0)
	s_barrier
	v_mfma_f32_16x16x32_bf16 v[132:135], v[112:115], v[182:185], 0
	v_mfma_f32_16x16x32_bf16 v[128:131], v[152:155], v[182:185], 0
	v_mfma_f32_16x16x32_bf16 v[124:127], v[112:115], v[190:193], 0
	v_mfma_f32_16x16x32_bf16 v[120:123], v[152:155], v[190:193], 0
	v_mfma_f32_16x16x32_bf16 v[108:111], v[112:115], v[202:205], 0
	v_mfma_f32_16x16x32_bf16 v[104:107], v[152:155], v[202:205], 0
	v_mfma_f32_16x16x32_bf16 v[100:103], v[112:115], v[210:213], 0
	v_mfma_f32_16x16x32_bf16 v[96:99], v[152:155], v[210:213], 0
	v_mfma_f32_16x16x32_bf16 v[132:135], v[116:119], v[186:189], v[132:135]
	v_mfma_f32_16x16x32_bf16 v[128:131], v[156:159], v[186:189], v[128:131]
	v_mfma_f32_16x16x32_bf16 v[124:127], v[116:119], v[198:201], v[124:127]
	v_mfma_f32_16x16x32_bf16 v[120:123], v[156:159], v[198:201], v[120:123]
	v_mfma_f32_16x16x32_bf16 v[108:111], v[116:119], v[206:209], v[108:111]
	v_mfma_f32_16x16x32_bf16 v[104:107], v[156:159], v[206:209], v[104:107]
	v_mfma_f32_16x16x32_bf16 v[100:103], v[116:119], v[214:217], v[100:103]
	v_mfma_f32_16x16x32_bf16 v[96:99], v[156:159], v[214:217], v[96:99]
	v_mfma_f32_16x16x32_bf16 v[60:63], v[160:163], v[182:185], 0
	v_mfma_f32_16x16x32_bf16 v[56:59], v[174:177], v[182:185], 0
	v_mfma_f32_16x16x32_bf16 v[52:55], v[160:163], v[190:193], 0
	v_mfma_f32_16x16x32_bf16 v[48:51], v[174:177], v[190:193], 0
	v_mfma_f32_16x16x32_bf16 v[44:47], v[160:163], v[202:205], 0
	v_mfma_f32_16x16x32_bf16 v[40:43], v[174:177], v[202:205], 0
	v_mfma_f32_16x16x32_bf16 v[36:39], v[160:163], v[210:213], 0
	v_mfma_f32_16x16x32_bf16 v[32:35], v[174:177], v[210:213], 0
	v_mfma_f32_16x16x32_bf16 v[60:63], v[170:173], v[186:189], v[60:63]
	v_mfma_f32_16x16x32_bf16 v[56:59], v[178:181], v[186:189], v[56:59]
	v_mfma_f32_16x16x32_bf16 v[52:55], v[170:173], v[198:201], v[52:55]
	v_mfma_f32_16x16x32_bf16 v[48:51], v[178:181], v[198:201], v[48:51]
	v_mfma_f32_16x16x32_bf16 v[44:47], v[170:173], v[206:209], v[44:47]
	v_mfma_f32_16x16x32_bf16 v[40:43], v[178:181], v[206:209], v[40:43]
	v_mfma_f32_16x16x32_bf16 v[36:39], v[170:173], v[214:217], v[36:39]
	v_mfma_f32_16x16x32_bf16 v[32:35], v[178:181], v[214:217], v[32:35]
	s_barrier
	s_add_i32 s68, s60, s51
	s_add_u32 s98, s46, s10
	s_addc_u32 s99, s47, s11
	s_add_u32 s100, s48, s10
	s_addc_u32 s101, s49, s11
	s_mov_b32 m0, s68
	ds_read_b128 v[182:185], v169 offset:16384
	ds_read_b128 v[186:189], v169 offset:17408
	ds_read_b128 v[190:193], v169 offset:18432
	ds_read_b128 v[198:201], v169 offset:19456
	ds_read_b128 v[202:205], v169 offset:20480
	ds_read_b128 v[206:209], v169 offset:21504
	ds_read_b128 v[210:213], v169 offset:22528
	ds_read_b128 v[214:217], v169 offset:23552
	global_load_lds_dwordx4 v138, s[46:47]
	s_add_i32 m0, s68, 0x2000
	s_add_u32 s68, s46, 0x20000
	s_addc_u32 s69, s47, 0
	s_add_i32 s70, s61, s51
	global_load_lds_dwordx4 v142, s[46:47]
	s_mov_b32 m0, s70
	s_nop 0
	global_load_lds_dwordx4 v138, s[68:69]
	s_add_i32 m0, s70, 0x2000
	s_nop 0
	global_load_lds_dwordx4 v142, s[68:69]
	s_mov_b32 m0, s35
	s_nop 0
	global_load_lds_dwordx4 v136, s[48:49]
	s_mov_b32 m0, s52
	s_nop 0
	global_load_lds_dwordx4 v140, s[48:49]
	s_waitcnt vmcnt(8)
	s_waitcnt lgkmcnt(0)
	s_barrier
; #define PG8_STAGE(bufoff, gbase, voff) do { _Pragma("unroll") for (int _i = 0; _i < 2; ++_i) \
;         __builtin_amdgcn_global_load_lds((const unsigned*)((const char*)(gbase) + (voff)[_i]), (PG8_LAS unsigned*)(lds + (bufoff) + ldsw + _i * 8192), 16, 0, 0); } while (0)
; #define PG8_LDA(dst, b, h) do { _Pragma("unroll") for (int m = 0; m < 4; ++m) _Pragma("unroll") for (int k = 0; k < 2; ++k) dst[m][k] = *(const PG8_LAS bf16x8*)(lds + PG8_SA(b, h) + aoff + m * 2048 + k * 1024); } while (0)
; #define PG8_LDB(dst, b, h) do { _Pragma("unroll") for (int n = 0; n < 2; ++n) _Pragma("unroll") for (int k = 0; k < 2; ++k) dst[n][k] = *(const PG8_LAS bf16x8*)(lds + PG8_SB(b, h) + boff + n * 2048 + k * 1024); } while (0)
; #define PG8_MMA(ai, bj, At, Bt) do { __builtin_amdgcn_s_setprio(1); _Pragma("unroll") for (int m = 0; m < 4; ++m) _Pragma("unroll") for (int n = 0; n < 2; ++n) _Pragma("unroll") for (int k = 0; k < 2; ++k) \
;         acc[ai][bj][m][n] = __builtin_amdgcn_mfma_f32_16x16x32_bf16(Bt[n][k], At[m][k], acc[ai][bj][m][n], 0, 0, 0); __builtin_amdgcn_s_setprio(0); } while (0)
; #define PG8_WAIT_V(n) asm volatile("s_waitcnt vmcnt(" #n ")" ::: "memory")
; #define PG8_WAIT_L(n) asm volatile("s_waitcnt lgkmcnt(" #n ")" ::: "memory")
; #define PG8_BAR __builtin_amdgcn_s_barrier()
; #define PG8_SCHED __builtin_amdgcn_sched_barrier(0)
; template <class Epi, class Sched, bool ALIGN_EPI = false, bool SP2 = false>
; __device__ __forceinline__ void gemm_phase(PG8_LAS unsigned char* lds, const Gemm g, const Sched& S, const Epi& E) {
;     ...
;             PG8_LDA(At, 0, 1); PG8_STAGE(PG8_SB(0, 0), b2, voffB); PG8_STAGE(PG8_SB(0, 1), b2 + hstep, voffB); PG8_STAGE(PG8_SA(0, 0), a2, voffA);
;             PG8_WAIT_V(8); PG8_WAIT_L(0); PG8_BAR; PG8_MMA(1, 0, At, B0); PG8_MMA(1, 1, At, B1); PG8_BAR; PG8_SCHED;
;             PG8_LDB(B0, 1, 0); PG8_LDB(B1, 1, 1); PG8_SCHED; PG8_LDA(At, 1, 0); PG8_STAGE(PG8_SA(0, 1), a2 + hstep, voffA);
;             PG8_WAIT_V(8); PG8_WAIT_L(0); PG8_BAR; PG8_MMA(0, 0, At, B0); PG8_MMA(0, 1, At, B1); PG8_BAR; PG8_SCHED;
	v_mfma_f32_16x16x32_bf16 v[92:95], v[112:115], v[182:185], 0
	v_mfma_f32_16x16x32_bf16 v[88:91], v[152:155], v[182:185], 0
	v_mfma_f32_16x16x32_bf16 v[84:87], v[112:115], v[190:193], 0
	v_mfma_f32_16x16x32_bf16 v[80:83], v[152:155], v[190:193], 0
	v_mfma_f32_16x16x32_bf16 v[76:79], v[112:115], v[202:205], 0
	v_mfma_f32_16x16x32_bf16 v[72:75], v[152:155], v[202:205], 0
	v_mfma_f32_16x16x32_bf16 v[68:71], v[112:115], v[210:213], 0
	v_mfma_f32_16x16x32_bf16 v[64:67], v[152:155], v[210:213], 0
	v_mfma_f32_16x16x32_bf16 v[92:95], v[116:119], v[186:189], v[92:95]
	v_mfma_f32_16x16x32_bf16 v[88:91], v[156:159], v[186:189], v[88:91]
	v_mfma_f32_16x16x32_bf16 v[84:87], v[116:119], v[198:201], v[84:87]
	v_mfma_f32_16x16x32_bf16 v[80:83], v[156:159], v[198:201], v[80:83]
	v_mfma_f32_16x16x32_bf16 v[76:79], v[116:119], v[206:209], v[76:79]
	v_mfma_f32_16x16x32_bf16 v[72:75], v[156:159], v[206:209], v[72:75]
	v_mfma_f32_16x16x32_bf16 v[68:71], v[116:119], v[214:217], v[68:71]
	v_mfma_f32_16x16x32_bf16 v[64:67], v[156:159], v[214:217], v[64:67]
	v_mfma_f32_16x16x32_bf16 v[28:31], v[160:163], v[182:185], 0
	v_mfma_f32_16x16x32_bf16 v[24:27], v[174:177], v[182:185], 0
	v_mfma_f32_16x16x32_bf16 v[20:23], v[160:163], v[190:193], 0
	v_mfma_f32_16x16x32_bf16 v[16:19], v[174:177], v[190:193], 0
	v_mfma_f32_16x16x32_bf16 v[12:15], v[160:163], v[202:205], 0
	v_mfma_f32_16x16x32_bf16 v[8:11], v[174:177], v[202:205], 0
	v_mfma_f32_16x16x32_bf16 v[4:7], v[160:163], v[210:213], 0
	v_mfma_f32_16x16x32_bf16 v[0:3], v[174:177], v[210:213], 0
	v_mfma_f32_16x16x32_bf16 v[28:31], v[170:173], v[186:189], v[28:31]
	v_mfma_f32_16x16x32_bf16 v[24:27], v[178:181], v[186:189], v[24:27]
	v_mfma_f32_16x16x32_bf16 v[20:23], v[170:173], v[198:201], v[20:23]
	v_mfma_f32_16x16x32_bf16 v[16:19], v[178:181], v[198:201], v[16:19]
	v_mfma_f32_16x16x32_bf16 v[12:15], v[170:173], v[206:209], v[12:15]
	v_mfma_f32_16x16x32_bf16 v[8:11], v[178:181], v[206:209], v[8:11]
	v_mfma_f32_16x16x32_bf16 v[4:7], v[170:173], v[214:217], v[4:7]
	v_mfma_f32_16x16x32_bf16 v[0:3], v[178:181], v[214:217], v[0:3]
	s_barrier
	s_add_i32 s68, 0, 0x18000
	s_add_i32 s69, 0, 0x1c000
	v_add_u32_e32 v156, s68, v165
	v_add_u32_e32 v178, s69, v165
	ds_read_b128 v[112:115], v156
	ds_read_b128 v[116:119], v156 offset:1024
	ds_read_b128 v[152:155], v156 offset:2048
	ds_read_b128 v[156:159], v156 offset:3072
	ds_read_b128 v[160:163], v178
	ds_read_b128 v[170:173], v178 offset:1024
	ds_read_b128 v[174:177], v178 offset:2048
	ds_read_b128 v[178:181], v178 offset:3072
	s_add_u32 s48, s48, 0x20000
	s_addc_u32 s49, s49, 0
	s_mov_b32 m0, s53
	ds_read_b128 v[182:185], v169 offset:32768
	ds_read_b128 v[186:189], v169 offset:33792
	ds_read_b128 v[190:193], v169 offset:34816
	ds_read_b128 v[198:201], v169 offset:35840
	ds_read_b128 v[202:205], v169 offset:36864
	ds_read_b128 v[206:209], v169 offset:37888
	ds_read_b128 v[210:213], v169 offset:38912
	ds_read_b128 v[214:217], v169 offset:39936
	global_load_lds_dwordx4 v136, s[48:49]
	s_mov_b32 m0, s54
	s_nop 0
	global_load_lds_dwordx4 v140, s[48:49]
	s_waitcnt vmcnt(8)
	s_waitcnt lgkmcnt(0)
	s_barrier
	v_mfma_f32_16x16x32_bf16 v[132:135], v[112:115], v[182:185], v[132:135]
	v_mfma_f32_16x16x32_bf16 v[128:131], v[152:155], v[182:185], v[128:131]
	v_mfma_f32_16x16x32_bf16 v[124:127], v[112:115], v[190:193], v[124:127]
	v_mfma_f32_16x16x32_bf16 v[120:123], v[152:155], v[190:193], v[120:123]
	v_mfma_f32_16x16x32_bf16 v[108:111], v[112:115], v[202:205], v[108:111]
	v_mfma_f32_16x16x32_bf16 v[104:107], v[152:155], v[202:205], v[104:107]
	v_mfma_f32_16x16x32_bf16 v[100:103], v[112:115], v[210:213], v[100:103]
	v_mfma_f32_16x16x32_bf16 v[96:99], v[152:155], v[210:213], v[96:99]
	v_mfma_f32_16x16x32_bf16 v[132:135], v[116:119], v[186:189], v[132:135]
	v_mfma_f32_16x16x32_bf16 v[128:131], v[156:159], v[186:189], v[128:131]
	v_mfma_f32_16x16x32_bf16 v[124:127], v[116:119], v[198:201], v[124:127]
	v_mfma_f32_16x16x32_bf16 v[120:123], v[156:159], v[198:201], v[120:123]
	v_mfma_f32_16x16x32_bf16 v[108:111], v[116:119], v[206:209], v[108:111]
	v_mfma_f32_16x16x32_bf16 v[104:107], v[156:159], v[206:209], v[104:107]
	v_mfma_f32_16x16x32_bf16 v[100:103], v[116:119], v[214:217], v[100:103]
	v_mfma_f32_16x16x32_bf16 v[96:99], v[156:159], v[214:217], v[96:99]
	v_mfma_f32_16x16x32_bf16 v[60:63], v[160:163], v[182:185], v[60:63]
	v_mfma_f32_16x16x32_bf16 v[56:59], v[174:177], v[182:185], v[56:59]
	v_mfma_f32_16x16x32_bf16 v[52:55], v[160:163], v[190:193], v[52:55]
	v_mfma_f32_16x16x32_bf16 v[48:51], v[174:177], v[190:193], v[48:51]
	v_mfma_f32_16x16x32_bf16 v[44:47], v[160:163], v[202:205], v[44:47]
	v_mfma_f32_16x16x32_bf16 v[40:43], v[174:177], v[202:205], v[40:43]
	v_mfma_f32_16x16x32_bf16 v[36:39], v[160:163], v[210:213], v[36:39]
	v_mfma_f32_16x16x32_bf16 v[32:35], v[174:177], v[210:213], v[32:35]
	v_mfma_f32_16x16x32_bf16 v[60:63], v[170:173], v[186:189], v[60:63]
	v_mfma_f32_16x16x32_bf16 v[56:59], v[178:181], v[186:189], v[56:59]
	v_mfma_f32_16x16x32_bf16 v[52:55], v[170:173], v[198:201], v[52:55]
	v_mfma_f32_16x16x32_bf16 v[48:51], v[178:181], v[198:201], v[48:51]
	v_mfma_f32_16x16x32_bf16 v[44:47], v[170:173], v[206:209], v[44:47]
	v_mfma_f32_16x16x32_bf16 v[40:43], v[178:181], v[206:209], v[40:43]
	v_mfma_f32_16x16x32_bf16 v[36:39], v[170:173], v[214:217], v[36:39]
	v_mfma_f32_16x16x32_bf16 v[32:35], v[178:181], v[214:217], v[32:35]
	s_barrier
; #define PG8_STAGE(bufoff, gbase, voff) do { _Pragma("unroll") for (int _i = 0; _i < 2; ++_i) \
;         __builtin_amdgcn_global_load_lds((const unsigned*)((const char*)(gbase) + (voff)[_i]), (PG8_LAS unsigned*)(lds + (bufoff) + ldsw + _i * 8192), 16, 0, 0); } while (0)
; #define PG8_LDA(dst, b, h) do { _Pragma("unroll") for (int m = 0; m < 4; ++m) _Pragma("unroll") for (int k = 0; k < 2; ++k) dst[m][k] = *(const PG8_LAS bf16x8*)(lds + PG8_SA(b, h) + aoff + m * 2048 + k * 1024); } while (0)
; #define PG8_LDB(dst, b, h) do { _Pragma("unroll") for (int n = 0; n < 2; ++n) _Pragma("unroll") for (int k = 0; k < 2; ++k) dst[n][k] = *(const PG8_LAS bf16x8*)(lds + PG8_SB(b, h) + boff + n * 2048 + k * 1024); } while (0)
; template <class Epi, class Sched, bool ALIGN_EPI = false, bool SP2 = false>
; __device__ __forceinline__ void gemm_phase(PG8_LAS unsigned char* lds, const Gemm g, const Sched& S, const Epi& E) {
;     ...
;         for (int t = 0; t < nt; t += 2) {
;             const bool last = (t == nt - 2);
;             const char* a1 = cA + (size_t)(t + 1) * kstep;
;             const char* a2 = last ? nA : cA + (size_t)(t + 2) * kstep; const char* b2 = last ? nB : cB + (size_t)(t + 2) * kstep;
;             const char* a3 = a2 + kstep; const char* b3 = b2 + kstep;
;             if (last && has_next) S.a_ready(nxt);
;             if constexpr (SP2) {
;             PG8_LDB(B0, 0, 0); PG8_LDB(B1, 0, 1); PG8_SCHED; PG8_LDA(At, 0, 0); PG8_STAGE(PG8_SA(1, 1), a1 + hstep, voffA);
;             PG8_WAIT_V(8); PG8_WAIT_L(0); PG8_BAR; PG8_MMA(0, 0, At, B0); PG8_MMA(0, 1, At, B1); PG8_BAR; PG8_SCHED;
;             PG8_LDA(At, 0, 1); PG8_STAGE(PG8_SB(0, 0), b2, voffB); PG8_STAGE(PG8_SB(0, 1), b2 + hstep, voffB); PG8_STAGE(PG8_SA(0, 0), a2, voffA);
;             PG8_WAIT_V(8); PG8_WAIT_L(0); PG8_BAR; PG8_MMA(1, 0, At, B0); PG8_MMA(1, 1, At, B1); PG8_BAR; PG8_SCHED;
;             PG8_LDB(B0, 1, 0); PG8_LDB(B1, 1, 1); PG8_SCHED; PG8_LDA(At, 1, 0); PG8_STAGE(PG8_SA(0, 1), a2 + hstep, voffA);
;             PG8_WAIT_V(8); PG8_WAIT_L(0); PG8_BAR; PG8_MMA(0, 0, At, B0); PG8_MMA(0, 1, At, B1); PG8_BAR; PG8_SCHED;
;             PG8_LDA(At, 1, 1); PG8_STAGE(PG8_SB(1, 0), b3, voffB); PG8_STAGE(PG8_SB(1, 1), b3 + hstep, voffB); PG8_STAGE(PG8_SA(1, 0), a3, voffA);
;             PG8_WAIT_V(8); PG8_WAIT_L(0); PG8_BAR; PG8_MMA(1, 0, At, B0); PG8_MMA(1, 1, At, B1); PG8_BAR; PG8_SCHED;
	s_add_i32 s48, s68, s51
	s_mov_b32 m0, s48
	ds_read_b128 v[182:185], v169 offset:49152
	ds_read_b128 v[186:189], v169 offset:50176
	ds_read_b128 v[190:193], v169 offset:51200
	ds_read_b128 v[198:201], v169 offset:52224
	ds_read_b128 v[202:205], v169 offset:53248
	ds_read_b128 v[206:209], v169 offset:54272
	ds_read_b128 v[210:213], v169 offset:55296
	ds_read_b128 v[214:217], v169 offset:56320
	global_load_lds_dwordx4 v138, s[98:99]
	s_add_i32 m0, s48, 0x2000
	s_add_u32 s46, s46, 0x20080
	s_addc_u32 s47, s47, 0
	s_add_i32 s48, s69, s51
	global_load_lds_dwordx4 v142, s[98:99]
	s_mov_b32 m0, s48
	s_nop 0
	global_load_lds_dwordx4 v138, s[46:47]
	s_add_i32 m0, s48, 0x2000
	s_nop 0
	global_load_lds_dwordx4 v142, s[46:47]
	s_mov_b32 m0, s56
	s_nop 0
	global_load_lds_dwordx4 v136, s[100:101]
	s_mov_b32 m0, s57
	s_nop 0
	global_load_lds_dwordx4 v140, s[100:101]
	s_waitcnt vmcnt(8)
	s_waitcnt lgkmcnt(0)
	s_barrier
	v_mfma_f32_16x16x32_bf16 v[92:95], v[112:115], v[182:185], v[92:95]
	v_mfma_f32_16x16x32_bf16 v[88:91], v[152:155], v[182:185], v[88:91]
	v_mfma_f32_16x16x32_bf16 v[84:87], v[112:115], v[190:193], v[84:87]
	v_mfma_f32_16x16x32_bf16 v[80:83], v[152:155], v[190:193], v[80:83]
	v_mfma_f32_16x16x32_bf16 v[76:79], v[112:115], v[202:205], v[76:79]
	v_mfma_f32_16x16x32_bf16 v[72:75], v[152:155], v[202:205], v[72:75]
	v_mfma_f32_16x16x32_bf16 v[68:71], v[112:115], v[210:213], v[68:71]
	v_mfma_f32_16x16x32_bf16 v[64:67], v[152:155], v[210:213], v[64:67]
	v_mfma_f32_16x16x32_bf16 v[92:95], v[116:119], v[186:189], v[92:95]
	v_mfma_f32_16x16x32_bf16 v[88:91], v[156:159], v[186:189], v[88:91]
	v_mfma_f32_16x16x32_bf16 v[84:87], v[116:119], v[198:201], v[84:87]
	v_mfma_f32_16x16x32_bf16 v[80:83], v[156:159], v[198:201], v[80:83]
	v_mfma_f32_16x16x32_bf16 v[76:79], v[116:119], v[206:209], v[76:79]
	v_mfma_f32_16x16x32_bf16 v[72:75], v[156:159], v[206:209], v[72:75]
	v_mfma_f32_16x16x32_bf16 v[68:71], v[116:119], v[214:217], v[68:71]
	v_mfma_f32_16x16x32_bf16 v[64:67], v[156:159], v[214:217], v[64:67]
	v_mfma_f32_16x16x32_bf16 v[28:31], v[160:163], v[182:185], v[28:31]
	v_mfma_f32_16x16x32_bf16 v[24:27], v[174:177], v[182:185], v[24:27]
	v_mfma_f32_16x16x32_bf16 v[20:23], v[160:163], v[190:193], v[20:23]
	v_mfma_f32_16x16x32_bf16 v[16:19], v[174:177], v[190:193], v[16:19]
	v_mfma_f32_16x16x32_bf16 v[12:15], v[160:163], v[202:205], v[12:15]
	v_mfma_f32_16x16x32_bf16 v[8:11], v[174:177], v[202:205], v[8:11]
	v_mfma_f32_16x16x32_bf16 v[4:7], v[160:163], v[210:213], v[4:7]
	v_mfma_f32_16x16x32_bf16 v[0:3], v[174:177], v[210:213], v[0:3]
	v_mfma_f32_16x16x32_bf16 v[28:31], v[170:173], v[186:189], v[28:31]
	v_mfma_f32_16x16x32_bf16 v[24:27], v[178:181], v[186:189], v[24:27]
	v_mfma_f32_16x16x32_bf16 v[20:23], v[170:173], v[198:201], v[20:23]
	v_mfma_f32_16x16x32_bf16 v[16:19], v[178:181], v[198:201], v[16:19]
	v_mfma_f32_16x16x32_bf16 v[12:15], v[170:173], v[206:209], v[12:15]
	v_mfma_f32_16x16x32_bf16 v[8:11], v[178:181], v[206:209], v[8:11]
	v_mfma_f32_16x16x32_bf16 v[4:7], v[170:173], v[214:217], v[4:7]
	v_mfma_f32_16x16x32_bf16 v[0:3], v[178:181], v[214:217], v[0:3]
	s_barrier
	s_add_i32 s67, s67, 2
	s_add_u32 s20, s20, 0x100
	s_addc_u32 s21, s21, 0
	s_add_u32 s65, s65, 0x100
	s_addc_u32 s66, s66, 0
	s_cmp_gt_u32 s67, 5
.LBB0_624:
	ds_read_b128 v[112:115], v167
	ds_read_b128 v[116:119], v167 offset:1024
	ds_read_b128 v[152:155], v167 offset:2048
	ds_read_b128 v[156:159], v167 offset:3072
	ds_read_b128 v[160:163], v168
	ds_read_b128 v[170:173], v168 offset:1024
	ds_read_b128 v[174:177], v168 offset:2048
	ds_read_b128 v[178:181], v168 offset:3072
	s_add_u32 s46, s20, 0xfffe0080
	s_addc_u32 s47, s21, -1
	s_cmp_eq_u32 s67, 4
	s_cselect_b32 s49, s17, s47
	s_cselect_b32 s48, s63, s46
	s_cselect_b32 s47, s15, s66
	s_cselect_b32 s46, s64, s65
	s_add_i32 m0, s35, 0xc000
	ds_read_b128 v[182:185], v169
	ds_read_b128 v[186:189], v169 offset:1024
	ds_read_b128 v[190:193], v169 offset:2048
	ds_read_b128 v[198:201], v169 offset:3072
	ds_read_b128 v[202:205], v169 offset:4096
	ds_read_b128 v[206:209], v169 offset:5120
	ds_read_b128 v[210:213], v169 offset:6144
	ds_read_b128 v[214:217], v169 offset:7168
	global_load_lds_dwordx4 v144, s[20:21]
	s_add_i32 m0, s35, 0xe000
	s_nop 0
	global_load_lds_dwordx4 v146, s[20:21]
	s_waitcnt vmcnt(8)
	s_waitcnt lgkmcnt(0)
	s_barrier
	v_mfma_f32_16x16x32_bf16 v[132:135], v[112:115], v[182:185], v[132:135]
	v_mfma_f32_16x16x32_bf16 v[128:131], v[152:155], v[182:185], v[128:131]
	v_mfma_f32_16x16x32_bf16 v[124:127], v[112:115], v[190:193], v[124:127]
	v_mfma_f32_16x16x32_bf16 v[120:123], v[152:155], v[190:193], v[120:123]
	v_mfma_f32_16x16x32_bf16 v[108:111], v[112:115], v[202:205], v[108:111]
	v_mfma_f32_16x16x32_bf16 v[104:107], v[152:155], v[202:205], v[104:107]
	v_mfma_f32_16x16x32_bf16 v[100:103], v[112:115], v[210:213], v[100:103]
	v_mfma_f32_16x16x32_bf16 v[96:99], v[152:155], v[210:213], v[96:99]
	v_mfma_f32_16x16x32_bf16 v[132:135], v[116:119], v[186:189], v[132:135]
	v_mfma_f32_16x16x32_bf16 v[128:131], v[156:159], v[186:189], v[128:131]
	v_mfma_f32_16x16x32_bf16 v[124:127], v[116:119], v[198:201], v[124:127]
	v_mfma_f32_16x16x32_bf16 v[120:123], v[156:159], v[198:201], v[120:123]
	v_mfma_f32_16x16x32_bf16 v[108:111], v[116:119], v[206:209], v[108:111]
	v_mfma_f32_16x16x32_bf16 v[104:107], v[156:159], v[206:209], v[104:107]
	v_mfma_f32_16x16x32_bf16 v[100:103], v[116:119], v[214:217], v[100:103]
	v_mfma_f32_16x16x32_bf16 v[96:99], v[156:159], v[214:217], v[96:99]
	v_mfma_f32_16x16x32_bf16 v[60:63], v[160:163], v[182:185], v[60:63]
	v_mfma_f32_16x16x32_bf16 v[56:59], v[174:177], v[182:185], v[56:59]
	v_mfma_f32_16x16x32_bf16 v[52:55], v[160:163], v[190:193], v[52:55]
	v_mfma_f32_16x16x32_bf16 v[48:51], v[174:177], v[190:193], v[48:51]
	v_mfma_f32_16x16x32_bf16 v[44:47], v[160:163], v[202:205], v[44:47]
	v_mfma_f32_16x16x32_bf16 v[40:43], v[174:177], v[202:205], v[40:43]
	v_mfma_f32_16x16x32_bf16 v[36:39], v[160:163], v[210:213], v[36:39]
	v_mfma_f32_16x16x32_bf16 v[32:35], v[174:177], v[210:213], v[32:35]
	v_mfma_f32_16x16x32_bf16 v[60:63], v[170:173], v[186:189], v[60:63]
	v_mfma_f32_16x16x32_bf16 v[56:59], v[178:181], v[186:189], v[56:59]
	v_mfma_f32_16x16x32_bf16 v[52:55], v[170:173], v[198:201], v[52:55]
	v_mfma_f32_16x16x32_bf16 v[48:51], v[178:181], v[198:201], v[48:51]
	v_mfma_f32_16x16x32_bf16 v[44:47], v[170:173], v[206:209], v[44:47]
	v_mfma_f32_16x16x32_bf16 v[40:43], v[178:181], v[206:209], v[40:43]
	v_mfma_f32_16x16x32_bf16 v[36:39], v[170:173], v[214:217], v[36:39]
	v_mfma_f32_16x16x32_bf16 v[32:35], v[178:181], v[214:217], v[32:35]
	s_barrier
; #define PG8_STAGE(bufoff, gbase, voff) do { _Pragma("unroll") for (int _i = 0; _i < 2; ++_i) \
;         __builtin_amdgcn_global_load_lds((const unsigned*)((const char*)(gbase) + (voff)[_i]), (PG8_LAS unsigned*)(lds + (bufoff) + ldsw + _i * 8192), 16, 0, 0); } while (0)
; #define PG8_LDA(dst, b, h) do { _Pragma("unroll") for (int m = 0; m < 4; ++m) _Pragma("unroll") for (int k = 0; k < 2; ++k) dst[m][k] = *(const PG8_LAS bf16x8*)(lds + PG8_SA(b, h) + aoff + m * 2048 + k * 1024); } while (0)
; #define PG8_LDB(dst, b, h) do { _Pragma("unroll") for (int n = 0; n < 2; ++n) _Pragma("unroll") for (int k = 0; k < 2; ++k) dst[n][k] = *(const PG8_LAS bf16x8*)(lds + PG8_SB(b, h) + boff + n * 2048 + k * 1024); } while (0)
; #define PG8_MMA(ai, bj, At, Bt) do { __builtin_amdgcn_s_setprio(1); _Pragma("unroll") for (int m = 0; m < 4; ++m) _Pragma("unroll") for (int n = 0; n < 2; ++n) _Pragma("unroll") for (int k = 0; k < 2; ++k) \
;         acc[ai][bj][m][n] = __builtin_amdgcn_mfma_f32_16x16x32_bf16(Bt[n][k], At[m][k], acc[ai][bj][m][n], 0, 0, 0); __builtin_amdgcn_s_setprio(0); } while (0)
; #define PG8_WAIT_V(n) asm volatile("s_waitcnt vmcnt(" #n ")" ::: "memory")
; #define PG8_WAIT_L(n) asm volatile("s_waitcnt lgkmcnt(" #n ")" ::: "memory")
; #define PG8_BAR __builtin_amdgcn_s_barrier()
; #define PG8_SCHED __builtin_amdgcn_sched_barrier(0)
; template <class Epi, class Sched, bool ALIGN_EPI = false, bool SP2 = false>
; __device__ __forceinline__ void gemm_phase(PG8_LAS unsigned char* lds, const Gemm g, const Sched& S, const Epi& E) {
;     ...
;             PG8_LDA(At, 0, 1); PG8_STAGE(PG8_SB(0, 0), b2, voffB); PG8_STAGE(PG8_SB(0, 1), b2 + hstep, voffB); PG8_STAGE(PG8_SA(0, 0), a2, voffA);
;             PG8_WAIT_V(8); PG8_WAIT_L(0); PG8_BAR; PG8_MMA(1, 0, At, B0); PG8_MMA(1, 1, At, B1); PG8_BAR; PG8_SCHED;
;             PG8_LDB(B0, 1, 0); PG8_LDB(B1, 1, 1); PG8_SCHED; PG8_LDA(At, 1, 0); PG8_STAGE(PG8_SA(0, 1), a2 + hstep, voffA);
	s_add_i32 s68, s60, s51
	s_add_u32 s98, s46, s10
	s_addc_u32 s99, s47, s11
	s_add_u32 s100, s48, s10
	s_addc_u32 s101, s49, s11
	s_mov_b32 m0, s68
	ds_read_b128 v[182:185], v169 offset:16384
	ds_read_b128 v[186:189], v169 offset:17408
	ds_read_b128 v[190:193], v169 offset:18432
	ds_read_b128 v[198:201], v169 offset:19456
	ds_read_b128 v[202:205], v169 offset:20480
	ds_read_b128 v[206:209], v169 offset:21504
	ds_read_b128 v[210:213], v169 offset:22528
	ds_read_b128 v[214:217], v169 offset:23552
	global_load_lds_dwordx4 v138, s[46:47]
	s_add_i32 m0, s68, 0x2000
	s_add_u32 s68, s46, 0x20000
	s_addc_u32 s69, s47, 0
	s_add_i32 s70, s61, s51
	global_load_lds_dwordx4 v142, s[46:47]
	s_mov_b32 m0, s70
	s_nop 0
	global_load_lds_dwordx4 v138, s[68:69]
	s_add_i32 m0, s70, 0x2000
	s_nop 0
	global_load_lds_dwordx4 v142, s[68:69]
	s_mov_b32 m0, s35
	s_nop 0
	global_load_lds_dwordx4 v136, s[48:49]
	s_mov_b32 m0, s52
	s_nop 0
	global_load_lds_dwordx4 v140, s[48:49]
	s_waitcnt vmcnt(8)
	s_waitcnt lgkmcnt(0)
	s_barrier
	v_mfma_f32_16x16x32_bf16 v[92:95], v[112:115], v[182:185], v[92:95]
	v_mfma_f32_16x16x32_bf16 v[88:91], v[152:155], v[182:185], v[88:91]
	v_mfma_f32_16x16x32_bf16 v[84:87], v[112:115], v[190:193], v[84:87]
	v_mfma_f32_16x16x32_bf16 v[80:83], v[152:155], v[190:193], v[80:83]
	v_mfma_f32_16x16x32_bf16 v[76:79], v[112:115], v[202:205], v[76:79]
	v_mfma_f32_16x16x32_bf16 v[72:75], v[152:155], v[202:205], v[72:75]
	v_mfma_f32_16x16x32_bf16 v[68:71], v[112:115], v[210:213], v[68:71]
	v_mfma_f32_16x16x32_bf16 v[64:67], v[152:155], v[210:213], v[64:67]
	v_mfma_f32_16x16x32_bf16 v[92:95], v[116:119], v[186:189], v[92:95]
	v_mfma_f32_16x16x32_bf16 v[88:91], v[156:159], v[186:189], v[88:91]
	v_mfma_f32_16x16x32_bf16 v[84:87], v[116:119], v[198:201], v[84:87]
	v_mfma_f32_16x16x32_bf16 v[80:83], v[156:159], v[198:201], v[80:83]
	v_mfma_f32_16x16x32_bf16 v[76:79], v[116:119], v[206:209], v[76:79]
	v_mfma_f32_16x16x32_bf16 v[72:75], v[156:159], v[206:209], v[72:75]
	v_mfma_f32_16x16x32_bf16 v[68:71], v[116:119], v[214:217], v[68:71]
	v_mfma_f32_16x16x32_bf16 v[64:67], v[156:159], v[214:217], v[64:67]
	v_mfma_f32_16x16x32_bf16 v[28:31], v[160:163], v[182:185], v[28:31]
	v_mfma_f32_16x16x32_bf16 v[24:27], v[174:177], v[182:185], v[24:27]
	v_mfma_f32_16x16x32_bf16 v[20:23], v[160:163], v[190:193], v[20:23]
	v_mfma_f32_16x16x32_bf16 v[16:19], v[174:177], v[190:193], v[16:19]
	v_mfma_f32_16x16x32_bf16 v[12:15], v[160:163], v[202:205], v[12:15]
	v_mfma_f32_16x16x32_bf16 v[8:11], v[174:177], v[202:205], v[8:11]
	v_mfma_f32_16x16x32_bf16 v[4:7], v[160:163], v[210:213], v[4:7]
	v_mfma_f32_16x16x32_bf16 v[0:3], v[174:177], v[210:213], v[0:3]
	v_mfma_f32_16x16x32_bf16 v[28:31], v[170:173], v[186:189], v[28:31]
	v_mfma_f32_16x16x32_bf16 v[24:27], v[178:181], v[186:189], v[24:27]
	v_mfma_f32_16x16x32_bf16 v[20:23], v[170:173], v[198:201], v[20:23]
	v_mfma_f32_16x16x32_bf16 v[16:19], v[178:181], v[198:201], v[16:19]
	v_mfma_f32_16x16x32_bf16 v[12:15], v[170:173], v[206:209], v[12:15]
	v_mfma_f32_16x16x32_bf16 v[8:11], v[178:181], v[206:209], v[8:11]
	v_mfma_f32_16x16x32_bf16 v[4:7], v[170:173], v[214:217], v[4:7]
	v_mfma_f32_16x16x32_bf16 v[0:3], v[178:181], v[214:217], v[0:3]
	s_barrier
	s_add_i32 s68, 0, 0x18000
	s_add_i32 s69, 0, 0x1c000
	v_add_u32_e32 v156, s68, v165
	v_add_u32_e32 v178, s69, v165
	ds_read_b128 v[112:115], v156
	ds_read_b128 v[116:119], v156 offset:1024
	ds_read_b128 v[152:155], v156 offset:2048
	ds_read_b128 v[156:159], v156 offset:3072
	ds_read_b128 v[160:163], v178
	ds_read_b128 v[170:173], v178 offset:1024
	ds_read_b128 v[174:177], v178 offset:2048
	ds_read_b128 v[178:181], v178 offset:3072
	s_add_u32 s48, s48, 0x20000
	s_addc_u32 s49, s49, 0
	s_mov_b32 m0, s53
	ds_read_b128 v[182:185], v169 offset:32768
	ds_read_b128 v[186:189], v169 offset:33792
	ds_read_b128 v[190:193], v169 offset:34816
	ds_read_b128 v[198:201], v169 offset:35840
	ds_read_b128 v[202:205], v169 offset:36864
	ds_read_b128 v[206:209], v169 offset:37888
	ds_read_b128 v[210:213], v169 offset:38912
	ds_read_b128 v[214:217], v169 offset:39936
	global_load_lds_dwordx4 v136, s[48:49]
	s_mov_b32 m0, s54
	s_nop 0
	global_load_lds_dwordx4 v140, s[48:49]
	s_waitcnt vmcnt(8)
	s_waitcnt lgkmcnt(0)
	s_barrier
; #define PG8_STAGE(bufoff, gbase, voff) do { _Pragma("unroll") for (int _i = 0; _i < 2; ++_i) \
;         __builtin_amdgcn_global_load_lds((const unsigned*)((const char*)(gbase) + (voff)[_i]), (PG8_LAS unsigned*)(lds + (bufoff) + ldsw + _i * 8192), 16, 0, 0); } while (0)
; #define PG8_LDA(dst, b, h) do { _Pragma("unroll") for (int m = 0; m < 4; ++m) _Pragma("unroll") for (int k = 0; k < 2; ++k) dst[m][k] = *(const PG8_LAS bf16x8*)(lds + PG8_SA(b, h) + aoff + m * 2048 + k * 1024); } while (0)
; #define PG8_MMA(ai, bj, At, Bt) do { __builtin_amdgcn_s_setprio(1); _Pragma("unroll") for (int m = 0; m < 4; ++m) _Pragma("unroll") for (int n = 0; n < 2; ++n) _Pragma("unroll") for (int k = 0; k < 2; ++k) \
;         acc[ai][bj][m][n] = __builtin_amdgcn_mfma_f32_16x16x32_bf16(Bt[n][k], At[m][k], acc[ai][bj][m][n], 0, 0, 0); __builtin_amdgcn_s_setprio(0); } while (0)
; #define PG8_WAIT_V(n) asm volatile("s_waitcnt vmcnt(" #n ")" ::: "memory")
; #define PG8_WAIT_L(n) asm volatile("s_waitcnt lgkmcnt(" #n ")" ::: "memory")
; #define PG8_BAR __builtin_amdgcn_s_barrier()
; #define PG8_SCHED __builtin_amdgcn_sched_barrier(0)
; template <class Epi, class Sched, bool ALIGN_EPI = false, bool SP2 = false>
; __device__ __forceinline__ void gemm_phase(PG8_LAS unsigned char* lds, const Gemm g, const Sched& S, const Epi& E) {
;     ...
;             PG8_WAIT_V(8); PG8_WAIT_L(0); PG8_BAR; PG8_MMA(0, 0, At, B0); PG8_MMA(0, 1, At, B1); PG8_BAR; PG8_SCHED;
;             PG8_LDA(At, 1, 1); PG8_STAGE(PG8_SB(1, 0), b3, voffB); PG8_STAGE(PG8_SB(1, 1), b3 + hstep, voffB); PG8_STAGE(PG8_SA(1, 0), a3, voffA);
;             PG8_WAIT_V(8); PG8_WAIT_L(0); PG8_BAR; PG8_MMA(1, 0, At, B0); PG8_MMA(1, 1, At, B1); PG8_BAR; PG8_SCHED;
;     ...
;         if constexpr (ALIGN_EPI) { if (wr == 0) PG8_BAR; }
	v_mfma_f32_16x16x32_bf16 v[132:135], v[112:115], v[182:185], v[132:135]
	v_mfma_f32_16x16x32_bf16 v[128:131], v[152:155], v[182:185], v[128:131]
	v_mfma_f32_16x16x32_bf16 v[124:127], v[112:115], v[190:193], v[124:127]
	v_mfma_f32_16x16x32_bf16 v[120:123], v[152:155], v[190:193], v[120:123]
	v_mfma_f32_16x16x32_bf16 v[108:111], v[112:115], v[202:205], v[108:111]
	v_mfma_f32_16x16x32_bf16 v[104:107], v[152:155], v[202:205], v[104:107]
	v_mfma_f32_16x16x32_bf16 v[100:103], v[112:115], v[210:213], v[100:103]
	v_mfma_f32_16x16x32_bf16 v[96:99], v[152:155], v[210:213], v[96:99]
	v_mfma_f32_16x16x32_bf16 v[132:135], v[116:119], v[186:189], v[132:135]
	v_mfma_f32_16x16x32_bf16 v[128:131], v[156:159], v[186:189], v[128:131]
	v_mfma_f32_16x16x32_bf16 v[124:127], v[116:119], v[198:201], v[124:127]
	v_mfma_f32_16x16x32_bf16 v[120:123], v[156:159], v[198:201], v[120:123]
	v_mfma_f32_16x16x32_bf16 v[108:111], v[116:119], v[206:209], v[108:111]
	v_mfma_f32_16x16x32_bf16 v[104:107], v[156:159], v[206:209], v[104:107]
	v_mfma_f32_16x16x32_bf16 v[100:103], v[116:119], v[214:217], v[100:103]
	v_mfma_f32_16x16x32_bf16 v[96:99], v[156:159], v[214:217], v[96:99]
	v_mfma_f32_16x16x32_bf16 v[60:63], v[160:163], v[182:185], v[60:63]
	v_mfma_f32_16x16x32_bf16 v[56:59], v[174:177], v[182:185], v[56:59]
	v_mfma_f32_16x16x32_bf16 v[52:55], v[160:163], v[190:193], v[52:55]
	v_mfma_f32_16x16x32_bf16 v[48:51], v[174:177], v[190:193], v[48:51]
	v_mfma_f32_16x16x32_bf16 v[44:47], v[160:163], v[202:205], v[44:47]
	v_mfma_f32_16x16x32_bf16 v[40:43], v[174:177], v[202:205], v[40:43]
	v_mfma_f32_16x16x32_bf16 v[36:39], v[160:163], v[210:213], v[36:39]
	v_mfma_f32_16x16x32_bf16 v[32:35], v[174:177], v[210:213], v[32:35]
	v_mfma_f32_16x16x32_bf16 v[60:63], v[170:173], v[186:189], v[60:63]
	v_mfma_f32_16x16x32_bf16 v[56:59], v[178:181], v[186:189], v[56:59]
	v_mfma_f32_16x16x32_bf16 v[52:55], v[170:173], v[198:201], v[52:55]
	v_mfma_f32_16x16x32_bf16 v[48:51], v[178:181], v[198:201], v[48:51]
	v_mfma_f32_16x16x32_bf16 v[44:47], v[170:173], v[206:209], v[44:47]
	v_mfma_f32_16x16x32_bf16 v[40:43], v[178:181], v[206:209], v[40:43]
	v_mfma_f32_16x16x32_bf16 v[36:39], v[170:173], v[214:217], v[36:39]
	v_mfma_f32_16x16x32_bf16 v[32:35], v[178:181], v[214:217], v[32:35]
	s_barrier
	s_add_i32 s48, s68, s51
	s_mov_b32 m0, s48
	ds_read_b128 v[182:185], v169 offset:49152
	ds_read_b128 v[186:189], v169 offset:50176
	ds_read_b128 v[190:193], v169 offset:51200
	ds_read_b128 v[198:201], v169 offset:52224
	ds_read_b128 v[202:205], v169 offset:53248
	ds_read_b128 v[206:209], v169 offset:54272
	ds_read_b128 v[210:213], v169 offset:55296
	ds_read_b128 v[214:217], v169 offset:56320
	global_load_lds_dwordx4 v138, s[98:99]
	s_add_i32 m0, s48, 0x2000
	s_add_u32 s46, s46, 0x20080
	s_addc_u32 s47, s47, 0
	s_add_i32 s48, s69, s51
	global_load_lds_dwordx4 v142, s[98:99]
	s_mov_b32 m0, s48
	s_nop 0
	global_load_lds_dwordx4 v138, s[46:47]
	s_add_i32 m0, s48, 0x2000
	s_nop 0
	global_load_lds_dwordx4 v142, s[46:47]
	s_mov_b32 m0, s56
	s_nop 0
	global_load_lds_dwordx4 v136, s[100:101]
	s_mov_b32 m0, s57
	s_nop 0
	global_load_lds_dwordx4 v140, s[100:101]
	s_waitcnt vmcnt(8)
	s_waitcnt lgkmcnt(0)
	s_barrier
	v_mfma_f32_16x16x32_bf16 v[92:95], v[112:115], v[182:185], v[92:95]
	v_mfma_f32_16x16x32_bf16 v[88:91], v[152:155], v[182:185], v[88:91]
	v_mfma_f32_16x16x32_bf16 v[84:87], v[112:115], v[190:193], v[84:87]
	v_mfma_f32_16x16x32_bf16 v[80:83], v[152:155], v[190:193], v[80:83]
	v_mfma_f32_16x16x32_bf16 v[76:79], v[112:115], v[202:205], v[76:79]
	v_mfma_f32_16x16x32_bf16 v[72:75], v[152:155], v[202:205], v[72:75]
	v_mfma_f32_16x16x32_bf16 v[68:71], v[112:115], v[210:213], v[68:71]
	v_mfma_f32_16x16x32_bf16 v[64:67], v[152:155], v[210:213], v[64:67]
	v_mfma_f32_16x16x32_bf16 v[92:95], v[116:119], v[186:189], v[92:95]
	v_mfma_f32_16x16x32_bf16 v[88:91], v[156:159], v[186:189], v[88:91]
	v_mfma_f32_16x16x32_bf16 v[84:87], v[116:119], v[198:201], v[84:87]
	v_mfma_f32_16x16x32_bf16 v[80:83], v[156:159], v[198:201], v[80:83]
	v_mfma_f32_16x16x32_bf16 v[76:79], v[116:119], v[206:209], v[76:79]
	v_mfma_f32_16x16x32_bf16 v[72:75], v[156:159], v[206:209], v[72:75]
	v_mfma_f32_16x16x32_bf16 v[68:71], v[116:119], v[214:217], v[68:71]
	v_mfma_f32_16x16x32_bf16 v[64:67], v[156:159], v[214:217], v[64:67]
	v_mfma_f32_16x16x32_bf16 v[28:31], v[160:163], v[182:185], v[28:31]
	v_mfma_f32_16x16x32_bf16 v[24:27], v[174:177], v[182:185], v[24:27]
	v_mfma_f32_16x16x32_bf16 v[20:23], v[160:163], v[190:193], v[20:23]
	v_mfma_f32_16x16x32_bf16 v[16:19], v[174:177], v[190:193], v[16:19]
	v_mfma_f32_16x16x32_bf16 v[12:15], v[160:163], v[202:205], v[12:15]
	v_mfma_f32_16x16x32_bf16 v[8:11], v[174:177], v[202:205], v[8:11]
	v_mfma_f32_16x16x32_bf16 v[4:7], v[160:163], v[210:213], v[4:7]
	v_mfma_f32_16x16x32_bf16 v[0:3], v[174:177], v[210:213], v[0:3]
	v_mfma_f32_16x16x32_bf16 v[28:31], v[170:173], v[186:189], v[28:31]
	v_mfma_f32_16x16x32_bf16 v[24:27], v[178:181], v[186:189], v[24:27]
	v_mfma_f32_16x16x32_bf16 v[20:23], v[170:173], v[198:201], v[20:23]
	v_mfma_f32_16x16x32_bf16 v[16:19], v[178:181], v[198:201], v[16:19]
	v_mfma_f32_16x16x32_bf16 v[12:15], v[170:173], v[206:209], v[12:15]
	v_mfma_f32_16x16x32_bf16 v[8:11], v[178:181], v[206:209], v[8:11]
	v_mfma_f32_16x16x32_bf16 v[4:7], v[170:173], v[214:217], v[4:7]
	v_mfma_f32_16x16x32_bf16 v[0:3], v[178:181], v[214:217], v[0:3]
	s_barrier
	s_add_i32 s67, s67, 2
	s_add_u32 s20, s20, 0x100
	s_addc_u32 s21, s21, 0
	s_add_u32 s65, s65, 0x100
	s_addc_u32 s66, s66, 0
	s_cmp_gt_u32 s67, 5
	s_cbranch_scc0 .LBB0_624
	s_and_b64 vcc, exec, s[12:13]
	s_cbranch_vccz .LBB0_627
	s_barrier

; #define PG8_STAGE(bufoff, gbase, voff) do { _Pragma("unroll") for (int _i = 0; _i < 2; ++_i) \
;         __builtin_amdgcn_global_load_lds((const unsigned*)((const char*)(gbase) + (voff)[_i]), (PG8_LAS unsigned*)(lds + (bufoff) + ldsw + _i * 8192), 16, 0, 0); } while (0)
; #define PG8_LDA(dst, b, h) do { _Pragma("unroll") for (int m = 0; m < 4; ++m) _Pragma("unroll") for (int k = 0; k < 2; ++k) dst[m][k] = *(const PG8_LAS bf16x8*)(lds + PG8_SA(b, h) + aoff + m * 2048 + k * 1024); } while (0)
; #define PG8_LDB(dst, b, h) do { _Pragma("unroll") for (int n = 0; n < 2; ++n) _Pragma("unroll") for (int k = 0; k < 2; ++k) dst[n][k] = *(const PG8_LAS bf16x8*)(lds + PG8_SB(b, h) + boff + n * 2048 + k * 1024); } while (0)
; #define PG8_WAIT_V(n) asm volatile("s_waitcnt vmcnt(" #n ")" ::: "memory")
; #define PG8_WAIT_L(n) asm volatile("s_waitcnt lgkmcnt(" #n ")" ::: "memory")
; template <class Epi, class Sched, bool ALIGN_EPI = false, bool SP2 = false>
; __device__ __forceinline__ void gemm_phase(PG8_LAS unsigned char* lds, const Gemm g, const Sched& S, const Epi& E) {
;     ...
;         const bool has_next = S.next(ui + 1, nxt);
;         const char* nA = has_next ? (const char*)g.A + (size_t)nxt.pm * tstep : cA; const char* nB = has_next ? (const char*)g.Bt + (size_t)nxt.pn * tstep : cB;
;         for (int t = 0; t < nt; t += 2) {
;             const bool last = (t == nt - 2);
;             const char* a1 = cA + (size_t)(t + 1) * kstep;
;             const char* a2 = last ? nA : cA + (size_t)(t + 2) * kstep; const char* b2 = last ? nB : cB + (size_t)(t + 2) * kstep;
;             const char* a3 = a2 + kstep; const char* b3 = b2 + kstep;
;             if (last && has_next) S.a_ready(nxt);
;             if constexpr (SP2) {
;             PG8_LDB(B0, 0, 0); PG8_LDB(B1, 0, 1); PG8_SCHED; PG8_LDA(At, 0, 0); PG8_STAGE(PG8_SA(1, 1), a1 + hstep, voffA);
;             PG8_WAIT_V(8); PG8_WAIT_L(0); PG8_BAR; PG8_MMA(0, 0, At, B0); PG8_MMA(0, 1, At, B1); PG8_BAR; PG8_SCHED;
;             PG8_LDA(At, 0, 1); PG8_STAGE(PG8_SB(0, 0), b2, voffB); PG8_STAGE(PG8_SB(0, 1), b2 + hstep, voffB); PG8_STAGE(PG8_SA(0, 0), a2, voffA);
;             PG8_WAIT_V(8); PG8_WAIT_L(0); PG8_BAR; PG8_MMA(1, 0, At, B0); PG8_MMA(1, 1, At, B1); PG8_BAR; PG8_SCHED;
;             PG8_LDB(B0, 1, 0); PG8_LDB(B1, 1, 1); PG8_SCHED; PG8_LDA(At, 1, 0); PG8_STAGE(PG8_SA(0, 1), a2 + hstep, voffA);
.LBB0_704:
	s_ashr_i32 s47, s46, 31
	s_lshl_b64 s[48:49], s[46:47], 19
	s_add_u32 s48, s42, s48
	s_addc_u32 s49, s43, s49
	s_and_b64 s[50:51], s[6:7], exec
	s_cselect_b32 s35, s49, s21
	s_cselect_b32 s47, s48, s20
	s_ashr_i32 s45, s44, 31
	s_lshl_b64 s[50:51], s[44:45], 19
	s_add_u32 s50, s3, s50
	s_addc_u32 s51, s33, s51
	s_and_b64 s[56:57], s[6:7], exec
	s_cselect_b32 s45, s51, s55
	s_cselect_b32 s73, s50, s54
	s_add_u32 s20, s20, 0x40080
	s_addc_u32 s21, s21, 0
	s_add_u32 s74, s54, 0x100
	s_addc_u32 s75, s55, 0
	s_mov_b32 s76, -2
	s_waitcnt lgkmcnt(0)
	ds_read_b128 v[96:99], v223
	ds_read_b128 v[108:111], v223 offset:1024
	ds_read_b128 v[120:123], v223 offset:2048
	ds_read_b128 v[128:131], v223 offset:3072
	ds_read_b128 v[144:147], v224
	ds_read_b128 v[148:151], v224 offset:1024
	ds_read_b128 v[152:155], v224 offset:2048
	ds_read_b128 v[156:159], v224 offset:3072
	s_add_u32 s54, s20, 0xfffc0080
	s_addc_u32 s55, s21, -1
	s_cmp_eq_u32 s76, 12
	s_cselect_b32 s57, s35, s55
	s_cselect_b32 s56, s47, s54
	s_cselect_b32 s55, s45, s75
	s_cselect_b32 s54, s73, s74
	s_add_i32 m0, s53, 0xc000
	ds_read_b128 v[160:163], v225
	ds_read_b128 v[164:167], v225 offset:1024
	ds_read_b128 v[168:171], v225 offset:2048
	ds_read_b128 v[172:175], v225 offset:3072
	ds_read_b128 v[176:179], v225 offset:4096
	ds_read_b128 v[180:183], v225 offset:5120
	ds_read_b128 v[202:205], v225 offset:6144
	ds_read_b128 v[206:209], v225 offset:7168
	global_load_lds_dwordx4 v192, s[20:21]
	s_add_i32 m0, s53, 0xe000
	s_nop 0
	global_load_lds_dwordx4 v194, s[20:21]
	s_waitcnt vmcnt(8)
	s_waitcnt lgkmcnt(0)
	s_barrier
	v_mfma_f32_16x16x32_bf16 v[140:143], v[96:99], v[160:163], 0
	v_mfma_f32_16x16x32_bf16 v[136:139], v[120:123], v[160:163], 0
	v_mfma_f32_16x16x32_bf16 v[116:119], v[96:99], v[168:171], 0
	v_mfma_f32_16x16x32_bf16 v[112:115], v[120:123], v[168:171], 0
	v_mfma_f32_16x16x32_bf16 v[92:95], v[96:99], v[176:179], 0
	v_mfma_f32_16x16x32_bf16 v[88:91], v[120:123], v[176:179], 0
	v_mfma_f32_16x16x32_bf16 v[76:79], v[96:99], v[202:205], 0
	v_mfma_f32_16x16x32_bf16 v[72:75], v[120:123], v[202:205], 0
	v_mfma_f32_16x16x32_bf16 v[140:143], v[108:111], v[164:167], v[140:143]
	v_mfma_f32_16x16x32_bf16 v[136:139], v[128:131], v[164:167], v[136:139]
	v_mfma_f32_16x16x32_bf16 v[116:119], v[108:111], v[172:175], v[116:119]
	v_mfma_f32_16x16x32_bf16 v[112:115], v[128:131], v[172:175], v[112:115]
	v_mfma_f32_16x16x32_bf16 v[92:95], v[108:111], v[180:183], v[92:95]
	v_mfma_f32_16x16x32_bf16 v[88:91], v[128:131], v[180:183], v[88:91]
	v_mfma_f32_16x16x32_bf16 v[76:79], v[108:111], v[206:209], v[76:79]
	v_mfma_f32_16x16x32_bf16 v[72:75], v[128:131], v[206:209], v[72:75]
	v_mfma_f32_16x16x32_bf16 v[132:135], v[144:147], v[160:163], 0
	v_mfma_f32_16x16x32_bf16 v[124:127], v[152:155], v[160:163], 0
	v_mfma_f32_16x16x32_bf16 v[104:107], v[144:147], v[168:171], 0
	v_mfma_f32_16x16x32_bf16 v[100:103], v[152:155], v[168:171], 0
	v_mfma_f32_16x16x32_bf16 v[84:87], v[144:147], v[176:179], 0
	v_mfma_f32_16x16x32_bf16 v[80:83], v[152:155], v[176:179], 0
	v_mfma_f32_16x16x32_bf16 v[68:71], v[144:147], v[202:205], 0
	v_mfma_f32_16x16x32_bf16 v[64:67], v[152:155], v[202:205], 0
	v_mfma_f32_16x16x32_bf16 v[132:135], v[148:151], v[164:167], v[132:135]
	v_mfma_f32_16x16x32_bf16 v[124:127], v[156:159], v[164:167], v[124:127]
	v_mfma_f32_16x16x32_bf16 v[104:107], v[148:151], v[172:175], v[104:107]
	v_mfma_f32_16x16x32_bf16 v[100:103], v[156:159], v[172:175], v[100:103]
	v_mfma_f32_16x16x32_bf16 v[84:87], v[148:151], v[180:183], v[84:87]
	v_mfma_f32_16x16x32_bf16 v[80:83], v[156:159], v[180:183], v[80:83]
	v_mfma_f32_16x16x32_bf16 v[68:71], v[148:151], v[206:209], v[68:71]
	v_mfma_f32_16x16x32_bf16 v[64:67], v[156:159], v[206:209], v[64:67]
	s_barrier
	s_add_i32 s77, s71, s58
	s_add_u32 s98, s54, s12
	s_addc_u32 s99, s55, s13
	s_add_u32 s100, s56, s12
	s_addc_u32 s101, s57, s13
	s_mov_b32 m0, s77
	ds_read_b128 v[160:163], v225 offset:16384
	ds_read_b128 v[164:167], v225 offset:17408
	ds_read_b128 v[168:171], v225 offset:18432
	ds_read_b128 v[172:175], v225 offset:19456
	ds_read_b128 v[176:179], v225 offset:20480
	ds_read_b128 v[180:183], v225 offset:21504
	ds_read_b128 v[202:205], v225 offset:22528
	ds_read_b128 v[206:209], v225 offset:23552
	global_load_lds_dwordx4 v186, s[54:55]
	s_add_i32 m0, s77, 0x2000
	s_add_u32 s78, s54, 0x40000
	s_addc_u32 s79, s55, 0
	s_add_i32 s77, s72, s58
	global_load_lds_dwordx4 v190, s[54:55]
	s_mov_b32 m0, s77
	s_nop 0
	global_load_lds_dwordx4 v186, s[78:79]
	s_add_i32 m0, s77, 0x2000
	s_nop 0
	global_load_lds_dwordx4 v190, s[78:79]
	s_mov_b32 m0, s53
	s_nop 0
	global_load_lds_dwordx4 v184, s[56:57]
	s_mov_b32 m0, s59
	s_nop 0
	global_load_lds_dwordx4 v188, s[56:57]
	s_waitcnt vmcnt(8)
	s_waitcnt lgkmcnt(0)
	s_barrier
; #define PG8_STAGE(bufoff, gbase, voff) do { _Pragma("unroll") for (int _i = 0; _i < 2; ++_i) \
;         __builtin_amdgcn_global_load_lds((const unsigned*)((const char*)(gbase) + (voff)[_i]), (PG8_LAS unsigned*)(lds + (bufoff) + ldsw + _i * 8192), 16, 0, 0); } while (0)
; #define PG8_LDA(dst, b, h) do { _Pragma("unroll") for (int m = 0; m < 4; ++m) _Pragma("unroll") for (int k = 0; k < 2; ++k) dst[m][k] = *(const PG8_LAS bf16x8*)(lds + PG8_SA(b, h) + aoff + m * 2048 + k * 1024); } while (0)
; #define PG8_LDB(dst, b, h) do { _Pragma("unroll") for (int n = 0; n < 2; ++n) _Pragma("unroll") for (int k = 0; k < 2; ++k) dst[n][k] = *(const PG8_LAS bf16x8*)(lds + PG8_SB(b, h) + boff + n * 2048 + k * 1024); } while (0)
; #define PG8_MMA(ai, bj, At, Bt) do { __builtin_amdgcn_s_setprio(1); _Pragma("unroll") for (int m = 0; m < 4; ++m) _Pragma("unroll") for (int n = 0; n < 2; ++n) _Pragma("unroll") for (int k = 0; k < 2; ++k) \
;         acc[ai][bj][m][n] = __builtin_amdgcn_mfma_f32_16x16x32_bf16(Bt[n][k], At[m][k], acc[ai][bj][m][n], 0, 0, 0); __builtin_amdgcn_s_setprio(0); } while (0)
; #define PG8_WAIT_V(n) asm volatile("s_waitcnt vmcnt(" #n ")" ::: "memory")
; #define PG8_WAIT_L(n) asm volatile("s_waitcnt lgkmcnt(" #n ")" ::: "memory")
; #define PG8_BAR __builtin_amdgcn_s_barrier()
; #define PG8_SCHED __builtin_amdgcn_sched_barrier(0)
; template <class Epi, class Sched, bool ALIGN_EPI = false, bool SP2 = false>
; __device__ __forceinline__ void gemm_phase(PG8_LAS unsigned char* lds, const Gemm g, const Sched& S, const Epi& E) {
;     ...
;             PG8_LDA(At, 0, 1); PG8_STAGE(PG8_SB(0, 0), b2, voffB); PG8_STAGE(PG8_SB(0, 1), b2 + hstep, voffB); PG8_STAGE(PG8_SA(0, 0), a2, voffA);
;             PG8_WAIT_V(8); PG8_WAIT_L(0); PG8_BAR; PG8_MMA(1, 0, At, B0); PG8_MMA(1, 1, At, B1); PG8_BAR; PG8_SCHED;
;             PG8_LDB(B0, 1, 0); PG8_LDB(B1, 1, 1); PG8_SCHED; PG8_LDA(At, 1, 0); PG8_STAGE(PG8_SA(0, 1), a2 + hstep, voffA);
;             PG8_WAIT_V(8); PG8_WAIT_L(0); PG8_BAR; PG8_MMA(0, 0, At, B0); PG8_MMA(0, 1, At, B1); PG8_BAR; PG8_SCHED;
	v_mfma_f32_16x16x32_bf16 v[60:63], v[96:99], v[160:163], 0
	v_mfma_f32_16x16x32_bf16 v[56:59], v[120:123], v[160:163], 0
	v_mfma_f32_16x16x32_bf16 v[44:47], v[96:99], v[168:171], 0
	v_mfma_f32_16x16x32_bf16 v[40:43], v[120:123], v[168:171], 0
	v_mfma_f32_16x16x32_bf16 v[28:31], v[96:99], v[176:179], 0
	v_mfma_f32_16x16x32_bf16 v[24:27], v[120:123], v[176:179], 0
	v_mfma_f32_16x16x32_bf16 v[12:15], v[96:99], v[202:205], 0
	v_mfma_f32_16x16x32_bf16 v[8:11], v[120:123], v[202:205], 0
	v_mfma_f32_16x16x32_bf16 v[60:63], v[108:111], v[164:167], v[60:63]
	v_mfma_f32_16x16x32_bf16 v[56:59], v[128:131], v[164:167], v[56:59]
	v_mfma_f32_16x16x32_bf16 v[44:47], v[108:111], v[172:175], v[44:47]
	v_mfma_f32_16x16x32_bf16 v[40:43], v[128:131], v[172:175], v[40:43]
	v_mfma_f32_16x16x32_bf16 v[28:31], v[108:111], v[180:183], v[28:31]
	v_mfma_f32_16x16x32_bf16 v[24:27], v[128:131], v[180:183], v[24:27]
	v_mfma_f32_16x16x32_bf16 v[12:15], v[108:111], v[206:209], v[12:15]
	v_mfma_f32_16x16x32_bf16 v[8:11], v[128:131], v[206:209], v[8:11]
	v_mfma_f32_16x16x32_bf16 v[52:55], v[144:147], v[160:163], 0
	v_mfma_f32_16x16x32_bf16 v[48:51], v[152:155], v[160:163], 0
	v_mfma_f32_16x16x32_bf16 v[36:39], v[144:147], v[168:171], 0
	v_mfma_f32_16x16x32_bf16 v[32:35], v[152:155], v[168:171], 0
	v_mfma_f32_16x16x32_bf16 v[20:23], v[144:147], v[176:179], 0
	v_mfma_f32_16x16x32_bf16 v[16:19], v[152:155], v[176:179], 0
	v_mfma_f32_16x16x32_bf16 v[4:7], v[144:147], v[202:205], 0
	v_mfma_f32_16x16x32_bf16 v[0:3], v[152:155], v[202:205], 0
	v_mfma_f32_16x16x32_bf16 v[52:55], v[148:151], v[164:167], v[52:55]
	v_mfma_f32_16x16x32_bf16 v[48:51], v[156:159], v[164:167], v[48:51]
	v_mfma_f32_16x16x32_bf16 v[36:39], v[148:151], v[172:175], v[36:39]
	v_mfma_f32_16x16x32_bf16 v[32:35], v[156:159], v[172:175], v[32:35]
	v_mfma_f32_16x16x32_bf16 v[20:23], v[148:151], v[180:183], v[20:23]
	v_mfma_f32_16x16x32_bf16 v[16:19], v[156:159], v[180:183], v[16:19]
	v_mfma_f32_16x16x32_bf16 v[4:7], v[148:151], v[206:209], v[4:7]
	v_mfma_f32_16x16x32_bf16 v[0:3], v[156:159], v[206:209], v[0:3]
	s_barrier
	s_add_i32 s77, 0, 0x18000
	s_add_i32 s78, 0, 0x1c000
	v_add_u32_e32 v128, s77, v221
	v_add_u32_e32 v156, s78, v221
	ds_read_b128 v[96:99], v128
	ds_read_b128 v[108:111], v128 offset:1024
	ds_read_b128 v[120:123], v128 offset:2048
	ds_read_b128 v[128:131], v128 offset:3072
	ds_read_b128 v[144:147], v156
	ds_read_b128 v[148:151], v156 offset:1024
	ds_read_b128 v[152:155], v156 offset:2048
	ds_read_b128 v[156:159], v156 offset:3072
	s_add_u32 s56, s56, 0x40000
	s_addc_u32 s57, s57, 0
	s_mov_b32 m0, s60
	ds_read_b128 v[160:163], v225 offset:32768
	ds_read_b128 v[164:167], v225 offset:33792
	ds_read_b128 v[168:171], v225 offset:34816
	ds_read_b128 v[172:175], v225 offset:35840
	ds_read_b128 v[176:179], v225 offset:36864
	ds_read_b128 v[180:183], v225 offset:37888
	ds_read_b128 v[202:205], v225 offset:38912
	ds_read_b128 v[206:209], v225 offset:39936
	global_load_lds_dwordx4 v184, s[56:57]
	s_mov_b32 m0, s61
	s_nop 0
	global_load_lds_dwordx4 v188, s[56:57]
	s_waitcnt vmcnt(8)
	s_waitcnt lgkmcnt(0)
	s_barrier
	v_mfma_f32_16x16x32_bf16 v[140:143], v[96:99], v[160:163], v[140:143]
	v_mfma_f32_16x16x32_bf16 v[136:139], v[120:123], v[160:163], v[136:139]
	v_mfma_f32_16x16x32_bf16 v[116:119], v[96:99], v[168:171], v[116:119]
	v_mfma_f32_16x16x32_bf16 v[112:115], v[120:123], v[168:171], v[112:115]
	v_mfma_f32_16x16x32_bf16 v[92:95], v[96:99], v[176:179], v[92:95]
	v_mfma_f32_16x16x32_bf16 v[88:91], v[120:123], v[176:179], v[88:91]
	v_mfma_f32_16x16x32_bf16 v[76:79], v[96:99], v[202:205], v[76:79]
	v_mfma_f32_16x16x32_bf16 v[72:75], v[120:123], v[202:205], v[72:75]
	v_mfma_f32_16x16x32_bf16 v[140:143], v[108:111], v[164:167], v[140:143]
	v_mfma_f32_16x16x32_bf16 v[136:139], v[128:131], v[164:167], v[136:139]
	v_mfma_f32_16x16x32_bf16 v[116:119], v[108:111], v[172:175], v[116:119]
	v_mfma_f32_16x16x32_bf16 v[112:115], v[128:131], v[172:175], v[112:115]
	v_mfma_f32_16x16x32_bf16 v[92:95], v[108:111], v[180:183], v[92:95]
	v_mfma_f32_16x16x32_bf16 v[88:91], v[128:131], v[180:183], v[88:91]
	v_mfma_f32_16x16x32_bf16 v[76:79], v[108:111], v[206:209], v[76:79]
	v_mfma_f32_16x16x32_bf16 v[72:75], v[128:131], v[206:209], v[72:75]
	v_mfma_f32_16x16x32_bf16 v[132:135], v[144:147], v[160:163], v[132:135]
	v_mfma_f32_16x16x32_bf16 v[124:127], v[152:155], v[160:163], v[124:127]
	v_mfma_f32_16x16x32_bf16 v[104:107], v[144:147], v[168:171], v[104:107]
	v_mfma_f32_16x16x32_bf16 v[100:103], v[152:155], v[168:171], v[100:103]
	v_mfma_f32_16x16x32_bf16 v[84:87], v[144:147], v[176:179], v[84:87]
	v_mfma_f32_16x16x32_bf16 v[80:83], v[152:155], v[176:179], v[80:83]
	v_mfma_f32_16x16x32_bf16 v[68:71], v[144:147], v[202:205], v[68:71]
	v_mfma_f32_16x16x32_bf16 v[64:67], v[152:155], v[202:205], v[64:67]
	v_mfma_f32_16x16x32_bf16 v[132:135], v[148:151], v[164:167], v[132:135]
	v_mfma_f32_16x16x32_bf16 v[124:127], v[156:159], v[164:167], v[124:127]
	v_mfma_f32_16x16x32_bf16 v[104:107], v[148:151], v[172:175], v[104:107]
	v_mfma_f32_16x16x32_bf16 v[100:103], v[156:159], v[172:175], v[100:103]
	v_mfma_f32_16x16x32_bf16 v[84:87], v[148:151], v[180:183], v[84:87]
	v_mfma_f32_16x16x32_bf16 v[80:83], v[156:159], v[180:183], v[80:83]
	v_mfma_f32_16x16x32_bf16 v[68:71], v[148:151], v[206:209], v[68:71]
	v_mfma_f32_16x16x32_bf16 v[64:67], v[156:159], v[206:209], v[64:67]
	s_barrier
; #define PG8_STAGE(bufoff, gbase, voff) do { _Pragma("unroll") for (int _i = 0; _i < 2; ++_i) \
;         __builtin_amdgcn_global_load_lds((const unsigned*)((const char*)(gbase) + (voff)[_i]), (PG8_LAS unsigned*)(lds + (bufoff) + ldsw + _i * 8192), 16, 0, 0); } while (0)
; #define PG8_LDA(dst, b, h) do { _Pragma("unroll") for (int m = 0; m < 4; ++m) _Pragma("unroll") for (int k = 0; k < 2; ++k) dst[m][k] = *(const PG8_LAS bf16x8*)(lds + PG8_SA(b, h) + aoff + m * 2048 + k * 1024); } while (0)
; #define PG8_LDB(dst, b, h) do { _Pragma("unroll") for (int n = 0; n < 2; ++n) _Pragma("unroll") for (int k = 0; k < 2; ++k) dst[n][k] = *(const PG8_LAS bf16x8*)(lds + PG8_SB(b, h) + boff + n * 2048 + k * 1024); } while (0)
; template <class Epi, class Sched, bool ALIGN_EPI = false, bool SP2 = false>
; __device__ __forceinline__ void gemm_phase(PG8_LAS unsigned char* lds, const Gemm g, const Sched& S, const Epi& E) {
;     ...
;         for (int t = 0; t < nt; t += 2) {
;             const bool last = (t == nt - 2);
;             const char* a1 = cA + (size_t)(t + 1) * kstep;
;             const char* a2 = last ? nA : cA + (size_t)(t + 2) * kstep; const char* b2 = last ? nB : cB + (size_t)(t + 2) * kstep;
;             const char* a3 = a2 + kstep; const char* b3 = b2 + kstep;
;             if (last && has_next) S.a_ready(nxt);
;             if constexpr (SP2) {
;             PG8_LDB(B0, 0, 0); PG8_LDB(B1, 0, 1); PG8_SCHED; PG8_LDA(At, 0, 0); PG8_STAGE(PG8_SA(1, 1), a1 + hstep, voffA);
;             PG8_WAIT_V(8); PG8_WAIT_L(0); PG8_BAR; PG8_MMA(0, 0, At, B0); PG8_MMA(0, 1, At, B1); PG8_BAR; PG8_SCHED;
;             PG8_LDA(At, 0, 1); PG8_STAGE(PG8_SB(0, 0), b2, voffB); PG8_STAGE(PG8_SB(0, 1), b2 + hstep, voffB); PG8_STAGE(PG8_SA(0, 0), a2, voffA);
;             PG8_WAIT_V(8); PG8_WAIT_L(0); PG8_BAR; PG8_MMA(1, 0, At, B0); PG8_MMA(1, 1, At, B1); PG8_BAR; PG8_SCHED;
;             PG8_LDB(B0, 1, 0); PG8_LDB(B1, 1, 1); PG8_SCHED; PG8_LDA(At, 1, 0); PG8_STAGE(PG8_SA(0, 1), a2 + hstep, voffA);
;             PG8_WAIT_V(8); PG8_WAIT_L(0); PG8_BAR; PG8_MMA(0, 0, At, B0); PG8_MMA(0, 1, At, B1); PG8_BAR; PG8_SCHED;
;             PG8_LDA(At, 1, 1); PG8_STAGE(PG8_SB(1, 0), b3, voffB); PG8_STAGE(PG8_SB(1, 1), b3 + hstep, voffB); PG8_STAGE(PG8_SA(1, 0), a3, voffA);
;             PG8_WAIT_V(8); PG8_WAIT_L(0); PG8_BAR; PG8_MMA(1, 0, At, B0); PG8_MMA(1, 1, At, B1); PG8_BAR; PG8_SCHED;
	s_add_i32 s56, s77, s58
	s_mov_b32 m0, s56
	ds_read_b128 v[160:163], v225 offset:49152
	ds_read_b128 v[164:167], v225 offset:50176
	ds_read_b128 v[168:171], v225 offset:51200
	ds_read_b128 v[172:175], v225 offset:52224
	ds_read_b128 v[176:179], v225 offset:53248
	ds_read_b128 v[180:183], v225 offset:54272
	ds_read_b128 v[202:205], v225 offset:55296
	ds_read_b128 v[206:209], v225 offset:56320
	global_load_lds_dwordx4 v186, s[98:99]
	s_add_i32 m0, s56, 0x2000
	s_add_u32 s54, s54, 0x40080
	s_addc_u32 s55, s55, 0
	s_add_i32 s56, s78, s58
	global_load_lds_dwordx4 v190, s[98:99]
	s_mov_b32 m0, s56
	s_nop 0
	global_load_lds_dwordx4 v186, s[54:55]
	s_add_i32 m0, s56, 0x2000
	s_nop 0
	global_load_lds_dwordx4 v190, s[54:55]
	s_mov_b32 m0, s66
	s_nop 0
	global_load_lds_dwordx4 v184, s[100:101]
	s_mov_b32 m0, s67
	s_nop 0
	global_load_lds_dwordx4 v188, s[100:101]
	s_waitcnt vmcnt(8)
	s_waitcnt lgkmcnt(0)
	s_barrier
	v_mfma_f32_16x16x32_bf16 v[60:63], v[96:99], v[160:163], v[60:63]
	v_mfma_f32_16x16x32_bf16 v[56:59], v[120:123], v[160:163], v[56:59]
	v_mfma_f32_16x16x32_bf16 v[44:47], v[96:99], v[168:171], v[44:47]
	v_mfma_f32_16x16x32_bf16 v[40:43], v[120:123], v[168:171], v[40:43]
	v_mfma_f32_16x16x32_bf16 v[28:31], v[96:99], v[176:179], v[28:31]
	v_mfma_f32_16x16x32_bf16 v[24:27], v[120:123], v[176:179], v[24:27]
	v_mfma_f32_16x16x32_bf16 v[12:15], v[96:99], v[202:205], v[12:15]
	v_mfma_f32_16x16x32_bf16 v[8:11], v[120:123], v[202:205], v[8:11]
	v_mfma_f32_16x16x32_bf16 v[60:63], v[108:111], v[164:167], v[60:63]
	v_mfma_f32_16x16x32_bf16 v[56:59], v[128:131], v[164:167], v[56:59]
	v_mfma_f32_16x16x32_bf16 v[44:47], v[108:111], v[172:175], v[44:47]
	v_mfma_f32_16x16x32_bf16 v[40:43], v[128:131], v[172:175], v[40:43]
	v_mfma_f32_16x16x32_bf16 v[28:31], v[108:111], v[180:183], v[28:31]
	v_mfma_f32_16x16x32_bf16 v[24:27], v[128:131], v[180:183], v[24:27]
	v_mfma_f32_16x16x32_bf16 v[12:15], v[108:111], v[206:209], v[12:15]
	v_mfma_f32_16x16x32_bf16 v[8:11], v[128:131], v[206:209], v[8:11]
	v_mfma_f32_16x16x32_bf16 v[52:55], v[144:147], v[160:163], v[52:55]
	v_mfma_f32_16x16x32_bf16 v[48:51], v[152:155], v[160:163], v[48:51]
	v_mfma_f32_16x16x32_bf16 v[36:39], v[144:147], v[168:171], v[36:39]
	v_mfma_f32_16x16x32_bf16 v[32:35], v[152:155], v[168:171], v[32:35]
	v_mfma_f32_16x16x32_bf16 v[20:23], v[144:147], v[176:179], v[20:23]
	v_mfma_f32_16x16x32_bf16 v[16:19], v[152:155], v[176:179], v[16:19]
	v_mfma_f32_16x16x32_bf16 v[4:7], v[144:147], v[202:205], v[4:7]
	v_mfma_f32_16x16x32_bf16 v[0:3], v[152:155], v[202:205], v[0:3]
	v_mfma_f32_16x16x32_bf16 v[52:55], v[148:151], v[164:167], v[52:55]
	v_mfma_f32_16x16x32_bf16 v[48:51], v[156:159], v[164:167], v[48:51]
	v_mfma_f32_16x16x32_bf16 v[36:39], v[148:151], v[172:175], v[36:39]
	v_mfma_f32_16x16x32_bf16 v[32:35], v[156:159], v[172:175], v[32:35]
	v_mfma_f32_16x16x32_bf16 v[20:23], v[148:151], v[180:183], v[20:23]
	v_mfma_f32_16x16x32_bf16 v[16:19], v[156:159], v[180:183], v[16:19]
	v_mfma_f32_16x16x32_bf16 v[4:7], v[148:151], v[206:209], v[4:7]
	v_mfma_f32_16x16x32_bf16 v[0:3], v[156:159], v[206:209], v[0:3]
	s_barrier
	s_add_i32 s76, s76, 2
	s_add_u32 s20, s20, 0x100
	s_addc_u32 s21, s21, 0
	s_add_u32 s74, s74, 0x100
	s_addc_u32 s75, s75, 0
	s_cmp_gt_u32 s76, 13
.LBB0_705:
	ds_read_b128 v[96:99], v223
	ds_read_b128 v[108:111], v223 offset:1024
	ds_read_b128 v[120:123], v223 offset:2048
	ds_read_b128 v[128:131], v223 offset:3072
	ds_read_b128 v[144:147], v224
	ds_read_b128 v[148:151], v224 offset:1024
	ds_read_b128 v[152:155], v224 offset:2048
	ds_read_b128 v[156:159], v224 offset:3072
	s_add_u32 s54, s20, 0xfffc0080
	s_addc_u32 s55, s21, -1
	s_cmp_eq_u32 s76, 12
	s_cselect_b32 s57, s35, s55
	s_cselect_b32 s56, s47, s54
	s_cselect_b32 s55, s45, s75
	s_cselect_b32 s54, s73, s74
	s_add_i32 m0, s53, 0xc000
	ds_read_b128 v[160:163], v225
	ds_read_b128 v[164:167], v225 offset:1024
	ds_read_b128 v[168:171], v225 offset:2048
	ds_read_b128 v[172:175], v225 offset:3072
	ds_read_b128 v[176:179], v225 offset:4096
	ds_read_b128 v[180:183], v225 offset:5120
	ds_read_b128 v[202:205], v225 offset:6144
	ds_read_b128 v[206:209], v225 offset:7168
	global_load_lds_dwordx4 v192, s[20:21]
	s_add_i32 m0, s53, 0xe000
	s_nop 0
	global_load_lds_dwordx4 v194, s[20:21]
	s_waitcnt vmcnt(8)
	s_waitcnt lgkmcnt(0)
	s_barrier
	v_mfma_f32_16x16x32_bf16 v[140:143], v[96:99], v[160:163], v[140:143]
	v_mfma_f32_16x16x32_bf16 v[136:139], v[120:123], v[160:163], v[136:139]
	v_mfma_f32_16x16x32_bf16 v[116:119], v[96:99], v[168:171], v[116:119]
	v_mfma_f32_16x16x32_bf16 v[112:115], v[120:123], v[168:171], v[112:115]
	v_mfma_f32_16x16x32_bf16 v[92:95], v[96:99], v[176:179], v[92:95]
	v_mfma_f32_16x16x32_bf16 v[88:91], v[120:123], v[176:179], v[88:91]
	v_mfma_f32_16x16x32_bf16 v[76:79], v[96:99], v[202:205], v[76:79]
	v_mfma_f32_16x16x32_bf16 v[72:75], v[120:123], v[202:205], v[72:75]
	v_mfma_f32_16x16x32_bf16 v[140:143], v[108:111], v[164:167], v[140:143]
	v_mfma_f32_16x16x32_bf16 v[136:139], v[128:131], v[164:167], v[136:139]
	v_mfma_f32_16x16x32_bf16 v[116:119], v[108:111], v[172:175], v[116:119]
	v_mfma_f32_16x16x32_bf16 v[112:115], v[128:131], v[172:175], v[112:115]
	v_mfma_f32_16x16x32_bf16 v[92:95], v[108:111], v[180:183], v[92:95]
	v_mfma_f32_16x16x32_bf16 v[88:91], v[128:131], v[180:183], v[88:91]
	v_mfma_f32_16x16x32_bf16 v[76:79], v[108:111], v[206:209], v[76:79]
	v_mfma_f32_16x16x32_bf16 v[72:75], v[128:131], v[206:209], v[72:75]
	v_mfma_f32_16x16x32_bf16 v[132:135], v[144:147], v[160:163], v[132:135]
	v_mfma_f32_16x16x32_bf16 v[124:127], v[152:155], v[160:163], v[124:127]
	v_mfma_f32_16x16x32_bf16 v[104:107], v[144:147], v[168:171], v[104:107]
	v_mfma_f32_16x16x32_bf16 v[100:103], v[152:155], v[168:171], v[100:103]
	v_mfma_f32_16x16x32_bf16 v[84:87], v[144:147], v[176:179], v[84:87]
	v_mfma_f32_16x16x32_bf16 v[80:83], v[152:155], v[176:179], v[80:83]
	v_mfma_f32_16x16x32_bf16 v[68:71], v[144:147], v[202:205], v[68:71]
	v_mfma_f32_16x16x32_bf16 v[64:67], v[152:155], v[202:205], v[64:67]
	v_mfma_f32_16x16x32_bf16 v[132:135], v[148:151], v[164:167], v[132:135]
	v_mfma_f32_16x16x32_bf16 v[124:127], v[156:159], v[164:167], v[124:127]
	v_mfma_f32_16x16x32_bf16 v[104:107], v[148:151], v[172:175], v[104:107]
	v_mfma_f32_16x16x32_bf16 v[100:103], v[156:159], v[172:175], v[100:103]
	v_mfma_f32_16x16x32_bf16 v[84:87], v[148:151], v[180:183], v[84:87]
	v_mfma_f32_16x16x32_bf16 v[80:83], v[156:159], v[180:183], v[80:83]
	v_mfma_f32_16x16x32_bf16 v[68:71], v[148:151], v[206:209], v[68:71]
	v_mfma_f32_16x16x32_bf16 v[64:67], v[156:159], v[206:209], v[64:67]
	s_barrier
; #define PG8_STAGE(bufoff, gbase, voff) do { _Pragma("unroll") for (int _i = 0; _i < 2; ++_i) \
;         __builtin_amdgcn_global_load_lds((const unsigned*)((const char*)(gbase) + (voff)[_i]), (PG8_LAS unsigned*)(lds + (bufoff) + ldsw + _i * 8192), 16, 0, 0); } while (0)
; #define PG8_LDA(dst, b, h) do { _Pragma("unroll") for (int m = 0; m < 4; ++m) _Pragma("unroll") for (int k = 0; k < 2; ++k) dst[m][k] = *(const PG8_LAS bf16x8*)(lds + PG8_SA(b, h) + aoff + m * 2048 + k * 1024); } while (0)
; #define PG8_LDB(dst, b, h) do { _Pragma("unroll") for (int n = 0; n < 2; ++n) _Pragma("unroll") for (int k = 0; k < 2; ++k) dst[n][k] = *(const PG8_LAS bf16x8*)(lds + PG8_SB(b, h) + boff + n * 2048 + k * 1024); } while (0)
; #define PG8_MMA(ai, bj, At, Bt) do { __builtin_amdgcn_s_setprio(1); _Pragma("unroll") for (int m = 0; m < 4; ++m) _Pragma("unroll") for (int n = 0; n < 2; ++n) _Pragma("unroll") for (int k = 0; k < 2; ++k) \
;         acc[ai][bj][m][n] = __builtin_amdgcn_mfma_f32_16x16x32_bf16(Bt[n][k], At[m][k], acc[ai][bj][m][n], 0, 0, 0); __builtin_amdgcn_s_setprio(0); } while (0)
; #define PG8_WAIT_V(n) asm volatile("s_waitcnt vmcnt(" #n ")" ::: "memory")
; #define PG8_WAIT_L(n) asm volatile("s_waitcnt lgkmcnt(" #n ")" ::: "memory")
; #define PG8_BAR __builtin_amdgcn_s_barrier()
; #define PG8_SCHED __builtin_amdgcn_sched_barrier(0)
; template <class Epi, class Sched, bool ALIGN_EPI = false, bool SP2 = false>
; __device__ __forceinline__ void gemm_phase(PG8_LAS unsigned char* lds, const Gemm g, const Sched& S, const Epi& E) {
;     ...
;             PG8_LDA(At, 0, 1); PG8_STAGE(PG8_SB(0, 0), b2, voffB); PG8_STAGE(PG8_SB(0, 1), b2 + hstep, voffB); PG8_STAGE(PG8_SA(0, 0), a2, voffA);
;             PG8_WAIT_V(8); PG8_WAIT_L(0); PG8_BAR; PG8_MMA(1, 0, At, B0); PG8_MMA(1, 1, At, B1); PG8_BAR; PG8_SCHED;
;             PG8_LDB(B0, 1, 0); PG8_LDB(B1, 1, 1); PG8_SCHED; PG8_LDA(At, 1, 0); PG8_STAGE(PG8_SA(0, 1), a2 + hstep, voffA);
	s_add_i32 s77, s71, s58
	s_add_u32 s98, s54, s12
	s_addc_u32 s99, s55, s13
	s_add_u32 s100, s56, s12
	s_addc_u32 s101, s57, s13
	s_mov_b32 m0, s77
	ds_read_b128 v[160:163], v225 offset:16384
	ds_read_b128 v[164:167], v225 offset:17408
	ds_read_b128 v[168:171], v225 offset:18432
	ds_read_b128 v[172:175], v225 offset:19456
	ds_read_b128 v[176:179], v225 offset:20480
	ds_read_b128 v[180:183], v225 offset:21504
	ds_read_b128 v[202:205], v225 offset:22528
	ds_read_b128 v[206:209], v225 offset:23552
	global_load_lds_dwordx4 v186, s[54:55]
	s_add_i32 m0, s77, 0x2000
	s_add_u32 s78, s54, 0x40000
	s_addc_u32 s79, s55, 0
	s_add_i32 s77, s72, s58
	global_load_lds_dwordx4 v190, s[54:55]
	s_mov_b32 m0, s77
	s_nop 0
	global_load_lds_dwordx4 v186, s[78:79]
	s_add_i32 m0, s77, 0x2000
	s_nop 0
	global_load_lds_dwordx4 v190, s[78:79]
	s_mov_b32 m0, s53
	s_nop 0
	global_load_lds_dwordx4 v184, s[56:57]
	s_mov_b32 m0, s59
	s_nop 0
	global_load_lds_dwordx4 v188, s[56:57]
	s_waitcnt vmcnt(8)
	s_waitcnt lgkmcnt(0)
	s_barrier
	v_mfma_f32_16x16x32_bf16 v[60:63], v[96:99], v[160:163], v[60:63]
	v_mfma_f32_16x16x32_bf16 v[56:59], v[120:123], v[160:163], v[56:59]
	v_mfma_f32_16x16x32_bf16 v[44:47], v[96:99], v[168:171], v[44:47]
	v_mfma_f32_16x16x32_bf16 v[40:43], v[120:123], v[168:171], v[40:43]
	v_mfma_f32_16x16x32_bf16 v[28:31], v[96:99], v[176:179], v[28:31]
	v_mfma_f32_16x16x32_bf16 v[24:27], v[120:123], v[176:179], v[24:27]
	v_mfma_f32_16x16x32_bf16 v[12:15], v[96:99], v[202:205], v[12:15]
	v_mfma_f32_16x16x32_bf16 v[8:11], v[120:123], v[202:205], v[8:11]
	v_mfma_f32_16x16x32_bf16 v[60:63], v[108:111], v[164:167], v[60:63]
	v_mfma_f32_16x16x32_bf16 v[56:59], v[128:131], v[164:167], v[56:59]
	v_mfma_f32_16x16x32_bf16 v[44:47], v[108:111], v[172:175], v[44:47]
	v_mfma_f32_16x16x32_bf16 v[40:43], v[128:131], v[172:175], v[40:43]
	v_mfma_f32_16x16x32_bf16 v[28:31], v[108:111], v[180:183], v[28:31]
	v_mfma_f32_16x16x32_bf16 v[24:27], v[128:131], v[180:183], v[24:27]
	v_mfma_f32_16x16x32_bf16 v[12:15], v[108:111], v[206:209], v[12:15]
	v_mfma_f32_16x16x32_bf16 v[8:11], v[128:131], v[206:209], v[8:11]
	v_mfma_f32_16x16x32_bf16 v[52:55], v[144:147], v[160:163], v[52:55]
	v_mfma_f32_16x16x32_bf16 v[48:51], v[152:155], v[160:163], v[48:51]
	v_mfma_f32_16x16x32_bf16 v[36:39], v[144:147], v[168:171], v[36:39]
	v_mfma_f32_16x16x32_bf16 v[32:35], v[152:155], v[168:171], v[32:35]
	v_mfma_f32_16x16x32_bf16 v[20:23], v[144:147], v[176:179], v[20:23]
	v_mfma_f32_16x16x32_bf16 v[16:19], v[152:155], v[176:179], v[16:19]
	v_mfma_f32_16x16x32_bf16 v[4:7], v[144:147], v[202:205], v[4:7]
	v_mfma_f32_16x16x32_bf16 v[0:3], v[152:155], v[202:205], v[0:3]
	v_mfma_f32_16x16x32_bf16 v[52:55], v[148:151], v[164:167], v[52:55]
	v_mfma_f32_16x16x32_bf16 v[48:51], v[156:159], v[164:167], v[48:51]
	v_mfma_f32_16x16x32_bf16 v[36:39], v[148:151], v[172:175], v[36:39]
	v_mfma_f32_16x16x32_bf16 v[32:35], v[156:159], v[172:175], v[32:35]
	v_mfma_f32_16x16x32_bf16 v[20:23], v[148:151], v[180:183], v[20:23]
	v_mfma_f32_16x16x32_bf16 v[16:19], v[156:159], v[180:183], v[16:19]
	v_mfma_f32_16x16x32_bf16 v[4:7], v[148:151], v[206:209], v[4:7]
	v_mfma_f32_16x16x32_bf16 v[0:3], v[156:159], v[206:209], v[0:3]
	s_barrier
	s_add_i32 s77, 0, 0x18000
	s_add_i32 s78, 0, 0x1c000
	v_add_u32_e32 v128, s77, v221
	v_add_u32_e32 v156, s78, v221
	ds_read_b128 v[96:99], v128
	ds_read_b128 v[108:111], v128 offset:1024
	ds_read_b128 v[120:123], v128 offset:2048
	ds_read_b128 v[128:131], v128 offset:3072
	ds_read_b128 v[144:147], v156
	ds_read_b128 v[148:151], v156 offset:1024
	ds_read_b128 v[152:155], v156 offset:2048
	ds_read_b128 v[156:159], v156 offset:3072
	s_add_u32 s56, s56, 0x40000
	s_addc_u32 s57, s57, 0
	s_mov_b32 m0, s60
	ds_read_b128 v[160:163], v225 offset:32768
	ds_read_b128 v[164:167], v225 offset:33792
	ds_read_b128 v[168:171], v225 offset:34816
	ds_read_b128 v[172:175], v225 offset:35840
	ds_read_b128 v[176:179], v225 offset:36864
	ds_read_b128 v[180:183], v225 offset:37888
	ds_read_b128 v[202:205], v225 offset:38912
	ds_read_b128 v[206:209], v225 offset:39936
	global_load_lds_dwordx4 v184, s[56:57]
	s_mov_b32 m0, s61
	s_nop 0
	global_load_lds_dwordx4 v188, s[56:57]
	s_waitcnt vmcnt(8)
	s_waitcnt lgkmcnt(0)
	s_barrier
; #define PG8_STAGE(bufoff, gbase, voff) do { _Pragma("unroll") for (int _i = 0; _i < 2; ++_i) \
;         __builtin_amdgcn_global_load_lds((const unsigned*)((const char*)(gbase) + (voff)[_i]), (PG8_LAS unsigned*)(lds + (bufoff) + ldsw + _i * 8192), 16, 0, 0); } while (0)
; #define PG8_LDA(dst, b, h) do { _Pragma("unroll") for (int m = 0; m < 4; ++m) _Pragma("unroll") for (int k = 0; k < 2; ++k) dst[m][k] = *(const PG8_LAS bf16x8*)(lds + PG8_SA(b, h) + aoff + m * 2048 + k * 1024); } while (0)
; #define PG8_MMA(ai, bj, At, Bt) do { __builtin_amdgcn_s_setprio(1); _Pragma("unroll") for (int m = 0; m < 4; ++m) _Pragma("unroll") for (int n = 0; n < 2; ++n) _Pragma("unroll") for (int k = 0; k < 2; ++k) \
;         acc[ai][bj][m][n] = __builtin_amdgcn_mfma_f32_16x16x32_bf16(Bt[n][k], At[m][k], acc[ai][bj][m][n], 0, 0, 0); __builtin_amdgcn_s_setprio(0); } while (0)
; #define PG8_WAIT_V(n) asm volatile("s_waitcnt vmcnt(" #n ")" ::: "memory")
; #define PG8_WAIT_L(n) asm volatile("s_waitcnt lgkmcnt(" #n ")" ::: "memory")
; #define PG8_BAR __builtin_amdgcn_s_barrier()
; #define PG8_SCHED __builtin_amdgcn_sched_barrier(0)
; template <class Epi, class Sched, bool ALIGN_EPI = false, bool SP2 = false>
; __device__ __forceinline__ void gemm_phase(PG8_LAS unsigned char* lds, const Gemm g, const Sched& S, const Epi& E) {
;     ...
;             PG8_WAIT_V(8); PG8_WAIT_L(0); PG8_BAR; PG8_MMA(0, 0, At, B0); PG8_MMA(0, 1, At, B1); PG8_BAR; PG8_SCHED;
;             PG8_LDA(At, 1, 1); PG8_STAGE(PG8_SB(1, 0), b3, voffB); PG8_STAGE(PG8_SB(1, 1), b3 + hstep, voffB); PG8_STAGE(PG8_SA(1, 0), a3, voffA);
;             PG8_WAIT_V(8); PG8_WAIT_L(0); PG8_BAR; PG8_MMA(1, 0, At, B0); PG8_MMA(1, 1, At, B1); PG8_BAR; PG8_SCHED;
;     ...
;         if constexpr (ALIGN_EPI) { if (wr == 0) PG8_BAR; }
	v_mfma_f32_16x16x32_bf16 v[140:143], v[96:99], v[160:163], v[140:143]
	v_mfma_f32_16x16x32_bf16 v[136:139], v[120:123], v[160:163], v[136:139]
	v_mfma_f32_16x16x32_bf16 v[116:119], v[96:99], v[168:171], v[116:119]
	v_mfma_f32_16x16x32_bf16 v[112:115], v[120:123], v[168:171], v[112:115]
	v_mfma_f32_16x16x32_bf16 v[92:95], v[96:99], v[176:179], v[92:95]
	v_mfma_f32_16x16x32_bf16 v[88:91], v[120:123], v[176:179], v[88:91]
	v_mfma_f32_16x16x32_bf16 v[76:79], v[96:99], v[202:205], v[76:79]
	v_mfma_f32_16x16x32_bf16 v[72:75], v[120:123], v[202:205], v[72:75]
	v_mfma_f32_16x16x32_bf16 v[140:143], v[108:111], v[164:167], v[140:143]
	v_mfma_f32_16x16x32_bf16 v[136:139], v[128:131], v[164:167], v[136:139]
	v_mfma_f32_16x16x32_bf16 v[116:119], v[108:111], v[172:175], v[116:119]
	v_mfma_f32_16x16x32_bf16 v[112:115], v[128:131], v[172:175], v[112:115]
	v_mfma_f32_16x16x32_bf16 v[92:95], v[108:111], v[180:183], v[92:95]
	v_mfma_f32_16x16x32_bf16 v[88:91], v[128:131], v[180:183], v[88:91]
	v_mfma_f32_16x16x32_bf16 v[76:79], v[108:111], v[206:209], v[76:79]
	v_mfma_f32_16x16x32_bf16 v[72:75], v[128:131], v[206:209], v[72:75]
	v_mfma_f32_16x16x32_bf16 v[132:135], v[144:147], v[160:163], v[132:135]
	v_mfma_f32_16x16x32_bf16 v[124:127], v[152:155], v[160:163], v[124:127]
	v_mfma_f32_16x16x32_bf16 v[104:107], v[144:147], v[168:171], v[104:107]
	v_mfma_f32_16x16x32_bf16 v[100:103], v[152:155], v[168:171], v[100:103]
	v_mfma_f32_16x16x32_bf16 v[84:87], v[144:147], v[176:179], v[84:87]
	v_mfma_f32_16x16x32_bf16 v[80:83], v[152:155], v[176:179], v[80:83]
	v_mfma_f32_16x16x32_bf16 v[68:71], v[144:147], v[202:205], v[68:71]
	v_mfma_f32_16x16x32_bf16 v[64:67], v[152:155], v[202:205], v[64:67]
	v_mfma_f32_16x16x32_bf16 v[132:135], v[148:151], v[164:167], v[132:135]
	v_mfma_f32_16x16x32_bf16 v[124:127], v[156:159], v[164:167], v[124:127]
	v_mfma_f32_16x16x32_bf16 v[104:107], v[148:151], v[172:175], v[104:107]
	v_mfma_f32_16x16x32_bf16 v[100:103], v[156:159], v[172:175], v[100:103]
	v_mfma_f32_16x16x32_bf16 v[84:87], v[148:151], v[180:183], v[84:87]
	v_mfma_f32_16x16x32_bf16 v[80:83], v[156:159], v[180:183], v[80:83]
	v_mfma_f32_16x16x32_bf16 v[68:71], v[148:151], v[206:209], v[68:71]
	v_mfma_f32_16x16x32_bf16 v[64:67], v[156:159], v[206:209], v[64:67]
	s_barrier
	s_add_i32 s56, s77, s58
	s_mov_b32 m0, s56
	ds_read_b128 v[160:163], v225 offset:49152
	ds_read_b128 v[164:167], v225 offset:50176
	ds_read_b128 v[168:171], v225 offset:51200
	ds_read_b128 v[172:175], v225 offset:52224
	ds_read_b128 v[176:179], v225 offset:53248
	ds_read_b128 v[180:183], v225 offset:54272
	ds_read_b128 v[202:205], v225 offset:55296
	ds_read_b128 v[206:209], v225 offset:56320
	global_load_lds_dwordx4 v186, s[98:99]
	s_add_i32 m0, s56, 0x2000
	s_add_u32 s54, s54, 0x40080
	s_addc_u32 s55, s55, 0
	s_add_i32 s56, s78, s58
	global_load_lds_dwordx4 v190, s[98:99]
	s_mov_b32 m0, s56
	s_nop 0
	global_load_lds_dwordx4 v186, s[54:55]
	s_add_i32 m0, s56, 0x2000
	s_nop 0
	global_load_lds_dwordx4 v190, s[54:55]
	s_mov_b32 m0, s66
	s_nop 0
	global_load_lds_dwordx4 v184, s[100:101]
	s_mov_b32 m0, s67
	s_nop 0
	global_load_lds_dwordx4 v188, s[100:101]
	s_waitcnt vmcnt(8)
	s_waitcnt lgkmcnt(0)
	s_barrier
	v_mfma_f32_16x16x32_bf16 v[60:63], v[96:99], v[160:163], v[60:63]
	v_mfma_f32_16x16x32_bf16 v[56:59], v[120:123], v[160:163], v[56:59]
	v_mfma_f32_16x16x32_bf16 v[44:47], v[96:99], v[168:171], v[44:47]
	v_mfma_f32_16x16x32_bf16 v[40:43], v[120:123], v[168:171], v[40:43]
	v_mfma_f32_16x16x32_bf16 v[28:31], v[96:99], v[176:179], v[28:31]
	v_mfma_f32_16x16x32_bf16 v[24:27], v[120:123], v[176:179], v[24:27]
	v_mfma_f32_16x16x32_bf16 v[12:15], v[96:99], v[202:205], v[12:15]
	v_mfma_f32_16x16x32_bf16 v[8:11], v[120:123], v[202:205], v[8:11]
	v_mfma_f32_16x16x32_bf16 v[60:63], v[108:111], v[164:167], v[60:63]
	v_mfma_f32_16x16x32_bf16 v[56:59], v[128:131], v[164:167], v[56:59]
	v_mfma_f32_16x16x32_bf16 v[44:47], v[108:111], v[172:175], v[44:47]
	v_mfma_f32_16x16x32_bf16 v[40:43], v[128:131], v[172:175], v[40:43]
	v_mfma_f32_16x16x32_bf16 v[28:31], v[108:111], v[180:183], v[28:31]
	v_mfma_f32_16x16x32_bf16 v[24:27], v[128:131], v[180:183], v[24:27]
	v_mfma_f32_16x16x32_bf16 v[12:15], v[108:111], v[206:209], v[12:15]
	v_mfma_f32_16x16x32_bf16 v[8:11], v[128:131], v[206:209], v[8:11]
	v_mfma_f32_16x16x32_bf16 v[52:55], v[144:147], v[160:163], v[52:55]
	v_mfma_f32_16x16x32_bf16 v[48:51], v[152:155], v[160:163], v[48:51]
	v_mfma_f32_16x16x32_bf16 v[36:39], v[144:147], v[168:171], v[36:39]
	v_mfma_f32_16x16x32_bf16 v[32:35], v[152:155], v[168:171], v[32:35]
	v_mfma_f32_16x16x32_bf16 v[20:23], v[144:147], v[176:179], v[20:23]
	v_mfma_f32_16x16x32_bf16 v[16:19], v[152:155], v[176:179], v[16:19]
	v_mfma_f32_16x16x32_bf16 v[4:7], v[144:147], v[202:205], v[4:7]
	v_mfma_f32_16x16x32_bf16 v[0:3], v[152:155], v[202:205], v[0:3]
	v_mfma_f32_16x16x32_bf16 v[52:55], v[148:151], v[164:167], v[52:55]
	v_mfma_f32_16x16x32_bf16 v[48:51], v[156:159], v[164:167], v[48:51]
	v_mfma_f32_16x16x32_bf16 v[36:39], v[148:151], v[172:175], v[36:39]
	v_mfma_f32_16x16x32_bf16 v[32:35], v[156:159], v[172:175], v[32:35]
	v_mfma_f32_16x16x32_bf16 v[20:23], v[148:151], v[180:183], v[20:23]
	v_mfma_f32_16x16x32_bf16 v[16:19], v[156:159], v[180:183], v[16:19]
	v_mfma_f32_16x16x32_bf16 v[4:7], v[148:151], v[206:209], v[4:7]
	v_mfma_f32_16x16x32_bf16 v[0:3], v[156:159], v[206:209], v[0:3]
	s_barrier
	s_add_i32 s76, s76, 2
	s_add_u32 s20, s20, 0x100
	s_addc_u32 s21, s21, 0
	s_add_u32 s74, s74, 0x100
	s_addc_u32 s75, s75, 0
	s_cmp_gt_u32 s76, 13
	s_cbranch_scc0 .LBB0_705
	s_and_b64 vcc, exec, s[14:15]
	s_cbranch_vccz .LBB0_708
	s_barrier

; #define PG8_STAGE(bufoff, gbase, voff) do { _Pragma("unroll") for (int _i = 0; _i < 2; ++_i) \
;         __builtin_amdgcn_global_load_lds((const unsigned*)((const char*)(gbase) + (voff)[_i]), (PG8_LAS unsigned*)(lds + (bufoff) + ldsw + _i * 8192), 16, 0, 0); } while (0)
; #define PG8_LDA(dst, b, h) do { _Pragma("unroll") for (int m = 0; m < 4; ++m) _Pragma("unroll") for (int k = 0; k < 2; ++k) dst[m][k] = *(const PG8_LAS bf16x8*)(lds + PG8_SA(b, h) + aoff + m * 2048 + k * 1024); } while (0)
; #define PG8_LDB(dst, b, h) do { _Pragma("unroll") for (int n = 0; n < 2; ++n) _Pragma("unroll") for (int k = 0; k < 2; ++k) dst[n][k] = *(const PG8_LAS bf16x8*)(lds + PG8_SB(b, h) + boff + n * 2048 + k * 1024); } while (0)
; #define PG8_WAIT_V(n) asm volatile("s_waitcnt vmcnt(" #n ")" ::: "memory")
; #define PG8_WAIT_L(n) asm volatile("s_waitcnt lgkmcnt(" #n ")" ::: "memory")
; template <class Epi, class Sched, bool ALIGN_EPI = false, bool SP2 = false>
; __device__ __forceinline__ void gemm_phase(PG8_LAS unsigned char* lds, const Gemm g, const Sched& S, const Epi& E) {
;     ...
;         const bool has_next = S.next(ui + 1, nxt);
;         const char* nA = has_next ? (const char*)g.A + (size_t)nxt.pm * tstep : cA; const char* nB = has_next ? (const char*)g.Bt + (size_t)nxt.pn * tstep : cB;
;         for (int t = 0; t < nt; t += 2) {
;             const bool last = (t == nt - 2);
;             const char* a1 = cA + (size_t)(t + 1) * kstep;
;             const char* a2 = last ? nA : cA + (size_t)(t + 2) * kstep; const char* b2 = last ? nB : cB + (size_t)(t + 2) * kstep;
;             const char* a3 = a2 + kstep; const char* b3 = b2 + kstep;
;             if (last && has_next) S.a_ready(nxt);
;             if constexpr (SP2) {
;             PG8_LDB(B0, 0, 0); PG8_LDB(B1, 0, 1); PG8_SCHED; PG8_LDA(At, 0, 0); PG8_STAGE(PG8_SA(1, 1), a1 + hstep, voffA);
;             PG8_WAIT_V(8); PG8_WAIT_L(0); PG8_BAR; PG8_MMA(0, 0, At, B0); PG8_MMA(0, 1, At, B1); PG8_BAR; PG8_SCHED;
;             PG8_LDA(At, 0, 1); PG8_STAGE(PG8_SB(0, 0), b2, voffB); PG8_STAGE(PG8_SB(0, 1), b2 + hstep, voffB); PG8_STAGE(PG8_SA(0, 0), a2, voffA);
;             PG8_WAIT_V(8); PG8_WAIT_L(0); PG8_BAR; PG8_MMA(1, 0, At, B0); PG8_MMA(1, 1, At, B1); PG8_BAR; PG8_SCHED;
;             PG8_LDB(B0, 1, 0); PG8_LDB(B1, 1, 1); PG8_SCHED; PG8_LDA(At, 1, 0); PG8_STAGE(PG8_SA(0, 1), a2 + hstep, voffA);
.LBB0_809:
	s_ashr_i32 s15, s14, 31
	s_lshl_b64 s[16:17], s[14:15], 19
	s_add_u32 s16, s36, s16
	s_addc_u32 s17, s37, s17
	s_and_b64 s[18:19], s[4:5], exec
	s_cselect_b32 s15, s17, s21
	s_cselect_b32 s65, s16, s20
	s_ashr_i32 s13, s12, 31
	s_lshl_b64 s[18:19], s[12:13], 19
	s_add_u32 s18, s50, s18
	s_addc_u32 s19, s51, s19
	s_and_b64 s[44:45], s[4:5], exec
	s_cselect_b32 s13, s19, s39
	s_cselect_b32 s66, s18, s38
	s_add_u32 s20, s20, 0x40080
	s_addc_u32 s21, s21, 0
	s_add_u32 s67, s38, 0x100
	s_addc_u32 s68, s39, 0
	s_mov_b32 s69, -2
	ds_read_b128 v[154:157], v150
	ds_read_b128 v[158:161], v150 offset:1024
	ds_read_b128 v[162:165], v150 offset:2048
	ds_read_b128 v[166:169], v150 offset:3072
	ds_read_b128 v[170:173], v151
	ds_read_b128 v[174:177], v151 offset:1024
	ds_read_b128 v[178:181], v151 offset:2048
	ds_read_b128 v[182:185], v151 offset:3072
	s_add_u32 s38, s20, 0xfffc0080
	s_addc_u32 s39, s21, -1
	s_cmp_eq_u32 s69, 12
	s_cselect_b32 s45, s15, s39
	s_cselect_b32 s44, s65, s38
	s_cselect_b32 s39, s13, s68
	s_cselect_b32 s38, s66, s67
	s_add_i32 m0, s35, 0xc000
	ds_read_b128 v[186:189], v152
	ds_read_b128 v[190:193], v152 offset:1024
	ds_read_b128 v[198:201], v152 offset:2048
	ds_read_b128 v[202:205], v152 offset:3072
	ds_read_b128 v[206:209], v152 offset:4096
	ds_read_b128 v[210:213], v152 offset:5120
	ds_read_b128 v[214:217], v152 offset:6144
	ds_read_b128 v[218:221], v152 offset:7168
	global_load_lds_dwordx4 v136, s[20:21]
	s_add_i32 m0, s35, 0xe000
	s_nop 0
	global_load_lds_dwordx4 v138, s[20:21]
	s_waitcnt vmcnt(8)
	s_waitcnt lgkmcnt(0)
	s_barrier
	v_mfma_f32_16x16x32_bf16 v[124:127], v[154:157], v[186:189], 0
	v_mfma_f32_16x16x32_bf16 v[116:119], v[162:165], v[186:189], 0
	v_mfma_f32_16x16x32_bf16 v[108:111], v[154:157], v[198:201], 0
	v_mfma_f32_16x16x32_bf16 v[100:103], v[162:165], v[198:201], 0
	v_mfma_f32_16x16x32_bf16 v[92:95], v[154:157], v[206:209], 0
	v_mfma_f32_16x16x32_bf16 v[84:87], v[162:165], v[206:209], 0
	v_mfma_f32_16x16x32_bf16 v[76:79], v[154:157], v[214:217], 0
	v_mfma_f32_16x16x32_bf16 v[68:71], v[162:165], v[214:217], 0
	v_mfma_f32_16x16x32_bf16 v[124:127], v[158:161], v[190:193], v[124:127]
	v_mfma_f32_16x16x32_bf16 v[116:119], v[166:169], v[190:193], v[116:119]
	v_mfma_f32_16x16x32_bf16 v[108:111], v[158:161], v[202:205], v[108:111]
	v_mfma_f32_16x16x32_bf16 v[100:103], v[166:169], v[202:205], v[100:103]
	v_mfma_f32_16x16x32_bf16 v[92:95], v[158:161], v[210:213], v[92:95]
	v_mfma_f32_16x16x32_bf16 v[84:87], v[166:169], v[210:213], v[84:87]
	v_mfma_f32_16x16x32_bf16 v[76:79], v[158:161], v[218:221], v[76:79]
	v_mfma_f32_16x16x32_bf16 v[68:71], v[166:169], v[218:221], v[68:71]
	v_mfma_f32_16x16x32_bf16 v[120:123], v[170:173], v[186:189], 0
	v_mfma_f32_16x16x32_bf16 v[112:115], v[178:181], v[186:189], 0
	v_mfma_f32_16x16x32_bf16 v[104:107], v[170:173], v[198:201], 0
	v_mfma_f32_16x16x32_bf16 v[96:99], v[178:181], v[198:201], 0
	v_mfma_f32_16x16x32_bf16 v[88:91], v[170:173], v[206:209], 0
	v_mfma_f32_16x16x32_bf16 v[80:83], v[178:181], v[206:209], 0
	v_mfma_f32_16x16x32_bf16 v[72:75], v[170:173], v[214:217], 0
	v_mfma_f32_16x16x32_bf16 v[64:67], v[178:181], v[214:217], 0
	v_mfma_f32_16x16x32_bf16 v[120:123], v[174:177], v[190:193], v[120:123]
	v_mfma_f32_16x16x32_bf16 v[112:115], v[182:185], v[190:193], v[112:115]
	v_mfma_f32_16x16x32_bf16 v[104:107], v[174:177], v[202:205], v[104:107]
	v_mfma_f32_16x16x32_bf16 v[96:99], v[182:185], v[202:205], v[96:99]
	v_mfma_f32_16x16x32_bf16 v[88:91], v[174:177], v[210:213], v[88:91]
	v_mfma_f32_16x16x32_bf16 v[80:83], v[182:185], v[210:213], v[80:83]
	v_mfma_f32_16x16x32_bf16 v[72:75], v[174:177], v[218:221], v[72:75]
	v_mfma_f32_16x16x32_bf16 v[64:67], v[182:185], v[218:221], v[64:67]
	s_barrier
	s_add_i32 s70, s60, s52
	s_add_u32 s98, s38, s8
	s_addc_u32 s99, s39, s9
	s_add_u32 s100, s44, s8
	s_addc_u32 s101, s45, s9
	s_mov_b32 m0, s70
	ds_read_b128 v[186:189], v152 offset:16384
	ds_read_b128 v[190:193], v152 offset:17408
	ds_read_b128 v[198:201], v152 offset:18432
	ds_read_b128 v[202:205], v152 offset:19456
	ds_read_b128 v[206:209], v152 offset:20480
	ds_read_b128 v[210:213], v152 offset:21504
	ds_read_b128 v[214:217], v152 offset:22528
	ds_read_b128 v[218:221], v152 offset:23552
	global_load_lds_dwordx4 v132, s[38:39]
	s_add_i32 m0, s70, 0x2000
	s_add_u32 s70, s38, 0x40000
	s_addc_u32 s71, s39, 0
	s_add_i32 s72, s61, s52
	global_load_lds_dwordx4 v128, s[38:39]
	s_mov_b32 m0, s72
	s_nop 0
	global_load_lds_dwordx4 v132, s[70:71]
	s_add_i32 m0, s72, 0x2000
	s_nop 0
	global_load_lds_dwordx4 v128, s[70:71]
	s_mov_b32 m0, s35
	s_nop 0
	global_load_lds_dwordx4 v134, s[44:45]
	s_mov_b32 m0, s54
	s_nop 0
	global_load_lds_dwordx4 v130, s[44:45]
	s_waitcnt vmcnt(8)
	s_waitcnt lgkmcnt(0)
	s_barrier
; #define PG8_STAGE(bufoff, gbase, voff) do { _Pragma("unroll") for (int _i = 0; _i < 2; ++_i) \
;         __builtin_amdgcn_global_load_lds((const unsigned*)((const char*)(gbase) + (voff)[_i]), (PG8_LAS unsigned*)(lds + (bufoff) + ldsw + _i * 8192), 16, 0, 0); } while (0)
; #define PG8_LDA(dst, b, h) do { _Pragma("unroll") for (int m = 0; m < 4; ++m) _Pragma("unroll") for (int k = 0; k < 2; ++k) dst[m][k] = *(const PG8_LAS bf16x8*)(lds + PG8_SA(b, h) + aoff + m * 2048 + k * 1024); } while (0)
; #define PG8_LDB(dst, b, h) do { _Pragma("unroll") for (int n = 0; n < 2; ++n) _Pragma("unroll") for (int k = 0; k < 2; ++k) dst[n][k] = *(const PG8_LAS bf16x8*)(lds + PG8_SB(b, h) + boff + n * 2048 + k * 1024); } while (0)
; #define PG8_MMA(ai, bj, At, Bt) do { __builtin_amdgcn_s_setprio(1); _Pragma("unroll") for (int m = 0; m < 4; ++m) _Pragma("unroll") for (int n = 0; n < 2; ++n) _Pragma("unroll") for (int k = 0; k < 2; ++k) \
;         acc[ai][bj][m][n] = __builtin_amdgcn_mfma_f32_16x16x32_bf16(Bt[n][k], At[m][k], acc[ai][bj][m][n], 0, 0, 0); __builtin_amdgcn_s_setprio(0); } while (0)
; #define PG8_WAIT_V(n) asm volatile("s_waitcnt vmcnt(" #n ")" ::: "memory")
; #define PG8_WAIT_L(n) asm volatile("s_waitcnt lgkmcnt(" #n ")" ::: "memory")
; #define PG8_BAR __builtin_amdgcn_s_barrier()
; #define PG8_SCHED __builtin_amdgcn_sched_barrier(0)
; template <class Epi, class Sched, bool ALIGN_EPI = false, bool SP2 = false>
; __device__ __forceinline__ void gemm_phase(PG8_LAS unsigned char* lds, const Gemm g, const Sched& S, const Epi& E) {
;     ...
;             PG8_LDA(At, 0, 1); PG8_STAGE(PG8_SB(0, 0), b2, voffB); PG8_STAGE(PG8_SB(0, 1), b2 + hstep, voffB); PG8_STAGE(PG8_SA(0, 0), a2, voffA);
;             PG8_WAIT_V(8); PG8_WAIT_L(0); PG8_BAR; PG8_MMA(1, 0, At, B0); PG8_MMA(1, 1, At, B1); PG8_BAR; PG8_SCHED;
;             PG8_LDB(B0, 1, 0); PG8_LDB(B1, 1, 1); PG8_SCHED; PG8_LDA(At, 1, 0); PG8_STAGE(PG8_SA(0, 1), a2 + hstep, voffA);
;             PG8_WAIT_V(8); PG8_WAIT_L(0); PG8_BAR; PG8_MMA(0, 0, At, B0); PG8_MMA(0, 1, At, B1); PG8_BAR; PG8_SCHED;
	v_mfma_f32_16x16x32_bf16 v[60:63], v[154:157], v[186:189], 0
	v_mfma_f32_16x16x32_bf16 v[52:55], v[162:165], v[186:189], 0
	v_mfma_f32_16x16x32_bf16 v[44:47], v[154:157], v[198:201], 0
	v_mfma_f32_16x16x32_bf16 v[36:39], v[162:165], v[198:201], 0
	v_mfma_f32_16x16x32_bf16 v[28:31], v[154:157], v[206:209], 0
	v_mfma_f32_16x16x32_bf16 v[20:23], v[162:165], v[206:209], 0
	v_mfma_f32_16x16x32_bf16 v[12:15], v[154:157], v[214:217], 0
	v_mfma_f32_16x16x32_bf16 v[4:7], v[162:165], v[214:217], 0
	v_mfma_f32_16x16x32_bf16 v[60:63], v[158:161], v[190:193], v[60:63]
	v_mfma_f32_16x16x32_bf16 v[52:55], v[166:169], v[190:193], v[52:55]
	v_mfma_f32_16x16x32_bf16 v[44:47], v[158:161], v[202:205], v[44:47]
	v_mfma_f32_16x16x32_bf16 v[36:39], v[166:169], v[202:205], v[36:39]
	v_mfma_f32_16x16x32_bf16 v[28:31], v[158:161], v[210:213], v[28:31]
	v_mfma_f32_16x16x32_bf16 v[20:23], v[166:169], v[210:213], v[20:23]
	v_mfma_f32_16x16x32_bf16 v[12:15], v[158:161], v[218:221], v[12:15]
	v_mfma_f32_16x16x32_bf16 v[4:7], v[166:169], v[218:221], v[4:7]
	v_mfma_f32_16x16x32_bf16 v[56:59], v[170:173], v[186:189], 0
	v_mfma_f32_16x16x32_bf16 v[48:51], v[178:181], v[186:189], 0
	v_mfma_f32_16x16x32_bf16 v[40:43], v[170:173], v[198:201], 0
	v_mfma_f32_16x16x32_bf16 v[32:35], v[178:181], v[198:201], 0
	v_mfma_f32_16x16x32_bf16 v[24:27], v[170:173], v[206:209], 0
	v_mfma_f32_16x16x32_bf16 v[16:19], v[178:181], v[206:209], 0
	v_mfma_f32_16x16x32_bf16 v[8:11], v[170:173], v[214:217], 0
	v_mfma_f32_16x16x32_bf16 v[0:3], v[178:181], v[214:217], 0
	v_mfma_f32_16x16x32_bf16 v[56:59], v[174:177], v[190:193], v[56:59]
	v_mfma_f32_16x16x32_bf16 v[48:51], v[182:185], v[190:193], v[48:51]
	v_mfma_f32_16x16x32_bf16 v[40:43], v[174:177], v[202:205], v[40:43]
	v_mfma_f32_16x16x32_bf16 v[32:35], v[182:185], v[202:205], v[32:35]
	v_mfma_f32_16x16x32_bf16 v[24:27], v[174:177], v[210:213], v[24:27]
	v_mfma_f32_16x16x32_bf16 v[16:19], v[182:185], v[210:213], v[16:19]
	v_mfma_f32_16x16x32_bf16 v[8:11], v[174:177], v[218:221], v[8:11]
	v_mfma_f32_16x16x32_bf16 v[0:3], v[182:185], v[218:221], v[0:3]
	s_barrier
	s_add_i32 s70, 0, 0x18000
	v_add_u32_e32 v153, s70, v147
	s_add_i32 s71, 0, 0x1c000
	ds_read_b128 v[154:157], v153
	ds_read_b128 v[158:161], v153 offset:1024
	ds_read_b128 v[162:165], v153 offset:2048
	ds_read_b128 v[166:169], v153 offset:3072
	v_add_u32_e32 v153, s71, v147
	ds_read_b128 v[170:173], v153
	ds_read_b128 v[174:177], v153 offset:1024
	ds_read_b128 v[178:181], v153 offset:2048
	ds_read_b128 v[182:185], v153 offset:3072
	s_add_u32 s44, s44, 0x40000
	s_addc_u32 s45, s45, 0
	s_mov_b32 m0, s55
	ds_read_b128 v[186:189], v152 offset:32768
	ds_read_b128 v[190:193], v152 offset:33792
	ds_read_b128 v[198:201], v152 offset:34816
	ds_read_b128 v[202:205], v152 offset:35840
	ds_read_b128 v[206:209], v152 offset:36864
	ds_read_b128 v[210:213], v152 offset:37888
	ds_read_b128 v[214:217], v152 offset:38912
	ds_read_b128 v[218:221], v152 offset:39936
	global_load_lds_dwordx4 v134, s[44:45]
	s_mov_b32 m0, s56
	s_nop 0
	global_load_lds_dwordx4 v130, s[44:45]
	s_waitcnt vmcnt(8)
	s_waitcnt lgkmcnt(0)
	s_barrier
	v_mfma_f32_16x16x32_bf16 v[124:127], v[154:157], v[186:189], v[124:127]
	v_mfma_f32_16x16x32_bf16 v[116:119], v[162:165], v[186:189], v[116:119]
	v_mfma_f32_16x16x32_bf16 v[108:111], v[154:157], v[198:201], v[108:111]
	v_mfma_f32_16x16x32_bf16 v[100:103], v[162:165], v[198:201], v[100:103]
	v_mfma_f32_16x16x32_bf16 v[92:95], v[154:157], v[206:209], v[92:95]
	v_mfma_f32_16x16x32_bf16 v[84:87], v[162:165], v[206:209], v[84:87]
	v_mfma_f32_16x16x32_bf16 v[76:79], v[154:157], v[214:217], v[76:79]
	v_mfma_f32_16x16x32_bf16 v[68:71], v[162:165], v[214:217], v[68:71]
	v_mfma_f32_16x16x32_bf16 v[124:127], v[158:161], v[190:193], v[124:127]
	v_mfma_f32_16x16x32_bf16 v[116:119], v[166:169], v[190:193], v[116:119]
	v_mfma_f32_16x16x32_bf16 v[108:111], v[158:161], v[202:205], v[108:111]
	v_mfma_f32_16x16x32_bf16 v[100:103], v[166:169], v[202:205], v[100:103]
	v_mfma_f32_16x16x32_bf16 v[92:95], v[158:161], v[210:213], v[92:95]
	v_mfma_f32_16x16x32_bf16 v[84:87], v[166:169], v[210:213], v[84:87]
	v_mfma_f32_16x16x32_bf16 v[76:79], v[158:161], v[218:221], v[76:79]
	v_mfma_f32_16x16x32_bf16 v[68:71], v[166:169], v[218:221], v[68:71]
	v_mfma_f32_16x16x32_bf16 v[120:123], v[170:173], v[186:189], v[120:123]
	v_mfma_f32_16x16x32_bf16 v[112:115], v[178:181], v[186:189], v[112:115]
	v_mfma_f32_16x16x32_bf16 v[104:107], v[170:173], v[198:201], v[104:107]
	v_mfma_f32_16x16x32_bf16 v[96:99], v[178:181], v[198:201], v[96:99]
	v_mfma_f32_16x16x32_bf16 v[88:91], v[170:173], v[206:209], v[88:91]
	v_mfma_f32_16x16x32_bf16 v[80:83], v[178:181], v[206:209], v[80:83]
	v_mfma_f32_16x16x32_bf16 v[72:75], v[170:173], v[214:217], v[72:75]
	v_mfma_f32_16x16x32_bf16 v[64:67], v[178:181], v[214:217], v[64:67]
	v_mfma_f32_16x16x32_bf16 v[120:123], v[174:177], v[190:193], v[120:123]
	v_mfma_f32_16x16x32_bf16 v[112:115], v[182:185], v[190:193], v[112:115]
	v_mfma_f32_16x16x32_bf16 v[104:107], v[174:177], v[202:205], v[104:107]
	v_mfma_f32_16x16x32_bf16 v[96:99], v[182:185], v[202:205], v[96:99]
	v_mfma_f32_16x16x32_bf16 v[88:91], v[174:177], v[210:213], v[88:91]
	v_mfma_f32_16x16x32_bf16 v[80:83], v[182:185], v[210:213], v[80:83]
	v_mfma_f32_16x16x32_bf16 v[72:75], v[174:177], v[218:221], v[72:75]
	v_mfma_f32_16x16x32_bf16 v[64:67], v[182:185], v[218:221], v[64:67]
	s_barrier
; #define PG8_STAGE(bufoff, gbase, voff) do { _Pragma("unroll") for (int _i = 0; _i < 2; ++_i) \
;         __builtin_amdgcn_global_load_lds((const unsigned*)((const char*)(gbase) + (voff)[_i]), (PG8_LAS unsigned*)(lds + (bufoff) + ldsw + _i * 8192), 16, 0, 0); } while (0)
; #define PG8_LDA(dst, b, h) do { _Pragma("unroll") for (int m = 0; m < 4; ++m) _Pragma("unroll") for (int k = 0; k < 2; ++k) dst[m][k] = *(const PG8_LAS bf16x8*)(lds + PG8_SA(b, h) + aoff + m * 2048 + k * 1024); } while (0)
; #define PG8_LDB(dst, b, h) do { _Pragma("unroll") for (int n = 0; n < 2; ++n) _Pragma("unroll") for (int k = 0; k < 2; ++k) dst[n][k] = *(const PG8_LAS bf16x8*)(lds + PG8_SB(b, h) + boff + n * 2048 + k * 1024); } while (0)
; template <class Epi, class Sched, bool ALIGN_EPI = false, bool SP2 = false>
; __device__ __forceinline__ void gemm_phase(PG8_LAS unsigned char* lds, const Gemm g, const Sched& S, const Epi& E) {
;     ...
;         for (int t = 0; t < nt; t += 2) {
;             const bool last = (t == nt - 2);
;             const char* a1 = cA + (size_t)(t + 1) * kstep;
;             const char* a2 = last ? nA : cA + (size_t)(t + 2) * kstep; const char* b2 = last ? nB : cB + (size_t)(t + 2) * kstep;
;             const char* a3 = a2 + kstep; const char* b3 = b2 + kstep;
;             if (last && has_next) S.a_ready(nxt);
;             if constexpr (SP2) {
;             PG8_LDB(B0, 0, 0); PG8_LDB(B1, 0, 1); PG8_SCHED; PG8_LDA(At, 0, 0); PG8_STAGE(PG8_SA(1, 1), a1 + hstep, voffA);
;             PG8_WAIT_V(8); PG8_WAIT_L(0); PG8_BAR; PG8_MMA(0, 0, At, B0); PG8_MMA(0, 1, At, B1); PG8_BAR; PG8_SCHED;
;             PG8_LDA(At, 0, 1); PG8_STAGE(PG8_SB(0, 0), b2, voffB); PG8_STAGE(PG8_SB(0, 1), b2 + hstep, voffB); PG8_STAGE(PG8_SA(0, 0), a2, voffA);
;             PG8_WAIT_V(8); PG8_WAIT_L(0); PG8_BAR; PG8_MMA(1, 0, At, B0); PG8_MMA(1, 1, At, B1); PG8_BAR; PG8_SCHED;
;             PG8_LDB(B0, 1, 0); PG8_LDB(B1, 1, 1); PG8_SCHED; PG8_LDA(At, 1, 0); PG8_STAGE(PG8_SA(0, 1), a2 + hstep, voffA);
;             PG8_WAIT_V(8); PG8_WAIT_L(0); PG8_BAR; PG8_MMA(0, 0, At, B0); PG8_MMA(0, 1, At, B1); PG8_BAR; PG8_SCHED;
;             PG8_LDA(At, 1, 1); PG8_STAGE(PG8_SB(1, 0), b3, voffB); PG8_STAGE(PG8_SB(1, 1), b3 + hstep, voffB); PG8_STAGE(PG8_SA(1, 0), a3, voffA);
;             PG8_WAIT_V(8); PG8_WAIT_L(0); PG8_BAR; PG8_MMA(1, 0, At, B0); PG8_MMA(1, 1, At, B1); PG8_BAR; PG8_SCHED;
	s_add_i32 s44, s70, s52
	s_mov_b32 m0, s44
	ds_read_b128 v[186:189], v152 offset:49152
	ds_read_b128 v[190:193], v152 offset:50176
	ds_read_b128 v[198:201], v152 offset:51200
	ds_read_b128 v[202:205], v152 offset:52224
	ds_read_b128 v[206:209], v152 offset:53248
	ds_read_b128 v[210:213], v152 offset:54272
	ds_read_b128 v[214:217], v152 offset:55296
	ds_read_b128 v[218:221], v152 offset:56320
	global_load_lds_dwordx4 v132, s[98:99]
	s_add_i32 m0, s44, 0x2000
	s_add_u32 s38, s38, 0x40080
	s_addc_u32 s39, s39, 0
	s_add_i32 s44, s71, s52
	global_load_lds_dwordx4 v128, s[98:99]
	s_mov_b32 m0, s44
	s_nop 0
	global_load_lds_dwordx4 v132, s[38:39]
	s_add_i32 m0, s44, 0x2000
	s_nop 0
	global_load_lds_dwordx4 v128, s[38:39]
	s_mov_b32 m0, s58
	s_nop 0
	global_load_lds_dwordx4 v134, s[100:101]
	s_mov_b32 m0, s59
	s_nop 0
	global_load_lds_dwordx4 v130, s[100:101]
	s_waitcnt vmcnt(8)
	s_waitcnt lgkmcnt(0)
	s_barrier
	v_mfma_f32_16x16x32_bf16 v[60:63], v[154:157], v[186:189], v[60:63]
	v_mfma_f32_16x16x32_bf16 v[52:55], v[162:165], v[186:189], v[52:55]
	v_mfma_f32_16x16x32_bf16 v[44:47], v[154:157], v[198:201], v[44:47]
	v_mfma_f32_16x16x32_bf16 v[36:39], v[162:165], v[198:201], v[36:39]
	v_mfma_f32_16x16x32_bf16 v[28:31], v[154:157], v[206:209], v[28:31]
	v_mfma_f32_16x16x32_bf16 v[20:23], v[162:165], v[206:209], v[20:23]
	v_mfma_f32_16x16x32_bf16 v[12:15], v[154:157], v[214:217], v[12:15]
	v_mfma_f32_16x16x32_bf16 v[4:7], v[162:165], v[214:217], v[4:7]
	v_mfma_f32_16x16x32_bf16 v[60:63], v[158:161], v[190:193], v[60:63]
	v_mfma_f32_16x16x32_bf16 v[52:55], v[166:169], v[190:193], v[52:55]
	v_mfma_f32_16x16x32_bf16 v[44:47], v[158:161], v[202:205], v[44:47]
	v_mfma_f32_16x16x32_bf16 v[36:39], v[166:169], v[202:205], v[36:39]
	v_mfma_f32_16x16x32_bf16 v[28:31], v[158:161], v[210:213], v[28:31]
	v_mfma_f32_16x16x32_bf16 v[20:23], v[166:169], v[210:213], v[20:23]
	v_mfma_f32_16x16x32_bf16 v[12:15], v[158:161], v[218:221], v[12:15]
	v_mfma_f32_16x16x32_bf16 v[4:7], v[166:169], v[218:221], v[4:7]
	v_mfma_f32_16x16x32_bf16 v[56:59], v[170:173], v[186:189], v[56:59]
	v_mfma_f32_16x16x32_bf16 v[48:51], v[178:181], v[186:189], v[48:51]
	v_mfma_f32_16x16x32_bf16 v[40:43], v[170:173], v[198:201], v[40:43]
	v_mfma_f32_16x16x32_bf16 v[32:35], v[178:181], v[198:201], v[32:35]
	v_mfma_f32_16x16x32_bf16 v[24:27], v[170:173], v[206:209], v[24:27]
	v_mfma_f32_16x16x32_bf16 v[16:19], v[178:181], v[206:209], v[16:19]
	v_mfma_f32_16x16x32_bf16 v[8:11], v[170:173], v[214:217], v[8:11]
	v_mfma_f32_16x16x32_bf16 v[0:3], v[178:181], v[214:217], v[0:3]
	v_mfma_f32_16x16x32_bf16 v[56:59], v[174:177], v[190:193], v[56:59]
	v_mfma_f32_16x16x32_bf16 v[48:51], v[182:185], v[190:193], v[48:51]
	v_mfma_f32_16x16x32_bf16 v[40:43], v[174:177], v[202:205], v[40:43]
	v_mfma_f32_16x16x32_bf16 v[32:35], v[182:185], v[202:205], v[32:35]
	v_mfma_f32_16x16x32_bf16 v[24:27], v[174:177], v[210:213], v[24:27]
	v_mfma_f32_16x16x32_bf16 v[16:19], v[182:185], v[210:213], v[16:19]
	v_mfma_f32_16x16x32_bf16 v[8:11], v[174:177], v[218:221], v[8:11]
	v_mfma_f32_16x16x32_bf16 v[0:3], v[182:185], v[218:221], v[0:3]
	s_barrier
	s_add_i32 s69, s69, 2
	s_add_u32 s20, s20, 0x100
	s_addc_u32 s21, s21, 0
	s_add_u32 s67, s67, 0x100
	s_addc_u32 s68, s68, 0
	s_cmp_gt_u32 s69, 13
.LBB0_810:
	ds_read_b128 v[154:157], v150
	ds_read_b128 v[158:161], v150 offset:1024
	ds_read_b128 v[162:165], v150 offset:2048
	ds_read_b128 v[166:169], v150 offset:3072
	ds_read_b128 v[170:173], v151
	ds_read_b128 v[174:177], v151 offset:1024
	ds_read_b128 v[178:181], v151 offset:2048
	ds_read_b128 v[182:185], v151 offset:3072
	s_add_u32 s38, s20, 0xfffc0080
	s_addc_u32 s39, s21, -1
	s_cmp_eq_u32 s69, 12
	s_cselect_b32 s45, s15, s39
	s_cselect_b32 s44, s65, s38
	s_cselect_b32 s39, s13, s68
	s_cselect_b32 s38, s66, s67
	s_add_i32 m0, s35, 0xc000
	ds_read_b128 v[186:189], v152
	ds_read_b128 v[190:193], v152 offset:1024
	ds_read_b128 v[198:201], v152 offset:2048
	ds_read_b128 v[202:205], v152 offset:3072
	ds_read_b128 v[206:209], v152 offset:4096
	ds_read_b128 v[210:213], v152 offset:5120
	ds_read_b128 v[214:217], v152 offset:6144
	ds_read_b128 v[218:221], v152 offset:7168
	global_load_lds_dwordx4 v136, s[20:21]
	s_add_i32 m0, s35, 0xe000
	s_nop 0
	global_load_lds_dwordx4 v138, s[20:21]
	s_waitcnt vmcnt(8)
	s_waitcnt lgkmcnt(0)
	s_barrier
	v_mfma_f32_16x16x32_bf16 v[124:127], v[154:157], v[186:189], v[124:127]
	v_mfma_f32_16x16x32_bf16 v[116:119], v[162:165], v[186:189], v[116:119]
	v_mfma_f32_16x16x32_bf16 v[108:111], v[154:157], v[198:201], v[108:111]
	v_mfma_f32_16x16x32_bf16 v[100:103], v[162:165], v[198:201], v[100:103]
	v_mfma_f32_16x16x32_bf16 v[92:95], v[154:157], v[206:209], v[92:95]
	v_mfma_f32_16x16x32_bf16 v[84:87], v[162:165], v[206:209], v[84:87]
	v_mfma_f32_16x16x32_bf16 v[76:79], v[154:157], v[214:217], v[76:79]
	v_mfma_f32_16x16x32_bf16 v[68:71], v[162:165], v[214:217], v[68:71]
	v_mfma_f32_16x16x32_bf16 v[124:127], v[158:161], v[190:193], v[124:127]
	v_mfma_f32_16x16x32_bf16 v[116:119], v[166:169], v[190:193], v[116:119]
	v_mfma_f32_16x16x32_bf16 v[108:111], v[158:161], v[202:205], v[108:111]
	v_mfma_f32_16x16x32_bf16 v[100:103], v[166:169], v[202:205], v[100:103]
	v_mfma_f32_16x16x32_bf16 v[92:95], v[158:161], v[210:213], v[92:95]
	v_mfma_f32_16x16x32_bf16 v[84:87], v[166:169], v[210:213], v[84:87]
	v_mfma_f32_16x16x32_bf16 v[76:79], v[158:161], v[218:221], v[76:79]
	v_mfma_f32_16x16x32_bf16 v[68:71], v[166:169], v[218:221], v[68:71]
	v_mfma_f32_16x16x32_bf16 v[120:123], v[170:173], v[186:189], v[120:123]
	v_mfma_f32_16x16x32_bf16 v[112:115], v[178:181], v[186:189], v[112:115]
	v_mfma_f32_16x16x32_bf16 v[104:107], v[170:173], v[198:201], v[104:107]
	v_mfma_f32_16x16x32_bf16 v[96:99], v[178:181], v[198:201], v[96:99]
	v_mfma_f32_16x16x32_bf16 v[88:91], v[170:173], v[206:209], v[88:91]
	v_mfma_f32_16x16x32_bf16 v[80:83], v[178:181], v[206:209], v[80:83]
	v_mfma_f32_16x16x32_bf16 v[72:75], v[170:173], v[214:217], v[72:75]
	v_mfma_f32_16x16x32_bf16 v[64:67], v[178:181], v[214:217], v[64:67]
	v_mfma_f32_16x16x32_bf16 v[120:123], v[174:177], v[190:193], v[120:123]
	v_mfma_f32_16x16x32_bf16 v[112:115], v[182:185], v[190:193], v[112:115]
	v_mfma_f32_16x16x32_bf16 v[104:107], v[174:177], v[202:205], v[104:107]
	v_mfma_f32_16x16x32_bf16 v[96:99], v[182:185], v[202:205], v[96:99]
	v_mfma_f32_16x16x32_bf16 v[88:91], v[174:177], v[210:213], v[88:91]
	v_mfma_f32_16x16x32_bf16 v[80:83], v[182:185], v[210:213], v[80:83]
	v_mfma_f32_16x16x32_bf16 v[72:75], v[174:177], v[218:221], v[72:75]
	v_mfma_f32_16x16x32_bf16 v[64:67], v[182:185], v[218:221], v[64:67]
	s_barrier
; #define PG8_STAGE(bufoff, gbase, voff) do { _Pragma("unroll") for (int _i = 0; _i < 2; ++_i) \
;         __builtin_amdgcn_global_load_lds((const unsigned*)((const char*)(gbase) + (voff)[_i]), (PG8_LAS unsigned*)(lds + (bufoff) + ldsw + _i * 8192), 16, 0, 0); } while (0)
; #define PG8_LDA(dst, b, h) do { _Pragma("unroll") for (int m = 0; m < 4; ++m) _Pragma("unroll") for (int k = 0; k < 2; ++k) dst[m][k] = *(const PG8_LAS bf16x8*)(lds + PG8_SA(b, h) + aoff + m * 2048 + k * 1024); } while (0)
; #define PG8_LDB(dst, b, h) do { _Pragma("unroll") for (int n = 0; n < 2; ++n) _Pragma("unroll") for (int k = 0; k < 2; ++k) dst[n][k] = *(const PG8_LAS bf16x8*)(lds + PG8_SB(b, h) + boff + n * 2048 + k * 1024); } while (0)
; #define PG8_MMA(ai, bj, At, Bt) do { __builtin_amdgcn_s_setprio(1); _Pragma("unroll") for (int m = 0; m < 4; ++m) _Pragma("unroll") for (int n = 0; n < 2; ++n) _Pragma("unroll") for (int k = 0; k < 2; ++k) \
;         acc[ai][bj][m][n] = __builtin_amdgcn_mfma_f32_16x16x32_bf16(Bt[n][k], At[m][k], acc[ai][bj][m][n], 0, 0, 0); __builtin_amdgcn_s_setprio(0); } while (0)
; #define PG8_WAIT_V(n) asm volatile("s_waitcnt vmcnt(" #n ")" ::: "memory")
; #define PG8_WAIT_L(n) asm volatile("s_waitcnt lgkmcnt(" #n ")" ::: "memory")
; #define PG8_BAR __builtin_amdgcn_s_barrier()
; #define PG8_SCHED __builtin_amdgcn_sched_barrier(0)
; template <class Epi, class Sched, bool ALIGN_EPI = false, bool SP2 = false>
; __device__ __forceinline__ void gemm_phase(PG8_LAS unsigned char* lds, const Gemm g, const Sched& S, const Epi& E) {
;     ...
;             PG8_LDA(At, 0, 1); PG8_STAGE(PG8_SB(0, 0), b2, voffB); PG8_STAGE(PG8_SB(0, 1), b2 + hstep, voffB); PG8_STAGE(PG8_SA(0, 0), a2, voffA);
;             PG8_WAIT_V(8); PG8_WAIT_L(0); PG8_BAR; PG8_MMA(1, 0, At, B0); PG8_MMA(1, 1, At, B1); PG8_BAR; PG8_SCHED;
;             PG8_LDB(B0, 1, 0); PG8_LDB(B1, 1, 1); PG8_SCHED; PG8_LDA(At, 1, 0); PG8_STAGE(PG8_SA(0, 1), a2 + hstep, voffA);
	s_add_i32 s70, s60, s52
	s_add_u32 s98, s38, s8
	s_addc_u32 s99, s39, s9
	s_add_u32 s100, s44, s8
	s_addc_u32 s101, s45, s9
	s_mov_b32 m0, s70
	ds_read_b128 v[186:189], v152 offset:16384
	ds_read_b128 v[190:193], v152 offset:17408
	ds_read_b128 v[198:201], v152 offset:18432
	ds_read_b128 v[202:205], v152 offset:19456
	ds_read_b128 v[206:209], v152 offset:20480
	ds_read_b128 v[210:213], v152 offset:21504
	ds_read_b128 v[214:217], v152 offset:22528
	ds_read_b128 v[218:221], v152 offset:23552
	global_load_lds_dwordx4 v132, s[38:39]
	s_add_i32 m0, s70, 0x2000
	s_add_u32 s70, s38, 0x40000
	s_addc_u32 s71, s39, 0
	s_add_i32 s72, s61, s52
	global_load_lds_dwordx4 v128, s[38:39]
	s_mov_b32 m0, s72
	s_nop 0
	global_load_lds_dwordx4 v132, s[70:71]
	s_add_i32 m0, s72, 0x2000
	s_nop 0
	global_load_lds_dwordx4 v128, s[70:71]
	s_mov_b32 m0, s35
	s_nop 0
	global_load_lds_dwordx4 v134, s[44:45]
	s_mov_b32 m0, s54
	s_nop 0
	global_load_lds_dwordx4 v130, s[44:45]
	s_waitcnt vmcnt(8)
	s_waitcnt lgkmcnt(0)
	s_barrier
	v_mfma_f32_16x16x32_bf16 v[60:63], v[154:157], v[186:189], v[60:63]
	v_mfma_f32_16x16x32_bf16 v[52:55], v[162:165], v[186:189], v[52:55]
	v_mfma_f32_16x16x32_bf16 v[44:47], v[154:157], v[198:201], v[44:47]
	v_mfma_f32_16x16x32_bf16 v[36:39], v[162:165], v[198:201], v[36:39]
	v_mfma_f32_16x16x32_bf16 v[28:31], v[154:157], v[206:209], v[28:31]
	v_mfma_f32_16x16x32_bf16 v[20:23], v[162:165], v[206:209], v[20:23]
	v_mfma_f32_16x16x32_bf16 v[12:15], v[154:157], v[214:217], v[12:15]
	v_mfma_f32_16x16x32_bf16 v[4:7], v[162:165], v[214:217], v[4:7]
	v_mfma_f32_16x16x32_bf16 v[60:63], v[158:161], v[190:193], v[60:63]
	v_mfma_f32_16x16x32_bf16 v[52:55], v[166:169], v[190:193], v[52:55]
	v_mfma_f32_16x16x32_bf16 v[44:47], v[158:161], v[202:205], v[44:47]
	v_mfma_f32_16x16x32_bf16 v[36:39], v[166:169], v[202:205], v[36:39]
	v_mfma_f32_16x16x32_bf16 v[28:31], v[158:161], v[210:213], v[28:31]
	v_mfma_f32_16x16x32_bf16 v[20:23], v[166:169], v[210:213], v[20:23]
	v_mfma_f32_16x16x32_bf16 v[12:15], v[158:161], v[218:221], v[12:15]
	v_mfma_f32_16x16x32_bf16 v[4:7], v[166:169], v[218:221], v[4:7]
	v_mfma_f32_16x16x32_bf16 v[56:59], v[170:173], v[186:189], v[56:59]
	v_mfma_f32_16x16x32_bf16 v[48:51], v[178:181], v[186:189], v[48:51]
	v_mfma_f32_16x16x32_bf16 v[40:43], v[170:173], v[198:201], v[40:43]
	v_mfma_f32_16x16x32_bf16 v[32:35], v[178:181], v[198:201], v[32:35]
	v_mfma_f32_16x16x32_bf16 v[24:27], v[170:173], v[206:209], v[24:27]
	v_mfma_f32_16x16x32_bf16 v[16:19], v[178:181], v[206:209], v[16:19]
	v_mfma_f32_16x16x32_bf16 v[8:11], v[170:173], v[214:217], v[8:11]
	v_mfma_f32_16x16x32_bf16 v[0:3], v[178:181], v[214:217], v[0:3]
	v_mfma_f32_16x16x32_bf16 v[56:59], v[174:177], v[190:193], v[56:59]
	v_mfma_f32_16x16x32_bf16 v[48:51], v[182:185], v[190:193], v[48:51]
	v_mfma_f32_16x16x32_bf16 v[40:43], v[174:177], v[202:205], v[40:43]
	v_mfma_f32_16x16x32_bf16 v[32:35], v[182:185], v[202:205], v[32:35]
	v_mfma_f32_16x16x32_bf16 v[24:27], v[174:177], v[210:213], v[24:27]
	v_mfma_f32_16x16x32_bf16 v[16:19], v[182:185], v[210:213], v[16:19]
	v_mfma_f32_16x16x32_bf16 v[8:11], v[174:177], v[218:221], v[8:11]
	v_mfma_f32_16x16x32_bf16 v[0:3], v[182:185], v[218:221], v[0:3]
	s_barrier
	s_add_i32 s70, 0, 0x18000
	v_add_u32_e32 v153, s70, v147
	s_add_i32 s71, 0, 0x1c000
	ds_read_b128 v[154:157], v153
	ds_read_b128 v[158:161], v153 offset:1024
	ds_read_b128 v[162:165], v153 offset:2048
	ds_read_b128 v[166:169], v153 offset:3072
	v_add_u32_e32 v153, s71, v147
	ds_read_b128 v[170:173], v153
	ds_read_b128 v[174:177], v153 offset:1024
	ds_read_b128 v[178:181], v153 offset:2048
	ds_read_b128 v[182:185], v153 offset:3072
	s_add_u32 s44, s44, 0x40000
	s_addc_u32 s45, s45, 0
	s_mov_b32 m0, s55
	ds_read_b128 v[186:189], v152 offset:32768
	ds_read_b128 v[190:193], v152 offset:33792
	ds_read_b128 v[198:201], v152 offset:34816
	ds_read_b128 v[202:205], v152 offset:35840
	ds_read_b128 v[206:209], v152 offset:36864
	ds_read_b128 v[210:213], v152 offset:37888
	ds_read_b128 v[214:217], v152 offset:38912
	ds_read_b128 v[218:221], v152 offset:39936
	global_load_lds_dwordx4 v134, s[44:45]
	s_mov_b32 m0, s56
	s_nop 0
	global_load_lds_dwordx4 v130, s[44:45]
	s_waitcnt vmcnt(8)
	s_waitcnt lgkmcnt(0)
	s_barrier
; #define PG8_STAGE(bufoff, gbase, voff) do { _Pragma("unroll") for (int _i = 0; _i < 2; ++_i) \
;         __builtin_amdgcn_global_load_lds((const unsigned*)((const char*)(gbase) + (voff)[_i]), (PG8_LAS unsigned*)(lds + (bufoff) + ldsw + _i * 8192), 16, 0, 0); } while (0)
; #define PG8_LDA(dst, b, h) do { _Pragma("unroll") for (int m = 0; m < 4; ++m) _Pragma("unroll") for (int k = 0; k < 2; ++k) dst[m][k] = *(const PG8_LAS bf16x8*)(lds + PG8_SA(b, h) + aoff + m * 2048 + k * 1024); } while (0)
; #define PG8_MMA(ai, bj, At, Bt) do { __builtin_amdgcn_s_setprio(1); _Pragma("unroll") for (int m = 0; m < 4; ++m) _Pragma("unroll") for (int n = 0; n < 2; ++n) _Pragma("unroll") for (int k = 0; k < 2; ++k) \
;         acc[ai][bj][m][n] = __builtin_amdgcn_mfma_f32_16x16x32_bf16(Bt[n][k], At[m][k], acc[ai][bj][m][n], 0, 0, 0); __builtin_amdgcn_s_setprio(0); } while (0)
; #define PG8_WAIT_V(n) asm volatile("s_waitcnt vmcnt(" #n ")" ::: "memory")
; #define PG8_WAIT_L(n) asm volatile("s_waitcnt lgkmcnt(" #n ")" ::: "memory")
; #define PG8_BAR __builtin_amdgcn_s_barrier()
; #define PG8_SCHED __builtin_amdgcn_sched_barrier(0)
; template <class Epi, class Sched, bool ALIGN_EPI = false, bool SP2 = false>
; __device__ __forceinline__ void gemm_phase(PG8_LAS unsigned char* lds, const Gemm g, const Sched& S, const Epi& E) {
;     ...
;             PG8_WAIT_V(8); PG8_WAIT_L(0); PG8_BAR; PG8_MMA(0, 0, At, B0); PG8_MMA(0, 1, At, B1); PG8_BAR; PG8_SCHED;
;             PG8_LDA(At, 1, 1); PG8_STAGE(PG8_SB(1, 0), b3, voffB); PG8_STAGE(PG8_SB(1, 1), b3 + hstep, voffB); PG8_STAGE(PG8_SA(1, 0), a3, voffA);
;             PG8_WAIT_V(8); PG8_WAIT_L(0); PG8_BAR; PG8_MMA(1, 0, At, B0); PG8_MMA(1, 1, At, B1); PG8_BAR; PG8_SCHED;
;     ...
;         if constexpr (ALIGN_EPI) { if (wr == 0) PG8_BAR; }
	v_mfma_f32_16x16x32_bf16 v[124:127], v[154:157], v[186:189], v[124:127]
	v_mfma_f32_16x16x32_bf16 v[116:119], v[162:165], v[186:189], v[116:119]
	v_mfma_f32_16x16x32_bf16 v[108:111], v[154:157], v[198:201], v[108:111]
	v_mfma_f32_16x16x32_bf16 v[100:103], v[162:165], v[198:201], v[100:103]
	v_mfma_f32_16x16x32_bf16 v[92:95], v[154:157], v[206:209], v[92:95]
	v_mfma_f32_16x16x32_bf16 v[84:87], v[162:165], v[206:209], v[84:87]
	v_mfma_f32_16x16x32_bf16 v[76:79], v[154:157], v[214:217], v[76:79]
	v_mfma_f32_16x16x32_bf16 v[68:71], v[162:165], v[214:217], v[68:71]
	v_mfma_f32_16x16x32_bf16 v[124:127], v[158:161], v[190:193], v[124:127]
	v_mfma_f32_16x16x32_bf16 v[116:119], v[166:169], v[190:193], v[116:119]
	v_mfma_f32_16x16x32_bf16 v[108:111], v[158:161], v[202:205], v[108:111]
	v_mfma_f32_16x16x32_bf16 v[100:103], v[166:169], v[202:205], v[100:103]
	v_mfma_f32_16x16x32_bf16 v[92:95], v[158:161], v[210:213], v[92:95]
	v_mfma_f32_16x16x32_bf16 v[84:87], v[166:169], v[210:213], v[84:87]
	v_mfma_f32_16x16x32_bf16 v[76:79], v[158:161], v[218:221], v[76:79]
	v_mfma_f32_16x16x32_bf16 v[68:71], v[166:169], v[218:221], v[68:71]
	v_mfma_f32_16x16x32_bf16 v[120:123], v[170:173], v[186:189], v[120:123]
	v_mfma_f32_16x16x32_bf16 v[112:115], v[178:181], v[186:189], v[112:115]
	v_mfma_f32_16x16x32_bf16 v[104:107], v[170:173], v[198:201], v[104:107]
	v_mfma_f32_16x16x32_bf16 v[96:99], v[178:181], v[198:201], v[96:99]
	v_mfma_f32_16x16x32_bf16 v[88:91], v[170:173], v[206:209], v[88:91]
	v_mfma_f32_16x16x32_bf16 v[80:83], v[178:181], v[206:209], v[80:83]
	v_mfma_f32_16x16x32_bf16 v[72:75], v[170:173], v[214:217], v[72:75]
	v_mfma_f32_16x16x32_bf16 v[64:67], v[178:181], v[214:217], v[64:67]
	v_mfma_f32_16x16x32_bf16 v[120:123], v[174:177], v[190:193], v[120:123]
	v_mfma_f32_16x16x32_bf16 v[112:115], v[182:185], v[190:193], v[112:115]
	v_mfma_f32_16x16x32_bf16 v[104:107], v[174:177], v[202:205], v[104:107]
	v_mfma_f32_16x16x32_bf16 v[96:99], v[182:185], v[202:205], v[96:99]
	v_mfma_f32_16x16x32_bf16 v[88:91], v[174:177], v[210:213], v[88:91]
	v_mfma_f32_16x16x32_bf16 v[80:83], v[182:185], v[210:213], v[80:83]
	v_mfma_f32_16x16x32_bf16 v[72:75], v[174:177], v[218:221], v[72:75]
	v_mfma_f32_16x16x32_bf16 v[64:67], v[182:185], v[218:221], v[64:67]
	s_barrier
	s_add_i32 s44, s70, s52
	s_mov_b32 m0, s44
	ds_read_b128 v[186:189], v152 offset:49152
	ds_read_b128 v[190:193], v152 offset:50176
	ds_read_b128 v[198:201], v152 offset:51200
	ds_read_b128 v[202:205], v152 offset:52224
	ds_read_b128 v[206:209], v152 offset:53248
	ds_read_b128 v[210:213], v152 offset:54272
	ds_read_b128 v[214:217], v152 offset:55296
	ds_read_b128 v[218:221], v152 offset:56320
	global_load_lds_dwordx4 v132, s[98:99]
	s_add_i32 m0, s44, 0x2000
	s_add_u32 s38, s38, 0x40080
	s_addc_u32 s39, s39, 0
	s_add_i32 s44, s71, s52
	global_load_lds_dwordx4 v128, s[98:99]
	s_mov_b32 m0, s44
	s_nop 0
	global_load_lds_dwordx4 v132, s[38:39]
	s_add_i32 m0, s44, 0x2000
	s_nop 0
	global_load_lds_dwordx4 v128, s[38:39]
	s_mov_b32 m0, s58
	s_nop 0
	global_load_lds_dwordx4 v134, s[100:101]
	s_mov_b32 m0, s59
	s_nop 0
	global_load_lds_dwordx4 v130, s[100:101]
	s_waitcnt vmcnt(8)
	s_waitcnt lgkmcnt(0)
	s_barrier
	v_mfma_f32_16x16x32_bf16 v[60:63], v[154:157], v[186:189], v[60:63]
	v_mfma_f32_16x16x32_bf16 v[52:55], v[162:165], v[186:189], v[52:55]
	v_mfma_f32_16x16x32_bf16 v[44:47], v[154:157], v[198:201], v[44:47]
	v_mfma_f32_16x16x32_bf16 v[36:39], v[162:165], v[198:201], v[36:39]
	v_mfma_f32_16x16x32_bf16 v[28:31], v[154:157], v[206:209], v[28:31]
	v_mfma_f32_16x16x32_bf16 v[20:23], v[162:165], v[206:209], v[20:23]
	v_mfma_f32_16x16x32_bf16 v[12:15], v[154:157], v[214:217], v[12:15]
	v_mfma_f32_16x16x32_bf16 v[4:7], v[162:165], v[214:217], v[4:7]
	v_mfma_f32_16x16x32_bf16 v[60:63], v[158:161], v[190:193], v[60:63]
	v_mfma_f32_16x16x32_bf16 v[52:55], v[166:169], v[190:193], v[52:55]
	v_mfma_f32_16x16x32_bf16 v[44:47], v[158:161], v[202:205], v[44:47]
	v_mfma_f32_16x16x32_bf16 v[36:39], v[166:169], v[202:205], v[36:39]
	v_mfma_f32_16x16x32_bf16 v[28:31], v[158:161], v[210:213], v[28:31]
	v_mfma_f32_16x16x32_bf16 v[20:23], v[166:169], v[210:213], v[20:23]
	v_mfma_f32_16x16x32_bf16 v[12:15], v[158:161], v[218:221], v[12:15]
	v_mfma_f32_16x16x32_bf16 v[4:7], v[166:169], v[218:221], v[4:7]
	v_mfma_f32_16x16x32_bf16 v[56:59], v[170:173], v[186:189], v[56:59]
	v_mfma_f32_16x16x32_bf16 v[48:51], v[178:181], v[186:189], v[48:51]
	v_mfma_f32_16x16x32_bf16 v[40:43], v[170:173], v[198:201], v[40:43]
	v_mfma_f32_16x16x32_bf16 v[32:35], v[178:181], v[198:201], v[32:35]
	v_mfma_f32_16x16x32_bf16 v[24:27], v[170:173], v[206:209], v[24:27]
	v_mfma_f32_16x16x32_bf16 v[16:19], v[178:181], v[206:209], v[16:19]
	v_mfma_f32_16x16x32_bf16 v[8:11], v[170:173], v[214:217], v[8:11]
	v_mfma_f32_16x16x32_bf16 v[0:3], v[178:181], v[214:217], v[0:3]
	v_mfma_f32_16x16x32_bf16 v[56:59], v[174:177], v[190:193], v[56:59]
	v_mfma_f32_16x16x32_bf16 v[48:51], v[182:185], v[190:193], v[48:51]
	v_mfma_f32_16x16x32_bf16 v[40:43], v[174:177], v[202:205], v[40:43]
	v_mfma_f32_16x16x32_bf16 v[32:35], v[182:185], v[202:205], v[32:35]
	v_mfma_f32_16x16x32_bf16 v[24:27], v[174:177], v[210:213], v[24:27]
	v_mfma_f32_16x16x32_bf16 v[16:19], v[182:185], v[210:213], v[16:19]
	v_mfma_f32_16x16x32_bf16 v[8:11], v[174:177], v[218:221], v[8:11]
	v_mfma_f32_16x16x32_bf16 v[0:3], v[182:185], v[218:221], v[0:3]
	s_barrier
	s_add_i32 s69, s69, 2
	s_add_u32 s20, s20, 0x100
	s_addc_u32 s21, s21, 0
	s_add_u32 s67, s67, 0x100
	s_addc_u32 s68, s68, 0
	s_cmp_gt_u32 s69, 13
	s_cbranch_scc0 .LBB0_810
	s_and_b64 vcc, exec, s[10:11]
	s_cbranch_vccz .LBB0_813
	s_barrier

; #define PG8_STAGE(bufoff, gbase, voff) do { _Pragma("unroll") for (int _i = 0; _i < 2; ++_i) \
;         __builtin_amdgcn_global_load_lds((const unsigned*)((const char*)(gbase) + (voff)[_i]), (PG8_LAS unsigned*)(lds + (bufoff) + ldsw + _i * 8192), 16, 0, 0); } while (0)
; #define PG8_LDA(dst, b, h) do { _Pragma("unroll") for (int m = 0; m < 4; ++m) _Pragma("unroll") for (int k = 0; k < 2; ++k) dst[m][k] = *(const PG8_LAS bf16x8*)(lds + PG8_SA(b, h) + aoff + m * 2048 + k * 1024); } while (0)
; #define PG8_LDB(dst, b, h) do { _Pragma("unroll") for (int n = 0; n < 2; ++n) _Pragma("unroll") for (int k = 0; k < 2; ++k) dst[n][k] = *(const PG8_LAS bf16x8*)(lds + PG8_SB(b, h) + boff + n * 2048 + k * 1024); } while (0)
; #define PG8_WAIT_V(n) asm volatile("s_waitcnt vmcnt(" #n ")" ::: "memory")
; #define PG8_WAIT_L(n) asm volatile("s_waitcnt lgkmcnt(" #n ")" ::: "memory")
; #define PG8_BAR __builtin_amdgcn_s_barrier()
; #define PG8_SCHED __builtin_amdgcn_sched_barrier(0)
; template <class Epi, class Sched, bool ALIGN_EPI = false, bool SP2 = false>
; __device__ __forceinline__ void gemm_phase(PG8_LAS unsigned char* lds, const Gemm g, const Sched& S, const Epi& E) {
;     ...
;         for (int t = 0; t < nt; t += 2) {
;             const bool last = (t == nt - 2);
;             const char* a1 = cA + (size_t)(t + 1) * kstep;
;             const char* a2 = last ? nA : cA + (size_t)(t + 2) * kstep; const char* b2 = last ? nB : cB + (size_t)(t + 2) * kstep;
;             const char* a3 = a2 + kstep; const char* b3 = b2 + kstep;
;             if (last && has_next) S.a_ready(nxt);
;             if constexpr (SP2) {
;             PG8_LDB(B0, 0, 0); PG8_LDB(B1, 0, 1); PG8_SCHED; PG8_LDA(At, 0, 0); PG8_STAGE(PG8_SA(1, 1), a1 + hstep, voffA);
;             PG8_WAIT_V(8); PG8_WAIT_L(0); PG8_BAR; PG8_MMA(0, 0, At, B0); PG8_MMA(0, 1, At, B1); PG8_BAR; PG8_SCHED;
;             PG8_LDA(At, 0, 1); PG8_STAGE(PG8_SB(0, 0), b2, voffB); PG8_STAGE(PG8_SB(0, 1), b2 + hstep, voffB); PG8_STAGE(PG8_SA(0, 0), a2, voffA);
;             PG8_WAIT_V(8); PG8_WAIT_L(0); PG8_BAR; PG8_MMA(1, 0, At, B0); PG8_MMA(1, 1, At, B1); PG8_BAR; PG8_SCHED;
;             PG8_LDB(B0, 1, 0); PG8_LDB(B1, 1, 1); PG8_SCHED; PG8_LDA(At, 1, 0); PG8_STAGE(PG8_SA(0, 1), a2 + hstep, voffA);
;             PG8_WAIT_V(8); PG8_WAIT_L(0); PG8_BAR; PG8_MMA(0, 0, At, B0); PG8_MMA(0, 1, At, B1); PG8_BAR; PG8_SCHED;
.LBB0_894:
	s_add_u32 s20, s20, 0xb0080
	s_addc_u32 s21, s21, 0
	s_add_u32 s70, s34, 0x100
	s_addc_u32 s71, s35, 0
	s_mov_b32 s72, -2
	s_waitcnt lgkmcnt(0)
	ds_read_b128 v[96:99], v223
	ds_read_b128 v[108:111], v223 offset:1024
	ds_read_b128 v[120:123], v223 offset:2048
	ds_read_b128 v[128:131], v223 offset:3072
	ds_read_b128 v[144:147], v224
	ds_read_b128 v[148:151], v224 offset:1024
	ds_read_b128 v[152:155], v224 offset:2048
	ds_read_b128 v[156:159], v224 offset:3072
	s_add_u32 s34, s20, 0xfff50080
	s_addc_u32 s35, s21, -1
	s_cmp_eq_u32 s72, 40
	s_cselect_b32 s49, s1, s35
	s_cselect_b32 s48, s0, s34
	s_cselect_b32 s35, s47, s71
	s_cselect_b32 s34, s46, s70
	s_add_i32 m0, s51, 0xc000
	ds_read_b128 v[160:163], v225
	ds_read_b128 v[164:167], v225 offset:1024
	ds_read_b128 v[168:171], v225 offset:2048
	ds_read_b128 v[172:175], v225 offset:3072
	ds_read_b128 v[176:179], v225 offset:4096
	ds_read_b128 v[180:183], v225 offset:5120
	ds_read_b128 v[202:205], v225 offset:6144
	ds_read_b128 v[206:209], v225 offset:7168
	global_load_lds_dwordx4 v192, s[20:21]
	s_add_i32 m0, s51, 0xe000
	s_nop 0
	global_load_lds_dwordx4 v194, s[20:21]
	s_waitcnt vmcnt(8)
	s_waitcnt lgkmcnt(0)
	s_barrier
	v_mfma_f32_16x16x32_bf16 v[140:143], v[96:99], v[160:163], 0
	v_mfma_f32_16x16x32_bf16 v[136:139], v[120:123], v[160:163], 0
	v_mfma_f32_16x16x32_bf16 v[116:119], v[96:99], v[168:171], 0
	v_mfma_f32_16x16x32_bf16 v[112:115], v[120:123], v[168:171], 0
	v_mfma_f32_16x16x32_bf16 v[92:95], v[96:99], v[176:179], 0
	v_mfma_f32_16x16x32_bf16 v[88:91], v[120:123], v[176:179], 0
	v_mfma_f32_16x16x32_bf16 v[76:79], v[96:99], v[202:205], 0
	v_mfma_f32_16x16x32_bf16 v[72:75], v[120:123], v[202:205], 0
	v_mfma_f32_16x16x32_bf16 v[140:143], v[108:111], v[164:167], v[140:143]
	v_mfma_f32_16x16x32_bf16 v[136:139], v[128:131], v[164:167], v[136:139]
	v_mfma_f32_16x16x32_bf16 v[116:119], v[108:111], v[172:175], v[116:119]
	v_mfma_f32_16x16x32_bf16 v[112:115], v[128:131], v[172:175], v[112:115]
	v_mfma_f32_16x16x32_bf16 v[92:95], v[108:111], v[180:183], v[92:95]
	v_mfma_f32_16x16x32_bf16 v[88:91], v[128:131], v[180:183], v[88:91]
	v_mfma_f32_16x16x32_bf16 v[76:79], v[108:111], v[206:209], v[76:79]
	v_mfma_f32_16x16x32_bf16 v[72:75], v[128:131], v[206:209], v[72:75]
	v_mfma_f32_16x16x32_bf16 v[132:135], v[144:147], v[160:163], 0
	v_mfma_f32_16x16x32_bf16 v[124:127], v[152:155], v[160:163], 0
	v_mfma_f32_16x16x32_bf16 v[104:107], v[144:147], v[168:171], 0
	v_mfma_f32_16x16x32_bf16 v[100:103], v[152:155], v[168:171], 0
	v_mfma_f32_16x16x32_bf16 v[84:87], v[144:147], v[176:179], 0
	v_mfma_f32_16x16x32_bf16 v[80:83], v[152:155], v[176:179], 0
	v_mfma_f32_16x16x32_bf16 v[68:71], v[144:147], v[202:205], 0
	v_mfma_f32_16x16x32_bf16 v[64:67], v[152:155], v[202:205], 0
	v_mfma_f32_16x16x32_bf16 v[132:135], v[148:151], v[164:167], v[132:135]
	v_mfma_f32_16x16x32_bf16 v[124:127], v[156:159], v[164:167], v[124:127]
	v_mfma_f32_16x16x32_bf16 v[104:107], v[148:151], v[172:175], v[104:107]
	v_mfma_f32_16x16x32_bf16 v[100:103], v[156:159], v[172:175], v[100:103]
	v_mfma_f32_16x16x32_bf16 v[84:87], v[148:151], v[180:183], v[84:87]
	v_mfma_f32_16x16x32_bf16 v[80:83], v[156:159], v[180:183], v[80:83]
	v_mfma_f32_16x16x32_bf16 v[68:71], v[148:151], v[206:209], v[68:71]
	v_mfma_f32_16x16x32_bf16 v[64:67], v[156:159], v[206:209], v[64:67]
	s_barrier
	s_add_i32 s73, s64, s50
	s_add_u32 s98, s34, s12
	s_addc_u32 s99, s35, s13
	s_add_u32 s100, s48, s12
	s_addc_u32 s101, s49, s13
	s_mov_b32 m0, s73
	ds_read_b128 v[160:163], v225 offset:16384
	ds_read_b128 v[164:167], v225 offset:17408
	ds_read_b128 v[168:171], v225 offset:18432
	ds_read_b128 v[172:175], v225 offset:19456
	ds_read_b128 v[176:179], v225 offset:20480
	ds_read_b128 v[180:183], v225 offset:21504
	ds_read_b128 v[202:205], v225 offset:22528
	ds_read_b128 v[206:209], v225 offset:23552
	global_load_lds_dwordx4 v186, s[34:35]
	s_add_i32 m0, s73, 0x2000
	s_add_u32 s74, s34, 0xb0000
	s_addc_u32 s75, s35, 0
	s_add_i32 s73, s65, s50
	global_load_lds_dwordx4 v190, s[34:35]
	s_mov_b32 m0, s73
	s_nop 0
	global_load_lds_dwordx4 v186, s[74:75]
	s_add_i32 m0, s73, 0x2000
	s_nop 0
	global_load_lds_dwordx4 v190, s[74:75]
	s_mov_b32 m0, s51
	s_nop 0
	global_load_lds_dwordx4 v184, s[48:49]
	s_mov_b32 m0, s52
	s_nop 0
	global_load_lds_dwordx4 v188, s[48:49]
	s_waitcnt vmcnt(8)
	s_waitcnt lgkmcnt(0)
	s_barrier
	v_mfma_f32_16x16x32_bf16 v[60:63], v[96:99], v[160:163], 0
	v_mfma_f32_16x16x32_bf16 v[56:59], v[120:123], v[160:163], 0
	v_mfma_f32_16x16x32_bf16 v[44:47], v[96:99], v[168:171], 0
	v_mfma_f32_16x16x32_bf16 v[40:43], v[120:123], v[168:171], 0
	v_mfma_f32_16x16x32_bf16 v[28:31], v[96:99], v[176:179], 0
	v_mfma_f32_16x16x32_bf16 v[24:27], v[120:123], v[176:179], 0
	v_mfma_f32_16x16x32_bf16 v[12:15], v[96:99], v[202:205], 0
	v_mfma_f32_16x16x32_bf16 v[8:11], v[120:123], v[202:205], 0
	v_mfma_f32_16x16x32_bf16 v[60:63], v[108:111], v[164:167], v[60:63]
	v_mfma_f32_16x16x32_bf16 v[56:59], v[128:131], v[164:167], v[56:59]
	v_mfma_f32_16x16x32_bf16 v[44:47], v[108:111], v[172:175], v[44:47]
	v_mfma_f32_16x16x32_bf16 v[40:43], v[128:131], v[172:175], v[40:43]
	v_mfma_f32_16x16x32_bf16 v[28:31], v[108:111], v[180:183], v[28:31]
	v_mfma_f32_16x16x32_bf16 v[24:27], v[128:131], v[180:183], v[24:27]
	v_mfma_f32_16x16x32_bf16 v[12:15], v[108:111], v[206:209], v[12:15]
	v_mfma_f32_16x16x32_bf16 v[8:11], v[128:131], v[206:209], v[8:11]
	v_mfma_f32_16x16x32_bf16 v[52:55], v[144:147], v[160:163], 0
	v_mfma_f32_16x16x32_bf16 v[48:51], v[152:155], v[160:163], 0
	v_mfma_f32_16x16x32_bf16 v[36:39], v[144:147], v[168:171], 0
	v_mfma_f32_16x16x32_bf16 v[32:35], v[152:155], v[168:171], 0
	v_mfma_f32_16x16x32_bf16 v[20:23], v[144:147], v[176:179], 0
	v_mfma_f32_16x16x32_bf16 v[16:19], v[152:155], v[176:179], 0
	v_mfma_f32_16x16x32_bf16 v[4:7], v[144:147], v[202:205], 0
	v_mfma_f32_16x16x32_bf16 v[0:3], v[152:155], v[202:205], 0
	v_mfma_f32_16x16x32_bf16 v[52:55], v[148:151], v[164:167], v[52:55]
	v_mfma_f32_16x16x32_bf16 v[48:51], v[156:159], v[164:167], v[48:51]
	v_mfma_f32_16x16x32_bf16 v[36:39], v[148:151], v[172:175], v[36:39]
	v_mfma_f32_16x16x32_bf16 v[32:35], v[156:159], v[172:175], v[32:35]
	v_mfma_f32_16x16x32_bf16 v[20:23], v[148:151], v[180:183], v[20:23]
	v_mfma_f32_16x16x32_bf16 v[16:19], v[156:159], v[180:183], v[16:19]
	v_mfma_f32_16x16x32_bf16 v[4:7], v[148:151], v[206:209], v[4:7]
	v_mfma_f32_16x16x32_bf16 v[0:3], v[156:159], v[206:209], v[0:3]
	s_barrier
; #define PG8_STAGE(bufoff, gbase, voff) do { _Pragma("unroll") for (int _i = 0; _i < 2; ++_i) \
;         __builtin_amdgcn_global_load_lds((const unsigned*)((const char*)(gbase) + (voff)[_i]), (PG8_LAS unsigned*)(lds + (bufoff) + ldsw + _i * 8192), 16, 0, 0); } while (0)
; #define PG8_LDA(dst, b, h) do { _Pragma("unroll") for (int m = 0; m < 4; ++m) _Pragma("unroll") for (int k = 0; k < 2; ++k) dst[m][k] = *(const PG8_LAS bf16x8*)(lds + PG8_SA(b, h) + aoff + m * 2048 + k * 1024); } while (0)
; #define PG8_LDB(dst, b, h) do { _Pragma("unroll") for (int n = 0; n < 2; ++n) _Pragma("unroll") for (int k = 0; k < 2; ++k) dst[n][k] = *(const PG8_LAS bf16x8*)(lds + PG8_SB(b, h) + boff + n * 2048 + k * 1024); } while (0)
; #define PG8_MMA(ai, bj, At, Bt) do { __builtin_amdgcn_s_setprio(1); _Pragma("unroll") for (int m = 0; m < 4; ++m) _Pragma("unroll") for (int n = 0; n < 2; ++n) _Pragma("unroll") for (int k = 0; k < 2; ++k) \
;         acc[ai][bj][m][n] = __builtin_amdgcn_mfma_f32_16x16x32_bf16(Bt[n][k], At[m][k], acc[ai][bj][m][n], 0, 0, 0); __builtin_amdgcn_s_setprio(0); } while (0)
; #define PG8_WAIT_V(n) asm volatile("s_waitcnt vmcnt(" #n ")" ::: "memory")
; #define PG8_WAIT_L(n) asm volatile("s_waitcnt lgkmcnt(" #n ")" ::: "memory")
; #define PG8_BAR __builtin_amdgcn_s_barrier()
; #define PG8_SCHED __builtin_amdgcn_sched_barrier(0)
; template <class Epi, class Sched, bool ALIGN_EPI = false, bool SP2 = false>
; __device__ __forceinline__ void gemm_phase(PG8_LAS unsigned char* lds, const Gemm g, const Sched& S, const Epi& E) {
;     ...
;             PG8_LDB(B0, 1, 0); PG8_LDB(B1, 1, 1); PG8_SCHED; PG8_LDA(At, 1, 0); PG8_STAGE(PG8_SA(0, 1), a2 + hstep, voffA);
;             PG8_WAIT_V(8); PG8_WAIT_L(0); PG8_BAR; PG8_MMA(0, 0, At, B0); PG8_MMA(0, 1, At, B1); PG8_BAR; PG8_SCHED;
;             PG8_LDA(At, 1, 1); PG8_STAGE(PG8_SB(1, 0), b3, voffB); PG8_STAGE(PG8_SB(1, 1), b3 + hstep, voffB); PG8_STAGE(PG8_SA(1, 0), a3, voffA);
;             PG8_WAIT_V(8); PG8_WAIT_L(0); PG8_BAR; PG8_MMA(1, 0, At, B0); PG8_MMA(1, 1, At, B1); PG8_BAR; PG8_SCHED;
	s_add_i32 s73, 0, 0x18000
	s_add_i32 s74, 0, 0x1c000
	v_add_u32_e32 v128, s73, v221
	v_add_u32_e32 v156, s74, v221
	ds_read_b128 v[96:99], v128
	ds_read_b128 v[108:111], v128 offset:1024
	ds_read_b128 v[120:123], v128 offset:2048
	ds_read_b128 v[128:131], v128 offset:3072
	ds_read_b128 v[144:147], v156
	ds_read_b128 v[148:151], v156 offset:1024
	ds_read_b128 v[152:155], v156 offset:2048
	ds_read_b128 v[156:159], v156 offset:3072
	s_add_u32 s48, s48, 0xb0000
	s_addc_u32 s49, s49, 0
	s_mov_b32 m0, s53
	ds_read_b128 v[160:163], v225 offset:32768
	ds_read_b128 v[164:167], v225 offset:33792
	ds_read_b128 v[168:171], v225 offset:34816
	ds_read_b128 v[172:175], v225 offset:35840
	ds_read_b128 v[176:179], v225 offset:36864
	ds_read_b128 v[180:183], v225 offset:37888
	ds_read_b128 v[202:205], v225 offset:38912
	ds_read_b128 v[206:209], v225 offset:39936
	global_load_lds_dwordx4 v184, s[48:49]
	s_mov_b32 m0, s54
	s_nop 0
	global_load_lds_dwordx4 v188, s[48:49]
	s_waitcnt vmcnt(8)
	s_waitcnt lgkmcnt(0)
	s_barrier
	v_mfma_f32_16x16x32_bf16 v[140:143], v[96:99], v[160:163], v[140:143]
	v_mfma_f32_16x16x32_bf16 v[136:139], v[120:123], v[160:163], v[136:139]
	v_mfma_f32_16x16x32_bf16 v[116:119], v[96:99], v[168:171], v[116:119]
	v_mfma_f32_16x16x32_bf16 v[112:115], v[120:123], v[168:171], v[112:115]
	v_mfma_f32_16x16x32_bf16 v[92:95], v[96:99], v[176:179], v[92:95]
	v_mfma_f32_16x16x32_bf16 v[88:91], v[120:123], v[176:179], v[88:91]
	v_mfma_f32_16x16x32_bf16 v[76:79], v[96:99], v[202:205], v[76:79]
	v_mfma_f32_16x16x32_bf16 v[72:75], v[120:123], v[202:205], v[72:75]
	v_mfma_f32_16x16x32_bf16 v[140:143], v[108:111], v[164:167], v[140:143]
	v_mfma_f32_16x16x32_bf16 v[136:139], v[128:131], v[164:167], v[136:139]
	v_mfma_f32_16x16x32_bf16 v[116:119], v[108:111], v[172:175], v[116:119]
	v_mfma_f32_16x16x32_bf16 v[112:115], v[128:131], v[172:175], v[112:115]
	v_mfma_f32_16x16x32_bf16 v[92:95], v[108:111], v[180:183], v[92:95]
	v_mfma_f32_16x16x32_bf16 v[88:91], v[128:131], v[180:183], v[88:91]
	v_mfma_f32_16x16x32_bf16 v[76:79], v[108:111], v[206:209], v[76:79]
	v_mfma_f32_16x16x32_bf16 v[72:75], v[128:131], v[206:209], v[72:75]
	v_mfma_f32_16x16x32_bf16 v[132:135], v[144:147], v[160:163], v[132:135]
	v_mfma_f32_16x16x32_bf16 v[124:127], v[152:155], v[160:163], v[124:127]
	v_mfma_f32_16x16x32_bf16 v[104:107], v[144:147], v[168:171], v[104:107]
	v_mfma_f32_16x16x32_bf16 v[100:103], v[152:155], v[168:171], v[100:103]
	v_mfma_f32_16x16x32_bf16 v[84:87], v[144:147], v[176:179], v[84:87]
	v_mfma_f32_16x16x32_bf16 v[80:83], v[152:155], v[176:179], v[80:83]
	v_mfma_f32_16x16x32_bf16 v[68:71], v[144:147], v[202:205], v[68:71]
	v_mfma_f32_16x16x32_bf16 v[64:67], v[152:155], v[202:205], v[64:67]
	v_mfma_f32_16x16x32_bf16 v[132:135], v[148:151], v[164:167], v[132:135]
	v_mfma_f32_16x16x32_bf16 v[124:127], v[156:159], v[164:167], v[124:127]
	v_mfma_f32_16x16x32_bf16 v[104:107], v[148:151], v[172:175], v[104:107]
	v_mfma_f32_16x16x32_bf16 v[100:103], v[156:159], v[172:175], v[100:103]
	v_mfma_f32_16x16x32_bf16 v[84:87], v[148:151], v[180:183], v[84:87]
	v_mfma_f32_16x16x32_bf16 v[80:83], v[156:159], v[180:183], v[80:83]
	v_mfma_f32_16x16x32_bf16 v[68:71], v[148:151], v[206:209], v[68:71]
	v_mfma_f32_16x16x32_bf16 v[64:67], v[156:159], v[206:209], v[64:67]
	s_barrier
	s_add_i32 s48, s73, s50
	s_mov_b32 m0, s48
	ds_read_b128 v[160:163], v225 offset:49152
	ds_read_b128 v[164:167], v225 offset:50176
	ds_read_b128 v[168:171], v225 offset:51200
	ds_read_b128 v[172:175], v225 offset:52224
	ds_read_b128 v[176:179], v225 offset:53248
	ds_read_b128 v[180:183], v225 offset:54272
	ds_read_b128 v[202:205], v225 offset:55296
	ds_read_b128 v[206:209], v225 offset:56320
	global_load_lds_dwordx4 v186, s[98:99]
	s_add_i32 m0, s48, 0x2000
	s_add_u32 s34, s34, 0xb0080
	s_addc_u32 s35, s35, 0
	s_add_i32 s48, s74, s50
	global_load_lds_dwordx4 v190, s[98:99]
	s_mov_b32 m0, s48
	s_nop 0
	global_load_lds_dwordx4 v186, s[34:35]
	s_add_i32 m0, s48, 0x2000
	s_nop 0
	global_load_lds_dwordx4 v190, s[34:35]
	s_mov_b32 m0, s59
	s_nop 0
	global_load_lds_dwordx4 v184, s[100:101]
	s_mov_b32 m0, s60
	s_nop 0
	global_load_lds_dwordx4 v188, s[100:101]
	s_waitcnt vmcnt(8)
	s_waitcnt lgkmcnt(0)
	s_barrier
	v_mfma_f32_16x16x32_bf16 v[60:63], v[96:99], v[160:163], v[60:63]
	v_mfma_f32_16x16x32_bf16 v[56:59], v[120:123], v[160:163], v[56:59]
	v_mfma_f32_16x16x32_bf16 v[44:47], v[96:99], v[168:171], v[44:47]
	v_mfma_f32_16x16x32_bf16 v[40:43], v[120:123], v[168:171], v[40:43]
	v_mfma_f32_16x16x32_bf16 v[28:31], v[96:99], v[176:179], v[28:31]
	v_mfma_f32_16x16x32_bf16 v[24:27], v[120:123], v[176:179], v[24:27]
	v_mfma_f32_16x16x32_bf16 v[12:15], v[96:99], v[202:205], v[12:15]
	v_mfma_f32_16x16x32_bf16 v[8:11], v[120:123], v[202:205], v[8:11]
	v_mfma_f32_16x16x32_bf16 v[60:63], v[108:111], v[164:167], v[60:63]
	v_mfma_f32_16x16x32_bf16 v[56:59], v[128:131], v[164:167], v[56:59]
	v_mfma_f32_16x16x32_bf16 v[44:47], v[108:111], v[172:175], v[44:47]
	v_mfma_f32_16x16x32_bf16 v[40:43], v[128:131], v[172:175], v[40:43]
	v_mfma_f32_16x16x32_bf16 v[28:31], v[108:111], v[180:183], v[28:31]
	v_mfma_f32_16x16x32_bf16 v[24:27], v[128:131], v[180:183], v[24:27]
	v_mfma_f32_16x16x32_bf16 v[12:15], v[108:111], v[206:209], v[12:15]
	v_mfma_f32_16x16x32_bf16 v[8:11], v[128:131], v[206:209], v[8:11]
	v_mfma_f32_16x16x32_bf16 v[52:55], v[144:147], v[160:163], v[52:55]
	v_mfma_f32_16x16x32_bf16 v[48:51], v[152:155], v[160:163], v[48:51]
	v_mfma_f32_16x16x32_bf16 v[36:39], v[144:147], v[168:171], v[36:39]
	v_mfma_f32_16x16x32_bf16 v[32:35], v[152:155], v[168:171], v[32:35]
	v_mfma_f32_16x16x32_bf16 v[20:23], v[144:147], v[176:179], v[20:23]
	v_mfma_f32_16x16x32_bf16 v[16:19], v[152:155], v[176:179], v[16:19]
	v_mfma_f32_16x16x32_bf16 v[4:7], v[144:147], v[202:205], v[4:7]
	v_mfma_f32_16x16x32_bf16 v[0:3], v[152:155], v[202:205], v[0:3]
	v_mfma_f32_16x16x32_bf16 v[52:55], v[148:151], v[164:167], v[52:55]
	v_mfma_f32_16x16x32_bf16 v[48:51], v[156:159], v[164:167], v[48:51]
	v_mfma_f32_16x16x32_bf16 v[36:39], v[148:151], v[172:175], v[36:39]
	v_mfma_f32_16x16x32_bf16 v[32:35], v[156:159], v[172:175], v[32:35]
	v_mfma_f32_16x16x32_bf16 v[20:23], v[148:151], v[180:183], v[20:23]
	v_mfma_f32_16x16x32_bf16 v[16:19], v[156:159], v[180:183], v[16:19]
	v_mfma_f32_16x16x32_bf16 v[4:7], v[148:151], v[206:209], v[4:7]
	v_mfma_f32_16x16x32_bf16 v[0:3], v[156:159], v[206:209], v[0:3]
	s_barrier
	s_add_i32 s72, s72, 2
	s_add_u32 s20, s20, 0x100
	s_addc_u32 s21, s21, 0
	s_add_u32 s70, s70, 0x100
	s_addc_u32 s71, s71, 0
	s_cmp_gt_u32 s72, 41
; #define PG8_STAGE(bufoff, gbase, voff) do { _Pragma("unroll") for (int _i = 0; _i < 2; ++_i) \
;         __builtin_amdgcn_global_load_lds((const unsigned*)((const char*)(gbase) + (voff)[_i]), (PG8_LAS unsigned*)(lds + (bufoff) + ldsw + _i * 8192), 16, 0, 0); } while (0)
; #define PG8_LDA(dst, b, h) do { _Pragma("unroll") for (int m = 0; m < 4; ++m) _Pragma("unroll") for (int k = 0; k < 2; ++k) dst[m][k] = *(const PG8_LAS bf16x8*)(lds + PG8_SA(b, h) + aoff + m * 2048 + k * 1024); } while (0)
; #define PG8_LDB(dst, b, h) do { _Pragma("unroll") for (int n = 0; n < 2; ++n) _Pragma("unroll") for (int k = 0; k < 2; ++k) dst[n][k] = *(const PG8_LAS bf16x8*)(lds + PG8_SB(b, h) + boff + n * 2048 + k * 1024); } while (0)
; #define PG8_MMA(ai, bj, At, Bt) do { __builtin_amdgcn_s_setprio(1); _Pragma("unroll") for (int m = 0; m < 4; ++m) _Pragma("unroll") for (int n = 0; n < 2; ++n) _Pragma("unroll") for (int k = 0; k < 2; ++k) \
;         acc[ai][bj][m][n] = __builtin_amdgcn_mfma_f32_16x16x32_bf16(Bt[n][k], At[m][k], acc[ai][bj][m][n], 0, 0, 0); __builtin_amdgcn_s_setprio(0); } while (0)
; #define PG8_WAIT_V(n) asm volatile("s_waitcnt vmcnt(" #n ")" ::: "memory")
; #define PG8_WAIT_L(n) asm volatile("s_waitcnt lgkmcnt(" #n ")" ::: "memory")
; #define PG8_BAR __builtin_amdgcn_s_barrier()
; #define PG8_SCHED __builtin_amdgcn_sched_barrier(0)
; template <class Epi, class Sched, bool ALIGN_EPI = false, bool SP2 = false>
; __device__ __forceinline__ void gemm_phase(PG8_LAS unsigned char* lds, const Gemm g, const Sched& S, const Epi& E) {
;     ...
;             PG8_LDB(B0, 0, 0); PG8_LDB(B1, 0, 1); PG8_SCHED; PG8_LDA(At, 0, 0); PG8_STAGE(PG8_SA(1, 1), a1 + hstep, voffA);
;             PG8_WAIT_V(8); PG8_WAIT_L(0); PG8_BAR; PG8_MMA(0, 0, At, B0); PG8_MMA(0, 1, At, B1); PG8_BAR; PG8_SCHED;
;             PG8_LDA(At, 0, 1); PG8_STAGE(PG8_SB(0, 0), b2, voffB); PG8_STAGE(PG8_SB(0, 1), b2 + hstep, voffB); PG8_STAGE(PG8_SA(0, 0), a2, voffA);
;             PG8_WAIT_V(8); PG8_WAIT_L(0); PG8_BAR; PG8_MMA(1, 0, At, B0); PG8_MMA(1, 1, At, B1); PG8_BAR; PG8_SCHED;
.LBB0_895:
	ds_read_b128 v[96:99], v223
	ds_read_b128 v[108:111], v223 offset:1024
	ds_read_b128 v[120:123], v223 offset:2048
	ds_read_b128 v[128:131], v223 offset:3072
	ds_read_b128 v[144:147], v224
	ds_read_b128 v[148:151], v224 offset:1024
	ds_read_b128 v[152:155], v224 offset:2048
	ds_read_b128 v[156:159], v224 offset:3072
	s_add_u32 s34, s20, 0xfff50080
	s_addc_u32 s35, s21, -1
	s_cmp_eq_u32 s72, 40
	s_cselect_b32 s49, s1, s35
	s_cselect_b32 s48, s0, s34
	s_cselect_b32 s35, s47, s71
	s_cselect_b32 s34, s46, s70
	s_add_i32 m0, s51, 0xc000
	ds_read_b128 v[160:163], v225
	ds_read_b128 v[164:167], v225 offset:1024
	ds_read_b128 v[168:171], v225 offset:2048
	ds_read_b128 v[172:175], v225 offset:3072
	ds_read_b128 v[176:179], v225 offset:4096
	ds_read_b128 v[180:183], v225 offset:5120
	ds_read_b128 v[202:205], v225 offset:6144
	ds_read_b128 v[206:209], v225 offset:7168
	global_load_lds_dwordx4 v192, s[20:21]
	s_add_i32 m0, s51, 0xe000
	s_nop 0
	global_load_lds_dwordx4 v194, s[20:21]
	s_waitcnt vmcnt(8)
	s_waitcnt lgkmcnt(0)
	s_barrier
	v_mfma_f32_16x16x32_bf16 v[140:143], v[96:99], v[160:163], v[140:143]
	v_mfma_f32_16x16x32_bf16 v[136:139], v[120:123], v[160:163], v[136:139]
	v_mfma_f32_16x16x32_bf16 v[116:119], v[96:99], v[168:171], v[116:119]
	v_mfma_f32_16x16x32_bf16 v[112:115], v[120:123], v[168:171], v[112:115]
	v_mfma_f32_16x16x32_bf16 v[92:95], v[96:99], v[176:179], v[92:95]
	v_mfma_f32_16x16x32_bf16 v[88:91], v[120:123], v[176:179], v[88:91]
	v_mfma_f32_16x16x32_bf16 v[76:79], v[96:99], v[202:205], v[76:79]
	v_mfma_f32_16x16x32_bf16 v[72:75], v[120:123], v[202:205], v[72:75]
	v_mfma_f32_16x16x32_bf16 v[140:143], v[108:111], v[164:167], v[140:143]
	v_mfma_f32_16x16x32_bf16 v[136:139], v[128:131], v[164:167], v[136:139]
	v_mfma_f32_16x16x32_bf16 v[116:119], v[108:111], v[172:175], v[116:119]
	v_mfma_f32_16x16x32_bf16 v[112:115], v[128:131], v[172:175], v[112:115]
	v_mfma_f32_16x16x32_bf16 v[92:95], v[108:111], v[180:183], v[92:95]
	v_mfma_f32_16x16x32_bf16 v[88:91], v[128:131], v[180:183], v[88:91]
	v_mfma_f32_16x16x32_bf16 v[76:79], v[108:111], v[206:209], v[76:79]
	v_mfma_f32_16x16x32_bf16 v[72:75], v[128:131], v[206:209], v[72:75]
	v_mfma_f32_16x16x32_bf16 v[132:135], v[144:147], v[160:163], v[132:135]
	v_mfma_f32_16x16x32_bf16 v[124:127], v[152:155], v[160:163], v[124:127]
	v_mfma_f32_16x16x32_bf16 v[104:107], v[144:147], v[168:171], v[104:107]
	v_mfma_f32_16x16x32_bf16 v[100:103], v[152:155], v[168:171], v[100:103]
	v_mfma_f32_16x16x32_bf16 v[84:87], v[144:147], v[176:179], v[84:87]
	v_mfma_f32_16x16x32_bf16 v[80:83], v[152:155], v[176:179], v[80:83]
	v_mfma_f32_16x16x32_bf16 v[68:71], v[144:147], v[202:205], v[68:71]
	v_mfma_f32_16x16x32_bf16 v[64:67], v[152:155], v[202:205], v[64:67]
	v_mfma_f32_16x16x32_bf16 v[132:135], v[148:151], v[164:167], v[132:135]
	v_mfma_f32_16x16x32_bf16 v[124:127], v[156:159], v[164:167], v[124:127]
	v_mfma_f32_16x16x32_bf16 v[104:107], v[148:151], v[172:175], v[104:107]
	v_mfma_f32_16x16x32_bf16 v[100:103], v[156:159], v[172:175], v[100:103]
	v_mfma_f32_16x16x32_bf16 v[84:87], v[148:151], v[180:183], v[84:87]
	v_mfma_f32_16x16x32_bf16 v[80:83], v[156:159], v[180:183], v[80:83]
	v_mfma_f32_16x16x32_bf16 v[68:71], v[148:151], v[206:209], v[68:71]
	v_mfma_f32_16x16x32_bf16 v[64:67], v[156:159], v[206:209], v[64:67]
	s_barrier
	s_add_i32 s73, s64, s50
	s_add_u32 s98, s34, s12
	s_addc_u32 s99, s35, s13
	s_add_u32 s100, s48, s12
	s_addc_u32 s101, s49, s13
	s_mov_b32 m0, s73
	ds_read_b128 v[160:163], v225 offset:16384
	ds_read_b128 v[164:167], v225 offset:17408
	ds_read_b128 v[168:171], v225 offset:18432
	ds_read_b128 v[172:175], v225 offset:19456
	ds_read_b128 v[176:179], v225 offset:20480
	ds_read_b128 v[180:183], v225 offset:21504
	ds_read_b128 v[202:205], v225 offset:22528
	ds_read_b128 v[206:209], v225 offset:23552
	global_load_lds_dwordx4 v186, s[34:35]
	s_add_i32 m0, s73, 0x2000
	s_add_u32 s74, s34, 0xb0000
	s_addc_u32 s75, s35, 0
	s_add_i32 s73, s65, s50
	global_load_lds_dwordx4 v190, s[34:35]
	s_mov_b32 m0, s73
	s_nop 0
	global_load_lds_dwordx4 v186, s[74:75]
	s_add_i32 m0, s73, 0x2000
	s_nop 0
	global_load_lds_dwordx4 v190, s[74:75]
	s_mov_b32 m0, s51
	s_nop 0
	global_load_lds_dwordx4 v184, s[48:49]
	s_mov_b32 m0, s52
	s_nop 0
	global_load_lds_dwordx4 v188, s[48:49]
	s_waitcnt vmcnt(8)
	s_waitcnt lgkmcnt(0)
	s_barrier
	v_mfma_f32_16x16x32_bf16 v[60:63], v[96:99], v[160:163], v[60:63]
	v_mfma_f32_16x16x32_bf16 v[56:59], v[120:123], v[160:163], v[56:59]
	v_mfma_f32_16x16x32_bf16 v[44:47], v[96:99], v[168:171], v[44:47]
	v_mfma_f32_16x16x32_bf16 v[40:43], v[120:123], v[168:171], v[40:43]
	v_mfma_f32_16x16x32_bf16 v[28:31], v[96:99], v[176:179], v[28:31]
	v_mfma_f32_16x16x32_bf16 v[24:27], v[120:123], v[176:179], v[24:27]
	v_mfma_f32_16x16x32_bf16 v[12:15], v[96:99], v[202:205], v[12:15]
	v_mfma_f32_16x16x32_bf16 v[8:11], v[120:123], v[202:205], v[8:11]
	v_mfma_f32_16x16x32_bf16 v[60:63], v[108:111], v[164:167], v[60:63]
	v_mfma_f32_16x16x32_bf16 v[56:59], v[128:131], v[164:167], v[56:59]
	v_mfma_f32_16x16x32_bf16 v[44:47], v[108:111], v[172:175], v[44:47]
	v_mfma_f32_16x16x32_bf16 v[40:43], v[128:131], v[172:175], v[40:43]
	v_mfma_f32_16x16x32_bf16 v[28:31], v[108:111], v[180:183], v[28:31]
	v_mfma_f32_16x16x32_bf16 v[24:27], v[128:131], v[180:183], v[24:27]
	v_mfma_f32_16x16x32_bf16 v[12:15], v[108:111], v[206:209], v[12:15]
	v_mfma_f32_16x16x32_bf16 v[8:11], v[128:131], v[206:209], v[8:11]
	v_mfma_f32_16x16x32_bf16 v[52:55], v[144:147], v[160:163], v[52:55]
	v_mfma_f32_16x16x32_bf16 v[48:51], v[152:155], v[160:163], v[48:51]
	v_mfma_f32_16x16x32_bf16 v[36:39], v[144:147], v[168:171], v[36:39]
	v_mfma_f32_16x16x32_bf16 v[32:35], v[152:155], v[168:171], v[32:35]
	v_mfma_f32_16x16x32_bf16 v[20:23], v[144:147], v[176:179], v[20:23]
	v_mfma_f32_16x16x32_bf16 v[16:19], v[152:155], v[176:179], v[16:19]
	v_mfma_f32_16x16x32_bf16 v[4:7], v[144:147], v[202:205], v[4:7]
	v_mfma_f32_16x16x32_bf16 v[0:3], v[152:155], v[202:205], v[0:3]
	v_mfma_f32_16x16x32_bf16 v[52:55], v[148:151], v[164:167], v[52:55]
	v_mfma_f32_16x16x32_bf16 v[48:51], v[156:159], v[164:167], v[48:51]
	v_mfma_f32_16x16x32_bf16 v[36:39], v[148:151], v[172:175], v[36:39]
	v_mfma_f32_16x16x32_bf16 v[32:35], v[156:159], v[172:175], v[32:35]
	v_mfma_f32_16x16x32_bf16 v[20:23], v[148:151], v[180:183], v[20:23]
	v_mfma_f32_16x16x32_bf16 v[16:19], v[156:159], v[180:183], v[16:19]
	v_mfma_f32_16x16x32_bf16 v[4:7], v[148:151], v[206:209], v[4:7]
	v_mfma_f32_16x16x32_bf16 v[0:3], v[156:159], v[206:209], v[0:3]
	s_barrier
; #define PG8_STAGE(bufoff, gbase, voff) do { _Pragma("unroll") for (int _i = 0; _i < 2; ++_i) \
;         __builtin_amdgcn_global_load_lds((const unsigned*)((const char*)(gbase) + (voff)[_i]), (PG8_LAS unsigned*)(lds + (bufoff) + ldsw + _i * 8192), 16, 0, 0); } while (0)
; #define PG8_LDA(dst, b, h) do { _Pragma("unroll") for (int m = 0; m < 4; ++m) _Pragma("unroll") for (int k = 0; k < 2; ++k) dst[m][k] = *(const PG8_LAS bf16x8*)(lds + PG8_SA(b, h) + aoff + m * 2048 + k * 1024); } while (0)
; #define PG8_LDB(dst, b, h) do { _Pragma("unroll") for (int n = 0; n < 2; ++n) _Pragma("unroll") for (int k = 0; k < 2; ++k) dst[n][k] = *(const PG8_LAS bf16x8*)(lds + PG8_SB(b, h) + boff + n * 2048 + k * 1024); } while (0)
; #define PG8_MMA(ai, bj, At, Bt) do { __builtin_amdgcn_s_setprio(1); _Pragma("unroll") for (int m = 0; m < 4; ++m) _Pragma("unroll") for (int n = 0; n < 2; ++n) _Pragma("unroll") for (int k = 0; k < 2; ++k) \
;         acc[ai][bj][m][n] = __builtin_amdgcn_mfma_f32_16x16x32_bf16(Bt[n][k], At[m][k], acc[ai][bj][m][n], 0, 0, 0); __builtin_amdgcn_s_setprio(0); } while (0)
; #define PG8_WAIT_V(n) asm volatile("s_waitcnt vmcnt(" #n ")" ::: "memory")
; #define PG8_WAIT_L(n) asm volatile("s_waitcnt lgkmcnt(" #n ")" ::: "memory")
; #define PG8_BAR __builtin_amdgcn_s_barrier()
; #define PG8_SCHED __builtin_amdgcn_sched_barrier(0)
; template <class Epi, class Sched, bool ALIGN_EPI = false, bool SP2 = false>
; __device__ __forceinline__ void gemm_phase(PG8_LAS unsigned char* lds, const Gemm g, const Sched& S, const Epi& E) {
;     ...
;             PG8_LDB(B0, 1, 0); PG8_LDB(B1, 1, 1); PG8_SCHED; PG8_LDA(At, 1, 0); PG8_STAGE(PG8_SA(0, 1), a2 + hstep, voffA);
;             PG8_WAIT_V(8); PG8_WAIT_L(0); PG8_BAR; PG8_MMA(0, 0, At, B0); PG8_MMA(0, 1, At, B1); PG8_BAR; PG8_SCHED;
;             PG8_LDA(At, 1, 1); PG8_STAGE(PG8_SB(1, 0), b3, voffB); PG8_STAGE(PG8_SB(1, 1), b3 + hstep, voffB); PG8_STAGE(PG8_SA(1, 0), a3, voffA);
;             PG8_WAIT_V(8); PG8_WAIT_L(0); PG8_BAR; PG8_MMA(1, 0, At, B0); PG8_MMA(1, 1, At, B1); PG8_BAR; PG8_SCHED;
;     ...
;         if constexpr (ALIGN_EPI) { if (wr == 0) PG8_BAR; }
	s_add_i32 s73, 0, 0x18000
	s_add_i32 s74, 0, 0x1c000
	v_add_u32_e32 v128, s73, v221
	v_add_u32_e32 v156, s74, v221
	ds_read_b128 v[96:99], v128
	ds_read_b128 v[108:111], v128 offset:1024
	ds_read_b128 v[120:123], v128 offset:2048
	ds_read_b128 v[128:131], v128 offset:3072
	ds_read_b128 v[144:147], v156
	ds_read_b128 v[148:151], v156 offset:1024
	ds_read_b128 v[152:155], v156 offset:2048
	ds_read_b128 v[156:159], v156 offset:3072
	s_add_u32 s48, s48, 0xb0000
	s_addc_u32 s49, s49, 0
	s_mov_b32 m0, s53
	ds_read_b128 v[160:163], v225 offset:32768
	ds_read_b128 v[164:167], v225 offset:33792
	ds_read_b128 v[168:171], v225 offset:34816
	ds_read_b128 v[172:175], v225 offset:35840
	ds_read_b128 v[176:179], v225 offset:36864
	ds_read_b128 v[180:183], v225 offset:37888
	ds_read_b128 v[202:205], v225 offset:38912
	ds_read_b128 v[206:209], v225 offset:39936
	global_load_lds_dwordx4 v184, s[48:49]
	s_mov_b32 m0, s54
	s_nop 0
	global_load_lds_dwordx4 v188, s[48:49]
	s_waitcnt vmcnt(8)
	s_waitcnt lgkmcnt(0)
	s_barrier
	v_mfma_f32_16x16x32_bf16 v[140:143], v[96:99], v[160:163], v[140:143]
	v_mfma_f32_16x16x32_bf16 v[136:139], v[120:123], v[160:163], v[136:139]
	v_mfma_f32_16x16x32_bf16 v[116:119], v[96:99], v[168:171], v[116:119]
	v_mfma_f32_16x16x32_bf16 v[112:115], v[120:123], v[168:171], v[112:115]
	v_mfma_f32_16x16x32_bf16 v[92:95], v[96:99], v[176:179], v[92:95]
	v_mfma_f32_16x16x32_bf16 v[88:91], v[120:123], v[176:179], v[88:91]
	v_mfma_f32_16x16x32_bf16 v[76:79], v[96:99], v[202:205], v[76:79]
	v_mfma_f32_16x16x32_bf16 v[72:75], v[120:123], v[202:205], v[72:75]
	v_mfma_f32_16x16x32_bf16 v[140:143], v[108:111], v[164:167], v[140:143]
	v_mfma_f32_16x16x32_bf16 v[136:139], v[128:131], v[164:167], v[136:139]
	v_mfma_f32_16x16x32_bf16 v[116:119], v[108:111], v[172:175], v[116:119]
	v_mfma_f32_16x16x32_bf16 v[112:115], v[128:131], v[172:175], v[112:115]
	v_mfma_f32_16x16x32_bf16 v[92:95], v[108:111], v[180:183], v[92:95]
	v_mfma_f32_16x16x32_bf16 v[88:91], v[128:131], v[180:183], v[88:91]
	v_mfma_f32_16x16x32_bf16 v[76:79], v[108:111], v[206:209], v[76:79]
	v_mfma_f32_16x16x32_bf16 v[72:75], v[128:131], v[206:209], v[72:75]
	v_mfma_f32_16x16x32_bf16 v[132:135], v[144:147], v[160:163], v[132:135]
	v_mfma_f32_16x16x32_bf16 v[124:127], v[152:155], v[160:163], v[124:127]
	v_mfma_f32_16x16x32_bf16 v[104:107], v[144:147], v[168:171], v[104:107]
	v_mfma_f32_16x16x32_bf16 v[100:103], v[152:155], v[168:171], v[100:103]
	v_mfma_f32_16x16x32_bf16 v[84:87], v[144:147], v[176:179], v[84:87]
	v_mfma_f32_16x16x32_bf16 v[80:83], v[152:155], v[176:179], v[80:83]
	v_mfma_f32_16x16x32_bf16 v[68:71], v[144:147], v[202:205], v[68:71]
	v_mfma_f32_16x16x32_bf16 v[64:67], v[152:155], v[202:205], v[64:67]
	v_mfma_f32_16x16x32_bf16 v[132:135], v[148:151], v[164:167], v[132:135]
	v_mfma_f32_16x16x32_bf16 v[124:127], v[156:159], v[164:167], v[124:127]
	v_mfma_f32_16x16x32_bf16 v[104:107], v[148:151], v[172:175], v[104:107]
	v_mfma_f32_16x16x32_bf16 v[100:103], v[156:159], v[172:175], v[100:103]
	v_mfma_f32_16x16x32_bf16 v[84:87], v[148:151], v[180:183], v[84:87]
	v_mfma_f32_16x16x32_bf16 v[80:83], v[156:159], v[180:183], v[80:83]
	v_mfma_f32_16x16x32_bf16 v[68:71], v[148:151], v[206:209], v[68:71]
	v_mfma_f32_16x16x32_bf16 v[64:67], v[156:159], v[206:209], v[64:67]
	s_barrier
	s_add_i32 s48, s73, s50
	s_mov_b32 m0, s48
	ds_read_b128 v[160:163], v225 offset:49152
	ds_read_b128 v[164:167], v225 offset:50176
	ds_read_b128 v[168:171], v225 offset:51200
	ds_read_b128 v[172:175], v225 offset:52224
	ds_read_b128 v[176:179], v225 offset:53248
	ds_read_b128 v[180:183], v225 offset:54272
	ds_read_b128 v[202:205], v225 offset:55296
	ds_read_b128 v[206:209], v225 offset:56320
	global_load_lds_dwordx4 v186, s[98:99]
	s_add_i32 m0, s48, 0x2000
	s_add_u32 s34, s34, 0xb0080
	s_addc_u32 s35, s35, 0
	s_add_i32 s48, s74, s50
	global_load_lds_dwordx4 v190, s[98:99]
	s_mov_b32 m0, s48
	s_nop 0
	global_load_lds_dwordx4 v186, s[34:35]
	s_add_i32 m0, s48, 0x2000
	s_nop 0
	global_load_lds_dwordx4 v190, s[34:35]
	s_mov_b32 m0, s59
	s_nop 0
	global_load_lds_dwordx4 v184, s[100:101]
	s_mov_b32 m0, s60
	s_nop 0
	global_load_lds_dwordx4 v188, s[100:101]
	s_waitcnt vmcnt(8)
	s_waitcnt lgkmcnt(0)
	s_barrier
	v_mfma_f32_16x16x32_bf16 v[60:63], v[96:99], v[160:163], v[60:63]
	v_mfma_f32_16x16x32_bf16 v[56:59], v[120:123], v[160:163], v[56:59]
	v_mfma_f32_16x16x32_bf16 v[44:47], v[96:99], v[168:171], v[44:47]
	v_mfma_f32_16x16x32_bf16 v[40:43], v[120:123], v[168:171], v[40:43]
	v_mfma_f32_16x16x32_bf16 v[28:31], v[96:99], v[176:179], v[28:31]
	v_mfma_f32_16x16x32_bf16 v[24:27], v[120:123], v[176:179], v[24:27]
	v_mfma_f32_16x16x32_bf16 v[12:15], v[96:99], v[202:205], v[12:15]
	v_mfma_f32_16x16x32_bf16 v[8:11], v[120:123], v[202:205], v[8:11]
	v_mfma_f32_16x16x32_bf16 v[60:63], v[108:111], v[164:167], v[60:63]
	v_mfma_f32_16x16x32_bf16 v[56:59], v[128:131], v[164:167], v[56:59]
	v_mfma_f32_16x16x32_bf16 v[44:47], v[108:111], v[172:175], v[44:47]
	v_mfma_f32_16x16x32_bf16 v[40:43], v[128:131], v[172:175], v[40:43]
	v_mfma_f32_16x16x32_bf16 v[28:31], v[108:111], v[180:183], v[28:31]
	v_mfma_f32_16x16x32_bf16 v[24:27], v[128:131], v[180:183], v[24:27]
	v_mfma_f32_16x16x32_bf16 v[12:15], v[108:111], v[206:209], v[12:15]
	v_mfma_f32_16x16x32_bf16 v[8:11], v[128:131], v[206:209], v[8:11]
	v_mfma_f32_16x16x32_bf16 v[52:55], v[144:147], v[160:163], v[52:55]
	v_mfma_f32_16x16x32_bf16 v[48:51], v[152:155], v[160:163], v[48:51]
	v_mfma_f32_16x16x32_bf16 v[36:39], v[144:147], v[168:171], v[36:39]
	v_mfma_f32_16x16x32_bf16 v[32:35], v[152:155], v[168:171], v[32:35]
	v_mfma_f32_16x16x32_bf16 v[20:23], v[144:147], v[176:179], v[20:23]
	v_mfma_f32_16x16x32_bf16 v[16:19], v[152:155], v[176:179], v[16:19]
	v_mfma_f32_16x16x32_bf16 v[4:7], v[144:147], v[202:205], v[4:7]
	v_mfma_f32_16x16x32_bf16 v[0:3], v[152:155], v[202:205], v[0:3]
	v_mfma_f32_16x16x32_bf16 v[52:55], v[148:151], v[164:167], v[52:55]
	v_mfma_f32_16x16x32_bf16 v[48:51], v[156:159], v[164:167], v[48:51]
	v_mfma_f32_16x16x32_bf16 v[36:39], v[148:151], v[172:175], v[36:39]
	v_mfma_f32_16x16x32_bf16 v[32:35], v[156:159], v[172:175], v[32:35]
	v_mfma_f32_16x16x32_bf16 v[20:23], v[148:151], v[180:183], v[20:23]
	v_mfma_f32_16x16x32_bf16 v[16:19], v[156:159], v[180:183], v[16:19]
	v_mfma_f32_16x16x32_bf16 v[4:7], v[148:151], v[206:209], v[4:7]
	v_mfma_f32_16x16x32_bf16 v[0:3], v[156:159], v[206:209], v[0:3]
	s_barrier
	s_add_i32 s72, s72, 2
	s_add_u32 s20, s20, 0x100
	s_addc_u32 s21, s21, 0
	s_add_u32 s70, s70, 0x100
	s_addc_u32 s71, s71, 0
	s_cmp_gt_u32 s72, 41
	s_cbranch_scc0 .LBB0_895
	s_and_b64 vcc, exec, s[14:15]
	s_cbranch_vccz .LBB0_898
	s_barrier

; #define PG8_STAGE(bufoff, gbase, voff) do { _Pragma("unroll") for (int _i = 0; _i < 2; ++_i) \
;         __builtin_amdgcn_global_load_lds((const unsigned*)((const char*)(gbase) + (voff)[_i]), (PG8_LAS unsigned*)(lds + (bufoff) + ldsw + _i * 8192), 16, 0, 0); } while (0)
; #define PG8_LDA(dst, b, h) do { _Pragma("unroll") for (int m = 0; m < 4; ++m) _Pragma("unroll") for (int k = 0; k < 2; ++k) dst[m][k] = *(const PG8_LAS bf16x8*)(lds + PG8_SA(b, h) + aoff + m * 2048 + k * 1024); } while (0)
; #define PG8_LDB(dst, b, h) do { _Pragma("unroll") for (int n = 0; n < 2; ++n) _Pragma("unroll") for (int k = 0; k < 2; ++k) dst[n][k] = *(const PG8_LAS bf16x8*)(lds + PG8_SB(b, h) + boff + n * 2048 + k * 1024); } while (0)
; #define PG8_WAIT_V(n) asm volatile("s_waitcnt vmcnt(" #n ")" ::: "memory")
; #define PG8_WAIT_L(n) asm volatile("s_waitcnt lgkmcnt(" #n ")" ::: "memory")
; #define PG8_BAR __builtin_amdgcn_s_barrier()
; #define PG8_SCHED __builtin_amdgcn_sched_barrier(0)
; template <class Epi, class Sched, bool ALIGN_EPI = false, bool SP2 = false>
; __device__ __forceinline__ void gemm_phase(PG8_LAS unsigned char* lds, const Gemm g, const Sched& S, const Epi& E) {
;     ...
;         const char* nA = has_next ? (const char*)g.A + (size_t)nxt.pm * tstep : cA; const char* nB = has_next ? (const char*)g.Bt + (size_t)nxt.pn * tstep : cB;
;         for (int t = 0; t < nt; t += 2) {
;             const bool last = (t == nt - 2);
;             const char* a1 = cA + (size_t)(t + 1) * kstep;
;             const char* a2 = last ? nA : cA + (size_t)(t + 2) * kstep; const char* b2 = last ? nB : cB + (size_t)(t + 2) * kstep;
;             const char* a3 = a2 + kstep; const char* b3 = b2 + kstep;
;             if (last && has_next) S.a_ready(nxt);
;             if constexpr (SP2) {
;             PG8_LDB(B0, 0, 0); PG8_LDB(B1, 0, 1); PG8_SCHED; PG8_LDA(At, 0, 0); PG8_STAGE(PG8_SA(1, 1), a1 + hstep, voffA);
;             PG8_WAIT_V(8); PG8_WAIT_L(0); PG8_BAR; PG8_MMA(0, 0, At, B0); PG8_MMA(0, 1, At, B1); PG8_BAR; PG8_SCHED;
;             PG8_LDA(At, 0, 1); PG8_STAGE(PG8_SB(0, 0), b2, voffB); PG8_STAGE(PG8_SB(0, 1), b2 + hstep, voffB); PG8_STAGE(PG8_SA(0, 0), a2, voffA);
;             PG8_WAIT_V(8); PG8_WAIT_L(0); PG8_BAR; PG8_MMA(1, 0, At, B0); PG8_MMA(1, 1, At, B1); PG8_BAR; PG8_SCHED;
.LBB0_1199:
	s_ashr_i32 s57, s56, 31
	s_lshl_b64 s[58:59], s[56:57], 19
	s_add_u32 s58, s36, s58
	s_addc_u32 s59, s37, s59
	s_and_b64 s[60:61], s[8:9], exec
	s_cselect_b32 s1, s59, s21
	s_cselect_b32 s57, s58, s20
	s_ashr_i32 s55, s54, 31
	s_lshl_b64 s[60:61], s[54:55], 19
	s_add_u32 s60, s68, s60
	s_addc_u32 s61, s69, s61
	s_and_b64 s[62:63], s[8:9], exec
	s_cselect_b32 s55, s61, s35
	s_cselect_b32 s85, s60, s34
	s_add_u32 s20, s20, 0x40080
	s_addc_u32 s21, s21, 0
	s_add_u32 s86, s34, 0x100
	s_addc_u32 s87, s35, 0
	s_mov_b32 s88, -2
	s_waitcnt lgkmcnt(0)
	ds_read_b128 v[140:143], v163
	ds_read_b128 v[168:171], v163 offset:1024
	ds_read_b128 v[172:175], v163 offset:2048
	ds_read_b128 v[176:179], v163 offset:3072
	ds_read_b128 v[180:183], v164
	ds_read_b128 v[184:187], v164 offset:1024
	ds_read_b128 v[188:191], v164 offset:2048
	ds_read_b128 v[192:195], v164 offset:3072
	s_add_u32 s34, s20, 0xfffc0080
	s_addc_u32 s35, s21, -1
	s_cmp_eq_u32 s88, 12
	s_cselect_b32 s63, s1, s35
	s_cselect_b32 s62, s57, s34
	s_cselect_b32 s35, s55, s87
	s_cselect_b32 s34, s85, s86
	s_add_i32 m0, s71, 0xc000
	ds_read_b128 v[198:201], v165
	ds_read_b128 v[202:205], v165 offset:1024
	ds_read_b128 v[206:209], v165 offset:2048
	ds_read_b128 v[210:213], v165 offset:3072
	ds_read_b128 v[214:217], v165 offset:4096
	ds_read_b128 v[218:221], v165 offset:5120
	ds_read_b128 v[222:225], v165 offset:6144
	ds_read_b128 v[226:229], v165 offset:7168
	global_load_lds_dwordx4 v132, s[20:21]
	s_add_i32 m0, s71, 0xe000
	s_nop 0
	global_load_lds_dwordx4 v134, s[20:21]
	s_waitcnt vmcnt(8)
	s_waitcnt lgkmcnt(0)
	s_barrier
	v_mfma_f32_16x16x32_bf16 v[124:127], v[140:143], v[198:201], 0
	v_mfma_f32_16x16x32_bf16 v[120:123], v[172:175], v[198:201], 0
	v_mfma_f32_16x16x32_bf16 v[108:111], v[140:143], v[206:209], 0
	v_mfma_f32_16x16x32_bf16 v[104:107], v[172:175], v[206:209], 0
	v_mfma_f32_16x16x32_bf16 v[92:95], v[140:143], v[214:217], 0
	v_mfma_f32_16x16x32_bf16 v[88:91], v[172:175], v[214:217], 0
	v_mfma_f32_16x16x32_bf16 v[76:79], v[140:143], v[222:225], 0
	v_mfma_f32_16x16x32_bf16 v[72:75], v[172:175], v[222:225], 0
	v_mfma_f32_16x16x32_bf16 v[124:127], v[168:171], v[202:205], v[124:127]
	v_mfma_f32_16x16x32_bf16 v[120:123], v[176:179], v[202:205], v[120:123]
	v_mfma_f32_16x16x32_bf16 v[108:111], v[168:171], v[210:213], v[108:111]
	v_mfma_f32_16x16x32_bf16 v[104:107], v[176:179], v[210:213], v[104:107]
	v_mfma_f32_16x16x32_bf16 v[92:95], v[168:171], v[218:221], v[92:95]
	v_mfma_f32_16x16x32_bf16 v[88:91], v[176:179], v[218:221], v[88:91]
	v_mfma_f32_16x16x32_bf16 v[76:79], v[168:171], v[226:229], v[76:79]
	v_mfma_f32_16x16x32_bf16 v[72:75], v[176:179], v[226:229], v[72:75]
	v_mfma_f32_16x16x32_bf16 v[116:119], v[180:183], v[198:201], 0
	v_mfma_f32_16x16x32_bf16 v[112:115], v[188:191], v[198:201], 0
	v_mfma_f32_16x16x32_bf16 v[100:103], v[180:183], v[206:209], 0
	v_mfma_f32_16x16x32_bf16 v[96:99], v[188:191], v[206:209], 0
	v_mfma_f32_16x16x32_bf16 v[84:87], v[180:183], v[214:217], 0
	v_mfma_f32_16x16x32_bf16 v[80:83], v[188:191], v[214:217], 0
	v_mfma_f32_16x16x32_bf16 v[68:71], v[180:183], v[222:225], 0
	v_mfma_f32_16x16x32_bf16 v[64:67], v[188:191], v[222:225], 0
	v_mfma_f32_16x16x32_bf16 v[116:119], v[184:187], v[202:205], v[116:119]
	v_mfma_f32_16x16x32_bf16 v[112:115], v[192:195], v[202:205], v[112:115]
	v_mfma_f32_16x16x32_bf16 v[100:103], v[184:187], v[210:213], v[100:103]
	v_mfma_f32_16x16x32_bf16 v[96:99], v[192:195], v[210:213], v[96:99]
	v_mfma_f32_16x16x32_bf16 v[84:87], v[184:187], v[218:221], v[84:87]
	v_mfma_f32_16x16x32_bf16 v[80:83], v[192:195], v[218:221], v[80:83]
	v_mfma_f32_16x16x32_bf16 v[68:71], v[184:187], v[226:229], v[68:71]
	v_mfma_f32_16x16x32_bf16 v[64:67], v[192:195], v[226:229], v[64:67]
	s_barrier
	s_add_i32 s89, s77, s70
	s_add_u32 s98, s34, s18
	s_addc_u32 s99, s35, s19
	s_add_u32 s100, s62, s18
	s_addc_u32 s101, s63, s19
	s_mov_b32 m0, s89
	ds_read_b128 v[198:201], v165 offset:16384
	ds_read_b128 v[202:205], v165 offset:17408
	ds_read_b128 v[206:209], v165 offset:18432
	ds_read_b128 v[210:213], v165 offset:19456
	ds_read_b128 v[214:217], v165 offset:20480
	ds_read_b128 v[218:221], v165 offset:21504
	ds_read_b128 v[222:225], v165 offset:22528
	ds_read_b128 v[226:229], v165 offset:23552
	global_load_lds_dwordx4 v146, s[34:35]
	s_add_i32 m0, s89, 0x2000
	s_add_u32 s90, s34, 0x40000
	s_addc_u32 s91, s35, 0
	s_add_i32 s89, s78, s70
	global_load_lds_dwordx4 v150, s[34:35]
	s_mov_b32 m0, s89
	s_nop 0
	global_load_lds_dwordx4 v146, s[90:91]
	s_add_i32 m0, s89, 0x2000
	s_nop 0
	global_load_lds_dwordx4 v150, s[90:91]
	s_mov_b32 m0, s71
	s_nop 0
	global_load_lds_dwordx4 v144, s[62:63]
	s_mov_b32 m0, s72
	s_nop 0
	global_load_lds_dwordx4 v148, s[62:63]
	s_waitcnt vmcnt(8)
	s_waitcnt lgkmcnt(0)
	s_barrier
; #define PG8_STAGE(bufoff, gbase, voff) do { _Pragma("unroll") for (int _i = 0; _i < 2; ++_i) \
;         __builtin_amdgcn_global_load_lds((const unsigned*)((const char*)(gbase) + (voff)[_i]), (PG8_LAS unsigned*)(lds + (bufoff) + ldsw + _i * 8192), 16, 0, 0); } while (0)
; #define PG8_LDA(dst, b, h) do { _Pragma("unroll") for (int m = 0; m < 4; ++m) _Pragma("unroll") for (int k = 0; k < 2; ++k) dst[m][k] = *(const PG8_LAS bf16x8*)(lds + PG8_SA(b, h) + aoff + m * 2048 + k * 1024); } while (0)
; #define PG8_LDB(dst, b, h) do { _Pragma("unroll") for (int n = 0; n < 2; ++n) _Pragma("unroll") for (int k = 0; k < 2; ++k) dst[n][k] = *(const PG8_LAS bf16x8*)(lds + PG8_SB(b, h) + boff + n * 2048 + k * 1024); } while (0)
; #define PG8_MMA(ai, bj, At, Bt) do { __builtin_amdgcn_s_setprio(1); _Pragma("unroll") for (int m = 0; m < 4; ++m) _Pragma("unroll") for (int n = 0; n < 2; ++n) _Pragma("unroll") for (int k = 0; k < 2; ++k) \
;         acc[ai][bj][m][n] = __builtin_amdgcn_mfma_f32_16x16x32_bf16(Bt[n][k], At[m][k], acc[ai][bj][m][n], 0, 0, 0); __builtin_amdgcn_s_setprio(0); } while (0)
; #define PG8_WAIT_V(n) asm volatile("s_waitcnt vmcnt(" #n ")" ::: "memory")
; #define PG8_WAIT_L(n) asm volatile("s_waitcnt lgkmcnt(" #n ")" ::: "memory")
; #define PG8_BAR __builtin_amdgcn_s_barrier()
; #define PG8_SCHED __builtin_amdgcn_sched_barrier(0)
; template <class Epi, class Sched, bool ALIGN_EPI = false, bool SP2 = false>
; __device__ __forceinline__ void gemm_phase(PG8_LAS unsigned char* lds, const Gemm g, const Sched& S, const Epi& E) {
;     ...
;             PG8_WAIT_V(8); PG8_WAIT_L(0); PG8_BAR; PG8_MMA(1, 0, At, B0); PG8_MMA(1, 1, At, B1); PG8_BAR; PG8_SCHED;
;             PG8_LDB(B0, 1, 0); PG8_LDB(B1, 1, 1); PG8_SCHED; PG8_LDA(At, 1, 0); PG8_STAGE(PG8_SA(0, 1), a2 + hstep, voffA);
;             PG8_WAIT_V(8); PG8_WAIT_L(0); PG8_BAR; PG8_MMA(0, 0, At, B0); PG8_MMA(0, 1, At, B1); PG8_BAR; PG8_SCHED;
	v_mfma_f32_16x16x32_bf16 v[60:63], v[140:143], v[198:201], 0
	v_mfma_f32_16x16x32_bf16 v[56:59], v[172:175], v[198:201], 0
	v_mfma_f32_16x16x32_bf16 v[48:51], v[140:143], v[206:209], 0
	v_mfma_f32_16x16x32_bf16 v[40:43], v[172:175], v[206:209], 0
	v_mfma_f32_16x16x32_bf16 v[32:35], v[140:143], v[214:217], 0
	v_mfma_f32_16x16x32_bf16 v[24:27], v[172:175], v[214:217], 0
	v_mfma_f32_16x16x32_bf16 v[16:19], v[140:143], v[222:225], 0
	v_mfma_f32_16x16x32_bf16 v[8:11], v[172:175], v[222:225], 0
	v_mfma_f32_16x16x32_bf16 v[60:63], v[168:171], v[202:205], v[60:63]
	v_mfma_f32_16x16x32_bf16 v[56:59], v[176:179], v[202:205], v[56:59]
	v_mfma_f32_16x16x32_bf16 v[48:51], v[168:171], v[210:213], v[48:51]
	v_mfma_f32_16x16x32_bf16 v[40:43], v[176:179], v[210:213], v[40:43]
	v_mfma_f32_16x16x32_bf16 v[32:35], v[168:171], v[218:221], v[32:35]
	v_mfma_f32_16x16x32_bf16 v[24:27], v[176:179], v[218:221], v[24:27]
	v_mfma_f32_16x16x32_bf16 v[16:19], v[168:171], v[226:229], v[16:19]
	v_mfma_f32_16x16x32_bf16 v[8:11], v[176:179], v[226:229], v[8:11]
	v_mfma_f32_16x16x32_bf16 v[52:55], v[180:183], v[198:201], 0
	v_mfma_f32_16x16x32_bf16 v[44:47], v[188:191], v[198:201], 0
	v_mfma_f32_16x16x32_bf16 v[36:39], v[180:183], v[206:209], 0
	v_mfma_f32_16x16x32_bf16 v[28:31], v[188:191], v[206:209], 0
	v_mfma_f32_16x16x32_bf16 v[20:23], v[180:183], v[214:217], 0
	v_mfma_f32_16x16x32_bf16 v[12:15], v[188:191], v[214:217], 0
	v_mfma_f32_16x16x32_bf16 v[4:7], v[180:183], v[222:225], 0
	v_mfma_f32_16x16x32_bf16 v[0:3], v[188:191], v[222:225], 0
	v_mfma_f32_16x16x32_bf16 v[52:55], v[184:187], v[202:205], v[52:55]
	v_mfma_f32_16x16x32_bf16 v[44:47], v[192:195], v[202:205], v[44:47]
	v_mfma_f32_16x16x32_bf16 v[36:39], v[184:187], v[210:213], v[36:39]
	v_mfma_f32_16x16x32_bf16 v[28:31], v[192:195], v[210:213], v[28:31]
	v_mfma_f32_16x16x32_bf16 v[20:23], v[184:187], v[218:221], v[20:23]
	v_mfma_f32_16x16x32_bf16 v[12:15], v[192:195], v[218:221], v[12:15]
	v_mfma_f32_16x16x32_bf16 v[4:7], v[184:187], v[226:229], v[4:7]
	v_mfma_f32_16x16x32_bf16 v[0:3], v[192:195], v[226:229], v[0:3]
	s_barrier
	s_add_i32 s89, 0, 0x18000
	v_add_u32_e32 v128, s89, v161
	s_add_i32 s90, 0, 0x1c000
	ds_read_b128 v[140:143], v128
	ds_read_b128 v[168:171], v128 offset:1024
	ds_read_b128 v[172:175], v128 offset:2048
	ds_read_b128 v[176:179], v128 offset:3072
	v_add_u32_e32 v128, s90, v161
	ds_read_b128 v[180:183], v128
	ds_read_b128 v[184:187], v128 offset:1024
	ds_read_b128 v[188:191], v128 offset:2048
	ds_read_b128 v[192:195], v128 offset:3072
	s_add_u32 s62, s62, 0x40000
	s_addc_u32 s63, s63, 0
	s_mov_b32 m0, s73
	ds_read_b128 v[198:201], v165 offset:32768
	ds_read_b128 v[202:205], v165 offset:33792
	ds_read_b128 v[206:209], v165 offset:34816
	ds_read_b128 v[210:213], v165 offset:35840
	ds_read_b128 v[214:217], v165 offset:36864
	ds_read_b128 v[218:221], v165 offset:37888
	ds_read_b128 v[222:225], v165 offset:38912
	ds_read_b128 v[226:229], v165 offset:39936
	global_load_lds_dwordx4 v144, s[62:63]
	s_mov_b32 m0, s74
	s_nop 0
	global_load_lds_dwordx4 v148, s[62:63]
	s_waitcnt vmcnt(8)
	s_waitcnt lgkmcnt(0)
	s_barrier
	v_mfma_f32_16x16x32_bf16 v[124:127], v[140:143], v[198:201], v[124:127]
	v_mfma_f32_16x16x32_bf16 v[120:123], v[172:175], v[198:201], v[120:123]
	v_mfma_f32_16x16x32_bf16 v[108:111], v[140:143], v[206:209], v[108:111]
	v_mfma_f32_16x16x32_bf16 v[104:107], v[172:175], v[206:209], v[104:107]
	v_mfma_f32_16x16x32_bf16 v[92:95], v[140:143], v[214:217], v[92:95]
	v_mfma_f32_16x16x32_bf16 v[88:91], v[172:175], v[214:217], v[88:91]
	v_mfma_f32_16x16x32_bf16 v[76:79], v[140:143], v[222:225], v[76:79]
	v_mfma_f32_16x16x32_bf16 v[72:75], v[172:175], v[222:225], v[72:75]
	v_mfma_f32_16x16x32_bf16 v[124:127], v[168:171], v[202:205], v[124:127]
	v_mfma_f32_16x16x32_bf16 v[120:123], v[176:179], v[202:205], v[120:123]
	v_mfma_f32_16x16x32_bf16 v[108:111], v[168:171], v[210:213], v[108:111]
	v_mfma_f32_16x16x32_bf16 v[104:107], v[176:179], v[210:213], v[104:107]
	v_mfma_f32_16x16x32_bf16 v[92:95], v[168:171], v[218:221], v[92:95]
	v_mfma_f32_16x16x32_bf16 v[88:91], v[176:179], v[218:221], v[88:91]
	v_mfma_f32_16x16x32_bf16 v[76:79], v[168:171], v[226:229], v[76:79]
	v_mfma_f32_16x16x32_bf16 v[72:75], v[176:179], v[226:229], v[72:75]
	v_mfma_f32_16x16x32_bf16 v[116:119], v[180:183], v[198:201], v[116:119]
	v_mfma_f32_16x16x32_bf16 v[112:115], v[188:191], v[198:201], v[112:115]
	v_mfma_f32_16x16x32_bf16 v[100:103], v[180:183], v[206:209], v[100:103]
	v_mfma_f32_16x16x32_bf16 v[96:99], v[188:191], v[206:209], v[96:99]
	v_mfma_f32_16x16x32_bf16 v[84:87], v[180:183], v[214:217], v[84:87]
	v_mfma_f32_16x16x32_bf16 v[80:83], v[188:191], v[214:217], v[80:83]
	v_mfma_f32_16x16x32_bf16 v[68:71], v[180:183], v[222:225], v[68:71]
	v_mfma_f32_16x16x32_bf16 v[64:67], v[188:191], v[222:225], v[64:67]
	v_mfma_f32_16x16x32_bf16 v[116:119], v[184:187], v[202:205], v[116:119]
	v_mfma_f32_16x16x32_bf16 v[112:115], v[192:195], v[202:205], v[112:115]
	v_mfma_f32_16x16x32_bf16 v[100:103], v[184:187], v[210:213], v[100:103]
	v_mfma_f32_16x16x32_bf16 v[96:99], v[192:195], v[210:213], v[96:99]
	v_mfma_f32_16x16x32_bf16 v[84:87], v[184:187], v[218:221], v[84:87]
	v_mfma_f32_16x16x32_bf16 v[80:83], v[192:195], v[218:221], v[80:83]
	v_mfma_f32_16x16x32_bf16 v[68:71], v[184:187], v[226:229], v[68:71]
	v_mfma_f32_16x16x32_bf16 v[64:67], v[192:195], v[226:229], v[64:67]
	s_barrier
; #define PG8_STAGE(bufoff, gbase, voff) do { _Pragma("unroll") for (int _i = 0; _i < 2; ++_i) \
;         __builtin_amdgcn_global_load_lds((const unsigned*)((const char*)(gbase) + (voff)[_i]), (PG8_LAS unsigned*)(lds + (bufoff) + ldsw + _i * 8192), 16, 0, 0); } while (0)
; #define PG8_LDA(dst, b, h) do { _Pragma("unroll") for (int m = 0; m < 4; ++m) _Pragma("unroll") for (int k = 0; k < 2; ++k) dst[m][k] = *(const PG8_LAS bf16x8*)(lds + PG8_SA(b, h) + aoff + m * 2048 + k * 1024); } while (0)
; #define PG8_LDB(dst, b, h) do { _Pragma("unroll") for (int n = 0; n < 2; ++n) _Pragma("unroll") for (int k = 0; k < 2; ++k) dst[n][k] = *(const PG8_LAS bf16x8*)(lds + PG8_SB(b, h) + boff + n * 2048 + k * 1024); } while (0)
; #define PG8_MMA(ai, bj, At, Bt) do { __builtin_amdgcn_s_setprio(1); _Pragma("unroll") for (int m = 0; m < 4; ++m) _Pragma("unroll") for (int n = 0; n < 2; ++n) _Pragma("unroll") for (int k = 0; k < 2; ++k) \
;         acc[ai][bj][m][n] = __builtin_amdgcn_mfma_f32_16x16x32_bf16(Bt[n][k], At[m][k], acc[ai][bj][m][n], 0, 0, 0); __builtin_amdgcn_s_setprio(0); } while (0)
; #define PG8_WAIT_V(n) asm volatile("s_waitcnt vmcnt(" #n ")" ::: "memory")
; #define PG8_WAIT_L(n) asm volatile("s_waitcnt lgkmcnt(" #n ")" ::: "memory")
; #define PG8_BAR __builtin_amdgcn_s_barrier()
; #define PG8_SCHED __builtin_amdgcn_sched_barrier(0)
; template <class Epi, class Sched, bool ALIGN_EPI = false, bool SP2 = false>
; __device__ __forceinline__ void gemm_phase(PG8_LAS unsigned char* lds, const Gemm g, const Sched& S, const Epi& E) {
;     ...
;             PG8_LDB(B0, 0, 0); PG8_LDB(B1, 0, 1); PG8_SCHED; PG8_LDA(At, 0, 0); PG8_STAGE(PG8_SA(1, 1), a1 + hstep, voffA);
;             PG8_WAIT_V(8); PG8_WAIT_L(0); PG8_BAR; PG8_MMA(0, 0, At, B0); PG8_MMA(0, 1, At, B1); PG8_BAR; PG8_SCHED;
;     ...
;             PG8_LDA(At, 1, 1); PG8_STAGE(PG8_SB(1, 0), b3, voffB); PG8_STAGE(PG8_SB(1, 1), b3 + hstep, voffB); PG8_STAGE(PG8_SA(1, 0), a3, voffA);
;             PG8_WAIT_V(8); PG8_WAIT_L(0); PG8_BAR; PG8_MMA(1, 0, At, B0); PG8_MMA(1, 1, At, B1); PG8_BAR; PG8_SCHED;
	s_add_i32 s62, s89, s70
	s_mov_b32 m0, s62
	ds_read_b128 v[198:201], v165 offset:49152
	ds_read_b128 v[202:205], v165 offset:50176
	ds_read_b128 v[206:209], v165 offset:51200
	ds_read_b128 v[210:213], v165 offset:52224
	ds_read_b128 v[214:217], v165 offset:53248
	ds_read_b128 v[218:221], v165 offset:54272
	ds_read_b128 v[222:225], v165 offset:55296
	ds_read_b128 v[226:229], v165 offset:56320
	global_load_lds_dwordx4 v146, s[98:99]
	s_add_i32 m0, s62, 0x2000
	s_add_u32 s34, s34, 0x40080
	s_addc_u32 s35, s35, 0
	s_add_i32 s62, s90, s70
	global_load_lds_dwordx4 v150, s[98:99]
	s_mov_b32 m0, s62
	s_nop 0
	global_load_lds_dwordx4 v146, s[34:35]
	s_add_i32 m0, s62, 0x2000
	s_nop 0
	global_load_lds_dwordx4 v150, s[34:35]
	s_mov_b32 m0, s75
	s_nop 0
	global_load_lds_dwordx4 v144, s[100:101]
	s_mov_b32 m0, s76
	s_nop 0
	global_load_lds_dwordx4 v148, s[100:101]
	s_waitcnt vmcnt(8)
	s_waitcnt lgkmcnt(0)
	s_barrier
	v_mfma_f32_16x16x32_bf16 v[60:63], v[140:143], v[198:201], v[60:63]
	v_mfma_f32_16x16x32_bf16 v[56:59], v[172:175], v[198:201], v[56:59]
	v_mfma_f32_16x16x32_bf16 v[48:51], v[140:143], v[206:209], v[48:51]
	v_mfma_f32_16x16x32_bf16 v[40:43], v[172:175], v[206:209], v[40:43]
	v_mfma_f32_16x16x32_bf16 v[32:35], v[140:143], v[214:217], v[32:35]
	v_mfma_f32_16x16x32_bf16 v[24:27], v[172:175], v[214:217], v[24:27]
	v_mfma_f32_16x16x32_bf16 v[16:19], v[140:143], v[222:225], v[16:19]
	v_mfma_f32_16x16x32_bf16 v[8:11], v[172:175], v[222:225], v[8:11]
	v_mfma_f32_16x16x32_bf16 v[60:63], v[168:171], v[202:205], v[60:63]
	v_mfma_f32_16x16x32_bf16 v[56:59], v[176:179], v[202:205], v[56:59]
	v_mfma_f32_16x16x32_bf16 v[48:51], v[168:171], v[210:213], v[48:51]
	v_mfma_f32_16x16x32_bf16 v[40:43], v[176:179], v[210:213], v[40:43]
	v_mfma_f32_16x16x32_bf16 v[32:35], v[168:171], v[218:221], v[32:35]
	v_mfma_f32_16x16x32_bf16 v[24:27], v[176:179], v[218:221], v[24:27]
	v_mfma_f32_16x16x32_bf16 v[16:19], v[168:171], v[226:229], v[16:19]
	v_mfma_f32_16x16x32_bf16 v[8:11], v[176:179], v[226:229], v[8:11]
	v_mfma_f32_16x16x32_bf16 v[52:55], v[180:183], v[198:201], v[52:55]
	v_mfma_f32_16x16x32_bf16 v[44:47], v[188:191], v[198:201], v[44:47]
	v_mfma_f32_16x16x32_bf16 v[36:39], v[180:183], v[206:209], v[36:39]
	v_mfma_f32_16x16x32_bf16 v[28:31], v[188:191], v[206:209], v[28:31]
	v_mfma_f32_16x16x32_bf16 v[20:23], v[180:183], v[214:217], v[20:23]
	v_mfma_f32_16x16x32_bf16 v[12:15], v[188:191], v[214:217], v[12:15]
	v_mfma_f32_16x16x32_bf16 v[4:7], v[180:183], v[222:225], v[4:7]
	v_mfma_f32_16x16x32_bf16 v[0:3], v[188:191], v[222:225], v[0:3]
	v_mfma_f32_16x16x32_bf16 v[52:55], v[184:187], v[202:205], v[52:55]
	v_mfma_f32_16x16x32_bf16 v[44:47], v[192:195], v[202:205], v[44:47]
	v_mfma_f32_16x16x32_bf16 v[36:39], v[184:187], v[210:213], v[36:39]
	v_mfma_f32_16x16x32_bf16 v[28:31], v[192:195], v[210:213], v[28:31]
	v_mfma_f32_16x16x32_bf16 v[20:23], v[184:187], v[218:221], v[20:23]
	v_mfma_f32_16x16x32_bf16 v[12:15], v[192:195], v[218:221], v[12:15]
	v_mfma_f32_16x16x32_bf16 v[4:7], v[184:187], v[226:229], v[4:7]
	v_mfma_f32_16x16x32_bf16 v[0:3], v[192:195], v[226:229], v[0:3]
	s_barrier
	s_add_i32 s88, s88, 2
	s_add_u32 s20, s20, 0x100
	s_addc_u32 s21, s21, 0
	s_add_u32 s86, s86, 0x100
	s_addc_u32 s87, s87, 0
	s_cmp_gt_u32 s88, 13
.LBB0_1200:
	ds_read_b128 v[140:143], v163
	ds_read_b128 v[168:171], v163 offset:1024
	ds_read_b128 v[172:175], v163 offset:2048
	ds_read_b128 v[176:179], v163 offset:3072
	ds_read_b128 v[180:183], v164
	ds_read_b128 v[184:187], v164 offset:1024
	ds_read_b128 v[188:191], v164 offset:2048
	ds_read_b128 v[192:195], v164 offset:3072
	s_add_u32 s34, s20, 0xfffc0080
	s_addc_u32 s35, s21, -1
	s_cmp_eq_u32 s88, 12
	s_cselect_b32 s63, s1, s35
	s_cselect_b32 s62, s57, s34
	s_cselect_b32 s35, s55, s87
	s_cselect_b32 s34, s85, s86
	s_add_i32 m0, s71, 0xc000
	ds_read_b128 v[198:201], v165
	ds_read_b128 v[202:205], v165 offset:1024
	ds_read_b128 v[206:209], v165 offset:2048
	ds_read_b128 v[210:213], v165 offset:3072
	ds_read_b128 v[214:217], v165 offset:4096
	ds_read_b128 v[218:221], v165 offset:5120
	ds_read_b128 v[222:225], v165 offset:6144
	ds_read_b128 v[226:229], v165 offset:7168
	global_load_lds_dwordx4 v132, s[20:21]
	s_add_i32 m0, s71, 0xe000
	s_nop 0
	global_load_lds_dwordx4 v134, s[20:21]
	s_waitcnt vmcnt(8)
	s_waitcnt lgkmcnt(0)
	s_barrier
	v_mfma_f32_16x16x32_bf16 v[124:127], v[140:143], v[198:201], v[124:127]
	v_mfma_f32_16x16x32_bf16 v[120:123], v[172:175], v[198:201], v[120:123]
	v_mfma_f32_16x16x32_bf16 v[108:111], v[140:143], v[206:209], v[108:111]
	v_mfma_f32_16x16x32_bf16 v[104:107], v[172:175], v[206:209], v[104:107]
	v_mfma_f32_16x16x32_bf16 v[92:95], v[140:143], v[214:217], v[92:95]
	v_mfma_f32_16x16x32_bf16 v[88:91], v[172:175], v[214:217], v[88:91]
	v_mfma_f32_16x16x32_bf16 v[76:79], v[140:143], v[222:225], v[76:79]
	v_mfma_f32_16x16x32_bf16 v[72:75], v[172:175], v[222:225], v[72:75]
	v_mfma_f32_16x16x32_bf16 v[124:127], v[168:171], v[202:205], v[124:127]
	v_mfma_f32_16x16x32_bf16 v[120:123], v[176:179], v[202:205], v[120:123]
	v_mfma_f32_16x16x32_bf16 v[108:111], v[168:171], v[210:213], v[108:111]
	v_mfma_f32_16x16x32_bf16 v[104:107], v[176:179], v[210:213], v[104:107]
	v_mfma_f32_16x16x32_bf16 v[92:95], v[168:171], v[218:221], v[92:95]
	v_mfma_f32_16x16x32_bf16 v[88:91], v[176:179], v[218:221], v[88:91]
	v_mfma_f32_16x16x32_bf16 v[76:79], v[168:171], v[226:229], v[76:79]
	v_mfma_f32_16x16x32_bf16 v[72:75], v[176:179], v[226:229], v[72:75]
	v_mfma_f32_16x16x32_bf16 v[116:119], v[180:183], v[198:201], v[116:119]
	v_mfma_f32_16x16x32_bf16 v[112:115], v[188:191], v[198:201], v[112:115]
	v_mfma_f32_16x16x32_bf16 v[100:103], v[180:183], v[206:209], v[100:103]
	v_mfma_f32_16x16x32_bf16 v[96:99], v[188:191], v[206:209], v[96:99]
	v_mfma_f32_16x16x32_bf16 v[84:87], v[180:183], v[214:217], v[84:87]
	v_mfma_f32_16x16x32_bf16 v[80:83], v[188:191], v[214:217], v[80:83]
	v_mfma_f32_16x16x32_bf16 v[68:71], v[180:183], v[222:225], v[68:71]
	v_mfma_f32_16x16x32_bf16 v[64:67], v[188:191], v[222:225], v[64:67]
	v_mfma_f32_16x16x32_bf16 v[116:119], v[184:187], v[202:205], v[116:119]
	v_mfma_f32_16x16x32_bf16 v[112:115], v[192:195], v[202:205], v[112:115]
	v_mfma_f32_16x16x32_bf16 v[100:103], v[184:187], v[210:213], v[100:103]
	v_mfma_f32_16x16x32_bf16 v[96:99], v[192:195], v[210:213], v[96:99]
	v_mfma_f32_16x16x32_bf16 v[84:87], v[184:187], v[218:221], v[84:87]
	v_mfma_f32_16x16x32_bf16 v[80:83], v[192:195], v[218:221], v[80:83]
	v_mfma_f32_16x16x32_bf16 v[68:71], v[184:187], v[226:229], v[68:71]
	v_mfma_f32_16x16x32_bf16 v[64:67], v[192:195], v[226:229], v[64:67]
	s_barrier
; #define PG8_STAGE(bufoff, gbase, voff) do { _Pragma("unroll") for (int _i = 0; _i < 2; ++_i) \
;         __builtin_amdgcn_global_load_lds((const unsigned*)((const char*)(gbase) + (voff)[_i]), (PG8_LAS unsigned*)(lds + (bufoff) + ldsw + _i * 8192), 16, 0, 0); } while (0)
; #define PG8_LDA(dst, b, h) do { _Pragma("unroll") for (int m = 0; m < 4; ++m) _Pragma("unroll") for (int k = 0; k < 2; ++k) dst[m][k] = *(const PG8_LAS bf16x8*)(lds + PG8_SA(b, h) + aoff + m * 2048 + k * 1024); } while (0)
; #define PG8_LDB(dst, b, h) do { _Pragma("unroll") for (int n = 0; n < 2; ++n) _Pragma("unroll") for (int k = 0; k < 2; ++k) dst[n][k] = *(const PG8_LAS bf16x8*)(lds + PG8_SB(b, h) + boff + n * 2048 + k * 1024); } while (0)
; #define PG8_MMA(ai, bj, At, Bt) do { __builtin_amdgcn_s_setprio(1); _Pragma("unroll") for (int m = 0; m < 4; ++m) _Pragma("unroll") for (int n = 0; n < 2; ++n) _Pragma("unroll") for (int k = 0; k < 2; ++k) \
;         acc[ai][bj][m][n] = __builtin_amdgcn_mfma_f32_16x16x32_bf16(Bt[n][k], At[m][k], acc[ai][bj][m][n], 0, 0, 0); __builtin_amdgcn_s_setprio(0); } while (0)
; #define PG8_WAIT_V(n) asm volatile("s_waitcnt vmcnt(" #n ")" ::: "memory")
; #define PG8_WAIT_L(n) asm volatile("s_waitcnt lgkmcnt(" #n ")" ::: "memory")
; #define PG8_BAR __builtin_amdgcn_s_barrier()
; #define PG8_SCHED __builtin_amdgcn_sched_barrier(0)
; template <class Epi, class Sched, bool ALIGN_EPI = false, bool SP2 = false>
; __device__ __forceinline__ void gemm_phase(PG8_LAS unsigned char* lds, const Gemm g, const Sched& S, const Epi& E) {
;     ...
;             PG8_WAIT_V(8); PG8_WAIT_L(0); PG8_BAR; PG8_MMA(0, 0, At, B0); PG8_MMA(0, 1, At, B1); PG8_BAR; PG8_SCHED;
;             PG8_LDA(At, 0, 1); PG8_STAGE(PG8_SB(0, 0), b2, voffB); PG8_STAGE(PG8_SB(0, 1), b2 + hstep, voffB); PG8_STAGE(PG8_SA(0, 0), a2, voffA);
;             PG8_WAIT_V(8); PG8_WAIT_L(0); PG8_BAR; PG8_MMA(1, 0, At, B0); PG8_MMA(1, 1, At, B1); PG8_BAR; PG8_SCHED;
;             PG8_LDB(B0, 1, 0); PG8_LDB(B1, 1, 1); PG8_SCHED; PG8_LDA(At, 1, 0); PG8_STAGE(PG8_SA(0, 1), a2 + hstep, voffA);
	s_add_i32 s89, s77, s70
	s_add_u32 s98, s34, s18
	s_addc_u32 s99, s35, s19
	s_add_u32 s100, s62, s18
	s_addc_u32 s101, s63, s19
	s_mov_b32 m0, s89
	ds_read_b128 v[198:201], v165 offset:16384
	ds_read_b128 v[202:205], v165 offset:17408
	ds_read_b128 v[206:209], v165 offset:18432
	ds_read_b128 v[210:213], v165 offset:19456
	ds_read_b128 v[214:217], v165 offset:20480
	ds_read_b128 v[218:221], v165 offset:21504
	ds_read_b128 v[222:225], v165 offset:22528
	ds_read_b128 v[226:229], v165 offset:23552
	global_load_lds_dwordx4 v146, s[34:35]
	s_add_i32 m0, s89, 0x2000
	s_add_u32 s90, s34, 0x40000
	s_addc_u32 s91, s35, 0
	s_add_i32 s89, s78, s70
	global_load_lds_dwordx4 v150, s[34:35]
	s_mov_b32 m0, s89
	s_nop 0
	global_load_lds_dwordx4 v146, s[90:91]
	s_add_i32 m0, s89, 0x2000
	s_nop 0
	global_load_lds_dwordx4 v150, s[90:91]
	s_mov_b32 m0, s71
	s_nop 0
	global_load_lds_dwordx4 v144, s[62:63]
	s_mov_b32 m0, s72
	s_nop 0
	global_load_lds_dwordx4 v148, s[62:63]
	s_waitcnt vmcnt(8)
	s_waitcnt lgkmcnt(0)
	s_barrier
	v_mfma_f32_16x16x32_bf16 v[60:63], v[140:143], v[198:201], v[60:63]
	v_mfma_f32_16x16x32_bf16 v[56:59], v[172:175], v[198:201], v[56:59]
	v_mfma_f32_16x16x32_bf16 v[48:51], v[140:143], v[206:209], v[48:51]
	v_mfma_f32_16x16x32_bf16 v[40:43], v[172:175], v[206:209], v[40:43]
	v_mfma_f32_16x16x32_bf16 v[32:35], v[140:143], v[214:217], v[32:35]
	v_mfma_f32_16x16x32_bf16 v[24:27], v[172:175], v[214:217], v[24:27]
	v_mfma_f32_16x16x32_bf16 v[16:19], v[140:143], v[222:225], v[16:19]
	v_mfma_f32_16x16x32_bf16 v[8:11], v[172:175], v[222:225], v[8:11]
	v_mfma_f32_16x16x32_bf16 v[60:63], v[168:171], v[202:205], v[60:63]
	v_mfma_f32_16x16x32_bf16 v[56:59], v[176:179], v[202:205], v[56:59]
	v_mfma_f32_16x16x32_bf16 v[48:51], v[168:171], v[210:213], v[48:51]
	v_mfma_f32_16x16x32_bf16 v[40:43], v[176:179], v[210:213], v[40:43]
	v_mfma_f32_16x16x32_bf16 v[32:35], v[168:171], v[218:221], v[32:35]
	v_mfma_f32_16x16x32_bf16 v[24:27], v[176:179], v[218:221], v[24:27]
	v_mfma_f32_16x16x32_bf16 v[16:19], v[168:171], v[226:229], v[16:19]
	v_mfma_f32_16x16x32_bf16 v[8:11], v[176:179], v[226:229], v[8:11]
	v_mfma_f32_16x16x32_bf16 v[52:55], v[180:183], v[198:201], v[52:55]
	v_mfma_f32_16x16x32_bf16 v[44:47], v[188:191], v[198:201], v[44:47]
	v_mfma_f32_16x16x32_bf16 v[36:39], v[180:183], v[206:209], v[36:39]
	v_mfma_f32_16x16x32_bf16 v[28:31], v[188:191], v[206:209], v[28:31]
	v_mfma_f32_16x16x32_bf16 v[20:23], v[180:183], v[214:217], v[20:23]
	v_mfma_f32_16x16x32_bf16 v[12:15], v[188:191], v[214:217], v[12:15]
	v_mfma_f32_16x16x32_bf16 v[4:7], v[180:183], v[222:225], v[4:7]
	v_mfma_f32_16x16x32_bf16 v[0:3], v[188:191], v[222:225], v[0:3]
	v_mfma_f32_16x16x32_bf16 v[52:55], v[184:187], v[202:205], v[52:55]
	v_mfma_f32_16x16x32_bf16 v[44:47], v[192:195], v[202:205], v[44:47]
	v_mfma_f32_16x16x32_bf16 v[36:39], v[184:187], v[210:213], v[36:39]
	v_mfma_f32_16x16x32_bf16 v[28:31], v[192:195], v[210:213], v[28:31]
	v_mfma_f32_16x16x32_bf16 v[20:23], v[184:187], v[218:221], v[20:23]
	v_mfma_f32_16x16x32_bf16 v[12:15], v[192:195], v[218:221], v[12:15]
	v_mfma_f32_16x16x32_bf16 v[4:7], v[184:187], v[226:229], v[4:7]
	v_mfma_f32_16x16x32_bf16 v[0:3], v[192:195], v[226:229], v[0:3]
	s_barrier
	s_add_i32 s89, 0, 0x18000
	v_add_u32_e32 v128, s89, v161
	s_add_i32 s90, 0, 0x1c000
	ds_read_b128 v[140:143], v128
	ds_read_b128 v[168:171], v128 offset:1024
	ds_read_b128 v[172:175], v128 offset:2048
	ds_read_b128 v[176:179], v128 offset:3072
	v_add_u32_e32 v128, s90, v161
	ds_read_b128 v[180:183], v128
	ds_read_b128 v[184:187], v128 offset:1024
	ds_read_b128 v[188:191], v128 offset:2048
	ds_read_b128 v[192:195], v128 offset:3072
	s_add_u32 s62, s62, 0x40000
	s_addc_u32 s63, s63, 0
	s_mov_b32 m0, s73
	ds_read_b128 v[198:201], v165 offset:32768
	ds_read_b128 v[202:205], v165 offset:33792
	ds_read_b128 v[206:209], v165 offset:34816
	ds_read_b128 v[210:213], v165 offset:35840
	ds_read_b128 v[214:217], v165 offset:36864
	ds_read_b128 v[218:221], v165 offset:37888
	ds_read_b128 v[222:225], v165 offset:38912
	ds_read_b128 v[226:229], v165 offset:39936
	global_load_lds_dwordx4 v144, s[62:63]
	s_mov_b32 m0, s74
	s_nop 0
	global_load_lds_dwordx4 v148, s[62:63]
	s_waitcnt vmcnt(8)
	s_waitcnt lgkmcnt(0)
	s_barrier
; #define PG8_STAGE(bufoff, gbase, voff) do { _Pragma("unroll") for (int _i = 0; _i < 2; ++_i) \
;         __builtin_amdgcn_global_load_lds((const unsigned*)((const char*)(gbase) + (voff)[_i]), (PG8_LAS unsigned*)(lds + (bufoff) + ldsw + _i * 8192), 16, 0, 0); } while (0)
; #define PG8_LDA(dst, b, h) do { _Pragma("unroll") for (int m = 0; m < 4; ++m) _Pragma("unroll") for (int k = 0; k < 2; ++k) dst[m][k] = *(const PG8_LAS bf16x8*)(lds + PG8_SA(b, h) + aoff + m * 2048 + k * 1024); } while (0)
; #define PG8_MMA(ai, bj, At, Bt) do { __builtin_amdgcn_s_setprio(1); _Pragma("unroll") for (int m = 0; m < 4; ++m) _Pragma("unroll") for (int n = 0; n < 2; ++n) _Pragma("unroll") for (int k = 0; k < 2; ++k) \
;         acc[ai][bj][m][n] = __builtin_amdgcn_mfma_f32_16x16x32_bf16(Bt[n][k], At[m][k], acc[ai][bj][m][n], 0, 0, 0); __builtin_amdgcn_s_setprio(0); } while (0)
; #define PG8_WAIT_V(n) asm volatile("s_waitcnt vmcnt(" #n ")" ::: "memory")
; #define PG8_WAIT_L(n) asm volatile("s_waitcnt lgkmcnt(" #n ")" ::: "memory")
; #define PG8_BAR __builtin_amdgcn_s_barrier()
; #define PG8_SCHED __builtin_amdgcn_sched_barrier(0)
; template <class Epi, class Sched, bool ALIGN_EPI = false, bool SP2 = false>
; __device__ __forceinline__ void gemm_phase(PG8_LAS unsigned char* lds, const Gemm g, const Sched& S, const Epi& E) {
;     ...
;             PG8_WAIT_V(8); PG8_WAIT_L(0); PG8_BAR; PG8_MMA(0, 0, At, B0); PG8_MMA(0, 1, At, B1); PG8_BAR; PG8_SCHED;
;             PG8_LDA(At, 1, 1); PG8_STAGE(PG8_SB(1, 0), b3, voffB); PG8_STAGE(PG8_SB(1, 1), b3 + hstep, voffB); PG8_STAGE(PG8_SA(1, 0), a3, voffA);
;             PG8_WAIT_V(8); PG8_WAIT_L(0); PG8_BAR; PG8_MMA(1, 0, At, B0); PG8_MMA(1, 1, At, B1); PG8_BAR; PG8_SCHED;
;     ...
;         if constexpr (ALIGN_EPI) { if (wr == 0) PG8_BAR; }
	v_mfma_f32_16x16x32_bf16 v[124:127], v[140:143], v[198:201], v[124:127]
	v_mfma_f32_16x16x32_bf16 v[120:123], v[172:175], v[198:201], v[120:123]
	v_mfma_f32_16x16x32_bf16 v[108:111], v[140:143], v[206:209], v[108:111]
	v_mfma_f32_16x16x32_bf16 v[104:107], v[172:175], v[206:209], v[104:107]
	v_mfma_f32_16x16x32_bf16 v[92:95], v[140:143], v[214:217], v[92:95]
	v_mfma_f32_16x16x32_bf16 v[88:91], v[172:175], v[214:217], v[88:91]
	v_mfma_f32_16x16x32_bf16 v[76:79], v[140:143], v[222:225], v[76:79]
	v_mfma_f32_16x16x32_bf16 v[72:75], v[172:175], v[222:225], v[72:75]
	v_mfma_f32_16x16x32_bf16 v[124:127], v[168:171], v[202:205], v[124:127]
	v_mfma_f32_16x16x32_bf16 v[120:123], v[176:179], v[202:205], v[120:123]
	v_mfma_f32_16x16x32_bf16 v[108:111], v[168:171], v[210:213], v[108:111]
	v_mfma_f32_16x16x32_bf16 v[104:107], v[176:179], v[210:213], v[104:107]
	v_mfma_f32_16x16x32_bf16 v[92:95], v[168:171], v[218:221], v[92:95]
	v_mfma_f32_16x16x32_bf16 v[88:91], v[176:179], v[218:221], v[88:91]
	v_mfma_f32_16x16x32_bf16 v[76:79], v[168:171], v[226:229], v[76:79]
	v_mfma_f32_16x16x32_bf16 v[72:75], v[176:179], v[226:229], v[72:75]
	v_mfma_f32_16x16x32_bf16 v[116:119], v[180:183], v[198:201], v[116:119]
	v_mfma_f32_16x16x32_bf16 v[112:115], v[188:191], v[198:201], v[112:115]
	v_mfma_f32_16x16x32_bf16 v[100:103], v[180:183], v[206:209], v[100:103]
	v_mfma_f32_16x16x32_bf16 v[96:99], v[188:191], v[206:209], v[96:99]
	v_mfma_f32_16x16x32_bf16 v[84:87], v[180:183], v[214:217], v[84:87]
	v_mfma_f32_16x16x32_bf16 v[80:83], v[188:191], v[214:217], v[80:83]
	v_mfma_f32_16x16x32_bf16 v[68:71], v[180:183], v[222:225], v[68:71]
	v_mfma_f32_16x16x32_bf16 v[64:67], v[188:191], v[222:225], v[64:67]
	v_mfma_f32_16x16x32_bf16 v[116:119], v[184:187], v[202:205], v[116:119]
	v_mfma_f32_16x16x32_bf16 v[112:115], v[192:195], v[202:205], v[112:115]
	v_mfma_f32_16x16x32_bf16 v[100:103], v[184:187], v[210:213], v[100:103]
	v_mfma_f32_16x16x32_bf16 v[96:99], v[192:195], v[210:213], v[96:99]
	v_mfma_f32_16x16x32_bf16 v[84:87], v[184:187], v[218:221], v[84:87]
	v_mfma_f32_16x16x32_bf16 v[80:83], v[192:195], v[218:221], v[80:83]
	v_mfma_f32_16x16x32_bf16 v[68:71], v[184:187], v[226:229], v[68:71]
	v_mfma_f32_16x16x32_bf16 v[64:67], v[192:195], v[226:229], v[64:67]
	s_barrier
	s_add_i32 s62, s89, s70
	s_mov_b32 m0, s62
	ds_read_b128 v[198:201], v165 offset:49152
	ds_read_b128 v[202:205], v165 offset:50176
	ds_read_b128 v[206:209], v165 offset:51200
	ds_read_b128 v[210:213], v165 offset:52224
	ds_read_b128 v[214:217], v165 offset:53248
	ds_read_b128 v[218:221], v165 offset:54272
	ds_read_b128 v[222:225], v165 offset:55296
	ds_read_b128 v[226:229], v165 offset:56320
	global_load_lds_dwordx4 v146, s[98:99]
	s_add_i32 m0, s62, 0x2000
	s_add_u32 s34, s34, 0x40080
	s_addc_u32 s35, s35, 0
	s_add_i32 s62, s90, s70
	global_load_lds_dwordx4 v150, s[98:99]
	s_mov_b32 m0, s62
	s_nop 0
	global_load_lds_dwordx4 v146, s[34:35]
	s_add_i32 m0, s62, 0x2000
	s_nop 0
	global_load_lds_dwordx4 v150, s[34:35]
	s_mov_b32 m0, s75
	s_nop 0
	global_load_lds_dwordx4 v144, s[100:101]
	s_mov_b32 m0, s76
	s_nop 0
	global_load_lds_dwordx4 v148, s[100:101]
	s_waitcnt vmcnt(8)
	s_waitcnt lgkmcnt(0)
	s_barrier
	v_mfma_f32_16x16x32_bf16 v[60:63], v[140:143], v[198:201], v[60:63]
	v_mfma_f32_16x16x32_bf16 v[56:59], v[172:175], v[198:201], v[56:59]
	v_mfma_f32_16x16x32_bf16 v[48:51], v[140:143], v[206:209], v[48:51]
	v_mfma_f32_16x16x32_bf16 v[40:43], v[172:175], v[206:209], v[40:43]
	v_mfma_f32_16x16x32_bf16 v[32:35], v[140:143], v[214:217], v[32:35]
	v_mfma_f32_16x16x32_bf16 v[24:27], v[172:175], v[214:217], v[24:27]
	v_mfma_f32_16x16x32_bf16 v[16:19], v[140:143], v[222:225], v[16:19]
	v_mfma_f32_16x16x32_bf16 v[8:11], v[172:175], v[222:225], v[8:11]
	v_mfma_f32_16x16x32_bf16 v[60:63], v[168:171], v[202:205], v[60:63]
	v_mfma_f32_16x16x32_bf16 v[56:59], v[176:179], v[202:205], v[56:59]
	v_mfma_f32_16x16x32_bf16 v[48:51], v[168:171], v[210:213], v[48:51]
	v_mfma_f32_16x16x32_bf16 v[40:43], v[176:179], v[210:213], v[40:43]
	v_mfma_f32_16x16x32_bf16 v[32:35], v[168:171], v[218:221], v[32:35]
	v_mfma_f32_16x16x32_bf16 v[24:27], v[176:179], v[218:221], v[24:27]
	v_mfma_f32_16x16x32_bf16 v[16:19], v[168:171], v[226:229], v[16:19]
	v_mfma_f32_16x16x32_bf16 v[8:11], v[176:179], v[226:229], v[8:11]
	v_mfma_f32_16x16x32_bf16 v[52:55], v[180:183], v[198:201], v[52:55]
	v_mfma_f32_16x16x32_bf16 v[44:47], v[188:191], v[198:201], v[44:47]
	v_mfma_f32_16x16x32_bf16 v[36:39], v[180:183], v[206:209], v[36:39]
	v_mfma_f32_16x16x32_bf16 v[28:31], v[188:191], v[206:209], v[28:31]
	v_mfma_f32_16x16x32_bf16 v[20:23], v[180:183], v[214:217], v[20:23]
	v_mfma_f32_16x16x32_bf16 v[12:15], v[188:191], v[214:217], v[12:15]
	v_mfma_f32_16x16x32_bf16 v[4:7], v[180:183], v[222:225], v[4:7]
	v_mfma_f32_16x16x32_bf16 v[0:3], v[188:191], v[222:225], v[0:3]
	v_mfma_f32_16x16x32_bf16 v[52:55], v[184:187], v[202:205], v[52:55]
	v_mfma_f32_16x16x32_bf16 v[44:47], v[192:195], v[202:205], v[44:47]
	v_mfma_f32_16x16x32_bf16 v[36:39], v[184:187], v[210:213], v[36:39]
	v_mfma_f32_16x16x32_bf16 v[28:31], v[192:195], v[210:213], v[28:31]
	v_mfma_f32_16x16x32_bf16 v[20:23], v[184:187], v[218:221], v[20:23]
	v_mfma_f32_16x16x32_bf16 v[12:15], v[192:195], v[218:221], v[12:15]
	v_mfma_f32_16x16x32_bf16 v[4:7], v[184:187], v[226:229], v[4:7]
	v_mfma_f32_16x16x32_bf16 v[0:3], v[192:195], v[226:229], v[0:3]
	s_barrier
	s_add_i32 s88, s88, 2
	s_add_u32 s20, s20, 0x100
	s_addc_u32 s21, s21, 0
	s_add_u32 s86, s86, 0x100
	s_addc_u32 s87, s87, 0
	s_cmp_gt_u32 s88, 13
	s_cbranch_scc0 .LBB0_1200
	s_and_b64 vcc, exec, s[38:39]
	s_cbranch_vccz .LBB0_1203
	s_barrier

; #define PG8_STAGE(bufoff, gbase, voff) do { _Pragma("unroll") for (int _i = 0; _i < 2; ++_i) \
;         __builtin_amdgcn_global_load_lds((const unsigned*)((const char*)(gbase) + (voff)[_i]), (PG8_LAS unsigned*)(lds + (bufoff) + ldsw + _i * 8192), 16, 0, 0); } while (0)
; #define PG8_LDA(dst, b, h) do { _Pragma("unroll") for (int m = 0; m < 4; ++m) _Pragma("unroll") for (int k = 0; k < 2; ++k) dst[m][k] = *(const PG8_LAS bf16x8*)(lds + PG8_SA(b, h) + aoff + m * 2048 + k * 1024); } while (0)
; #define PG8_LDB(dst, b, h) do { _Pragma("unroll") for (int n = 0; n < 2; ++n) _Pragma("unroll") for (int k = 0; k < 2; ++k) dst[n][k] = *(const PG8_LAS bf16x8*)(lds + PG8_SB(b, h) + boff + n * 2048 + k * 1024); } while (0)
; #define PG8_WAIT_V(n) asm volatile("s_waitcnt vmcnt(" #n ")" ::: "memory")
; #define PG8_WAIT_L(n) asm volatile("s_waitcnt lgkmcnt(" #n ")" ::: "memory")
; #define PG8_BAR __builtin_amdgcn_s_barrier()
; #define PG8_SCHED __builtin_amdgcn_sched_barrier(0)
; template <class Epi, class Sched, bool ALIGN_EPI = false, bool SP2 = false>
; __device__ __forceinline__ void gemm_phase(PG8_LAS unsigned char* lds, const Gemm g, const Sched& S, const Epi& E) {
;     ...
;         const char* nA = has_next ? (const char*)g.A + (size_t)nxt.pm * tstep : cA; const char* nB = has_next ? (const char*)g.Bt + (size_t)nxt.pn * tstep : cB;
;         for (int t = 0; t < nt; t += 2) {
;             const bool last = (t == nt - 2);
;             const char* a1 = cA + (size_t)(t + 1) * kstep;
;             const char* a2 = last ? nA : cA + (size_t)(t + 2) * kstep; const char* b2 = last ? nB : cB + (size_t)(t + 2) * kstep;
;             const char* a3 = a2 + kstep; const char* b3 = b2 + kstep;
;             if (last && has_next) S.a_ready(nxt);
;             if constexpr (SP2) {
;             PG8_LDB(B0, 0, 0); PG8_LDB(B1, 0, 1); PG8_SCHED; PG8_LDA(At, 0, 0); PG8_STAGE(PG8_SA(1, 1), a1 + hstep, voffA);
;             PG8_WAIT_V(8); PG8_WAIT_L(0); PG8_BAR; PG8_MMA(0, 0, At, B0); PG8_MMA(0, 1, At, B1); PG8_BAR; PG8_SCHED;
;             PG8_LDA(At, 0, 1); PG8_STAGE(PG8_SB(0, 0), b2, voffB); PG8_STAGE(PG8_SB(0, 1), b2 + hstep, voffB); PG8_STAGE(PG8_SA(0, 0), a2, voffA);
;             PG8_WAIT_V(8); PG8_WAIT_L(0); PG8_BAR; PG8_MMA(1, 0, At, B0); PG8_MMA(1, 1, At, B1); PG8_BAR; PG8_SCHED;
.LBB0_1445:
	s_ashr_i32 s15, s14, 31
	s_lshl_b64 s[16:17], s[14:15], 19
	s_add_u32 s16, s49, s16
	s_addc_u32 s17, s50, s17
	s_and_b64 s[18:19], s[4:5], exec
	s_cselect_b32 s15, s17, s21
	s_cselect_b32 s65, s16, s20
	s_ashr_i32 s13, s12, 31
	s_lshl_b64 s[18:19], s[12:13], 19
	s_add_u32 s18, s36, s18
	s_addc_u32 s19, s37, s19
	s_and_b64 s[44:45], s[4:5], exec
	s_cselect_b32 s13, s19, s39
	s_cselect_b32 s66, s18, s38
	s_add_u32 s20, s20, 0x40080
	s_addc_u32 s21, s21, 0
	s_add_u32 s67, s38, 0x100
	s_addc_u32 s68, s39, 0
	s_mov_b32 s69, -2
	ds_read_b128 v[128:131], v153
	ds_read_b128 v[132:135], v153 offset:1024
	ds_read_b128 v[136:139], v153 offset:2048
	ds_read_b128 v[140:143], v153 offset:3072
	ds_read_b128 v[172:175], v155
	ds_read_b128 v[176:179], v155 offset:1024
	ds_read_b128 v[180:183], v155 offset:2048
	ds_read_b128 v[184:187], v155 offset:3072
	s_add_u32 s38, s20, 0xfffc0080
	s_addc_u32 s39, s21, -1
	s_cmp_eq_u32 s69, 12
	s_cselect_b32 s45, s15, s39
	s_cselect_b32 s44, s65, s38
	s_cselect_b32 s39, s13, s68
	s_cselect_b32 s38, s66, s67
	s_add_i32 m0, s35, 0xc000
	ds_read_b128 v[188:191], v157
	ds_read_b128 v[192:195], v157 offset:1024
	ds_read_b128 v[198:201], v157 offset:2048
	ds_read_b128 v[202:205], v157 offset:3072
	ds_read_b128 v[206:209], v157 offset:4096
	ds_read_b128 v[210:213], v157 offset:5120
	ds_read_b128 v[214:217], v157 offset:6144
	ds_read_b128 v[218:221], v157 offset:7168
	global_load_lds_dwordx4 v162, s[20:21]
	s_add_i32 m0, s35, 0xe000
	s_nop 0
	global_load_lds_dwordx4 v164, s[20:21]
	s_waitcnt vmcnt(8)
	s_waitcnt lgkmcnt(0)
	s_barrier
	v_mfma_f32_16x16x32_bf16 v[124:127], v[128:131], v[188:191], 0
	v_mfma_f32_16x16x32_bf16 v[120:123], v[136:139], v[188:191], 0
	v_mfma_f32_16x16x32_bf16 v[108:111], v[128:131], v[198:201], 0
	v_mfma_f32_16x16x32_bf16 v[104:107], v[136:139], v[198:201], 0
	v_mfma_f32_16x16x32_bf16 v[96:99], v[128:131], v[206:209], 0
	v_mfma_f32_16x16x32_bf16 v[88:91], v[136:139], v[206:209], 0
	v_mfma_f32_16x16x32_bf16 v[80:83], v[128:131], v[214:217], 0
	v_mfma_f32_16x16x32_bf16 v[72:75], v[136:139], v[214:217], 0
	v_mfma_f32_16x16x32_bf16 v[124:127], v[132:135], v[192:195], v[124:127]
	v_mfma_f32_16x16x32_bf16 v[120:123], v[140:143], v[192:195], v[120:123]
	v_mfma_f32_16x16x32_bf16 v[108:111], v[132:135], v[202:205], v[108:111]
	v_mfma_f32_16x16x32_bf16 v[104:107], v[140:143], v[202:205], v[104:107]
	v_mfma_f32_16x16x32_bf16 v[96:99], v[132:135], v[210:213], v[96:99]
	v_mfma_f32_16x16x32_bf16 v[88:91], v[140:143], v[210:213], v[88:91]
	v_mfma_f32_16x16x32_bf16 v[80:83], v[132:135], v[218:221], v[80:83]
	v_mfma_f32_16x16x32_bf16 v[72:75], v[140:143], v[218:221], v[72:75]
	v_mfma_f32_16x16x32_bf16 v[116:119], v[172:175], v[188:191], 0
	v_mfma_f32_16x16x32_bf16 v[112:115], v[180:183], v[188:191], 0
	v_mfma_f32_16x16x32_bf16 v[100:103], v[172:175], v[198:201], 0
	v_mfma_f32_16x16x32_bf16 v[92:95], v[180:183], v[198:201], 0
	v_mfma_f32_16x16x32_bf16 v[84:87], v[172:175], v[206:209], 0
	v_mfma_f32_16x16x32_bf16 v[76:79], v[180:183], v[206:209], 0
	v_mfma_f32_16x16x32_bf16 v[68:71], v[172:175], v[214:217], 0
	v_mfma_f32_16x16x32_bf16 v[64:67], v[180:183], v[214:217], 0
	v_mfma_f32_16x16x32_bf16 v[116:119], v[176:179], v[192:195], v[116:119]
	v_mfma_f32_16x16x32_bf16 v[112:115], v[184:187], v[192:195], v[112:115]
	v_mfma_f32_16x16x32_bf16 v[100:103], v[176:179], v[202:205], v[100:103]
	v_mfma_f32_16x16x32_bf16 v[92:95], v[184:187], v[202:205], v[92:95]
	v_mfma_f32_16x16x32_bf16 v[84:87], v[176:179], v[210:213], v[84:87]
	v_mfma_f32_16x16x32_bf16 v[76:79], v[184:187], v[210:213], v[76:79]
	v_mfma_f32_16x16x32_bf16 v[68:71], v[176:179], v[218:221], v[68:71]
	v_mfma_f32_16x16x32_bf16 v[64:67], v[184:187], v[218:221], v[64:67]
	s_barrier
	s_add_i32 s70, s60, s51
	s_add_u32 s98, s38, s6
	s_addc_u32 s99, s39, s7
	s_add_u32 s100, s44, s6
	s_addc_u32 s101, s45, s7
	s_mov_b32 m0, s70
	ds_read_b128 v[188:191], v157 offset:16384
	ds_read_b128 v[192:195], v157 offset:17408
	ds_read_b128 v[198:201], v157 offset:18432
	ds_read_b128 v[202:205], v157 offset:19456
	ds_read_b128 v[206:209], v157 offset:20480
	ds_read_b128 v[210:213], v157 offset:21504
	ds_read_b128 v[214:217], v157 offset:22528
	ds_read_b128 v[218:221], v157 offset:23552
	global_load_lds_dwordx4 v146, s[38:39]
	s_add_i32 m0, s70, 0x2000
	s_add_u32 s70, s38, 0x40000
	s_addc_u32 s71, s39, 0
	s_add_i32 s72, s61, s51
	global_load_lds_dwordx4 v150, s[38:39]
	s_mov_b32 m0, s72
	s_nop 0
	global_load_lds_dwordx4 v146, s[70:71]
	s_add_i32 m0, s72, 0x2000
	s_nop 0
	global_load_lds_dwordx4 v150, s[70:71]
	s_mov_b32 m0, s35
	s_nop 0
	global_load_lds_dwordx4 v144, s[44:45]
	s_mov_b32 m0, s52
	s_nop 0
	global_load_lds_dwordx4 v148, s[44:45]
	s_waitcnt vmcnt(8)
	s_waitcnt lgkmcnt(0)
	s_barrier
; #define PG8_STAGE(bufoff, gbase, voff) do { _Pragma("unroll") for (int _i = 0; _i < 2; ++_i) \
;         __builtin_amdgcn_global_load_lds((const unsigned*)((const char*)(gbase) + (voff)[_i]), (PG8_LAS unsigned*)(lds + (bufoff) + ldsw + _i * 8192), 16, 0, 0); } while (0)
; #define PG8_LDA(dst, b, h) do { _Pragma("unroll") for (int m = 0; m < 4; ++m) _Pragma("unroll") for (int k = 0; k < 2; ++k) dst[m][k] = *(const PG8_LAS bf16x8*)(lds + PG8_SA(b, h) + aoff + m * 2048 + k * 1024); } while (0)
; #define PG8_LDB(dst, b, h) do { _Pragma("unroll") for (int n = 0; n < 2; ++n) _Pragma("unroll") for (int k = 0; k < 2; ++k) dst[n][k] = *(const PG8_LAS bf16x8*)(lds + PG8_SB(b, h) + boff + n * 2048 + k * 1024); } while (0)
; #define PG8_MMA(ai, bj, At, Bt) do { __builtin_amdgcn_s_setprio(1); _Pragma("unroll") for (int m = 0; m < 4; ++m) _Pragma("unroll") for (int n = 0; n < 2; ++n) _Pragma("unroll") for (int k = 0; k < 2; ++k) \
;         acc[ai][bj][m][n] = __builtin_amdgcn_mfma_f32_16x16x32_bf16(Bt[n][k], At[m][k], acc[ai][bj][m][n], 0, 0, 0); __builtin_amdgcn_s_setprio(0); } while (0)
; #define PG8_WAIT_V(n) asm volatile("s_waitcnt vmcnt(" #n ")" ::: "memory")
; #define PG8_WAIT_L(n) asm volatile("s_waitcnt lgkmcnt(" #n ")" ::: "memory")
; #define PG8_BAR __builtin_amdgcn_s_barrier()
; #define PG8_SCHED __builtin_amdgcn_sched_barrier(0)
; template <class Epi, class Sched, bool ALIGN_EPI = false, bool SP2 = false>
; __device__ __forceinline__ void gemm_phase(PG8_LAS unsigned char* lds, const Gemm g, const Sched& S, const Epi& E) {
;     ...
;             PG8_WAIT_V(8); PG8_WAIT_L(0); PG8_BAR; PG8_MMA(1, 0, At, B0); PG8_MMA(1, 1, At, B1); PG8_BAR; PG8_SCHED;
;             PG8_LDB(B0, 1, 0); PG8_LDB(B1, 1, 1); PG8_SCHED; PG8_LDA(At, 1, 0); PG8_STAGE(PG8_SA(0, 1), a2 + hstep, voffA);
;             PG8_WAIT_V(8); PG8_WAIT_L(0); PG8_BAR; PG8_MMA(0, 0, At, B0); PG8_MMA(0, 1, At, B1); PG8_BAR; PG8_SCHED;
	v_mfma_f32_16x16x32_bf16 v[60:63], v[128:131], v[188:191], 0
	v_mfma_f32_16x16x32_bf16 v[56:59], v[136:139], v[188:191], 0
	v_mfma_f32_16x16x32_bf16 v[48:51], v[128:131], v[198:201], 0
	v_mfma_f32_16x16x32_bf16 v[40:43], v[136:139], v[198:201], 0
	v_mfma_f32_16x16x32_bf16 v[32:35], v[128:131], v[206:209], 0
	v_mfma_f32_16x16x32_bf16 v[24:27], v[136:139], v[206:209], 0
	v_mfma_f32_16x16x32_bf16 v[16:19], v[128:131], v[214:217], 0
	v_mfma_f32_16x16x32_bf16 v[8:11], v[136:139], v[214:217], 0
	v_mfma_f32_16x16x32_bf16 v[60:63], v[132:135], v[192:195], v[60:63]
	v_mfma_f32_16x16x32_bf16 v[56:59], v[140:143], v[192:195], v[56:59]
	v_mfma_f32_16x16x32_bf16 v[48:51], v[132:135], v[202:205], v[48:51]
	v_mfma_f32_16x16x32_bf16 v[40:43], v[140:143], v[202:205], v[40:43]
	v_mfma_f32_16x16x32_bf16 v[32:35], v[132:135], v[210:213], v[32:35]
	v_mfma_f32_16x16x32_bf16 v[24:27], v[140:143], v[210:213], v[24:27]
	v_mfma_f32_16x16x32_bf16 v[16:19], v[132:135], v[218:221], v[16:19]
	v_mfma_f32_16x16x32_bf16 v[8:11], v[140:143], v[218:221], v[8:11]
	v_mfma_f32_16x16x32_bf16 v[52:55], v[172:175], v[188:191], 0
	v_mfma_f32_16x16x32_bf16 v[44:47], v[180:183], v[188:191], 0
	v_mfma_f32_16x16x32_bf16 v[36:39], v[172:175], v[198:201], 0
	v_mfma_f32_16x16x32_bf16 v[28:31], v[180:183], v[198:201], 0
	v_mfma_f32_16x16x32_bf16 v[20:23], v[172:175], v[206:209], 0
	v_mfma_f32_16x16x32_bf16 v[12:15], v[180:183], v[206:209], 0
	v_mfma_f32_16x16x32_bf16 v[4:7], v[172:175], v[214:217], 0
	v_mfma_f32_16x16x32_bf16 v[0:3], v[180:183], v[214:217], 0
	v_mfma_f32_16x16x32_bf16 v[52:55], v[176:179], v[192:195], v[52:55]
	v_mfma_f32_16x16x32_bf16 v[44:47], v[184:187], v[192:195], v[44:47]
	v_mfma_f32_16x16x32_bf16 v[36:39], v[176:179], v[202:205], v[36:39]
	v_mfma_f32_16x16x32_bf16 v[28:31], v[184:187], v[202:205], v[28:31]
	v_mfma_f32_16x16x32_bf16 v[20:23], v[176:179], v[210:213], v[20:23]
	v_mfma_f32_16x16x32_bf16 v[12:15], v[184:187], v[210:213], v[12:15]
	v_mfma_f32_16x16x32_bf16 v[4:7], v[176:179], v[218:221], v[4:7]
	v_mfma_f32_16x16x32_bf16 v[0:3], v[184:187], v[218:221], v[0:3]
	s_barrier
	s_add_i32 s70, 0, 0x18000
	s_add_i32 s71, 0, 0x1c000
	v_add_u32_e32 v140, s70, v170
	v_add_u32_e32 v159, s71, v170
	ds_read_b128 v[128:131], v140
	ds_read_b128 v[132:135], v140 offset:1024
	ds_read_b128 v[136:139], v140 offset:2048
	ds_read_b128 v[140:143], v140 offset:3072
	ds_read_b128 v[172:175], v159
	ds_read_b128 v[176:179], v159 offset:1024
	ds_read_b128 v[180:183], v159 offset:2048
	ds_read_b128 v[184:187], v159 offset:3072
	s_add_u32 s44, s44, 0x40000
	s_addc_u32 s45, s45, 0
	s_mov_b32 m0, s53
	ds_read_b128 v[188:191], v157 offset:32768
	ds_read_b128 v[192:195], v157 offset:33792
	ds_read_b128 v[198:201], v157 offset:34816
	ds_read_b128 v[202:205], v157 offset:35840
	ds_read_b128 v[206:209], v157 offset:36864
	ds_read_b128 v[210:213], v157 offset:37888
	ds_read_b128 v[214:217], v157 offset:38912
	ds_read_b128 v[218:221], v157 offset:39936
	global_load_lds_dwordx4 v144, s[44:45]
	s_mov_b32 m0, s54
	s_nop 0
	global_load_lds_dwordx4 v148, s[44:45]
	s_waitcnt vmcnt(8)
	s_waitcnt lgkmcnt(0)
	s_barrier
	v_mfma_f32_16x16x32_bf16 v[124:127], v[128:131], v[188:191], v[124:127]
	v_mfma_f32_16x16x32_bf16 v[120:123], v[136:139], v[188:191], v[120:123]
	v_mfma_f32_16x16x32_bf16 v[108:111], v[128:131], v[198:201], v[108:111]
	v_mfma_f32_16x16x32_bf16 v[104:107], v[136:139], v[198:201], v[104:107]
	v_mfma_f32_16x16x32_bf16 v[96:99], v[128:131], v[206:209], v[96:99]
	v_mfma_f32_16x16x32_bf16 v[88:91], v[136:139], v[206:209], v[88:91]
	v_mfma_f32_16x16x32_bf16 v[80:83], v[128:131], v[214:217], v[80:83]
	v_mfma_f32_16x16x32_bf16 v[72:75], v[136:139], v[214:217], v[72:75]
	v_mfma_f32_16x16x32_bf16 v[124:127], v[132:135], v[192:195], v[124:127]
	v_mfma_f32_16x16x32_bf16 v[120:123], v[140:143], v[192:195], v[120:123]
	v_mfma_f32_16x16x32_bf16 v[108:111], v[132:135], v[202:205], v[108:111]
	v_mfma_f32_16x16x32_bf16 v[104:107], v[140:143], v[202:205], v[104:107]
	v_mfma_f32_16x16x32_bf16 v[96:99], v[132:135], v[210:213], v[96:99]
	v_mfma_f32_16x16x32_bf16 v[88:91], v[140:143], v[210:213], v[88:91]
	v_mfma_f32_16x16x32_bf16 v[80:83], v[132:135], v[218:221], v[80:83]
	v_mfma_f32_16x16x32_bf16 v[72:75], v[140:143], v[218:221], v[72:75]
	v_mfma_f32_16x16x32_bf16 v[116:119], v[172:175], v[188:191], v[116:119]
	v_mfma_f32_16x16x32_bf16 v[112:115], v[180:183], v[188:191], v[112:115]
	v_mfma_f32_16x16x32_bf16 v[100:103], v[172:175], v[198:201], v[100:103]
	v_mfma_f32_16x16x32_bf16 v[92:95], v[180:183], v[198:201], v[92:95]
	v_mfma_f32_16x16x32_bf16 v[84:87], v[172:175], v[206:209], v[84:87]
	v_mfma_f32_16x16x32_bf16 v[76:79], v[180:183], v[206:209], v[76:79]
	v_mfma_f32_16x16x32_bf16 v[68:71], v[172:175], v[214:217], v[68:71]
	v_mfma_f32_16x16x32_bf16 v[64:67], v[180:183], v[214:217], v[64:67]
	v_mfma_f32_16x16x32_bf16 v[116:119], v[176:179], v[192:195], v[116:119]
	v_mfma_f32_16x16x32_bf16 v[112:115], v[184:187], v[192:195], v[112:115]
	v_mfma_f32_16x16x32_bf16 v[100:103], v[176:179], v[202:205], v[100:103]
	v_mfma_f32_16x16x32_bf16 v[92:95], v[184:187], v[202:205], v[92:95]
	v_mfma_f32_16x16x32_bf16 v[84:87], v[176:179], v[210:213], v[84:87]
	v_mfma_f32_16x16x32_bf16 v[76:79], v[184:187], v[210:213], v[76:79]
	v_mfma_f32_16x16x32_bf16 v[68:71], v[176:179], v[218:221], v[68:71]
	v_mfma_f32_16x16x32_bf16 v[64:67], v[184:187], v[218:221], v[64:67]
	s_barrier
; #define PG8_STAGE(bufoff, gbase, voff) do { _Pragma("unroll") for (int _i = 0; _i < 2; ++_i) \
;         __builtin_amdgcn_global_load_lds((const unsigned*)((const char*)(gbase) + (voff)[_i]), (PG8_LAS unsigned*)(lds + (bufoff) + ldsw + _i * 8192), 16, 0, 0); } while (0)
; #define PG8_LDA(dst, b, h) do { _Pragma("unroll") for (int m = 0; m < 4; ++m) _Pragma("unroll") for (int k = 0; k < 2; ++k) dst[m][k] = *(const PG8_LAS bf16x8*)(lds + PG8_SA(b, h) + aoff + m * 2048 + k * 1024); } while (0)
; #define PG8_LDB(dst, b, h) do { _Pragma("unroll") for (int n = 0; n < 2; ++n) _Pragma("unroll") for (int k = 0; k < 2; ++k) dst[n][k] = *(const PG8_LAS bf16x8*)(lds + PG8_SB(b, h) + boff + n * 2048 + k * 1024); } while (0)
; #define PG8_MMA(ai, bj, At, Bt) do { __builtin_amdgcn_s_setprio(1); _Pragma("unroll") for (int m = 0; m < 4; ++m) _Pragma("unroll") for (int n = 0; n < 2; ++n) _Pragma("unroll") for (int k = 0; k < 2; ++k) \
;         acc[ai][bj][m][n] = __builtin_amdgcn_mfma_f32_16x16x32_bf16(Bt[n][k], At[m][k], acc[ai][bj][m][n], 0, 0, 0); __builtin_amdgcn_s_setprio(0); } while (0)
; #define PG8_WAIT_V(n) asm volatile("s_waitcnt vmcnt(" #n ")" ::: "memory")
; #define PG8_WAIT_L(n) asm volatile("s_waitcnt lgkmcnt(" #n ")" ::: "memory")
; #define PG8_BAR __builtin_amdgcn_s_barrier()
; #define PG8_SCHED __builtin_amdgcn_sched_barrier(0)
; template <class Epi, class Sched, bool ALIGN_EPI = false, bool SP2 = false>
; __device__ __forceinline__ void gemm_phase(PG8_LAS unsigned char* lds, const Gemm g, const Sched& S, const Epi& E) {
;     ...
;             PG8_LDB(B0, 0, 0); PG8_LDB(B1, 0, 1); PG8_SCHED; PG8_LDA(At, 0, 0); PG8_STAGE(PG8_SA(1, 1), a1 + hstep, voffA);
;             PG8_WAIT_V(8); PG8_WAIT_L(0); PG8_BAR; PG8_MMA(0, 0, At, B0); PG8_MMA(0, 1, At, B1); PG8_BAR; PG8_SCHED;
;     ...
;             PG8_LDA(At, 1, 1); PG8_STAGE(PG8_SB(1, 0), b3, voffB); PG8_STAGE(PG8_SB(1, 1), b3 + hstep, voffB); PG8_STAGE(PG8_SA(1, 0), a3, voffA);
;             PG8_WAIT_V(8); PG8_WAIT_L(0); PG8_BAR; PG8_MMA(1, 0, At, B0); PG8_MMA(1, 1, At, B1); PG8_BAR; PG8_SCHED;
	s_add_i32 s44, s70, s51
	s_mov_b32 m0, s44
	ds_read_b128 v[188:191], v157 offset:49152
	ds_read_b128 v[192:195], v157 offset:50176
	ds_read_b128 v[198:201], v157 offset:51200
	ds_read_b128 v[202:205], v157 offset:52224
	ds_read_b128 v[206:209], v157 offset:53248
	ds_read_b128 v[210:213], v157 offset:54272
	ds_read_b128 v[214:217], v157 offset:55296
	ds_read_b128 v[218:221], v157 offset:56320
	global_load_lds_dwordx4 v146, s[98:99]
	s_add_i32 m0, s44, 0x2000
	s_add_u32 s38, s38, 0x40080
	s_addc_u32 s39, s39, 0
	s_add_i32 s44, s71, s51
	global_load_lds_dwordx4 v150, s[98:99]
	s_mov_b32 m0, s44
	s_nop 0
	global_load_lds_dwordx4 v146, s[38:39]
	s_add_i32 m0, s44, 0x2000
	s_nop 0
	global_load_lds_dwordx4 v150, s[38:39]
	s_mov_b32 m0, s58
	s_nop 0
	global_load_lds_dwordx4 v144, s[100:101]
	s_mov_b32 m0, s59
	s_nop 0
	global_load_lds_dwordx4 v148, s[100:101]
	s_waitcnt vmcnt(8)
	s_waitcnt lgkmcnt(0)
	s_barrier
	v_mfma_f32_16x16x32_bf16 v[60:63], v[128:131], v[188:191], v[60:63]
	v_mfma_f32_16x16x32_bf16 v[56:59], v[136:139], v[188:191], v[56:59]
	v_mfma_f32_16x16x32_bf16 v[48:51], v[128:131], v[198:201], v[48:51]
	v_mfma_f32_16x16x32_bf16 v[40:43], v[136:139], v[198:201], v[40:43]
	v_mfma_f32_16x16x32_bf16 v[32:35], v[128:131], v[206:209], v[32:35]
	v_mfma_f32_16x16x32_bf16 v[24:27], v[136:139], v[206:209], v[24:27]
	v_mfma_f32_16x16x32_bf16 v[16:19], v[128:131], v[214:217], v[16:19]
	v_mfma_f32_16x16x32_bf16 v[8:11], v[136:139], v[214:217], v[8:11]
	v_mfma_f32_16x16x32_bf16 v[60:63], v[132:135], v[192:195], v[60:63]
	v_mfma_f32_16x16x32_bf16 v[56:59], v[140:143], v[192:195], v[56:59]
	v_mfma_f32_16x16x32_bf16 v[48:51], v[132:135], v[202:205], v[48:51]
	v_mfma_f32_16x16x32_bf16 v[40:43], v[140:143], v[202:205], v[40:43]
	v_mfma_f32_16x16x32_bf16 v[32:35], v[132:135], v[210:213], v[32:35]
	v_mfma_f32_16x16x32_bf16 v[24:27], v[140:143], v[210:213], v[24:27]
	v_mfma_f32_16x16x32_bf16 v[16:19], v[132:135], v[218:221], v[16:19]
	v_mfma_f32_16x16x32_bf16 v[8:11], v[140:143], v[218:221], v[8:11]
	v_mfma_f32_16x16x32_bf16 v[52:55], v[172:175], v[188:191], v[52:55]
	v_mfma_f32_16x16x32_bf16 v[44:47], v[180:183], v[188:191], v[44:47]
	v_mfma_f32_16x16x32_bf16 v[36:39], v[172:175], v[198:201], v[36:39]
	v_mfma_f32_16x16x32_bf16 v[28:31], v[180:183], v[198:201], v[28:31]
	v_mfma_f32_16x16x32_bf16 v[20:23], v[172:175], v[206:209], v[20:23]
	v_mfma_f32_16x16x32_bf16 v[12:15], v[180:183], v[206:209], v[12:15]
	v_mfma_f32_16x16x32_bf16 v[4:7], v[172:175], v[214:217], v[4:7]
	v_mfma_f32_16x16x32_bf16 v[0:3], v[180:183], v[214:217], v[0:3]
	v_mfma_f32_16x16x32_bf16 v[52:55], v[176:179], v[192:195], v[52:55]
	v_mfma_f32_16x16x32_bf16 v[44:47], v[184:187], v[192:195], v[44:47]
	v_mfma_f32_16x16x32_bf16 v[36:39], v[176:179], v[202:205], v[36:39]
	v_mfma_f32_16x16x32_bf16 v[28:31], v[184:187], v[202:205], v[28:31]
	v_mfma_f32_16x16x32_bf16 v[20:23], v[176:179], v[210:213], v[20:23]
	v_mfma_f32_16x16x32_bf16 v[12:15], v[184:187], v[210:213], v[12:15]
	v_mfma_f32_16x16x32_bf16 v[4:7], v[176:179], v[218:221], v[4:7]
	v_mfma_f32_16x16x32_bf16 v[0:3], v[184:187], v[218:221], v[0:3]
	s_barrier
	s_add_i32 s69, s69, 2
	s_add_u32 s20, s20, 0x100
	s_addc_u32 s21, s21, 0
	s_add_u32 s67, s67, 0x100
	s_addc_u32 s68, s68, 0
	s_cmp_gt_u32 s69, 13
.LBB0_1446:
	ds_read_b128 v[128:131], v153
	ds_read_b128 v[132:135], v153 offset:1024
	ds_read_b128 v[136:139], v153 offset:2048
	ds_read_b128 v[140:143], v153 offset:3072
	ds_read_b128 v[172:175], v155
	ds_read_b128 v[176:179], v155 offset:1024
	ds_read_b128 v[180:183], v155 offset:2048
	ds_read_b128 v[184:187], v155 offset:3072
	s_add_u32 s38, s20, 0xfffc0080
	s_addc_u32 s39, s21, -1
	s_cmp_eq_u32 s69, 12
	s_cselect_b32 s45, s15, s39
	s_cselect_b32 s44, s65, s38
	s_cselect_b32 s39, s13, s68
	s_cselect_b32 s38, s66, s67
	s_add_i32 m0, s35, 0xc000
	ds_read_b128 v[188:191], v157
	ds_read_b128 v[192:195], v157 offset:1024
	ds_read_b128 v[198:201], v157 offset:2048
	ds_read_b128 v[202:205], v157 offset:3072
	ds_read_b128 v[206:209], v157 offset:4096
	ds_read_b128 v[210:213], v157 offset:5120
	ds_read_b128 v[214:217], v157 offset:6144
	ds_read_b128 v[218:221], v157 offset:7168
	global_load_lds_dwordx4 v162, s[20:21]
	s_add_i32 m0, s35, 0xe000
	s_nop 0
	global_load_lds_dwordx4 v164, s[20:21]
	s_waitcnt vmcnt(8)
	s_waitcnt lgkmcnt(0)
	s_barrier
	v_mfma_f32_16x16x32_bf16 v[124:127], v[128:131], v[188:191], v[124:127]
	v_mfma_f32_16x16x32_bf16 v[120:123], v[136:139], v[188:191], v[120:123]
	v_mfma_f32_16x16x32_bf16 v[108:111], v[128:131], v[198:201], v[108:111]
	v_mfma_f32_16x16x32_bf16 v[104:107], v[136:139], v[198:201], v[104:107]
	v_mfma_f32_16x16x32_bf16 v[96:99], v[128:131], v[206:209], v[96:99]
	v_mfma_f32_16x16x32_bf16 v[88:91], v[136:139], v[206:209], v[88:91]
	v_mfma_f32_16x16x32_bf16 v[80:83], v[128:131], v[214:217], v[80:83]
	v_mfma_f32_16x16x32_bf16 v[72:75], v[136:139], v[214:217], v[72:75]
	v_mfma_f32_16x16x32_bf16 v[124:127], v[132:135], v[192:195], v[124:127]
	v_mfma_f32_16x16x32_bf16 v[120:123], v[140:143], v[192:195], v[120:123]
	v_mfma_f32_16x16x32_bf16 v[108:111], v[132:135], v[202:205], v[108:111]
	v_mfma_f32_16x16x32_bf16 v[104:107], v[140:143], v[202:205], v[104:107]
	v_mfma_f32_16x16x32_bf16 v[96:99], v[132:135], v[210:213], v[96:99]
	v_mfma_f32_16x16x32_bf16 v[88:91], v[140:143], v[210:213], v[88:91]
	v_mfma_f32_16x16x32_bf16 v[80:83], v[132:135], v[218:221], v[80:83]
	v_mfma_f32_16x16x32_bf16 v[72:75], v[140:143], v[218:221], v[72:75]
	v_mfma_f32_16x16x32_bf16 v[116:119], v[172:175], v[188:191], v[116:119]
	v_mfma_f32_16x16x32_bf16 v[112:115], v[180:183], v[188:191], v[112:115]
	v_mfma_f32_16x16x32_bf16 v[100:103], v[172:175], v[198:201], v[100:103]
	v_mfma_f32_16x16x32_bf16 v[92:95], v[180:183], v[198:201], v[92:95]
	v_mfma_f32_16x16x32_bf16 v[84:87], v[172:175], v[206:209], v[84:87]
	v_mfma_f32_16x16x32_bf16 v[76:79], v[180:183], v[206:209], v[76:79]
	v_mfma_f32_16x16x32_bf16 v[68:71], v[172:175], v[214:217], v[68:71]
	v_mfma_f32_16x16x32_bf16 v[64:67], v[180:183], v[214:217], v[64:67]
	v_mfma_f32_16x16x32_bf16 v[116:119], v[176:179], v[192:195], v[116:119]
	v_mfma_f32_16x16x32_bf16 v[112:115], v[184:187], v[192:195], v[112:115]
	v_mfma_f32_16x16x32_bf16 v[100:103], v[176:179], v[202:205], v[100:103]
	v_mfma_f32_16x16x32_bf16 v[92:95], v[184:187], v[202:205], v[92:95]
	v_mfma_f32_16x16x32_bf16 v[84:87], v[176:179], v[210:213], v[84:87]
	v_mfma_f32_16x16x32_bf16 v[76:79], v[184:187], v[210:213], v[76:79]
	v_mfma_f32_16x16x32_bf16 v[68:71], v[176:179], v[218:221], v[68:71]
	v_mfma_f32_16x16x32_bf16 v[64:67], v[184:187], v[218:221], v[64:67]
	s_barrier
; #define PG8_STAGE(bufoff, gbase, voff) do { _Pragma("unroll") for (int _i = 0; _i < 2; ++_i) \
;         __builtin_amdgcn_global_load_lds((const unsigned*)((const char*)(gbase) + (voff)[_i]), (PG8_LAS unsigned*)(lds + (bufoff) + ldsw + _i * 8192), 16, 0, 0); } while (0)
; #define PG8_LDA(dst, b, h) do { _Pragma("unroll") for (int m = 0; m < 4; ++m) _Pragma("unroll") for (int k = 0; k < 2; ++k) dst[m][k] = *(const PG8_LAS bf16x8*)(lds + PG8_SA(b, h) + aoff + m * 2048 + k * 1024); } while (0)
; #define PG8_LDB(dst, b, h) do { _Pragma("unroll") for (int n = 0; n < 2; ++n) _Pragma("unroll") for (int k = 0; k < 2; ++k) dst[n][k] = *(const PG8_LAS bf16x8*)(lds + PG8_SB(b, h) + boff + n * 2048 + k * 1024); } while (0)
; #define PG8_MMA(ai, bj, At, Bt) do { __builtin_amdgcn_s_setprio(1); _Pragma("unroll") for (int m = 0; m < 4; ++m) _Pragma("unroll") for (int n = 0; n < 2; ++n) _Pragma("unroll") for (int k = 0; k < 2; ++k) \
;         acc[ai][bj][m][n] = __builtin_amdgcn_mfma_f32_16x16x32_bf16(Bt[n][k], At[m][k], acc[ai][bj][m][n], 0, 0, 0); __builtin_amdgcn_s_setprio(0); } while (0)
; #define PG8_WAIT_V(n) asm volatile("s_waitcnt vmcnt(" #n ")" ::: "memory")
; #define PG8_WAIT_L(n) asm volatile("s_waitcnt lgkmcnt(" #n ")" ::: "memory")
; #define PG8_BAR __builtin_amdgcn_s_barrier()
; #define PG8_SCHED __builtin_amdgcn_sched_barrier(0)
; template <class Epi, class Sched, bool ALIGN_EPI = false, bool SP2 = false>
; __device__ __forceinline__ void gemm_phase(PG8_LAS unsigned char* lds, const Gemm g, const Sched& S, const Epi& E) {
;     ...
;             PG8_WAIT_V(8); PG8_WAIT_L(0); PG8_BAR; PG8_MMA(0, 0, At, B0); PG8_MMA(0, 1, At, B1); PG8_BAR; PG8_SCHED;
;             PG8_LDA(At, 0, 1); PG8_STAGE(PG8_SB(0, 0), b2, voffB); PG8_STAGE(PG8_SB(0, 1), b2 + hstep, voffB); PG8_STAGE(PG8_SA(0, 0), a2, voffA);
;             PG8_WAIT_V(8); PG8_WAIT_L(0); PG8_BAR; PG8_MMA(1, 0, At, B0); PG8_MMA(1, 1, At, B1); PG8_BAR; PG8_SCHED;
;             PG8_LDB(B0, 1, 0); PG8_LDB(B1, 1, 1); PG8_SCHED; PG8_LDA(At, 1, 0); PG8_STAGE(PG8_SA(0, 1), a2 + hstep, voffA);
	s_add_i32 s70, s60, s51
	s_add_u32 s98, s38, s6
	s_addc_u32 s99, s39, s7
	s_add_u32 s100, s44, s6
	s_addc_u32 s101, s45, s7
	s_mov_b32 m0, s70
	ds_read_b128 v[188:191], v157 offset:16384
	ds_read_b128 v[192:195], v157 offset:17408
	ds_read_b128 v[198:201], v157 offset:18432
	ds_read_b128 v[202:205], v157 offset:19456
	ds_read_b128 v[206:209], v157 offset:20480
	ds_read_b128 v[210:213], v157 offset:21504
	ds_read_b128 v[214:217], v157 offset:22528
	ds_read_b128 v[218:221], v157 offset:23552
	global_load_lds_dwordx4 v146, s[38:39]
	s_add_i32 m0, s70, 0x2000
	s_add_u32 s70, s38, 0x40000
	s_addc_u32 s71, s39, 0
	s_add_i32 s72, s61, s51
	global_load_lds_dwordx4 v150, s[38:39]
	s_mov_b32 m0, s72
	s_nop 0
	global_load_lds_dwordx4 v146, s[70:71]
	s_add_i32 m0, s72, 0x2000
	s_nop 0
	global_load_lds_dwordx4 v150, s[70:71]
	s_mov_b32 m0, s35
	s_nop 0
	global_load_lds_dwordx4 v144, s[44:45]
	s_mov_b32 m0, s52
	s_nop 0
	global_load_lds_dwordx4 v148, s[44:45]
	s_waitcnt vmcnt(8)
	s_waitcnt lgkmcnt(0)
	s_barrier
	v_mfma_f32_16x16x32_bf16 v[60:63], v[128:131], v[188:191], v[60:63]
	v_mfma_f32_16x16x32_bf16 v[56:59], v[136:139], v[188:191], v[56:59]
	v_mfma_f32_16x16x32_bf16 v[48:51], v[128:131], v[198:201], v[48:51]
	v_mfma_f32_16x16x32_bf16 v[40:43], v[136:139], v[198:201], v[40:43]
	v_mfma_f32_16x16x32_bf16 v[32:35], v[128:131], v[206:209], v[32:35]
	v_mfma_f32_16x16x32_bf16 v[24:27], v[136:139], v[206:209], v[24:27]
	v_mfma_f32_16x16x32_bf16 v[16:19], v[128:131], v[214:217], v[16:19]
	v_mfma_f32_16x16x32_bf16 v[8:11], v[136:139], v[214:217], v[8:11]
	v_mfma_f32_16x16x32_bf16 v[60:63], v[132:135], v[192:195], v[60:63]
	v_mfma_f32_16x16x32_bf16 v[56:59], v[140:143], v[192:195], v[56:59]
	v_mfma_f32_16x16x32_bf16 v[48:51], v[132:135], v[202:205], v[48:51]
	v_mfma_f32_16x16x32_bf16 v[40:43], v[140:143], v[202:205], v[40:43]
	v_mfma_f32_16x16x32_bf16 v[32:35], v[132:135], v[210:213], v[32:35]
	v_mfma_f32_16x16x32_bf16 v[24:27], v[140:143], v[210:213], v[24:27]
	v_mfma_f32_16x16x32_bf16 v[16:19], v[132:135], v[218:221], v[16:19]
	v_mfma_f32_16x16x32_bf16 v[8:11], v[140:143], v[218:221], v[8:11]
	v_mfma_f32_16x16x32_bf16 v[52:55], v[172:175], v[188:191], v[52:55]
	v_mfma_f32_16x16x32_bf16 v[44:47], v[180:183], v[188:191], v[44:47]
	v_mfma_f32_16x16x32_bf16 v[36:39], v[172:175], v[198:201], v[36:39]
	v_mfma_f32_16x16x32_bf16 v[28:31], v[180:183], v[198:201], v[28:31]
	v_mfma_f32_16x16x32_bf16 v[20:23], v[172:175], v[206:209], v[20:23]
	v_mfma_f32_16x16x32_bf16 v[12:15], v[180:183], v[206:209], v[12:15]
	v_mfma_f32_16x16x32_bf16 v[4:7], v[172:175], v[214:217], v[4:7]
	v_mfma_f32_16x16x32_bf16 v[0:3], v[180:183], v[214:217], v[0:3]
	v_mfma_f32_16x16x32_bf16 v[52:55], v[176:179], v[192:195], v[52:55]
	v_mfma_f32_16x16x32_bf16 v[44:47], v[184:187], v[192:195], v[44:47]
	v_mfma_f32_16x16x32_bf16 v[36:39], v[176:179], v[202:205], v[36:39]
	v_mfma_f32_16x16x32_bf16 v[28:31], v[184:187], v[202:205], v[28:31]
	v_mfma_f32_16x16x32_bf16 v[20:23], v[176:179], v[210:213], v[20:23]
	v_mfma_f32_16x16x32_bf16 v[12:15], v[184:187], v[210:213], v[12:15]
	v_mfma_f32_16x16x32_bf16 v[4:7], v[176:179], v[218:221], v[4:7]
	v_mfma_f32_16x16x32_bf16 v[0:3], v[184:187], v[218:221], v[0:3]
	s_barrier
	s_add_i32 s70, 0, 0x18000
	s_add_i32 s71, 0, 0x1c000
	v_add_u32_e32 v140, s70, v170
	v_add_u32_e32 v159, s71, v170
	ds_read_b128 v[128:131], v140
	ds_read_b128 v[132:135], v140 offset:1024
	ds_read_b128 v[136:139], v140 offset:2048
	ds_read_b128 v[140:143], v140 offset:3072
	ds_read_b128 v[172:175], v159
	ds_read_b128 v[176:179], v159 offset:1024
	ds_read_b128 v[180:183], v159 offset:2048
	ds_read_b128 v[184:187], v159 offset:3072
	s_add_u32 s44, s44, 0x40000
	s_addc_u32 s45, s45, 0
	s_mov_b32 m0, s53
	ds_read_b128 v[188:191], v157 offset:32768
	ds_read_b128 v[192:195], v157 offset:33792
	ds_read_b128 v[198:201], v157 offset:34816
	ds_read_b128 v[202:205], v157 offset:35840
	ds_read_b128 v[206:209], v157 offset:36864
	ds_read_b128 v[210:213], v157 offset:37888
	ds_read_b128 v[214:217], v157 offset:38912
	ds_read_b128 v[218:221], v157 offset:39936
	global_load_lds_dwordx4 v144, s[44:45]
	s_mov_b32 m0, s54
	s_nop 0
	global_load_lds_dwordx4 v148, s[44:45]
	s_waitcnt vmcnt(8)
	s_waitcnt lgkmcnt(0)
	s_barrier
; #define PG8_STAGE(bufoff, gbase, voff) do { _Pragma("unroll") for (int _i = 0; _i < 2; ++_i) \
;         __builtin_amdgcn_global_load_lds((const unsigned*)((const char*)(gbase) + (voff)[_i]), (PG8_LAS unsigned*)(lds + (bufoff) + ldsw + _i * 8192), 16, 0, 0); } while (0)
; #define PG8_LDA(dst, b, h) do { _Pragma("unroll") for (int m = 0; m < 4; ++m) _Pragma("unroll") for (int k = 0; k < 2; ++k) dst[m][k] = *(const PG8_LAS bf16x8*)(lds + PG8_SA(b, h) + aoff + m * 2048 + k * 1024); } while (0)
; #define PG8_MMA(ai, bj, At, Bt) do { __builtin_amdgcn_s_setprio(1); _Pragma("unroll") for (int m = 0; m < 4; ++m) _Pragma("unroll") for (int n = 0; n < 2; ++n) _Pragma("unroll") for (int k = 0; k < 2; ++k) \
;         acc[ai][bj][m][n] = __builtin_amdgcn_mfma_f32_16x16x32_bf16(Bt[n][k], At[m][k], acc[ai][bj][m][n], 0, 0, 0); __builtin_amdgcn_s_setprio(0); } while (0)
; #define PG8_WAIT_V(n) asm volatile("s_waitcnt vmcnt(" #n ")" ::: "memory")
; #define PG8_WAIT_L(n) asm volatile("s_waitcnt lgkmcnt(" #n ")" ::: "memory")
; #define PG8_BAR __builtin_amdgcn_s_barrier()
; #define PG8_SCHED __builtin_amdgcn_sched_barrier(0)
; template <class Epi, class Sched, bool ALIGN_EPI = false, bool SP2 = false>
; __device__ __forceinline__ void gemm_phase(PG8_LAS unsigned char* lds, const Gemm g, const Sched& S, const Epi& E) {
;     ...
;             PG8_WAIT_V(8); PG8_WAIT_L(0); PG8_BAR; PG8_MMA(0, 0, At, B0); PG8_MMA(0, 1, At, B1); PG8_BAR; PG8_SCHED;
;             PG8_LDA(At, 1, 1); PG8_STAGE(PG8_SB(1, 0), b3, voffB); PG8_STAGE(PG8_SB(1, 1), b3 + hstep, voffB); PG8_STAGE(PG8_SA(1, 0), a3, voffA);
;             PG8_WAIT_V(8); PG8_WAIT_L(0); PG8_BAR; PG8_MMA(1, 0, At, B0); PG8_MMA(1, 1, At, B1); PG8_BAR; PG8_SCHED;
;     ...
;         if constexpr (ALIGN_EPI) { if (wr == 0) PG8_BAR; }
	v_mfma_f32_16x16x32_bf16 v[124:127], v[128:131], v[188:191], v[124:127]
	v_mfma_f32_16x16x32_bf16 v[120:123], v[136:139], v[188:191], v[120:123]
	v_mfma_f32_16x16x32_bf16 v[108:111], v[128:131], v[198:201], v[108:111]
	v_mfma_f32_16x16x32_bf16 v[104:107], v[136:139], v[198:201], v[104:107]
	v_mfma_f32_16x16x32_bf16 v[96:99], v[128:131], v[206:209], v[96:99]
	v_mfma_f32_16x16x32_bf16 v[88:91], v[136:139], v[206:209], v[88:91]
	v_mfma_f32_16x16x32_bf16 v[80:83], v[128:131], v[214:217], v[80:83]
	v_mfma_f32_16x16x32_bf16 v[72:75], v[136:139], v[214:217], v[72:75]
	v_mfma_f32_16x16x32_bf16 v[124:127], v[132:135], v[192:195], v[124:127]
	v_mfma_f32_16x16x32_bf16 v[120:123], v[140:143], v[192:195], v[120:123]
	v_mfma_f32_16x16x32_bf16 v[108:111], v[132:135], v[202:205], v[108:111]
	v_mfma_f32_16x16x32_bf16 v[104:107], v[140:143], v[202:205], v[104:107]
	v_mfma_f32_16x16x32_bf16 v[96:99], v[132:135], v[210:213], v[96:99]
	v_mfma_f32_16x16x32_bf16 v[88:91], v[140:143], v[210:213], v[88:91]
	v_mfma_f32_16x16x32_bf16 v[80:83], v[132:135], v[218:221], v[80:83]
	v_mfma_f32_16x16x32_bf16 v[72:75], v[140:143], v[218:221], v[72:75]
	v_mfma_f32_16x16x32_bf16 v[116:119], v[172:175], v[188:191], v[116:119]
	v_mfma_f32_16x16x32_bf16 v[112:115], v[180:183], v[188:191], v[112:115]
	v_mfma_f32_16x16x32_bf16 v[100:103], v[172:175], v[198:201], v[100:103]
	v_mfma_f32_16x16x32_bf16 v[92:95], v[180:183], v[198:201], v[92:95]
	v_mfma_f32_16x16x32_bf16 v[84:87], v[172:175], v[206:209], v[84:87]
	v_mfma_f32_16x16x32_bf16 v[76:79], v[180:183], v[206:209], v[76:79]
	v_mfma_f32_16x16x32_bf16 v[68:71], v[172:175], v[214:217], v[68:71]
	v_mfma_f32_16x16x32_bf16 v[64:67], v[180:183], v[214:217], v[64:67]
	v_mfma_f32_16x16x32_bf16 v[116:119], v[176:179], v[192:195], v[116:119]
	v_mfma_f32_16x16x32_bf16 v[112:115], v[184:187], v[192:195], v[112:115]
	v_mfma_f32_16x16x32_bf16 v[100:103], v[176:179], v[202:205], v[100:103]
	v_mfma_f32_16x16x32_bf16 v[92:95], v[184:187], v[202:205], v[92:95]
	v_mfma_f32_16x16x32_bf16 v[84:87], v[176:179], v[210:213], v[84:87]
	v_mfma_f32_16x16x32_bf16 v[76:79], v[184:187], v[210:213], v[76:79]
	v_mfma_f32_16x16x32_bf16 v[68:71], v[176:179], v[218:221], v[68:71]
	v_mfma_f32_16x16x32_bf16 v[64:67], v[184:187], v[218:221], v[64:67]
	s_barrier
	s_add_i32 s44, s70, s51
	s_mov_b32 m0, s44
	ds_read_b128 v[188:191], v157 offset:49152
	ds_read_b128 v[192:195], v157 offset:50176
	ds_read_b128 v[198:201], v157 offset:51200
	ds_read_b128 v[202:205], v157 offset:52224
	ds_read_b128 v[206:209], v157 offset:53248
	ds_read_b128 v[210:213], v157 offset:54272
	ds_read_b128 v[214:217], v157 offset:55296
	ds_read_b128 v[218:221], v157 offset:56320
	global_load_lds_dwordx4 v146, s[98:99]
	s_add_i32 m0, s44, 0x2000
	s_add_u32 s38, s38, 0x40080
	s_addc_u32 s39, s39, 0
	s_add_i32 s44, s71, s51
	global_load_lds_dwordx4 v150, s[98:99]
	s_mov_b32 m0, s44
	s_nop 0
	global_load_lds_dwordx4 v146, s[38:39]
	s_add_i32 m0, s44, 0x2000
	s_nop 0
	global_load_lds_dwordx4 v150, s[38:39]
	s_mov_b32 m0, s58
	s_nop 0
	global_load_lds_dwordx4 v144, s[100:101]
	s_mov_b32 m0, s59
	s_nop 0
	global_load_lds_dwordx4 v148, s[100:101]
	s_waitcnt vmcnt(8)
	s_waitcnt lgkmcnt(0)
	s_barrier
	v_mfma_f32_16x16x32_bf16 v[60:63], v[128:131], v[188:191], v[60:63]
	v_mfma_f32_16x16x32_bf16 v[56:59], v[136:139], v[188:191], v[56:59]
	v_mfma_f32_16x16x32_bf16 v[48:51], v[128:131], v[198:201], v[48:51]
	v_mfma_f32_16x16x32_bf16 v[40:43], v[136:139], v[198:201], v[40:43]
	v_mfma_f32_16x16x32_bf16 v[32:35], v[128:131], v[206:209], v[32:35]
	v_mfma_f32_16x16x32_bf16 v[24:27], v[136:139], v[206:209], v[24:27]
	v_mfma_f32_16x16x32_bf16 v[16:19], v[128:131], v[214:217], v[16:19]
	v_mfma_f32_16x16x32_bf16 v[8:11], v[136:139], v[214:217], v[8:11]
	v_mfma_f32_16x16x32_bf16 v[60:63], v[132:135], v[192:195], v[60:63]
	v_mfma_f32_16x16x32_bf16 v[56:59], v[140:143], v[192:195], v[56:59]
	v_mfma_f32_16x16x32_bf16 v[48:51], v[132:135], v[202:205], v[48:51]
	v_mfma_f32_16x16x32_bf16 v[40:43], v[140:143], v[202:205], v[40:43]
	v_mfma_f32_16x16x32_bf16 v[32:35], v[132:135], v[210:213], v[32:35]
	v_mfma_f32_16x16x32_bf16 v[24:27], v[140:143], v[210:213], v[24:27]
	v_mfma_f32_16x16x32_bf16 v[16:19], v[132:135], v[218:221], v[16:19]
	v_mfma_f32_16x16x32_bf16 v[8:11], v[140:143], v[218:221], v[8:11]
	v_mfma_f32_16x16x32_bf16 v[52:55], v[172:175], v[188:191], v[52:55]
	v_mfma_f32_16x16x32_bf16 v[44:47], v[180:183], v[188:191], v[44:47]
	v_mfma_f32_16x16x32_bf16 v[36:39], v[172:175], v[198:201], v[36:39]
	v_mfma_f32_16x16x32_bf16 v[28:31], v[180:183], v[198:201], v[28:31]
	v_mfma_f32_16x16x32_bf16 v[20:23], v[172:175], v[206:209], v[20:23]
	v_mfma_f32_16x16x32_bf16 v[12:15], v[180:183], v[206:209], v[12:15]
	v_mfma_f32_16x16x32_bf16 v[4:7], v[172:175], v[214:217], v[4:7]
	v_mfma_f32_16x16x32_bf16 v[0:3], v[180:183], v[214:217], v[0:3]
	v_mfma_f32_16x16x32_bf16 v[52:55], v[176:179], v[192:195], v[52:55]
	v_mfma_f32_16x16x32_bf16 v[44:47], v[184:187], v[192:195], v[44:47]
	v_mfma_f32_16x16x32_bf16 v[36:39], v[176:179], v[202:205], v[36:39]
	v_mfma_f32_16x16x32_bf16 v[28:31], v[184:187], v[202:205], v[28:31]
	v_mfma_f32_16x16x32_bf16 v[20:23], v[176:179], v[210:213], v[20:23]
	v_mfma_f32_16x16x32_bf16 v[12:15], v[184:187], v[210:213], v[12:15]
	v_mfma_f32_16x16x32_bf16 v[4:7], v[176:179], v[218:221], v[4:7]
	v_mfma_f32_16x16x32_bf16 v[0:3], v[184:187], v[218:221], v[0:3]
	s_barrier
	s_add_i32 s69, s69, 2
	s_add_u32 s20, s20, 0x100
	s_addc_u32 s21, s21, 0
	s_add_u32 s67, s67, 0x100
	s_addc_u32 s68, s68, 0
	s_cmp_gt_u32 s69, 13
	s_cbranch_scc0 .LBB0_1446
	s_and_b64 vcc, exec, s[8:9]
	s_cbranch_vccz .LBB0_1449
	s_barrier

; #define PG8_STAGE(bufoff, gbase, voff) do { _Pragma("unroll") for (int _i = 0; _i < 2; ++_i) \
;         __builtin_amdgcn_global_load_lds((const unsigned*)((const char*)(gbase) + (voff)[_i]), (PG8_LAS unsigned*)(lds + (bufoff) + ldsw + _i * 8192), 16, 0, 0); } while (0)
; #define PG8_LDA(dst, b, h) do { _Pragma("unroll") for (int m = 0; m < 4; ++m) _Pragma("unroll") for (int k = 0; k < 2; ++k) dst[m][k] = *(const PG8_LAS bf16x8*)(lds + PG8_SA(b, h) + aoff + m * 2048 + k * 1024); } while (0)
; #define PG8_LDB(dst, b, h) do { _Pragma("unroll") for (int n = 0; n < 2; ++n) _Pragma("unroll") for (int k = 0; k < 2; ++k) dst[n][k] = *(const PG8_LAS bf16x8*)(lds + PG8_SB(b, h) + boff + n * 2048 + k * 1024); } while (0)
; #define PG8_WAIT_V(n) asm volatile("s_waitcnt vmcnt(" #n ")" ::: "memory")
; #define PG8_WAIT_L(n) asm volatile("s_waitcnt lgkmcnt(" #n ")" ::: "memory")
; #define PG8_BAR __builtin_amdgcn_s_barrier()
; #define PG8_SCHED __builtin_amdgcn_sched_barrier(0)
; template <class Epi, class Sched, bool ALIGN_EPI = false, bool SP2 = false>
; __device__ __forceinline__ void gemm_phase(PG8_LAS unsigned char* lds, const Gemm g, const Sched& S, const Epi& E) {
;     ...
;         const char* nA = has_next ? (const char*)g.A + (size_t)nxt.pm * tstep : cA; const char* nB = has_next ? (const char*)g.Bt + (size_t)nxt.pn * tstep : cB;
;         for (int t = 0; t < nt; t += 2) {
;             const bool last = (t == nt - 2);
;             const char* a1 = cA + (size_t)(t + 1) * kstep;
;             const char* a2 = last ? nA : cA + (size_t)(t + 2) * kstep; const char* b2 = last ? nB : cB + (size_t)(t + 2) * kstep;
;             const char* a3 = a2 + kstep; const char* b3 = b2 + kstep;
;             if (last && has_next) S.a_ready(nxt);
;             if constexpr (SP2) {
;             PG8_LDB(B0, 0, 0); PG8_LDB(B1, 0, 1); PG8_SCHED; PG8_LDA(At, 0, 0); PG8_STAGE(PG8_SA(1, 1), a1 + hstep, voffA);
;             PG8_WAIT_V(8); PG8_WAIT_L(0); PG8_BAR; PG8_MMA(0, 0, At, B0); PG8_MMA(0, 1, At, B1); PG8_BAR; PG8_SCHED;
;             PG8_LDA(At, 0, 1); PG8_STAGE(PG8_SB(0, 0), b2, voffB); PG8_STAGE(PG8_SB(0, 1), b2 + hstep, voffB); PG8_STAGE(PG8_SA(0, 0), a2, voffA);
;             PG8_WAIT_V(8); PG8_WAIT_L(0); PG8_BAR; PG8_MMA(1, 0, At, B0); PG8_MMA(1, 1, At, B1); PG8_BAR; PG8_SCHED;
.LBB0_1634:
	s_ashr_i32 s47, s46, 31
	s_lshl_b64 s[48:49], s[46:47], 19
	s_add_u32 s48, s18, s48
	s_addc_u32 s49, s19, s49
	s_and_b64 s[50:51], s[6:7], exec
	s_cselect_b32 s35, s49, s21
	s_cselect_b32 s47, s48, s20
	s_ashr_i32 s45, s44, 31
	s_lshl_b64 s[50:51], s[44:45], 19
	s_add_u32 s50, s3, s50
	s_addc_u32 s51, s33, s51
	s_and_b64 s[56:57], s[6:7], exec
	s_cselect_b32 s45, s51, s55
	s_cselect_b32 s73, s50, s54
	s_add_u32 s20, s20, 0x40080
	s_addc_u32 s21, s21, 0
	s_add_u32 s74, s54, 0x100
	s_addc_u32 s75, s55, 0
	s_mov_b32 s76, -2
	s_waitcnt lgkmcnt(0)
	ds_read_b128 v[96:99], v223
	ds_read_b128 v[108:111], v223 offset:1024
	ds_read_b128 v[120:123], v223 offset:2048
	ds_read_b128 v[128:131], v223 offset:3072
	ds_read_b128 v[144:147], v224
	ds_read_b128 v[148:151], v224 offset:1024
	ds_read_b128 v[152:155], v224 offset:2048
	ds_read_b128 v[156:159], v224 offset:3072
	s_add_u32 s54, s20, 0xfffc0080
	s_addc_u32 s55, s21, -1
	s_cmp_eq_u32 s76, 12
	s_cselect_b32 s57, s35, s55
	s_cselect_b32 s56, s47, s54
	s_cselect_b32 s55, s45, s75
	s_cselect_b32 s54, s73, s74
	s_add_i32 m0, s53, 0xc000
	ds_read_b128 v[160:163], v225
	ds_read_b128 v[164:167], v225 offset:1024
	ds_read_b128 v[168:171], v225 offset:2048
	ds_read_b128 v[172:175], v225 offset:3072
	ds_read_b128 v[176:179], v225 offset:4096
	ds_read_b128 v[180:183], v225 offset:5120
	ds_read_b128 v[202:205], v225 offset:6144
	ds_read_b128 v[206:209], v225 offset:7168
	global_load_lds_dwordx4 v192, s[20:21]
	s_add_i32 m0, s53, 0xe000
	s_nop 0
	global_load_lds_dwordx4 v194, s[20:21]
	s_waitcnt vmcnt(8)
	s_waitcnt lgkmcnt(0)
	s_barrier
	v_mfma_f32_16x16x32_bf16 v[140:143], v[96:99], v[160:163], 0
	v_mfma_f32_16x16x32_bf16 v[136:139], v[120:123], v[160:163], 0
	v_mfma_f32_16x16x32_bf16 v[116:119], v[96:99], v[168:171], 0
	v_mfma_f32_16x16x32_bf16 v[112:115], v[120:123], v[168:171], 0
	v_mfma_f32_16x16x32_bf16 v[92:95], v[96:99], v[176:179], 0
	v_mfma_f32_16x16x32_bf16 v[88:91], v[120:123], v[176:179], 0
	v_mfma_f32_16x16x32_bf16 v[76:79], v[96:99], v[202:205], 0
	v_mfma_f32_16x16x32_bf16 v[72:75], v[120:123], v[202:205], 0
	v_mfma_f32_16x16x32_bf16 v[140:143], v[108:111], v[164:167], v[140:143]
	v_mfma_f32_16x16x32_bf16 v[136:139], v[128:131], v[164:167], v[136:139]
	v_mfma_f32_16x16x32_bf16 v[116:119], v[108:111], v[172:175], v[116:119]
	v_mfma_f32_16x16x32_bf16 v[112:115], v[128:131], v[172:175], v[112:115]
	v_mfma_f32_16x16x32_bf16 v[92:95], v[108:111], v[180:183], v[92:95]
	v_mfma_f32_16x16x32_bf16 v[88:91], v[128:131], v[180:183], v[88:91]
	v_mfma_f32_16x16x32_bf16 v[76:79], v[108:111], v[206:209], v[76:79]
	v_mfma_f32_16x16x32_bf16 v[72:75], v[128:131], v[206:209], v[72:75]
	v_mfma_f32_16x16x32_bf16 v[132:135], v[144:147], v[160:163], 0
	v_mfma_f32_16x16x32_bf16 v[124:127], v[152:155], v[160:163], 0
	v_mfma_f32_16x16x32_bf16 v[104:107], v[144:147], v[168:171], 0
	v_mfma_f32_16x16x32_bf16 v[100:103], v[152:155], v[168:171], 0
	v_mfma_f32_16x16x32_bf16 v[84:87], v[144:147], v[176:179], 0
	v_mfma_f32_16x16x32_bf16 v[80:83], v[152:155], v[176:179], 0
	v_mfma_f32_16x16x32_bf16 v[68:71], v[144:147], v[202:205], 0
	v_mfma_f32_16x16x32_bf16 v[64:67], v[152:155], v[202:205], 0
	v_mfma_f32_16x16x32_bf16 v[132:135], v[148:151], v[164:167], v[132:135]
	v_mfma_f32_16x16x32_bf16 v[124:127], v[156:159], v[164:167], v[124:127]
	v_mfma_f32_16x16x32_bf16 v[104:107], v[148:151], v[172:175], v[104:107]
	v_mfma_f32_16x16x32_bf16 v[100:103], v[156:159], v[172:175], v[100:103]
	v_mfma_f32_16x16x32_bf16 v[84:87], v[148:151], v[180:183], v[84:87]
	v_mfma_f32_16x16x32_bf16 v[80:83], v[156:159], v[180:183], v[80:83]
	v_mfma_f32_16x16x32_bf16 v[68:71], v[148:151], v[206:209], v[68:71]
	v_mfma_f32_16x16x32_bf16 v[64:67], v[156:159], v[206:209], v[64:67]
	s_barrier
	s_add_i32 s77, s71, s58
	s_add_u32 s98, s54, s12
	s_addc_u32 s99, s55, s13
	s_add_u32 s100, s56, s12
	s_addc_u32 s101, s57, s13
	s_mov_b32 m0, s77
	ds_read_b128 v[160:163], v225 offset:16384
	ds_read_b128 v[164:167], v225 offset:17408
	ds_read_b128 v[168:171], v225 offset:18432
	ds_read_b128 v[172:175], v225 offset:19456
	ds_read_b128 v[176:179], v225 offset:20480
	ds_read_b128 v[180:183], v225 offset:21504
	ds_read_b128 v[202:205], v225 offset:22528
	ds_read_b128 v[206:209], v225 offset:23552
	global_load_lds_dwordx4 v186, s[54:55]
	s_add_i32 m0, s77, 0x2000
	s_add_u32 s78, s54, 0x40000
	s_addc_u32 s79, s55, 0
	s_add_i32 s77, s72, s58
	global_load_lds_dwordx4 v190, s[54:55]
	s_mov_b32 m0, s77
	s_nop 0
	global_load_lds_dwordx4 v186, s[78:79]
	s_add_i32 m0, s77, 0x2000
	s_nop 0
	global_load_lds_dwordx4 v190, s[78:79]
	s_mov_b32 m0, s53
	s_nop 0
	global_load_lds_dwordx4 v184, s[56:57]
	s_mov_b32 m0, s59
	s_nop 0
	global_load_lds_dwordx4 v188, s[56:57]
	s_waitcnt vmcnt(8)
	s_waitcnt lgkmcnt(0)
	s_barrier
; #define PG8_STAGE(bufoff, gbase, voff) do { _Pragma("unroll") for (int _i = 0; _i < 2; ++_i) \
;         __builtin_amdgcn_global_load_lds((const unsigned*)((const char*)(gbase) + (voff)[_i]), (PG8_LAS unsigned*)(lds + (bufoff) + ldsw + _i * 8192), 16, 0, 0); } while (0)
; #define PG8_LDA(dst, b, h) do { _Pragma("unroll") for (int m = 0; m < 4; ++m) _Pragma("unroll") for (int k = 0; k < 2; ++k) dst[m][k] = *(const PG8_LAS bf16x8*)(lds + PG8_SA(b, h) + aoff + m * 2048 + k * 1024); } while (0)
; #define PG8_LDB(dst, b, h) do { _Pragma("unroll") for (int n = 0; n < 2; ++n) _Pragma("unroll") for (int k = 0; k < 2; ++k) dst[n][k] = *(const PG8_LAS bf16x8*)(lds + PG8_SB(b, h) + boff + n * 2048 + k * 1024); } while (0)
; #define PG8_MMA(ai, bj, At, Bt) do { __builtin_amdgcn_s_setprio(1); _Pragma("unroll") for (int m = 0; m < 4; ++m) _Pragma("unroll") for (int n = 0; n < 2; ++n) _Pragma("unroll") for (int k = 0; k < 2; ++k) \
;         acc[ai][bj][m][n] = __builtin_amdgcn_mfma_f32_16x16x32_bf16(Bt[n][k], At[m][k], acc[ai][bj][m][n], 0, 0, 0); __builtin_amdgcn_s_setprio(0); } while (0)
; #define PG8_WAIT_V(n) asm volatile("s_waitcnt vmcnt(" #n ")" ::: "memory")
; #define PG8_WAIT_L(n) asm volatile("s_waitcnt lgkmcnt(" #n ")" ::: "memory")
; #define PG8_BAR __builtin_amdgcn_s_barrier()
; #define PG8_SCHED __builtin_amdgcn_sched_barrier(0)
; template <class Epi, class Sched, bool ALIGN_EPI = false, bool SP2 = false>
; __device__ __forceinline__ void gemm_phase(PG8_LAS unsigned char* lds, const Gemm g, const Sched& S, const Epi& E) {
;     ...
;             PG8_WAIT_V(8); PG8_WAIT_L(0); PG8_BAR; PG8_MMA(1, 0, At, B0); PG8_MMA(1, 1, At, B1); PG8_BAR; PG8_SCHED;
;             PG8_LDB(B0, 1, 0); PG8_LDB(B1, 1, 1); PG8_SCHED; PG8_LDA(At, 1, 0); PG8_STAGE(PG8_SA(0, 1), a2 + hstep, voffA);
;             PG8_WAIT_V(8); PG8_WAIT_L(0); PG8_BAR; PG8_MMA(0, 0, At, B0); PG8_MMA(0, 1, At, B1); PG8_BAR; PG8_SCHED;
	v_mfma_f32_16x16x32_bf16 v[60:63], v[96:99], v[160:163], 0
	v_mfma_f32_16x16x32_bf16 v[56:59], v[120:123], v[160:163], 0
	v_mfma_f32_16x16x32_bf16 v[44:47], v[96:99], v[168:171], 0
	v_mfma_f32_16x16x32_bf16 v[40:43], v[120:123], v[168:171], 0
	v_mfma_f32_16x16x32_bf16 v[28:31], v[96:99], v[176:179], 0
	v_mfma_f32_16x16x32_bf16 v[24:27], v[120:123], v[176:179], 0
	v_mfma_f32_16x16x32_bf16 v[12:15], v[96:99], v[202:205], 0
	v_mfma_f32_16x16x32_bf16 v[8:11], v[120:123], v[202:205], 0
	v_mfma_f32_16x16x32_bf16 v[60:63], v[108:111], v[164:167], v[60:63]
	v_mfma_f32_16x16x32_bf16 v[56:59], v[128:131], v[164:167], v[56:59]
	v_mfma_f32_16x16x32_bf16 v[44:47], v[108:111], v[172:175], v[44:47]
	v_mfma_f32_16x16x32_bf16 v[40:43], v[128:131], v[172:175], v[40:43]
	v_mfma_f32_16x16x32_bf16 v[28:31], v[108:111], v[180:183], v[28:31]
	v_mfma_f32_16x16x32_bf16 v[24:27], v[128:131], v[180:183], v[24:27]
	v_mfma_f32_16x16x32_bf16 v[12:15], v[108:111], v[206:209], v[12:15]
	v_mfma_f32_16x16x32_bf16 v[8:11], v[128:131], v[206:209], v[8:11]
	v_mfma_f32_16x16x32_bf16 v[52:55], v[144:147], v[160:163], 0
	v_mfma_f32_16x16x32_bf16 v[48:51], v[152:155], v[160:163], 0
	v_mfma_f32_16x16x32_bf16 v[36:39], v[144:147], v[168:171], 0
	v_mfma_f32_16x16x32_bf16 v[32:35], v[152:155], v[168:171], 0
	v_mfma_f32_16x16x32_bf16 v[20:23], v[144:147], v[176:179], 0
	v_mfma_f32_16x16x32_bf16 v[16:19], v[152:155], v[176:179], 0
	v_mfma_f32_16x16x32_bf16 v[4:7], v[144:147], v[202:205], 0
	v_mfma_f32_16x16x32_bf16 v[0:3], v[152:155], v[202:205], 0
	v_mfma_f32_16x16x32_bf16 v[52:55], v[148:151], v[164:167], v[52:55]
	v_mfma_f32_16x16x32_bf16 v[48:51], v[156:159], v[164:167], v[48:51]
	v_mfma_f32_16x16x32_bf16 v[36:39], v[148:151], v[172:175], v[36:39]
	v_mfma_f32_16x16x32_bf16 v[32:35], v[156:159], v[172:175], v[32:35]
	v_mfma_f32_16x16x32_bf16 v[20:23], v[148:151], v[180:183], v[20:23]
	v_mfma_f32_16x16x32_bf16 v[16:19], v[156:159], v[180:183], v[16:19]
	v_mfma_f32_16x16x32_bf16 v[4:7], v[148:151], v[206:209], v[4:7]
	v_mfma_f32_16x16x32_bf16 v[0:3], v[156:159], v[206:209], v[0:3]
	s_barrier
	s_add_i32 s77, 0, 0x18000
	s_add_i32 s78, 0, 0x1c000
	v_add_u32_e32 v128, s77, v221
	v_add_u32_e32 v156, s78, v221
	ds_read_b128 v[96:99], v128
	ds_read_b128 v[108:111], v128 offset:1024
	ds_read_b128 v[120:123], v128 offset:2048
	ds_read_b128 v[128:131], v128 offset:3072
	ds_read_b128 v[144:147], v156
	ds_read_b128 v[148:151], v156 offset:1024
	ds_read_b128 v[152:155], v156 offset:2048
	ds_read_b128 v[156:159], v156 offset:3072
	s_add_u32 s56, s56, 0x40000
	s_addc_u32 s57, s57, 0
	s_mov_b32 m0, s60
	ds_read_b128 v[160:163], v225 offset:32768
	ds_read_b128 v[164:167], v225 offset:33792
	ds_read_b128 v[168:171], v225 offset:34816
	ds_read_b128 v[172:175], v225 offset:35840
	ds_read_b128 v[176:179], v225 offset:36864
	ds_read_b128 v[180:183], v225 offset:37888
	ds_read_b128 v[202:205], v225 offset:38912
	ds_read_b128 v[206:209], v225 offset:39936
	global_load_lds_dwordx4 v184, s[56:57]
	s_mov_b32 m0, s61
	s_nop 0
	global_load_lds_dwordx4 v188, s[56:57]
	s_waitcnt vmcnt(8)
	s_waitcnt lgkmcnt(0)
	s_barrier
	v_mfma_f32_16x16x32_bf16 v[140:143], v[96:99], v[160:163], v[140:143]
	v_mfma_f32_16x16x32_bf16 v[136:139], v[120:123], v[160:163], v[136:139]
	v_mfma_f32_16x16x32_bf16 v[116:119], v[96:99], v[168:171], v[116:119]
	v_mfma_f32_16x16x32_bf16 v[112:115], v[120:123], v[168:171], v[112:115]
	v_mfma_f32_16x16x32_bf16 v[92:95], v[96:99], v[176:179], v[92:95]
	v_mfma_f32_16x16x32_bf16 v[88:91], v[120:123], v[176:179], v[88:91]
	v_mfma_f32_16x16x32_bf16 v[76:79], v[96:99], v[202:205], v[76:79]
	v_mfma_f32_16x16x32_bf16 v[72:75], v[120:123], v[202:205], v[72:75]
	v_mfma_f32_16x16x32_bf16 v[140:143], v[108:111], v[164:167], v[140:143]
	v_mfma_f32_16x16x32_bf16 v[136:139], v[128:131], v[164:167], v[136:139]
	v_mfma_f32_16x16x32_bf16 v[116:119], v[108:111], v[172:175], v[116:119]
	v_mfma_f32_16x16x32_bf16 v[112:115], v[128:131], v[172:175], v[112:115]
	v_mfma_f32_16x16x32_bf16 v[92:95], v[108:111], v[180:183], v[92:95]
	v_mfma_f32_16x16x32_bf16 v[88:91], v[128:131], v[180:183], v[88:91]
	v_mfma_f32_16x16x32_bf16 v[76:79], v[108:111], v[206:209], v[76:79]
	v_mfma_f32_16x16x32_bf16 v[72:75], v[128:131], v[206:209], v[72:75]
	v_mfma_f32_16x16x32_bf16 v[132:135], v[144:147], v[160:163], v[132:135]
	v_mfma_f32_16x16x32_bf16 v[124:127], v[152:155], v[160:163], v[124:127]
	v_mfma_f32_16x16x32_bf16 v[104:107], v[144:147], v[168:171], v[104:107]
	v_mfma_f32_16x16x32_bf16 v[100:103], v[152:155], v[168:171], v[100:103]
	v_mfma_f32_16x16x32_bf16 v[84:87], v[144:147], v[176:179], v[84:87]
	v_mfma_f32_16x16x32_bf16 v[80:83], v[152:155], v[176:179], v[80:83]
	v_mfma_f32_16x16x32_bf16 v[68:71], v[144:147], v[202:205], v[68:71]
	v_mfma_f32_16x16x32_bf16 v[64:67], v[152:155], v[202:205], v[64:67]
	v_mfma_f32_16x16x32_bf16 v[132:135], v[148:151], v[164:167], v[132:135]
	v_mfma_f32_16x16x32_bf16 v[124:127], v[156:159], v[164:167], v[124:127]
	v_mfma_f32_16x16x32_bf16 v[104:107], v[148:151], v[172:175], v[104:107]
	v_mfma_f32_16x16x32_bf16 v[100:103], v[156:159], v[172:175], v[100:103]
	v_mfma_f32_16x16x32_bf16 v[84:87], v[148:151], v[180:183], v[84:87]
	v_mfma_f32_16x16x32_bf16 v[80:83], v[156:159], v[180:183], v[80:83]
	v_mfma_f32_16x16x32_bf16 v[68:71], v[148:151], v[206:209], v[68:71]
	v_mfma_f32_16x16x32_bf16 v[64:67], v[156:159], v[206:209], v[64:67]
	s_barrier
; #define PG8_STAGE(bufoff, gbase, voff) do { _Pragma("unroll") for (int _i = 0; _i < 2; ++_i) \
;         __builtin_amdgcn_global_load_lds((const unsigned*)((const char*)(gbase) + (voff)[_i]), (PG8_LAS unsigned*)(lds + (bufoff) + ldsw + _i * 8192), 16, 0, 0); } while (0)
; #define PG8_LDA(dst, b, h) do { _Pragma("unroll") for (int m = 0; m < 4; ++m) _Pragma("unroll") for (int k = 0; k < 2; ++k) dst[m][k] = *(const PG8_LAS bf16x8*)(lds + PG8_SA(b, h) + aoff + m * 2048 + k * 1024); } while (0)
; #define PG8_MMA(ai, bj, At, Bt) do { __builtin_amdgcn_s_setprio(1); _Pragma("unroll") for (int m = 0; m < 4; ++m) _Pragma("unroll") for (int n = 0; n < 2; ++n) _Pragma("unroll") for (int k = 0; k < 2; ++k) \
;         acc[ai][bj][m][n] = __builtin_amdgcn_mfma_f32_16x16x32_bf16(Bt[n][k], At[m][k], acc[ai][bj][m][n], 0, 0, 0); __builtin_amdgcn_s_setprio(0); } while (0)
; #define PG8_WAIT_V(n) asm volatile("s_waitcnt vmcnt(" #n ")" ::: "memory")
; #define PG8_WAIT_L(n) asm volatile("s_waitcnt lgkmcnt(" #n ")" ::: "memory")
; #define PG8_BAR __builtin_amdgcn_s_barrier()
; #define PG8_SCHED __builtin_amdgcn_sched_barrier(0)
; template <class Epi, class Sched, bool ALIGN_EPI = false, bool SP2 = false>
; __device__ __forceinline__ void gemm_phase(PG8_LAS unsigned char* lds, const Gemm g, const Sched& S, const Epi& E) {
;     ...
;             PG8_LDA(At, 1, 1); PG8_STAGE(PG8_SB(1, 0), b3, voffB); PG8_STAGE(PG8_SB(1, 1), b3 + hstep, voffB); PG8_STAGE(PG8_SA(1, 0), a3, voffA);
;             PG8_WAIT_V(8); PG8_WAIT_L(0); PG8_BAR; PG8_MMA(1, 0, At, B0); PG8_MMA(1, 1, At, B1); PG8_BAR; PG8_SCHED;
	s_add_i32 s56, s77, s58
	s_mov_b32 m0, s56
	ds_read_b128 v[160:163], v225 offset:49152
	ds_read_b128 v[164:167], v225 offset:50176
	ds_read_b128 v[168:171], v225 offset:51200
	ds_read_b128 v[172:175], v225 offset:52224
	ds_read_b128 v[176:179], v225 offset:53248
	ds_read_b128 v[180:183], v225 offset:54272
	ds_read_b128 v[202:205], v225 offset:55296
	ds_read_b128 v[206:209], v225 offset:56320
	global_load_lds_dwordx4 v186, s[98:99]
	s_add_i32 m0, s56, 0x2000
	s_add_u32 s54, s54, 0x40080
	s_addc_u32 s55, s55, 0
	s_add_i32 s56, s78, s58
	global_load_lds_dwordx4 v190, s[98:99]
	s_mov_b32 m0, s56
	s_nop 0
	global_load_lds_dwordx4 v186, s[54:55]
	s_add_i32 m0, s56, 0x2000
	s_nop 0
	global_load_lds_dwordx4 v190, s[54:55]
	s_mov_b32 m0, s66
	s_nop 0
	global_load_lds_dwordx4 v184, s[100:101]
	s_mov_b32 m0, s67
	s_nop 0
	global_load_lds_dwordx4 v188, s[100:101]
	s_waitcnt vmcnt(8)
	s_waitcnt lgkmcnt(0)
	s_barrier
	v_mfma_f32_16x16x32_bf16 v[60:63], v[96:99], v[160:163], v[60:63]
	v_mfma_f32_16x16x32_bf16 v[56:59], v[120:123], v[160:163], v[56:59]
	v_mfma_f32_16x16x32_bf16 v[44:47], v[96:99], v[168:171], v[44:47]
	v_mfma_f32_16x16x32_bf16 v[40:43], v[120:123], v[168:171], v[40:43]
	v_mfma_f32_16x16x32_bf16 v[28:31], v[96:99], v[176:179], v[28:31]
	v_mfma_f32_16x16x32_bf16 v[24:27], v[120:123], v[176:179], v[24:27]
	v_mfma_f32_16x16x32_bf16 v[12:15], v[96:99], v[202:205], v[12:15]
	v_mfma_f32_16x16x32_bf16 v[8:11], v[120:123], v[202:205], v[8:11]
	v_mfma_f32_16x16x32_bf16 v[60:63], v[108:111], v[164:167], v[60:63]
	v_mfma_f32_16x16x32_bf16 v[56:59], v[128:131], v[164:167], v[56:59]
	v_mfma_f32_16x16x32_bf16 v[44:47], v[108:111], v[172:175], v[44:47]
	v_mfma_f32_16x16x32_bf16 v[40:43], v[128:131], v[172:175], v[40:43]
	v_mfma_f32_16x16x32_bf16 v[28:31], v[108:111], v[180:183], v[28:31]
	v_mfma_f32_16x16x32_bf16 v[24:27], v[128:131], v[180:183], v[24:27]
	v_mfma_f32_16x16x32_bf16 v[12:15], v[108:111], v[206:209], v[12:15]
	v_mfma_f32_16x16x32_bf16 v[8:11], v[128:131], v[206:209], v[8:11]
	v_mfma_f32_16x16x32_bf16 v[52:55], v[144:147], v[160:163], v[52:55]
	v_mfma_f32_16x16x32_bf16 v[48:51], v[152:155], v[160:163], v[48:51]
	v_mfma_f32_16x16x32_bf16 v[36:39], v[144:147], v[168:171], v[36:39]
	v_mfma_f32_16x16x32_bf16 v[32:35], v[152:155], v[168:171], v[32:35]
	v_mfma_f32_16x16x32_bf16 v[20:23], v[144:147], v[176:179], v[20:23]
	v_mfma_f32_16x16x32_bf16 v[16:19], v[152:155], v[176:179], v[16:19]
	v_mfma_f32_16x16x32_bf16 v[4:7], v[144:147], v[202:205], v[4:7]
	v_mfma_f32_16x16x32_bf16 v[0:3], v[152:155], v[202:205], v[0:3]
	v_mfma_f32_16x16x32_bf16 v[52:55], v[148:151], v[164:167], v[52:55]
	v_mfma_f32_16x16x32_bf16 v[48:51], v[156:159], v[164:167], v[48:51]
	v_mfma_f32_16x16x32_bf16 v[36:39], v[148:151], v[172:175], v[36:39]
	v_mfma_f32_16x16x32_bf16 v[32:35], v[156:159], v[172:175], v[32:35]
	v_mfma_f32_16x16x32_bf16 v[20:23], v[148:151], v[180:183], v[20:23]
	v_mfma_f32_16x16x32_bf16 v[16:19], v[156:159], v[180:183], v[16:19]
	v_mfma_f32_16x16x32_bf16 v[4:7], v[148:151], v[206:209], v[4:7]
	v_mfma_f32_16x16x32_bf16 v[0:3], v[156:159], v[206:209], v[0:3]
	s_barrier
	s_add_i32 s76, s76, 2
	s_add_u32 s20, s20, 0x100
	s_addc_u32 s21, s21, 0
	s_add_u32 s74, s74, 0x100
	s_addc_u32 s75, s75, 0
	s_cmp_gt_u32 s76, 13

; #define PG8_STAGE(bufoff, gbase, voff) do { _Pragma("unroll") for (int _i = 0; _i < 2; ++_i) \
;         __builtin_amdgcn_global_load_lds((const unsigned*)((const char*)(gbase) + (voff)[_i]), (PG8_LAS unsigned*)(lds + (bufoff) + ldsw + _i * 8192), 16, 0, 0); } while (0)
; #define PG8_LDA(dst, b, h) do { _Pragma("unroll") for (int m = 0; m < 4; ++m) _Pragma("unroll") for (int k = 0; k < 2; ++k) dst[m][k] = *(const PG8_LAS bf16x8*)(lds + PG8_SA(b, h) + aoff + m * 2048 + k * 1024); } while (0)
; #define PG8_LDB(dst, b, h) do { _Pragma("unroll") for (int n = 0; n < 2; ++n) _Pragma("unroll") for (int k = 0; k < 2; ++k) dst[n][k] = *(const PG8_LAS bf16x8*)(lds + PG8_SB(b, h) + boff + n * 2048 + k * 1024); } while (0)
; #define PG8_WAIT_V(n) asm volatile("s_waitcnt vmcnt(" #n ")" ::: "memory")
; #define PG8_WAIT_L(n) asm volatile("s_waitcnt lgkmcnt(" #n ")" ::: "memory")
; #define PG8_BAR __builtin_amdgcn_s_barrier()
; #define PG8_SCHED __builtin_amdgcn_sched_barrier(0)
; template <class Epi, class Sched, bool ALIGN_EPI = false, bool SP2 = false>
; __device__ __forceinline__ void gemm_phase(PG8_LAS unsigned char* lds, const Gemm g, const Sched& S, const Epi& E) {
;     ...
;         const char* nA = has_next ? (const char*)g.A + (size_t)nxt.pm * tstep : cA; const char* nB = has_next ? (const char*)g.Bt + (size_t)nxt.pn * tstep : cB;
;         for (int t = 0; t < nt; t += 2) {
;             const bool last = (t == nt - 2);
;             const char* a1 = cA + (size_t)(t + 1) * kstep;
;             const char* a2 = last ? nA : cA + (size_t)(t + 2) * kstep; const char* b2 = last ? nB : cB + (size_t)(t + 2) * kstep;
;             const char* a3 = a2 + kstep; const char* b3 = b2 + kstep;
;             if (last && has_next) S.a_ready(nxt);
;             if constexpr (SP2) {
;             PG8_LDB(B0, 0, 0); PG8_LDB(B1, 0, 1); PG8_SCHED; PG8_LDA(At, 0, 0); PG8_STAGE(PG8_SA(1, 1), a1 + hstep, voffA);
;             PG8_WAIT_V(8); PG8_WAIT_L(0); PG8_BAR; PG8_MMA(0, 0, At, B0); PG8_MMA(0, 1, At, B1); PG8_BAR; PG8_SCHED;
;             PG8_LDA(At, 0, 1); PG8_STAGE(PG8_SB(0, 0), b2, voffB); PG8_STAGE(PG8_SB(0, 1), b2 + hstep, voffB); PG8_STAGE(PG8_SA(0, 0), a2, voffA);
;             PG8_WAIT_V(8); PG8_WAIT_L(0); PG8_BAR; PG8_MMA(1, 0, At, B0); PG8_MMA(1, 1, At, B1); PG8_BAR; PG8_SCHED;
.LBB0_1739:
	s_ashr_i32 s15, s14, 31
	s_lshl_b64 s[16:17], s[14:15], 19
	s_add_u32 s16, s36, s16
	s_addc_u32 s17, s37, s17
	s_and_b64 s[18:19], s[4:5], exec
	s_cselect_b32 s15, s17, s21
	s_cselect_b32 s63, s16, s20
	s_ashr_i32 s13, s12, 31
	s_lshl_b64 s[18:19], s[12:13], 19
	s_add_u32 s18, s48, s18
	s_addc_u32 s19, s49, s19
	s_and_b64 s[42:43], s[4:5], exec
	s_cselect_b32 s13, s19, s39
	s_cselect_b32 s64, s18, s38
	s_add_u32 s20, s20, 0x40080
	s_addc_u32 s21, s21, 0
	s_add_u32 s65, s38, 0x100
	s_addc_u32 s66, s39, 0
	s_mov_b32 s67, -2
	ds_read_b128 v[154:157], v150
	ds_read_b128 v[158:161], v150 offset:1024
	ds_read_b128 v[162:165], v150 offset:2048
	ds_read_b128 v[166:169], v150 offset:3072
	ds_read_b128 v[170:173], v151
	ds_read_b128 v[174:177], v151 offset:1024
	ds_read_b128 v[178:181], v151 offset:2048
	ds_read_b128 v[182:185], v151 offset:3072
	s_add_u32 s38, s20, 0xfffc0080
	s_addc_u32 s39, s21, -1
	s_cmp_eq_u32 s67, 12
	s_cselect_b32 s43, s15, s39
	s_cselect_b32 s42, s63, s38
	s_cselect_b32 s39, s13, s66
	s_cselect_b32 s38, s64, s65
	s_add_i32 m0, s35, 0xc000
	ds_read_b128 v[186:189], v152
	ds_read_b128 v[190:193], v152 offset:1024
	ds_read_b128 v[198:201], v152 offset:2048
	ds_read_b128 v[202:205], v152 offset:3072
	ds_read_b128 v[206:209], v152 offset:4096
	ds_read_b128 v[210:213], v152 offset:5120
	ds_read_b128 v[214:217], v152 offset:6144
	ds_read_b128 v[218:221], v152 offset:7168
	global_load_lds_dwordx4 v136, s[20:21]
	s_add_i32 m0, s35, 0xe000
	s_nop 0
	global_load_lds_dwordx4 v138, s[20:21]
	s_waitcnt vmcnt(8)
	s_waitcnt lgkmcnt(0)
	s_barrier
	v_mfma_f32_16x16x32_bf16 v[124:127], v[154:157], v[186:189], 0
	v_mfma_f32_16x16x32_bf16 v[116:119], v[162:165], v[186:189], 0
	v_mfma_f32_16x16x32_bf16 v[108:111], v[154:157], v[198:201], 0
	v_mfma_f32_16x16x32_bf16 v[100:103], v[162:165], v[198:201], 0
	v_mfma_f32_16x16x32_bf16 v[92:95], v[154:157], v[206:209], 0
	v_mfma_f32_16x16x32_bf16 v[84:87], v[162:165], v[206:209], 0
	v_mfma_f32_16x16x32_bf16 v[76:79], v[154:157], v[214:217], 0
	v_mfma_f32_16x16x32_bf16 v[68:71], v[162:165], v[214:217], 0
	v_mfma_f32_16x16x32_bf16 v[124:127], v[158:161], v[190:193], v[124:127]
	v_mfma_f32_16x16x32_bf16 v[116:119], v[166:169], v[190:193], v[116:119]
	v_mfma_f32_16x16x32_bf16 v[108:111], v[158:161], v[202:205], v[108:111]
	v_mfma_f32_16x16x32_bf16 v[100:103], v[166:169], v[202:205], v[100:103]
	v_mfma_f32_16x16x32_bf16 v[92:95], v[158:161], v[210:213], v[92:95]
	v_mfma_f32_16x16x32_bf16 v[84:87], v[166:169], v[210:213], v[84:87]
	v_mfma_f32_16x16x32_bf16 v[76:79], v[158:161], v[218:221], v[76:79]
	v_mfma_f32_16x16x32_bf16 v[68:71], v[166:169], v[218:221], v[68:71]
	v_mfma_f32_16x16x32_bf16 v[120:123], v[170:173], v[186:189], 0
	v_mfma_f32_16x16x32_bf16 v[112:115], v[178:181], v[186:189], 0
	v_mfma_f32_16x16x32_bf16 v[104:107], v[170:173], v[198:201], 0
	v_mfma_f32_16x16x32_bf16 v[96:99], v[178:181], v[198:201], 0
	v_mfma_f32_16x16x32_bf16 v[88:91], v[170:173], v[206:209], 0
	v_mfma_f32_16x16x32_bf16 v[80:83], v[178:181], v[206:209], 0
	v_mfma_f32_16x16x32_bf16 v[72:75], v[170:173], v[214:217], 0
	v_mfma_f32_16x16x32_bf16 v[64:67], v[178:181], v[214:217], 0
	v_mfma_f32_16x16x32_bf16 v[120:123], v[174:177], v[190:193], v[120:123]
	v_mfma_f32_16x16x32_bf16 v[112:115], v[182:185], v[190:193], v[112:115]
	v_mfma_f32_16x16x32_bf16 v[104:107], v[174:177], v[202:205], v[104:107]
	v_mfma_f32_16x16x32_bf16 v[96:99], v[182:185], v[202:205], v[96:99]
	v_mfma_f32_16x16x32_bf16 v[88:91], v[174:177], v[210:213], v[88:91]
	v_mfma_f32_16x16x32_bf16 v[80:83], v[182:185], v[210:213], v[80:83]
	v_mfma_f32_16x16x32_bf16 v[72:75], v[174:177], v[218:221], v[72:75]
	v_mfma_f32_16x16x32_bf16 v[64:67], v[182:185], v[218:221], v[64:67]
	s_barrier
	s_add_i32 s68, s58, s50
	s_add_u32 s98, s38, s8
	s_addc_u32 s99, s39, s9
	s_add_u32 s100, s42, s8
	s_addc_u32 s101, s43, s9
	s_mov_b32 m0, s68
	ds_read_b128 v[186:189], v152 offset:16384
	ds_read_b128 v[190:193], v152 offset:17408
	ds_read_b128 v[198:201], v152 offset:18432
	ds_read_b128 v[202:205], v152 offset:19456
	ds_read_b128 v[206:209], v152 offset:20480
	ds_read_b128 v[210:213], v152 offset:21504
	ds_read_b128 v[214:217], v152 offset:22528
	ds_read_b128 v[218:221], v152 offset:23552
	global_load_lds_dwordx4 v132, s[38:39]
	s_add_i32 m0, s68, 0x2000
	s_add_u32 s68, s38, 0x40000
	s_addc_u32 s69, s39, 0
	s_add_i32 s70, s59, s50
	global_load_lds_dwordx4 v128, s[38:39]
	s_mov_b32 m0, s70
	s_nop 0
	global_load_lds_dwordx4 v132, s[68:69]
	s_add_i32 m0, s70, 0x2000
	s_nop 0
	global_load_lds_dwordx4 v128, s[68:69]
	s_mov_b32 m0, s35
	s_nop 0
	global_load_lds_dwordx4 v134, s[42:43]
	s_mov_b32 m0, s52
	s_nop 0
	global_load_lds_dwordx4 v130, s[42:43]
	s_waitcnt vmcnt(8)
	s_waitcnt lgkmcnt(0)
	s_barrier
; #define PG8_STAGE(bufoff, gbase, voff) do { _Pragma("unroll") for (int _i = 0; _i < 2; ++_i) \
;         __builtin_amdgcn_global_load_lds((const unsigned*)((const char*)(gbase) + (voff)[_i]), (PG8_LAS unsigned*)(lds + (bufoff) + ldsw + _i * 8192), 16, 0, 0); } while (0)
; #define PG8_LDA(dst, b, h) do { _Pragma("unroll") for (int m = 0; m < 4; ++m) _Pragma("unroll") for (int k = 0; k < 2; ++k) dst[m][k] = *(const PG8_LAS bf16x8*)(lds + PG8_SA(b, h) + aoff + m * 2048 + k * 1024); } while (0)
; #define PG8_LDB(dst, b, h) do { _Pragma("unroll") for (int n = 0; n < 2; ++n) _Pragma("unroll") for (int k = 0; k < 2; ++k) dst[n][k] = *(const PG8_LAS bf16x8*)(lds + PG8_SB(b, h) + boff + n * 2048 + k * 1024); } while (0)
; #define PG8_MMA(ai, bj, At, Bt) do { __builtin_amdgcn_s_setprio(1); _Pragma("unroll") for (int m = 0; m < 4; ++m) _Pragma("unroll") for (int n = 0; n < 2; ++n) _Pragma("unroll") for (int k = 0; k < 2; ++k) \
;         acc[ai][bj][m][n] = __builtin_amdgcn_mfma_f32_16x16x32_bf16(Bt[n][k], At[m][k], acc[ai][bj][m][n], 0, 0, 0); __builtin_amdgcn_s_setprio(0); } while (0)
; #define PG8_WAIT_V(n) asm volatile("s_waitcnt vmcnt(" #n ")" ::: "memory")
; #define PG8_WAIT_L(n) asm volatile("s_waitcnt lgkmcnt(" #n ")" ::: "memory")
; #define PG8_BAR __builtin_amdgcn_s_barrier()
; #define PG8_SCHED __builtin_amdgcn_sched_barrier(0)
; template <class Epi, class Sched, bool ALIGN_EPI = false, bool SP2 = false>
; __device__ __forceinline__ void gemm_phase(PG8_LAS unsigned char* lds, const Gemm g, const Sched& S, const Epi& E) {
;     ...
;             PG8_WAIT_V(8); PG8_WAIT_L(0); PG8_BAR; PG8_MMA(1, 0, At, B0); PG8_MMA(1, 1, At, B1); PG8_BAR; PG8_SCHED;
;             PG8_LDB(B0, 1, 0); PG8_LDB(B1, 1, 1); PG8_SCHED; PG8_LDA(At, 1, 0); PG8_STAGE(PG8_SA(0, 1), a2 + hstep, voffA);
;             PG8_WAIT_V(8); PG8_WAIT_L(0); PG8_BAR; PG8_MMA(0, 0, At, B0); PG8_MMA(0, 1, At, B1); PG8_BAR; PG8_SCHED;
	v_mfma_f32_16x16x32_bf16 v[60:63], v[154:157], v[186:189], 0
	v_mfma_f32_16x16x32_bf16 v[52:55], v[162:165], v[186:189], 0
	v_mfma_f32_16x16x32_bf16 v[44:47], v[154:157], v[198:201], 0
	v_mfma_f32_16x16x32_bf16 v[36:39], v[162:165], v[198:201], 0
	v_mfma_f32_16x16x32_bf16 v[28:31], v[154:157], v[206:209], 0
	v_mfma_f32_16x16x32_bf16 v[20:23], v[162:165], v[206:209], 0
	v_mfma_f32_16x16x32_bf16 v[12:15], v[154:157], v[214:217], 0
	v_mfma_f32_16x16x32_bf16 v[4:7], v[162:165], v[214:217], 0
	v_mfma_f32_16x16x32_bf16 v[60:63], v[158:161], v[190:193], v[60:63]
	v_mfma_f32_16x16x32_bf16 v[52:55], v[166:169], v[190:193], v[52:55]
	v_mfma_f32_16x16x32_bf16 v[44:47], v[158:161], v[202:205], v[44:47]
	v_mfma_f32_16x16x32_bf16 v[36:39], v[166:169], v[202:205], v[36:39]
	v_mfma_f32_16x16x32_bf16 v[28:31], v[158:161], v[210:213], v[28:31]
	v_mfma_f32_16x16x32_bf16 v[20:23], v[166:169], v[210:213], v[20:23]
	v_mfma_f32_16x16x32_bf16 v[12:15], v[158:161], v[218:221], v[12:15]
	v_mfma_f32_16x16x32_bf16 v[4:7], v[166:169], v[218:221], v[4:7]
	v_mfma_f32_16x16x32_bf16 v[56:59], v[170:173], v[186:189], 0
	v_mfma_f32_16x16x32_bf16 v[48:51], v[178:181], v[186:189], 0
	v_mfma_f32_16x16x32_bf16 v[40:43], v[170:173], v[198:201], 0
	v_mfma_f32_16x16x32_bf16 v[32:35], v[178:181], v[198:201], 0
	v_mfma_f32_16x16x32_bf16 v[24:27], v[170:173], v[206:209], 0
	v_mfma_f32_16x16x32_bf16 v[16:19], v[178:181], v[206:209], 0
	v_mfma_f32_16x16x32_bf16 v[8:11], v[170:173], v[214:217], 0
	v_mfma_f32_16x16x32_bf16 v[0:3], v[178:181], v[214:217], 0
	v_mfma_f32_16x16x32_bf16 v[56:59], v[174:177], v[190:193], v[56:59]
	v_mfma_f32_16x16x32_bf16 v[48:51], v[182:185], v[190:193], v[48:51]
	v_mfma_f32_16x16x32_bf16 v[40:43], v[174:177], v[202:205], v[40:43]
	v_mfma_f32_16x16x32_bf16 v[32:35], v[182:185], v[202:205], v[32:35]
	v_mfma_f32_16x16x32_bf16 v[24:27], v[174:177], v[210:213], v[24:27]
	v_mfma_f32_16x16x32_bf16 v[16:19], v[182:185], v[210:213], v[16:19]
	v_mfma_f32_16x16x32_bf16 v[8:11], v[174:177], v[218:221], v[8:11]
	v_mfma_f32_16x16x32_bf16 v[0:3], v[182:185], v[218:221], v[0:3]
	s_barrier
	s_add_i32 s68, 0, 0x18000
	v_add_u32_e32 v153, s68, v147
	s_add_i32 s69, 0, 0x1c000
	ds_read_b128 v[154:157], v153
	ds_read_b128 v[158:161], v153 offset:1024
	ds_read_b128 v[162:165], v153 offset:2048
	ds_read_b128 v[166:169], v153 offset:3072
	v_add_u32_e32 v153, s69, v147
	ds_read_b128 v[170:173], v153
	ds_read_b128 v[174:177], v153 offset:1024
	ds_read_b128 v[178:181], v153 offset:2048
	ds_read_b128 v[182:185], v153 offset:3072
	s_add_u32 s42, s42, 0x40000
	s_addc_u32 s43, s43, 0
	s_mov_b32 m0, s53
	ds_read_b128 v[186:189], v152 offset:32768
	ds_read_b128 v[190:193], v152 offset:33792
	ds_read_b128 v[198:201], v152 offset:34816
	ds_read_b128 v[202:205], v152 offset:35840
	ds_read_b128 v[206:209], v152 offset:36864
	ds_read_b128 v[210:213], v152 offset:37888
	ds_read_b128 v[214:217], v152 offset:38912
	ds_read_b128 v[218:221], v152 offset:39936
	global_load_lds_dwordx4 v134, s[42:43]
	s_mov_b32 m0, s54
	s_nop 0
	global_load_lds_dwordx4 v130, s[42:43]
	s_waitcnt vmcnt(8)
	s_waitcnt lgkmcnt(0)
	s_barrier
	v_mfma_f32_16x16x32_bf16 v[124:127], v[154:157], v[186:189], v[124:127]
	v_mfma_f32_16x16x32_bf16 v[116:119], v[162:165], v[186:189], v[116:119]
	v_mfma_f32_16x16x32_bf16 v[108:111], v[154:157], v[198:201], v[108:111]
	v_mfma_f32_16x16x32_bf16 v[100:103], v[162:165], v[198:201], v[100:103]
	v_mfma_f32_16x16x32_bf16 v[92:95], v[154:157], v[206:209], v[92:95]
	v_mfma_f32_16x16x32_bf16 v[84:87], v[162:165], v[206:209], v[84:87]
	v_mfma_f32_16x16x32_bf16 v[76:79], v[154:157], v[214:217], v[76:79]
	v_mfma_f32_16x16x32_bf16 v[68:71], v[162:165], v[214:217], v[68:71]
	v_mfma_f32_16x16x32_bf16 v[124:127], v[158:161], v[190:193], v[124:127]
	v_mfma_f32_16x16x32_bf16 v[116:119], v[166:169], v[190:193], v[116:119]
	v_mfma_f32_16x16x32_bf16 v[108:111], v[158:161], v[202:205], v[108:111]
	v_mfma_f32_16x16x32_bf16 v[100:103], v[166:169], v[202:205], v[100:103]
	v_mfma_f32_16x16x32_bf16 v[92:95], v[158:161], v[210:213], v[92:95]
	v_mfma_f32_16x16x32_bf16 v[84:87], v[166:169], v[210:213], v[84:87]
	v_mfma_f32_16x16x32_bf16 v[76:79], v[158:161], v[218:221], v[76:79]
	v_mfma_f32_16x16x32_bf16 v[68:71], v[166:169], v[218:221], v[68:71]
	v_mfma_f32_16x16x32_bf16 v[120:123], v[170:173], v[186:189], v[120:123]
	v_mfma_f32_16x16x32_bf16 v[112:115], v[178:181], v[186:189], v[112:115]
	v_mfma_f32_16x16x32_bf16 v[104:107], v[170:173], v[198:201], v[104:107]
	v_mfma_f32_16x16x32_bf16 v[96:99], v[178:181], v[198:201], v[96:99]
	v_mfma_f32_16x16x32_bf16 v[88:91], v[170:173], v[206:209], v[88:91]
	v_mfma_f32_16x16x32_bf16 v[80:83], v[178:181], v[206:209], v[80:83]
	v_mfma_f32_16x16x32_bf16 v[72:75], v[170:173], v[214:217], v[72:75]
	v_mfma_f32_16x16x32_bf16 v[64:67], v[178:181], v[214:217], v[64:67]
	v_mfma_f32_16x16x32_bf16 v[120:123], v[174:177], v[190:193], v[120:123]
	v_mfma_f32_16x16x32_bf16 v[112:115], v[182:185], v[190:193], v[112:115]
	v_mfma_f32_16x16x32_bf16 v[104:107], v[174:177], v[202:205], v[104:107]
	v_mfma_f32_16x16x32_bf16 v[96:99], v[182:185], v[202:205], v[96:99]
	v_mfma_f32_16x16x32_bf16 v[88:91], v[174:177], v[210:213], v[88:91]
	v_mfma_f32_16x16x32_bf16 v[80:83], v[182:185], v[210:213], v[80:83]
	v_mfma_f32_16x16x32_bf16 v[72:75], v[174:177], v[218:221], v[72:75]
	v_mfma_f32_16x16x32_bf16 v[64:67], v[182:185], v[218:221], v[64:67]
	s_barrier
; #define PG8_STAGE(bufoff, gbase, voff) do { _Pragma("unroll") for (int _i = 0; _i < 2; ++_i) \
;         __builtin_amdgcn_global_load_lds((const unsigned*)((const char*)(gbase) + (voff)[_i]), (PG8_LAS unsigned*)(lds + (bufoff) + ldsw + _i * 8192), 16, 0, 0); } while (0)
; #define PG8_LDA(dst, b, h) do { _Pragma("unroll") for (int m = 0; m < 4; ++m) _Pragma("unroll") for (int k = 0; k < 2; ++k) dst[m][k] = *(const PG8_LAS bf16x8*)(lds + PG8_SA(b, h) + aoff + m * 2048 + k * 1024); } while (0)
; #define PG8_LDB(dst, b, h) do { _Pragma("unroll") for (int n = 0; n < 2; ++n) _Pragma("unroll") for (int k = 0; k < 2; ++k) dst[n][k] = *(const PG8_LAS bf16x8*)(lds + PG8_SB(b, h) + boff + n * 2048 + k * 1024); } while (0)
; #define PG8_MMA(ai, bj, At, Bt) do { __builtin_amdgcn_s_setprio(1); _Pragma("unroll") for (int m = 0; m < 4; ++m) _Pragma("unroll") for (int n = 0; n < 2; ++n) _Pragma("unroll") for (int k = 0; k < 2; ++k) \
;         acc[ai][bj][m][n] = __builtin_amdgcn_mfma_f32_16x16x32_bf16(Bt[n][k], At[m][k], acc[ai][bj][m][n], 0, 0, 0); __builtin_amdgcn_s_setprio(0); } while (0)
; #define PG8_WAIT_V(n) asm volatile("s_waitcnt vmcnt(" #n ")" ::: "memory")
; #define PG8_WAIT_L(n) asm volatile("s_waitcnt lgkmcnt(" #n ")" ::: "memory")
; #define PG8_BAR __builtin_amdgcn_s_barrier()
; #define PG8_SCHED __builtin_amdgcn_sched_barrier(0)
; template <class Epi, class Sched, bool ALIGN_EPI = false, bool SP2 = false>
; __device__ __forceinline__ void gemm_phase(PG8_LAS unsigned char* lds, const Gemm g, const Sched& S, const Epi& E) {
;     ...
;             PG8_LDB(B0, 0, 0); PG8_LDB(B1, 0, 1); PG8_SCHED; PG8_LDA(At, 0, 0); PG8_STAGE(PG8_SA(1, 1), a1 + hstep, voffA);
;             PG8_WAIT_V(8); PG8_WAIT_L(0); PG8_BAR; PG8_MMA(0, 0, At, B0); PG8_MMA(0, 1, At, B1); PG8_BAR; PG8_SCHED;
;     ...
;             PG8_LDA(At, 1, 1); PG8_STAGE(PG8_SB(1, 0), b3, voffB); PG8_STAGE(PG8_SB(1, 1), b3 + hstep, voffB); PG8_STAGE(PG8_SA(1, 0), a3, voffA);
;             PG8_WAIT_V(8); PG8_WAIT_L(0); PG8_BAR; PG8_MMA(1, 0, At, B0); PG8_MMA(1, 1, At, B1); PG8_BAR; PG8_SCHED;
	s_add_i32 s42, s68, s50
	s_mov_b32 m0, s42
	ds_read_b128 v[186:189], v152 offset:49152
	ds_read_b128 v[190:193], v152 offset:50176
	ds_read_b128 v[198:201], v152 offset:51200
	ds_read_b128 v[202:205], v152 offset:52224
	ds_read_b128 v[206:209], v152 offset:53248
	ds_read_b128 v[210:213], v152 offset:54272
	ds_read_b128 v[214:217], v152 offset:55296
	ds_read_b128 v[218:221], v152 offset:56320
	global_load_lds_dwordx4 v132, s[98:99]
	s_add_i32 m0, s42, 0x2000
	s_add_u32 s38, s38, 0x40080
	s_addc_u32 s39, s39, 0
	s_add_i32 s42, s69, s50
	global_load_lds_dwordx4 v128, s[98:99]
	s_mov_b32 m0, s42
	s_nop 0
	global_load_lds_dwordx4 v132, s[38:39]
	s_add_i32 m0, s42, 0x2000
	s_nop 0
	global_load_lds_dwordx4 v128, s[38:39]
	s_mov_b32 m0, s56
	s_nop 0
	global_load_lds_dwordx4 v134, s[100:101]
	s_mov_b32 m0, s57
	s_nop 0
	global_load_lds_dwordx4 v130, s[100:101]
	s_waitcnt vmcnt(8)
	s_waitcnt lgkmcnt(0)
	s_barrier
	v_mfma_f32_16x16x32_bf16 v[60:63], v[154:157], v[186:189], v[60:63]
	v_mfma_f32_16x16x32_bf16 v[52:55], v[162:165], v[186:189], v[52:55]
	v_mfma_f32_16x16x32_bf16 v[44:47], v[154:157], v[198:201], v[44:47]
	v_mfma_f32_16x16x32_bf16 v[36:39], v[162:165], v[198:201], v[36:39]
	v_mfma_f32_16x16x32_bf16 v[28:31], v[154:157], v[206:209], v[28:31]
	v_mfma_f32_16x16x32_bf16 v[20:23], v[162:165], v[206:209], v[20:23]
	v_mfma_f32_16x16x32_bf16 v[12:15], v[154:157], v[214:217], v[12:15]
	v_mfma_f32_16x16x32_bf16 v[4:7], v[162:165], v[214:217], v[4:7]
	v_mfma_f32_16x16x32_bf16 v[60:63], v[158:161], v[190:193], v[60:63]
	v_mfma_f32_16x16x32_bf16 v[52:55], v[166:169], v[190:193], v[52:55]
	v_mfma_f32_16x16x32_bf16 v[44:47], v[158:161], v[202:205], v[44:47]
	v_mfma_f32_16x16x32_bf16 v[36:39], v[166:169], v[202:205], v[36:39]
	v_mfma_f32_16x16x32_bf16 v[28:31], v[158:161], v[210:213], v[28:31]
	v_mfma_f32_16x16x32_bf16 v[20:23], v[166:169], v[210:213], v[20:23]
	v_mfma_f32_16x16x32_bf16 v[12:15], v[158:161], v[218:221], v[12:15]
	v_mfma_f32_16x16x32_bf16 v[4:7], v[166:169], v[218:221], v[4:7]
	v_mfma_f32_16x16x32_bf16 v[56:59], v[170:173], v[186:189], v[56:59]
	v_mfma_f32_16x16x32_bf16 v[48:51], v[178:181], v[186:189], v[48:51]
	v_mfma_f32_16x16x32_bf16 v[40:43], v[170:173], v[198:201], v[40:43]
	v_mfma_f32_16x16x32_bf16 v[32:35], v[178:181], v[198:201], v[32:35]
	v_mfma_f32_16x16x32_bf16 v[24:27], v[170:173], v[206:209], v[24:27]
	v_mfma_f32_16x16x32_bf16 v[16:19], v[178:181], v[206:209], v[16:19]
	v_mfma_f32_16x16x32_bf16 v[8:11], v[170:173], v[214:217], v[8:11]
	v_mfma_f32_16x16x32_bf16 v[0:3], v[178:181], v[214:217], v[0:3]
	v_mfma_f32_16x16x32_bf16 v[56:59], v[174:177], v[190:193], v[56:59]
	v_mfma_f32_16x16x32_bf16 v[48:51], v[182:185], v[190:193], v[48:51]
	v_mfma_f32_16x16x32_bf16 v[40:43], v[174:177], v[202:205], v[40:43]
	v_mfma_f32_16x16x32_bf16 v[32:35], v[182:185], v[202:205], v[32:35]
	v_mfma_f32_16x16x32_bf16 v[24:27], v[174:177], v[210:213], v[24:27]
	v_mfma_f32_16x16x32_bf16 v[16:19], v[182:185], v[210:213], v[16:19]
	v_mfma_f32_16x16x32_bf16 v[8:11], v[174:177], v[218:221], v[8:11]
	v_mfma_f32_16x16x32_bf16 v[0:3], v[182:185], v[218:221], v[0:3]
	s_barrier
	s_add_i32 s67, s67, 2
	s_add_u32 s20, s20, 0x100
	s_addc_u32 s21, s21, 0
	s_add_u32 s65, s65, 0x100
	s_addc_u32 s66, s66, 0
	s_cmp_gt_u32 s67, 13
.LBB0_1740:
	ds_read_b128 v[154:157], v150
	ds_read_b128 v[158:161], v150 offset:1024
	ds_read_b128 v[162:165], v150 offset:2048
	ds_read_b128 v[166:169], v150 offset:3072
	ds_read_b128 v[170:173], v151
	ds_read_b128 v[174:177], v151 offset:1024
	ds_read_b128 v[178:181], v151 offset:2048
	ds_read_b128 v[182:185], v151 offset:3072
	s_add_u32 s38, s20, 0xfffc0080
	s_addc_u32 s39, s21, -1
	s_cmp_eq_u32 s67, 12
	s_cselect_b32 s43, s15, s39
	s_cselect_b32 s42, s63, s38
	s_cselect_b32 s39, s13, s66
	s_cselect_b32 s38, s64, s65
	s_add_i32 m0, s35, 0xc000
	ds_read_b128 v[186:189], v152
	ds_read_b128 v[190:193], v152 offset:1024
	ds_read_b128 v[198:201], v152 offset:2048
	ds_read_b128 v[202:205], v152 offset:3072
	ds_read_b128 v[206:209], v152 offset:4096
	ds_read_b128 v[210:213], v152 offset:5120
	ds_read_b128 v[214:217], v152 offset:6144
	ds_read_b128 v[218:221], v152 offset:7168
	global_load_lds_dwordx4 v136, s[20:21]
	s_add_i32 m0, s35, 0xe000
	s_nop 0
	global_load_lds_dwordx4 v138, s[20:21]
	s_waitcnt vmcnt(8)
	s_waitcnt lgkmcnt(0)
	s_barrier
	v_mfma_f32_16x16x32_bf16 v[124:127], v[154:157], v[186:189], v[124:127]
	v_mfma_f32_16x16x32_bf16 v[116:119], v[162:165], v[186:189], v[116:119]
	v_mfma_f32_16x16x32_bf16 v[108:111], v[154:157], v[198:201], v[108:111]
	v_mfma_f32_16x16x32_bf16 v[100:103], v[162:165], v[198:201], v[100:103]
	v_mfma_f32_16x16x32_bf16 v[92:95], v[154:157], v[206:209], v[92:95]
	v_mfma_f32_16x16x32_bf16 v[84:87], v[162:165], v[206:209], v[84:87]
	v_mfma_f32_16x16x32_bf16 v[76:79], v[154:157], v[214:217], v[76:79]
	v_mfma_f32_16x16x32_bf16 v[68:71], v[162:165], v[214:217], v[68:71]
	v_mfma_f32_16x16x32_bf16 v[124:127], v[158:161], v[190:193], v[124:127]
	v_mfma_f32_16x16x32_bf16 v[116:119], v[166:169], v[190:193], v[116:119]
	v_mfma_f32_16x16x32_bf16 v[108:111], v[158:161], v[202:205], v[108:111]
	v_mfma_f32_16x16x32_bf16 v[100:103], v[166:169], v[202:205], v[100:103]
	v_mfma_f32_16x16x32_bf16 v[92:95], v[158:161], v[210:213], v[92:95]
	v_mfma_f32_16x16x32_bf16 v[84:87], v[166:169], v[210:213], v[84:87]
	v_mfma_f32_16x16x32_bf16 v[76:79], v[158:161], v[218:221], v[76:79]
	v_mfma_f32_16x16x32_bf16 v[68:71], v[166:169], v[218:221], v[68:71]
	v_mfma_f32_16x16x32_bf16 v[120:123], v[170:173], v[186:189], v[120:123]
	v_mfma_f32_16x16x32_bf16 v[112:115], v[178:181], v[186:189], v[112:115]
	v_mfma_f32_16x16x32_bf16 v[104:107], v[170:173], v[198:201], v[104:107]
	v_mfma_f32_16x16x32_bf16 v[96:99], v[178:181], v[198:201], v[96:99]
	v_mfma_f32_16x16x32_bf16 v[88:91], v[170:173], v[206:209], v[88:91]
	v_mfma_f32_16x16x32_bf16 v[80:83], v[178:181], v[206:209], v[80:83]
	v_mfma_f32_16x16x32_bf16 v[72:75], v[170:173], v[214:217], v[72:75]
	v_mfma_f32_16x16x32_bf16 v[64:67], v[178:181], v[214:217], v[64:67]
	v_mfma_f32_16x16x32_bf16 v[120:123], v[174:177], v[190:193], v[120:123]
	v_mfma_f32_16x16x32_bf16 v[112:115], v[182:185], v[190:193], v[112:115]
	v_mfma_f32_16x16x32_bf16 v[104:107], v[174:177], v[202:205], v[104:107]
	v_mfma_f32_16x16x32_bf16 v[96:99], v[182:185], v[202:205], v[96:99]
	v_mfma_f32_16x16x32_bf16 v[88:91], v[174:177], v[210:213], v[88:91]
	v_mfma_f32_16x16x32_bf16 v[80:83], v[182:185], v[210:213], v[80:83]
	v_mfma_f32_16x16x32_bf16 v[72:75], v[174:177], v[218:221], v[72:75]
	v_mfma_f32_16x16x32_bf16 v[64:67], v[182:185], v[218:221], v[64:67]
	s_barrier
; #define PG8_STAGE(bufoff, gbase, voff) do { _Pragma("unroll") for (int _i = 0; _i < 2; ++_i) \
;         __builtin_amdgcn_global_load_lds((const unsigned*)((const char*)(gbase) + (voff)[_i]), (PG8_LAS unsigned*)(lds + (bufoff) + ldsw + _i * 8192), 16, 0, 0); } while (0)
; #define PG8_LDA(dst, b, h) do { _Pragma("unroll") for (int m = 0; m < 4; ++m) _Pragma("unroll") for (int k = 0; k < 2; ++k) dst[m][k] = *(const PG8_LAS bf16x8*)(lds + PG8_SA(b, h) + aoff + m * 2048 + k * 1024); } while (0)
; #define PG8_LDB(dst, b, h) do { _Pragma("unroll") for (int n = 0; n < 2; ++n) _Pragma("unroll") for (int k = 0; k < 2; ++k) dst[n][k] = *(const PG8_LAS bf16x8*)(lds + PG8_SB(b, h) + boff + n * 2048 + k * 1024); } while (0)
; #define PG8_MMA(ai, bj, At, Bt) do { __builtin_amdgcn_s_setprio(1); _Pragma("unroll") for (int m = 0; m < 4; ++m) _Pragma("unroll") for (int n = 0; n < 2; ++n) _Pragma("unroll") for (int k = 0; k < 2; ++k) \
;         acc[ai][bj][m][n] = __builtin_amdgcn_mfma_f32_16x16x32_bf16(Bt[n][k], At[m][k], acc[ai][bj][m][n], 0, 0, 0); __builtin_amdgcn_s_setprio(0); } while (0)
; #define PG8_WAIT_V(n) asm volatile("s_waitcnt vmcnt(" #n ")" ::: "memory")
; #define PG8_WAIT_L(n) asm volatile("s_waitcnt lgkmcnt(" #n ")" ::: "memory")
; #define PG8_BAR __builtin_amdgcn_s_barrier()
; #define PG8_SCHED __builtin_amdgcn_sched_barrier(0)
; template <class Epi, class Sched, bool ALIGN_EPI = false, bool SP2 = false>
; __device__ __forceinline__ void gemm_phase(PG8_LAS unsigned char* lds, const Gemm g, const Sched& S, const Epi& E) {
;     ...
;             PG8_WAIT_V(8); PG8_WAIT_L(0); PG8_BAR; PG8_MMA(0, 0, At, B0); PG8_MMA(0, 1, At, B1); PG8_BAR; PG8_SCHED;
;             PG8_LDA(At, 0, 1); PG8_STAGE(PG8_SB(0, 0), b2, voffB); PG8_STAGE(PG8_SB(0, 1), b2 + hstep, voffB); PG8_STAGE(PG8_SA(0, 0), a2, voffA);
;             PG8_WAIT_V(8); PG8_WAIT_L(0); PG8_BAR; PG8_MMA(1, 0, At, B0); PG8_MMA(1, 1, At, B1); PG8_BAR; PG8_SCHED;
;             PG8_LDB(B0, 1, 0); PG8_LDB(B1, 1, 1); PG8_SCHED; PG8_LDA(At, 1, 0); PG8_STAGE(PG8_SA(0, 1), a2 + hstep, voffA);
	s_add_i32 s68, s58, s50
	s_add_u32 s98, s38, s8
	s_addc_u32 s99, s39, s9
	s_add_u32 s100, s42, s8
	s_addc_u32 s101, s43, s9
	s_mov_b32 m0, s68
	ds_read_b128 v[186:189], v152 offset:16384
	ds_read_b128 v[190:193], v152 offset:17408
	ds_read_b128 v[198:201], v152 offset:18432
	ds_read_b128 v[202:205], v152 offset:19456
	ds_read_b128 v[206:209], v152 offset:20480
	ds_read_b128 v[210:213], v152 offset:21504
	ds_read_b128 v[214:217], v152 offset:22528
	ds_read_b128 v[218:221], v152 offset:23552
	global_load_lds_dwordx4 v132, s[38:39]
	s_add_i32 m0, s68, 0x2000
	s_add_u32 s68, s38, 0x40000
	s_addc_u32 s69, s39, 0
	s_add_i32 s70, s59, s50
	global_load_lds_dwordx4 v128, s[38:39]
	s_mov_b32 m0, s70
	s_nop 0
	global_load_lds_dwordx4 v132, s[68:69]
	s_add_i32 m0, s70, 0x2000
	s_nop 0
	global_load_lds_dwordx4 v128, s[68:69]
	s_mov_b32 m0, s35
	s_nop 0
	global_load_lds_dwordx4 v134, s[42:43]
	s_mov_b32 m0, s52
	s_nop 0
	global_load_lds_dwordx4 v130, s[42:43]
	s_waitcnt vmcnt(8)
	s_waitcnt lgkmcnt(0)
	s_barrier
	v_mfma_f32_16x16x32_bf16 v[60:63], v[154:157], v[186:189], v[60:63]
	v_mfma_f32_16x16x32_bf16 v[52:55], v[162:165], v[186:189], v[52:55]
	v_mfma_f32_16x16x32_bf16 v[44:47], v[154:157], v[198:201], v[44:47]
	v_mfma_f32_16x16x32_bf16 v[36:39], v[162:165], v[198:201], v[36:39]
	v_mfma_f32_16x16x32_bf16 v[28:31], v[154:157], v[206:209], v[28:31]
	v_mfma_f32_16x16x32_bf16 v[20:23], v[162:165], v[206:209], v[20:23]
	v_mfma_f32_16x16x32_bf16 v[12:15], v[154:157], v[214:217], v[12:15]
	v_mfma_f32_16x16x32_bf16 v[4:7], v[162:165], v[214:217], v[4:7]
	v_mfma_f32_16x16x32_bf16 v[60:63], v[158:161], v[190:193], v[60:63]
	v_mfma_f32_16x16x32_bf16 v[52:55], v[166:169], v[190:193], v[52:55]
	v_mfma_f32_16x16x32_bf16 v[44:47], v[158:161], v[202:205], v[44:47]
	v_mfma_f32_16x16x32_bf16 v[36:39], v[166:169], v[202:205], v[36:39]
	v_mfma_f32_16x16x32_bf16 v[28:31], v[158:161], v[210:213], v[28:31]
	v_mfma_f32_16x16x32_bf16 v[20:23], v[166:169], v[210:213], v[20:23]
	v_mfma_f32_16x16x32_bf16 v[12:15], v[158:161], v[218:221], v[12:15]
	v_mfma_f32_16x16x32_bf16 v[4:7], v[166:169], v[218:221], v[4:7]
	v_mfma_f32_16x16x32_bf16 v[56:59], v[170:173], v[186:189], v[56:59]
	v_mfma_f32_16x16x32_bf16 v[48:51], v[178:181], v[186:189], v[48:51]
	v_mfma_f32_16x16x32_bf16 v[40:43], v[170:173], v[198:201], v[40:43]
	v_mfma_f32_16x16x32_bf16 v[32:35], v[178:181], v[198:201], v[32:35]
	v_mfma_f32_16x16x32_bf16 v[24:27], v[170:173], v[206:209], v[24:27]
	v_mfma_f32_16x16x32_bf16 v[16:19], v[178:181], v[206:209], v[16:19]
	v_mfma_f32_16x16x32_bf16 v[8:11], v[170:173], v[214:217], v[8:11]
	v_mfma_f32_16x16x32_bf16 v[0:3], v[178:181], v[214:217], v[0:3]
	v_mfma_f32_16x16x32_bf16 v[56:59], v[174:177], v[190:193], v[56:59]
	v_mfma_f32_16x16x32_bf16 v[48:51], v[182:185], v[190:193], v[48:51]
	v_mfma_f32_16x16x32_bf16 v[40:43], v[174:177], v[202:205], v[40:43]
	v_mfma_f32_16x16x32_bf16 v[32:35], v[182:185], v[202:205], v[32:35]
	v_mfma_f32_16x16x32_bf16 v[24:27], v[174:177], v[210:213], v[24:27]
	v_mfma_f32_16x16x32_bf16 v[16:19], v[182:185], v[210:213], v[16:19]
	v_mfma_f32_16x16x32_bf16 v[8:11], v[174:177], v[218:221], v[8:11]
	v_mfma_f32_16x16x32_bf16 v[0:3], v[182:185], v[218:221], v[0:3]
	s_barrier
	s_add_i32 s68, 0, 0x18000
	v_add_u32_e32 v153, s68, v147
	s_add_i32 s69, 0, 0x1c000
	ds_read_b128 v[154:157], v153
	ds_read_b128 v[158:161], v153 offset:1024
	ds_read_b128 v[162:165], v153 offset:2048
	ds_read_b128 v[166:169], v153 offset:3072
	v_add_u32_e32 v153, s69, v147
	ds_read_b128 v[170:173], v153
	ds_read_b128 v[174:177], v153 offset:1024
	ds_read_b128 v[178:181], v153 offset:2048
	ds_read_b128 v[182:185], v153 offset:3072
	s_add_u32 s42, s42, 0x40000
	s_addc_u32 s43, s43, 0
	s_mov_b32 m0, s53
	ds_read_b128 v[186:189], v152 offset:32768
	ds_read_b128 v[190:193], v152 offset:33792
	ds_read_b128 v[198:201], v152 offset:34816
	ds_read_b128 v[202:205], v152 offset:35840
	ds_read_b128 v[206:209], v152 offset:36864
	ds_read_b128 v[210:213], v152 offset:37888
	ds_read_b128 v[214:217], v152 offset:38912
	ds_read_b128 v[218:221], v152 offset:39936
	global_load_lds_dwordx4 v134, s[42:43]
	s_mov_b32 m0, s54
	s_nop 0
	global_load_lds_dwordx4 v130, s[42:43]
	s_waitcnt vmcnt(8)
	s_waitcnt lgkmcnt(0)
	s_barrier
; #define PG8_STAGE(bufoff, gbase, voff) do { _Pragma("unroll") for (int _i = 0; _i < 2; ++_i) \
;         __builtin_amdgcn_global_load_lds((const unsigned*)((const char*)(gbase) + (voff)[_i]), (PG8_LAS unsigned*)(lds + (bufoff) + ldsw + _i * 8192), 16, 0, 0); } while (0)
; #define PG8_LDA(dst, b, h) do { _Pragma("unroll") for (int m = 0; m < 4; ++m) _Pragma("unroll") for (int k = 0; k < 2; ++k) dst[m][k] = *(const PG8_LAS bf16x8*)(lds + PG8_SA(b, h) + aoff + m * 2048 + k * 1024); } while (0)
; #define PG8_MMA(ai, bj, At, Bt) do { __builtin_amdgcn_s_setprio(1); _Pragma("unroll") for (int m = 0; m < 4; ++m) _Pragma("unroll") for (int n = 0; n < 2; ++n) _Pragma("unroll") for (int k = 0; k < 2; ++k) \
;         acc[ai][bj][m][n] = __builtin_amdgcn_mfma_f32_16x16x32_bf16(Bt[n][k], At[m][k], acc[ai][bj][m][n], 0, 0, 0); __builtin_amdgcn_s_setprio(0); } while (0)
; #define PG8_WAIT_V(n) asm volatile("s_waitcnt vmcnt(" #n ")" ::: "memory")
; #define PG8_WAIT_L(n) asm volatile("s_waitcnt lgkmcnt(" #n ")" ::: "memory")
; #define PG8_BAR __builtin_amdgcn_s_barrier()
; #define PG8_SCHED __builtin_amdgcn_sched_barrier(0)
; template <class Epi, class Sched, bool ALIGN_EPI = false, bool SP2 = false>
; __device__ __forceinline__ void gemm_phase(PG8_LAS unsigned char* lds, const Gemm g, const Sched& S, const Epi& E) {
;     ...
;             PG8_WAIT_V(8); PG8_WAIT_L(0); PG8_BAR; PG8_MMA(0, 0, At, B0); PG8_MMA(0, 1, At, B1); PG8_BAR; PG8_SCHED;
;             PG8_LDA(At, 1, 1); PG8_STAGE(PG8_SB(1, 0), b3, voffB); PG8_STAGE(PG8_SB(1, 1), b3 + hstep, voffB); PG8_STAGE(PG8_SA(1, 0), a3, voffA);
;             PG8_WAIT_V(8); PG8_WAIT_L(0); PG8_BAR; PG8_MMA(1, 0, At, B0); PG8_MMA(1, 1, At, B1); PG8_BAR; PG8_SCHED;
;     ...
;         if constexpr (ALIGN_EPI) { if (wr == 0) PG8_BAR; }
	v_mfma_f32_16x16x32_bf16 v[124:127], v[154:157], v[186:189], v[124:127]
	v_mfma_f32_16x16x32_bf16 v[116:119], v[162:165], v[186:189], v[116:119]
	v_mfma_f32_16x16x32_bf16 v[108:111], v[154:157], v[198:201], v[108:111]
	v_mfma_f32_16x16x32_bf16 v[100:103], v[162:165], v[198:201], v[100:103]
	v_mfma_f32_16x16x32_bf16 v[92:95], v[154:157], v[206:209], v[92:95]
	v_mfma_f32_16x16x32_bf16 v[84:87], v[162:165], v[206:209], v[84:87]
	v_mfma_f32_16x16x32_bf16 v[76:79], v[154:157], v[214:217], v[76:79]
	v_mfma_f32_16x16x32_bf16 v[68:71], v[162:165], v[214:217], v[68:71]
	v_mfma_f32_16x16x32_bf16 v[124:127], v[158:161], v[190:193], v[124:127]
	v_mfma_f32_16x16x32_bf16 v[116:119], v[166:169], v[190:193], v[116:119]
	v_mfma_f32_16x16x32_bf16 v[108:111], v[158:161], v[202:205], v[108:111]
	v_mfma_f32_16x16x32_bf16 v[100:103], v[166:169], v[202:205], v[100:103]
	v_mfma_f32_16x16x32_bf16 v[92:95], v[158:161], v[210:213], v[92:95]
	v_mfma_f32_16x16x32_bf16 v[84:87], v[166:169], v[210:213], v[84:87]
	v_mfma_f32_16x16x32_bf16 v[76:79], v[158:161], v[218:221], v[76:79]
	v_mfma_f32_16x16x32_bf16 v[68:71], v[166:169], v[218:221], v[68:71]
	v_mfma_f32_16x16x32_bf16 v[120:123], v[170:173], v[186:189], v[120:123]
	v_mfma_f32_16x16x32_bf16 v[112:115], v[178:181], v[186:189], v[112:115]
	v_mfma_f32_16x16x32_bf16 v[104:107], v[170:173], v[198:201], v[104:107]
	v_mfma_f32_16x16x32_bf16 v[96:99], v[178:181], v[198:201], v[96:99]
	v_mfma_f32_16x16x32_bf16 v[88:91], v[170:173], v[206:209], v[88:91]
	v_mfma_f32_16x16x32_bf16 v[80:83], v[178:181], v[206:209], v[80:83]
	v_mfma_f32_16x16x32_bf16 v[72:75], v[170:173], v[214:217], v[72:75]
	v_mfma_f32_16x16x32_bf16 v[64:67], v[178:181], v[214:217], v[64:67]
	v_mfma_f32_16x16x32_bf16 v[120:123], v[174:177], v[190:193], v[120:123]
	v_mfma_f32_16x16x32_bf16 v[112:115], v[182:185], v[190:193], v[112:115]
	v_mfma_f32_16x16x32_bf16 v[104:107], v[174:177], v[202:205], v[104:107]
	v_mfma_f32_16x16x32_bf16 v[96:99], v[182:185], v[202:205], v[96:99]
	v_mfma_f32_16x16x32_bf16 v[88:91], v[174:177], v[210:213], v[88:91]
	v_mfma_f32_16x16x32_bf16 v[80:83], v[182:185], v[210:213], v[80:83]
	v_mfma_f32_16x16x32_bf16 v[72:75], v[174:177], v[218:221], v[72:75]
	v_mfma_f32_16x16x32_bf16 v[64:67], v[182:185], v[218:221], v[64:67]
	s_barrier
	s_add_i32 s42, s68, s50
	s_mov_b32 m0, s42
	ds_read_b128 v[186:189], v152 offset:49152
	ds_read_b128 v[190:193], v152 offset:50176
	ds_read_b128 v[198:201], v152 offset:51200
	ds_read_b128 v[202:205], v152 offset:52224
	ds_read_b128 v[206:209], v152 offset:53248
	ds_read_b128 v[210:213], v152 offset:54272
	ds_read_b128 v[214:217], v152 offset:55296
	ds_read_b128 v[218:221], v152 offset:56320
	global_load_lds_dwordx4 v132, s[98:99]
	s_add_i32 m0, s42, 0x2000
	s_add_u32 s38, s38, 0x40080
	s_addc_u32 s39, s39, 0
	s_add_i32 s42, s69, s50
	global_load_lds_dwordx4 v128, s[98:99]
	s_mov_b32 m0, s42
	s_nop 0
	global_load_lds_dwordx4 v132, s[38:39]
	s_add_i32 m0, s42, 0x2000
	s_nop 0
	global_load_lds_dwordx4 v128, s[38:39]
	s_mov_b32 m0, s56
	s_nop 0
	global_load_lds_dwordx4 v134, s[100:101]
	s_mov_b32 m0, s57
	s_nop 0
	global_load_lds_dwordx4 v130, s[100:101]
	s_waitcnt vmcnt(8)
	s_waitcnt lgkmcnt(0)
	s_barrier
	v_mfma_f32_16x16x32_bf16 v[60:63], v[154:157], v[186:189], v[60:63]
	v_mfma_f32_16x16x32_bf16 v[52:55], v[162:165], v[186:189], v[52:55]
	v_mfma_f32_16x16x32_bf16 v[44:47], v[154:157], v[198:201], v[44:47]
	v_mfma_f32_16x16x32_bf16 v[36:39], v[162:165], v[198:201], v[36:39]
	v_mfma_f32_16x16x32_bf16 v[28:31], v[154:157], v[206:209], v[28:31]
	v_mfma_f32_16x16x32_bf16 v[20:23], v[162:165], v[206:209], v[20:23]
	v_mfma_f32_16x16x32_bf16 v[12:15], v[154:157], v[214:217], v[12:15]
	v_mfma_f32_16x16x32_bf16 v[4:7], v[162:165], v[214:217], v[4:7]
	v_mfma_f32_16x16x32_bf16 v[60:63], v[158:161], v[190:193], v[60:63]
	v_mfma_f32_16x16x32_bf16 v[52:55], v[166:169], v[190:193], v[52:55]
	v_mfma_f32_16x16x32_bf16 v[44:47], v[158:161], v[202:205], v[44:47]
	v_mfma_f32_16x16x32_bf16 v[36:39], v[166:169], v[202:205], v[36:39]
	v_mfma_f32_16x16x32_bf16 v[28:31], v[158:161], v[210:213], v[28:31]
	v_mfma_f32_16x16x32_bf16 v[20:23], v[166:169], v[210:213], v[20:23]
	v_mfma_f32_16x16x32_bf16 v[12:15], v[158:161], v[218:221], v[12:15]
	v_mfma_f32_16x16x32_bf16 v[4:7], v[166:169], v[218:221], v[4:7]
	v_mfma_f32_16x16x32_bf16 v[56:59], v[170:173], v[186:189], v[56:59]
	v_mfma_f32_16x16x32_bf16 v[48:51], v[178:181], v[186:189], v[48:51]
	v_mfma_f32_16x16x32_bf16 v[40:43], v[170:173], v[198:201], v[40:43]
	v_mfma_f32_16x16x32_bf16 v[32:35], v[178:181], v[198:201], v[32:35]
	v_mfma_f32_16x16x32_bf16 v[24:27], v[170:173], v[206:209], v[24:27]
	v_mfma_f32_16x16x32_bf16 v[16:19], v[178:181], v[206:209], v[16:19]
	v_mfma_f32_16x16x32_bf16 v[8:11], v[170:173], v[214:217], v[8:11]
	v_mfma_f32_16x16x32_bf16 v[0:3], v[178:181], v[214:217], v[0:3]
	v_mfma_f32_16x16x32_bf16 v[56:59], v[174:177], v[190:193], v[56:59]
	v_mfma_f32_16x16x32_bf16 v[48:51], v[182:185], v[190:193], v[48:51]
	v_mfma_f32_16x16x32_bf16 v[40:43], v[174:177], v[202:205], v[40:43]
	v_mfma_f32_16x16x32_bf16 v[32:35], v[182:185], v[202:205], v[32:35]
	v_mfma_f32_16x16x32_bf16 v[24:27], v[174:177], v[210:213], v[24:27]
	v_mfma_f32_16x16x32_bf16 v[16:19], v[182:185], v[210:213], v[16:19]
	v_mfma_f32_16x16x32_bf16 v[8:11], v[174:177], v[218:221], v[8:11]
	v_mfma_f32_16x16x32_bf16 v[0:3], v[182:185], v[218:221], v[0:3]
	s_barrier
	s_add_i32 s67, s67, 2
	s_add_u32 s20, s20, 0x100
	s_addc_u32 s21, s21, 0
	s_add_u32 s65, s65, 0x100
	s_addc_u32 s66, s66, 0
	s_cmp_gt_u32 s67, 13
	s_cbranch_scc0 .LBB0_1740
	s_and_b64 vcc, exec, s[10:11]
	s_cbranch_vccz .LBB0_1743
	s_barrier

; #define PG8_STAGE(bufoff, gbase, voff) do { _Pragma("unroll") for (int _i = 0; _i < 2; ++_i) \
;         __builtin_amdgcn_global_load_lds((const unsigned*)((const char*)(gbase) + (voff)[_i]), (PG8_LAS unsigned*)(lds + (bufoff) + ldsw + _i * 8192), 16, 0, 0); } while (0)
; #define PG8_LDA(dst, b, h) do { _Pragma("unroll") for (int m = 0; m < 4; ++m) _Pragma("unroll") for (int k = 0; k < 2; ++k) dst[m][k] = *(const PG8_LAS bf16x8*)(lds + PG8_SA(b, h) + aoff + m * 2048 + k * 1024); } while (0)
; #define PG8_LDB(dst, b, h) do { _Pragma("unroll") for (int n = 0; n < 2; ++n) _Pragma("unroll") for (int k = 0; k < 2; ++k) dst[n][k] = *(const PG8_LAS bf16x8*)(lds + PG8_SB(b, h) + boff + n * 2048 + k * 1024); } while (0)
; #define PG8_WAIT_V(n) asm volatile("s_waitcnt vmcnt(" #n ")" ::: "memory")
; #define PG8_WAIT_L(n) asm volatile("s_waitcnt lgkmcnt(" #n ")" ::: "memory")
; #define PG8_BAR __builtin_amdgcn_s_barrier()
; #define PG8_SCHED __builtin_amdgcn_sched_barrier(0)
; template <class Epi, class Sched, bool ALIGN_EPI = false, bool SP2 = false>
; __device__ __forceinline__ void gemm_phase(PG8_LAS unsigned char* lds, const Gemm g, const Sched& S, const Epi& E) {
;     ...
;             const bool last = (t == nt - 2);
;             const char* a1 = cA + (size_t)(t + 1) * kstep;
;             const char* a2 = last ? nA : cA + (size_t)(t + 2) * kstep; const char* b2 = last ? nB : cB + (size_t)(t + 2) * kstep;
;             const char* a3 = a2 + kstep; const char* b3 = b2 + kstep;
;             if (last && has_next) S.a_ready(nxt);
;             if constexpr (SP2) {
;             PG8_LDB(B0, 0, 0); PG8_LDB(B1, 0, 1); PG8_SCHED; PG8_LDA(At, 0, 0); PG8_STAGE(PG8_SA(1, 1), a1 + hstep, voffA);
;             PG8_WAIT_V(8); PG8_WAIT_L(0); PG8_BAR; PG8_MMA(0, 0, At, B0); PG8_MMA(0, 1, At, B1); PG8_BAR; PG8_SCHED;
;             PG8_LDA(At, 0, 1); PG8_STAGE(PG8_SB(0, 0), b2, voffB); PG8_STAGE(PG8_SB(0, 1), b2 + hstep, voffB); PG8_STAGE(PG8_SA(0, 0), a2, voffA);
;             PG8_WAIT_V(8); PG8_WAIT_L(0); PG8_BAR; PG8_MMA(1, 0, At, B0); PG8_MMA(1, 1, At, B1); PG8_BAR; PG8_SCHED;
;             PG8_LDB(B0, 1, 0); PG8_LDB(B1, 1, 1); PG8_SCHED; PG8_LDA(At, 1, 0); PG8_STAGE(PG8_SA(0, 1), a2 + hstep, voffA);
;             PG8_WAIT_V(8); PG8_WAIT_L(0); PG8_BAR; PG8_MMA(0, 0, At, B0); PG8_MMA(0, 1, At, B1); PG8_BAR; PG8_SCHED;
.LBB0_1824:
	s_add_u32 s20, s20, 0xb0080
	s_addc_u32 s21, s21, 0
	s_add_u32 s68, s34, 0x100
	s_addc_u32 s69, s35, 0
	s_mov_b32 s70, -2
	s_waitcnt lgkmcnt(0)
	ds_read_b128 v[96:99], v222
	ds_read_b128 v[108:111], v222 offset:1024
	ds_read_b128 v[120:123], v222 offset:2048
	ds_read_b128 v[128:131], v222 offset:3072
	ds_read_b128 v[144:147], v223
	ds_read_b128 v[148:151], v223 offset:1024
	ds_read_b128 v[152:155], v223 offset:2048
	ds_read_b128 v[156:159], v223 offset:3072
	s_add_u32 s34, s20, 0xfff50080
	s_addc_u32 s35, s21, -1
	s_cmp_eq_u32 s70, 40
	s_cselect_b32 s47, s1, s35
	s_cselect_b32 s46, s0, s34
	s_cselect_b32 s35, s45, s69
	s_cselect_b32 s34, s44, s68
	s_add_i32 m0, s49, 0xc000
	ds_read_b128 v[160:163], v224
	ds_read_b128 v[164:167], v224 offset:1024
	ds_read_b128 v[168:171], v224 offset:2048
	ds_read_b128 v[172:175], v224 offset:3072
	ds_read_b128 v[176:179], v224 offset:4096
	ds_read_b128 v[180:183], v224 offset:5120
	ds_read_b128 v[202:205], v224 offset:6144
	ds_read_b128 v[206:209], v224 offset:7168
	global_load_lds_dwordx4 v192, s[20:21]
	s_add_i32 m0, s49, 0xe000
	s_nop 0
	global_load_lds_dwordx4 v194, s[20:21]
	s_waitcnt vmcnt(8)
	s_waitcnt lgkmcnt(0)
	s_barrier
	v_mfma_f32_16x16x32_bf16 v[140:143], v[96:99], v[160:163], 0
	v_mfma_f32_16x16x32_bf16 v[136:139], v[120:123], v[160:163], 0
	v_mfma_f32_16x16x32_bf16 v[116:119], v[96:99], v[168:171], 0
	v_mfma_f32_16x16x32_bf16 v[112:115], v[120:123], v[168:171], 0
	v_mfma_f32_16x16x32_bf16 v[92:95], v[96:99], v[176:179], 0
	v_mfma_f32_16x16x32_bf16 v[88:91], v[120:123], v[176:179], 0
	v_mfma_f32_16x16x32_bf16 v[76:79], v[96:99], v[202:205], 0
	v_mfma_f32_16x16x32_bf16 v[72:75], v[120:123], v[202:205], 0
	v_mfma_f32_16x16x32_bf16 v[140:143], v[108:111], v[164:167], v[140:143]
	v_mfma_f32_16x16x32_bf16 v[136:139], v[128:131], v[164:167], v[136:139]
	v_mfma_f32_16x16x32_bf16 v[116:119], v[108:111], v[172:175], v[116:119]
	v_mfma_f32_16x16x32_bf16 v[112:115], v[128:131], v[172:175], v[112:115]
	v_mfma_f32_16x16x32_bf16 v[92:95], v[108:111], v[180:183], v[92:95]
	v_mfma_f32_16x16x32_bf16 v[88:91], v[128:131], v[180:183], v[88:91]
	v_mfma_f32_16x16x32_bf16 v[76:79], v[108:111], v[206:209], v[76:79]
	v_mfma_f32_16x16x32_bf16 v[72:75], v[128:131], v[206:209], v[72:75]
	v_mfma_f32_16x16x32_bf16 v[132:135], v[144:147], v[160:163], 0
	v_mfma_f32_16x16x32_bf16 v[124:127], v[152:155], v[160:163], 0
	v_mfma_f32_16x16x32_bf16 v[104:107], v[144:147], v[168:171], 0
	v_mfma_f32_16x16x32_bf16 v[100:103], v[152:155], v[168:171], 0
	v_mfma_f32_16x16x32_bf16 v[84:87], v[144:147], v[176:179], 0
	v_mfma_f32_16x16x32_bf16 v[80:83], v[152:155], v[176:179], 0
	v_mfma_f32_16x16x32_bf16 v[68:71], v[144:147], v[202:205], 0
	v_mfma_f32_16x16x32_bf16 v[64:67], v[152:155], v[202:205], 0
	v_mfma_f32_16x16x32_bf16 v[132:135], v[148:151], v[164:167], v[132:135]
	v_mfma_f32_16x16x32_bf16 v[124:127], v[156:159], v[164:167], v[124:127]
	v_mfma_f32_16x16x32_bf16 v[104:107], v[148:151], v[172:175], v[104:107]
	v_mfma_f32_16x16x32_bf16 v[100:103], v[156:159], v[172:175], v[100:103]
	v_mfma_f32_16x16x32_bf16 v[84:87], v[148:151], v[180:183], v[84:87]
	v_mfma_f32_16x16x32_bf16 v[80:83], v[156:159], v[180:183], v[80:83]
	v_mfma_f32_16x16x32_bf16 v[68:71], v[148:151], v[206:209], v[68:71]
	v_mfma_f32_16x16x32_bf16 v[64:67], v[156:159], v[206:209], v[64:67]
	s_barrier
	s_add_i32 s71, s62, s48
	s_add_u32 s98, s34, s12
	s_addc_u32 s99, s35, s13
	s_add_u32 s100, s46, s12
	s_addc_u32 s101, s47, s13
	s_mov_b32 m0, s71
	ds_read_b128 v[160:163], v224 offset:16384
	ds_read_b128 v[164:167], v224 offset:17408
	ds_read_b128 v[168:171], v224 offset:18432
	ds_read_b128 v[172:175], v224 offset:19456
	ds_read_b128 v[176:179], v224 offset:20480
	ds_read_b128 v[180:183], v224 offset:21504
	ds_read_b128 v[202:205], v224 offset:22528
	ds_read_b128 v[206:209], v224 offset:23552
	global_load_lds_dwordx4 v186, s[34:35]
	s_add_i32 m0, s71, 0x2000
	s_add_u32 s72, s34, 0xb0000
	s_addc_u32 s73, s35, 0
	s_add_i32 s71, s63, s48
	global_load_lds_dwordx4 v190, s[34:35]
	s_mov_b32 m0, s71
	s_nop 0
	global_load_lds_dwordx4 v186, s[72:73]
	s_add_i32 m0, s71, 0x2000
	s_nop 0
	global_load_lds_dwordx4 v190, s[72:73]
	s_mov_b32 m0, s49
	s_nop 0
	global_load_lds_dwordx4 v184, s[46:47]
	s_mov_b32 m0, s50
	s_nop 0
	global_load_lds_dwordx4 v188, s[46:47]
	s_waitcnt vmcnt(8)
	s_waitcnt lgkmcnt(0)
	s_barrier
	v_mfma_f32_16x16x32_bf16 v[60:63], v[96:99], v[160:163], 0
	v_mfma_f32_16x16x32_bf16 v[56:59], v[120:123], v[160:163], 0
	v_mfma_f32_16x16x32_bf16 v[44:47], v[96:99], v[168:171], 0
	v_mfma_f32_16x16x32_bf16 v[40:43], v[120:123], v[168:171], 0
	v_mfma_f32_16x16x32_bf16 v[28:31], v[96:99], v[176:179], 0
	v_mfma_f32_16x16x32_bf16 v[24:27], v[120:123], v[176:179], 0
	v_mfma_f32_16x16x32_bf16 v[12:15], v[96:99], v[202:205], 0
	v_mfma_f32_16x16x32_bf16 v[8:11], v[120:123], v[202:205], 0
	v_mfma_f32_16x16x32_bf16 v[60:63], v[108:111], v[164:167], v[60:63]
	v_mfma_f32_16x16x32_bf16 v[56:59], v[128:131], v[164:167], v[56:59]
	v_mfma_f32_16x16x32_bf16 v[44:47], v[108:111], v[172:175], v[44:47]
	v_mfma_f32_16x16x32_bf16 v[40:43], v[128:131], v[172:175], v[40:43]
	v_mfma_f32_16x16x32_bf16 v[28:31], v[108:111], v[180:183], v[28:31]
	v_mfma_f32_16x16x32_bf16 v[24:27], v[128:131], v[180:183], v[24:27]
	v_mfma_f32_16x16x32_bf16 v[12:15], v[108:111], v[206:209], v[12:15]
	v_mfma_f32_16x16x32_bf16 v[8:11], v[128:131], v[206:209], v[8:11]
	v_mfma_f32_16x16x32_bf16 v[52:55], v[144:147], v[160:163], 0
	v_mfma_f32_16x16x32_bf16 v[48:51], v[152:155], v[160:163], 0
	v_mfma_f32_16x16x32_bf16 v[36:39], v[144:147], v[168:171], 0
	v_mfma_f32_16x16x32_bf16 v[32:35], v[152:155], v[168:171], 0
	v_mfma_f32_16x16x32_bf16 v[20:23], v[144:147], v[176:179], 0
	v_mfma_f32_16x16x32_bf16 v[16:19], v[152:155], v[176:179], 0
	v_mfma_f32_16x16x32_bf16 v[4:7], v[144:147], v[202:205], 0
	v_mfma_f32_16x16x32_bf16 v[0:3], v[152:155], v[202:205], 0
	v_mfma_f32_16x16x32_bf16 v[52:55], v[148:151], v[164:167], v[52:55]
	v_mfma_f32_16x16x32_bf16 v[48:51], v[156:159], v[164:167], v[48:51]
	v_mfma_f32_16x16x32_bf16 v[36:39], v[148:151], v[172:175], v[36:39]
	v_mfma_f32_16x16x32_bf16 v[32:35], v[156:159], v[172:175], v[32:35]
	v_mfma_f32_16x16x32_bf16 v[20:23], v[148:151], v[180:183], v[20:23]
	v_mfma_f32_16x16x32_bf16 v[16:19], v[156:159], v[180:183], v[16:19]
	v_mfma_f32_16x16x32_bf16 v[4:7], v[148:151], v[206:209], v[4:7]
	v_mfma_f32_16x16x32_bf16 v[0:3], v[156:159], v[206:209], v[0:3]
	s_barrier
; #define PG8_STAGE(bufoff, gbase, voff) do { _Pragma("unroll") for (int _i = 0; _i < 2; ++_i) \
;         __builtin_amdgcn_global_load_lds((const unsigned*)((const char*)(gbase) + (voff)[_i]), (PG8_LAS unsigned*)(lds + (bufoff) + ldsw + _i * 8192), 16, 0, 0); } while (0)
; #define PG8_LDA(dst, b, h) do { _Pragma("unroll") for (int m = 0; m < 4; ++m) _Pragma("unroll") for (int k = 0; k < 2; ++k) dst[m][k] = *(const PG8_LAS bf16x8*)(lds + PG8_SA(b, h) + aoff + m * 2048 + k * 1024); } while (0)
; #define PG8_LDB(dst, b, h) do { _Pragma("unroll") for (int n = 0; n < 2; ++n) _Pragma("unroll") for (int k = 0; k < 2; ++k) dst[n][k] = *(const PG8_LAS bf16x8*)(lds + PG8_SB(b, h) + boff + n * 2048 + k * 1024); } while (0)
; #define PG8_MMA(ai, bj, At, Bt) do { __builtin_amdgcn_s_setprio(1); _Pragma("unroll") for (int m = 0; m < 4; ++m) _Pragma("unroll") for (int n = 0; n < 2; ++n) _Pragma("unroll") for (int k = 0; k < 2; ++k) \
;         acc[ai][bj][m][n] = __builtin_amdgcn_mfma_f32_16x16x32_bf16(Bt[n][k], At[m][k], acc[ai][bj][m][n], 0, 0, 0); __builtin_amdgcn_s_setprio(0); } while (0)
; #define PG8_WAIT_V(n) asm volatile("s_waitcnt vmcnt(" #n ")" ::: "memory")
; #define PG8_WAIT_L(n) asm volatile("s_waitcnt lgkmcnt(" #n ")" ::: "memory")
; #define PG8_BAR __builtin_amdgcn_s_barrier()
; #define PG8_SCHED __builtin_amdgcn_sched_barrier(0)
; template <class Epi, class Sched, bool ALIGN_EPI = false, bool SP2 = false>
; __device__ __forceinline__ void gemm_phase(PG8_LAS unsigned char* lds, const Gemm g, const Sched& S, const Epi& E) {
;     ...
;             PG8_LDB(B0, 1, 0); PG8_LDB(B1, 1, 1); PG8_SCHED; PG8_LDA(At, 1, 0); PG8_STAGE(PG8_SA(0, 1), a2 + hstep, voffA);
;             PG8_WAIT_V(8); PG8_WAIT_L(0); PG8_BAR; PG8_MMA(0, 0, At, B0); PG8_MMA(0, 1, At, B1); PG8_BAR; PG8_SCHED;
;             PG8_LDA(At, 1, 1); PG8_STAGE(PG8_SB(1, 0), b3, voffB); PG8_STAGE(PG8_SB(1, 1), b3 + hstep, voffB); PG8_STAGE(PG8_SA(1, 0), a3, voffA);
;             PG8_WAIT_V(8); PG8_WAIT_L(0); PG8_BAR; PG8_MMA(1, 0, At, B0); PG8_MMA(1, 1, At, B1); PG8_BAR; PG8_SCHED;
	s_add_i32 s71, 0, 0x18000
	s_add_i32 s72, 0, 0x1c000
	v_add_u32_e32 v128, s71, v197
	v_add_u32_e32 v156, s72, v197
	ds_read_b128 v[96:99], v128
	ds_read_b128 v[108:111], v128 offset:1024
	ds_read_b128 v[120:123], v128 offset:2048
	ds_read_b128 v[128:131], v128 offset:3072
	ds_read_b128 v[144:147], v156
	ds_read_b128 v[148:151], v156 offset:1024
	ds_read_b128 v[152:155], v156 offset:2048
	ds_read_b128 v[156:159], v156 offset:3072
	s_add_u32 s46, s46, 0xb0000
	s_addc_u32 s47, s47, 0
	s_mov_b32 m0, s51
	ds_read_b128 v[160:163], v224 offset:32768
	ds_read_b128 v[164:167], v224 offset:33792
	ds_read_b128 v[168:171], v224 offset:34816
	ds_read_b128 v[172:175], v224 offset:35840
	ds_read_b128 v[176:179], v224 offset:36864
	ds_read_b128 v[180:183], v224 offset:37888
	ds_read_b128 v[202:205], v224 offset:38912
	ds_read_b128 v[206:209], v224 offset:39936
	global_load_lds_dwordx4 v184, s[46:47]
	s_mov_b32 m0, s52
	s_nop 0
	global_load_lds_dwordx4 v188, s[46:47]
	s_waitcnt vmcnt(8)
	s_waitcnt lgkmcnt(0)
	s_barrier
	v_mfma_f32_16x16x32_bf16 v[140:143], v[96:99], v[160:163], v[140:143]
	v_mfma_f32_16x16x32_bf16 v[136:139], v[120:123], v[160:163], v[136:139]
	v_mfma_f32_16x16x32_bf16 v[116:119], v[96:99], v[168:171], v[116:119]
	v_mfma_f32_16x16x32_bf16 v[112:115], v[120:123], v[168:171], v[112:115]
	v_mfma_f32_16x16x32_bf16 v[92:95], v[96:99], v[176:179], v[92:95]
	v_mfma_f32_16x16x32_bf16 v[88:91], v[120:123], v[176:179], v[88:91]
	v_mfma_f32_16x16x32_bf16 v[76:79], v[96:99], v[202:205], v[76:79]
	v_mfma_f32_16x16x32_bf16 v[72:75], v[120:123], v[202:205], v[72:75]
	v_mfma_f32_16x16x32_bf16 v[140:143], v[108:111], v[164:167], v[140:143]
	v_mfma_f32_16x16x32_bf16 v[136:139], v[128:131], v[164:167], v[136:139]
	v_mfma_f32_16x16x32_bf16 v[116:119], v[108:111], v[172:175], v[116:119]
	v_mfma_f32_16x16x32_bf16 v[112:115], v[128:131], v[172:175], v[112:115]
	v_mfma_f32_16x16x32_bf16 v[92:95], v[108:111], v[180:183], v[92:95]
	v_mfma_f32_16x16x32_bf16 v[88:91], v[128:131], v[180:183], v[88:91]
	v_mfma_f32_16x16x32_bf16 v[76:79], v[108:111], v[206:209], v[76:79]
	v_mfma_f32_16x16x32_bf16 v[72:75], v[128:131], v[206:209], v[72:75]
	v_mfma_f32_16x16x32_bf16 v[132:135], v[144:147], v[160:163], v[132:135]
	v_mfma_f32_16x16x32_bf16 v[124:127], v[152:155], v[160:163], v[124:127]
	v_mfma_f32_16x16x32_bf16 v[104:107], v[144:147], v[168:171], v[104:107]
	v_mfma_f32_16x16x32_bf16 v[100:103], v[152:155], v[168:171], v[100:103]
	v_mfma_f32_16x16x32_bf16 v[84:87], v[144:147], v[176:179], v[84:87]
	v_mfma_f32_16x16x32_bf16 v[80:83], v[152:155], v[176:179], v[80:83]
	v_mfma_f32_16x16x32_bf16 v[68:71], v[144:147], v[202:205], v[68:71]
	v_mfma_f32_16x16x32_bf16 v[64:67], v[152:155], v[202:205], v[64:67]
	v_mfma_f32_16x16x32_bf16 v[132:135], v[148:151], v[164:167], v[132:135]
	v_mfma_f32_16x16x32_bf16 v[124:127], v[156:159], v[164:167], v[124:127]
	v_mfma_f32_16x16x32_bf16 v[104:107], v[148:151], v[172:175], v[104:107]
	v_mfma_f32_16x16x32_bf16 v[100:103], v[156:159], v[172:175], v[100:103]
	v_mfma_f32_16x16x32_bf16 v[84:87], v[148:151], v[180:183], v[84:87]
	v_mfma_f32_16x16x32_bf16 v[80:83], v[156:159], v[180:183], v[80:83]
	v_mfma_f32_16x16x32_bf16 v[68:71], v[148:151], v[206:209], v[68:71]
	v_mfma_f32_16x16x32_bf16 v[64:67], v[156:159], v[206:209], v[64:67]
	s_barrier
	s_add_i32 s46, s71, s48
	s_mov_b32 m0, s46
	ds_read_b128 v[160:163], v224 offset:49152
	ds_read_b128 v[164:167], v224 offset:50176
	ds_read_b128 v[168:171], v224 offset:51200
	ds_read_b128 v[172:175], v224 offset:52224
	ds_read_b128 v[176:179], v224 offset:53248
	ds_read_b128 v[180:183], v224 offset:54272
	ds_read_b128 v[202:205], v224 offset:55296
	ds_read_b128 v[206:209], v224 offset:56320
	global_load_lds_dwordx4 v186, s[98:99]
	s_add_i32 m0, s46, 0x2000
	s_add_u32 s34, s34, 0xb0080
	s_addc_u32 s35, s35, 0
	s_add_i32 s46, s72, s48
	global_load_lds_dwordx4 v190, s[98:99]
	s_mov_b32 m0, s46
	s_nop 0
	global_load_lds_dwordx4 v186, s[34:35]
	s_add_i32 m0, s46, 0x2000
	s_nop 0
	global_load_lds_dwordx4 v190, s[34:35]
	s_mov_b32 m0, s57
	s_nop 0
	global_load_lds_dwordx4 v184, s[100:101]
	s_mov_b32 m0, s58
	s_nop 0
	global_load_lds_dwordx4 v188, s[100:101]
	s_waitcnt vmcnt(8)
	s_waitcnt lgkmcnt(0)
	s_barrier
	v_mfma_f32_16x16x32_bf16 v[60:63], v[96:99], v[160:163], v[60:63]
	v_mfma_f32_16x16x32_bf16 v[56:59], v[120:123], v[160:163], v[56:59]
	v_mfma_f32_16x16x32_bf16 v[44:47], v[96:99], v[168:171], v[44:47]
	v_mfma_f32_16x16x32_bf16 v[40:43], v[120:123], v[168:171], v[40:43]
	v_mfma_f32_16x16x32_bf16 v[28:31], v[96:99], v[176:179], v[28:31]
	v_mfma_f32_16x16x32_bf16 v[24:27], v[120:123], v[176:179], v[24:27]
	v_mfma_f32_16x16x32_bf16 v[12:15], v[96:99], v[202:205], v[12:15]
	v_mfma_f32_16x16x32_bf16 v[8:11], v[120:123], v[202:205], v[8:11]
	v_mfma_f32_16x16x32_bf16 v[60:63], v[108:111], v[164:167], v[60:63]
	v_mfma_f32_16x16x32_bf16 v[56:59], v[128:131], v[164:167], v[56:59]
	v_mfma_f32_16x16x32_bf16 v[44:47], v[108:111], v[172:175], v[44:47]
	v_mfma_f32_16x16x32_bf16 v[40:43], v[128:131], v[172:175], v[40:43]
	v_mfma_f32_16x16x32_bf16 v[28:31], v[108:111], v[180:183], v[28:31]
	v_mfma_f32_16x16x32_bf16 v[24:27], v[128:131], v[180:183], v[24:27]
	v_mfma_f32_16x16x32_bf16 v[12:15], v[108:111], v[206:209], v[12:15]
	v_mfma_f32_16x16x32_bf16 v[8:11], v[128:131], v[206:209], v[8:11]
	v_mfma_f32_16x16x32_bf16 v[52:55], v[144:147], v[160:163], v[52:55]
	v_mfma_f32_16x16x32_bf16 v[48:51], v[152:155], v[160:163], v[48:51]
	v_mfma_f32_16x16x32_bf16 v[36:39], v[144:147], v[168:171], v[36:39]
	v_mfma_f32_16x16x32_bf16 v[32:35], v[152:155], v[168:171], v[32:35]
	v_mfma_f32_16x16x32_bf16 v[20:23], v[144:147], v[176:179], v[20:23]
	v_mfma_f32_16x16x32_bf16 v[16:19], v[152:155], v[176:179], v[16:19]
	v_mfma_f32_16x16x32_bf16 v[4:7], v[144:147], v[202:205], v[4:7]
	v_mfma_f32_16x16x32_bf16 v[0:3], v[152:155], v[202:205], v[0:3]
	v_mfma_f32_16x16x32_bf16 v[52:55], v[148:151], v[164:167], v[52:55]
	v_mfma_f32_16x16x32_bf16 v[48:51], v[156:159], v[164:167], v[48:51]
	v_mfma_f32_16x16x32_bf16 v[36:39], v[148:151], v[172:175], v[36:39]
	v_mfma_f32_16x16x32_bf16 v[32:35], v[156:159], v[172:175], v[32:35]
	v_mfma_f32_16x16x32_bf16 v[20:23], v[148:151], v[180:183], v[20:23]
	v_mfma_f32_16x16x32_bf16 v[16:19], v[156:159], v[180:183], v[16:19]
	v_mfma_f32_16x16x32_bf16 v[4:7], v[148:151], v[206:209], v[4:7]
	v_mfma_f32_16x16x32_bf16 v[0:3], v[156:159], v[206:209], v[0:3]
	s_barrier
	s_add_i32 s70, s70, 2
	s_add_u32 s20, s20, 0x100
	s_addc_u32 s21, s21, 0
	s_add_u32 s68, s68, 0x100
	s_addc_u32 s69, s69, 0
	s_cmp_gt_u32 s70, 41
; #define PG8_STAGE(bufoff, gbase, voff) do { _Pragma("unroll") for (int _i = 0; _i < 2; ++_i) \
;         __builtin_amdgcn_global_load_lds((const unsigned*)((const char*)(gbase) + (voff)[_i]), (PG8_LAS unsigned*)(lds + (bufoff) + ldsw + _i * 8192), 16, 0, 0); } while (0)
; #define PG8_LDA(dst, b, h) do { _Pragma("unroll") for (int m = 0; m < 4; ++m) _Pragma("unroll") for (int k = 0; k < 2; ++k) dst[m][k] = *(const PG8_LAS bf16x8*)(lds + PG8_SA(b, h) + aoff + m * 2048 + k * 1024); } while (0)
; #define PG8_LDB(dst, b, h) do { _Pragma("unroll") for (int n = 0; n < 2; ++n) _Pragma("unroll") for (int k = 0; k < 2; ++k) dst[n][k] = *(const PG8_LAS bf16x8*)(lds + PG8_SB(b, h) + boff + n * 2048 + k * 1024); } while (0)
; #define PG8_MMA(ai, bj, At, Bt) do { __builtin_amdgcn_s_setprio(1); _Pragma("unroll") for (int m = 0; m < 4; ++m) _Pragma("unroll") for (int n = 0; n < 2; ++n) _Pragma("unroll") for (int k = 0; k < 2; ++k) \
;         acc[ai][bj][m][n] = __builtin_amdgcn_mfma_f32_16x16x32_bf16(Bt[n][k], At[m][k], acc[ai][bj][m][n], 0, 0, 0); __builtin_amdgcn_s_setprio(0); } while (0)
; #define PG8_WAIT_V(n) asm volatile("s_waitcnt vmcnt(" #n ")" ::: "memory")
; #define PG8_WAIT_L(n) asm volatile("s_waitcnt lgkmcnt(" #n ")" ::: "memory")
; #define PG8_BAR __builtin_amdgcn_s_barrier()
; #define PG8_SCHED __builtin_amdgcn_sched_barrier(0)
; template <class Epi, class Sched, bool ALIGN_EPI = false, bool SP2 = false>
; __device__ __forceinline__ void gemm_phase(PG8_LAS unsigned char* lds, const Gemm g, const Sched& S, const Epi& E) {
;     ...
;             PG8_LDB(B0, 0, 0); PG8_LDB(B1, 0, 1); PG8_SCHED; PG8_LDA(At, 0, 0); PG8_STAGE(PG8_SA(1, 1), a1 + hstep, voffA);
;             PG8_WAIT_V(8); PG8_WAIT_L(0); PG8_BAR; PG8_MMA(0, 0, At, B0); PG8_MMA(0, 1, At, B1); PG8_BAR; PG8_SCHED;
;             PG8_LDA(At, 0, 1); PG8_STAGE(PG8_SB(0, 0), b2, voffB); PG8_STAGE(PG8_SB(0, 1), b2 + hstep, voffB); PG8_STAGE(PG8_SA(0, 0), a2, voffA);
;             PG8_WAIT_V(8); PG8_WAIT_L(0); PG8_BAR; PG8_MMA(1, 0, At, B0); PG8_MMA(1, 1, At, B1); PG8_BAR; PG8_SCHED;
.LBB0_1825:
	ds_read_b128 v[96:99], v222
	ds_read_b128 v[108:111], v222 offset:1024
	ds_read_b128 v[120:123], v222 offset:2048
	ds_read_b128 v[128:131], v222 offset:3072
	ds_read_b128 v[144:147], v223
	ds_read_b128 v[148:151], v223 offset:1024
	ds_read_b128 v[152:155], v223 offset:2048
	ds_read_b128 v[156:159], v223 offset:3072
	s_add_u32 s34, s20, 0xfff50080
	s_addc_u32 s35, s21, -1
	s_cmp_eq_u32 s70, 40
	s_cselect_b32 s47, s1, s35
	s_cselect_b32 s46, s0, s34
	s_cselect_b32 s35, s45, s69
	s_cselect_b32 s34, s44, s68
	s_add_i32 m0, s49, 0xc000
	ds_read_b128 v[160:163], v224
	ds_read_b128 v[164:167], v224 offset:1024
	ds_read_b128 v[168:171], v224 offset:2048
	ds_read_b128 v[172:175], v224 offset:3072
	ds_read_b128 v[176:179], v224 offset:4096
	ds_read_b128 v[180:183], v224 offset:5120
	ds_read_b128 v[202:205], v224 offset:6144
	ds_read_b128 v[206:209], v224 offset:7168
	global_load_lds_dwordx4 v192, s[20:21]
	s_add_i32 m0, s49, 0xe000
	s_nop 0
	global_load_lds_dwordx4 v194, s[20:21]
	s_waitcnt vmcnt(8)
	s_waitcnt lgkmcnt(0)
	s_barrier
	v_mfma_f32_16x16x32_bf16 v[140:143], v[96:99], v[160:163], v[140:143]
	v_mfma_f32_16x16x32_bf16 v[136:139], v[120:123], v[160:163], v[136:139]
	v_mfma_f32_16x16x32_bf16 v[116:119], v[96:99], v[168:171], v[116:119]
	v_mfma_f32_16x16x32_bf16 v[112:115], v[120:123], v[168:171], v[112:115]
	v_mfma_f32_16x16x32_bf16 v[92:95], v[96:99], v[176:179], v[92:95]
	v_mfma_f32_16x16x32_bf16 v[88:91], v[120:123], v[176:179], v[88:91]
	v_mfma_f32_16x16x32_bf16 v[76:79], v[96:99], v[202:205], v[76:79]
	v_mfma_f32_16x16x32_bf16 v[72:75], v[120:123], v[202:205], v[72:75]
	v_mfma_f32_16x16x32_bf16 v[140:143], v[108:111], v[164:167], v[140:143]
	v_mfma_f32_16x16x32_bf16 v[136:139], v[128:131], v[164:167], v[136:139]
	v_mfma_f32_16x16x32_bf16 v[116:119], v[108:111], v[172:175], v[116:119]
	v_mfma_f32_16x16x32_bf16 v[112:115], v[128:131], v[172:175], v[112:115]
	v_mfma_f32_16x16x32_bf16 v[92:95], v[108:111], v[180:183], v[92:95]
	v_mfma_f32_16x16x32_bf16 v[88:91], v[128:131], v[180:183], v[88:91]
	v_mfma_f32_16x16x32_bf16 v[76:79], v[108:111], v[206:209], v[76:79]
	v_mfma_f32_16x16x32_bf16 v[72:75], v[128:131], v[206:209], v[72:75]
	v_mfma_f32_16x16x32_bf16 v[132:135], v[144:147], v[160:163], v[132:135]
	v_mfma_f32_16x16x32_bf16 v[124:127], v[152:155], v[160:163], v[124:127]
	v_mfma_f32_16x16x32_bf16 v[104:107], v[144:147], v[168:171], v[104:107]
	v_mfma_f32_16x16x32_bf16 v[100:103], v[152:155], v[168:171], v[100:103]
	v_mfma_f32_16x16x32_bf16 v[84:87], v[144:147], v[176:179], v[84:87]
	v_mfma_f32_16x16x32_bf16 v[80:83], v[152:155], v[176:179], v[80:83]
	v_mfma_f32_16x16x32_bf16 v[68:71], v[144:147], v[202:205], v[68:71]
	v_mfma_f32_16x16x32_bf16 v[64:67], v[152:155], v[202:205], v[64:67]
	v_mfma_f32_16x16x32_bf16 v[132:135], v[148:151], v[164:167], v[132:135]
	v_mfma_f32_16x16x32_bf16 v[124:127], v[156:159], v[164:167], v[124:127]
	v_mfma_f32_16x16x32_bf16 v[104:107], v[148:151], v[172:175], v[104:107]
	v_mfma_f32_16x16x32_bf16 v[100:103], v[156:159], v[172:175], v[100:103]
	v_mfma_f32_16x16x32_bf16 v[84:87], v[148:151], v[180:183], v[84:87]
	v_mfma_f32_16x16x32_bf16 v[80:83], v[156:159], v[180:183], v[80:83]
	v_mfma_f32_16x16x32_bf16 v[68:71], v[148:151], v[206:209], v[68:71]
	v_mfma_f32_16x16x32_bf16 v[64:67], v[156:159], v[206:209], v[64:67]
	s_barrier
	s_add_i32 s71, s62, s48
	s_add_u32 s98, s34, s12
	s_addc_u32 s99, s35, s13
	s_add_u32 s100, s46, s12
	s_addc_u32 s101, s47, s13
	s_mov_b32 m0, s71
	ds_read_b128 v[160:163], v224 offset:16384
	ds_read_b128 v[164:167], v224 offset:17408
	ds_read_b128 v[168:171], v224 offset:18432
	ds_read_b128 v[172:175], v224 offset:19456
	ds_read_b128 v[176:179], v224 offset:20480
	ds_read_b128 v[180:183], v224 offset:21504
	ds_read_b128 v[202:205], v224 offset:22528
	ds_read_b128 v[206:209], v224 offset:23552
	global_load_lds_dwordx4 v186, s[34:35]
	s_add_i32 m0, s71, 0x2000
	s_add_u32 s72, s34, 0xb0000
	s_addc_u32 s73, s35, 0
	s_add_i32 s71, s63, s48
	global_load_lds_dwordx4 v190, s[34:35]
	s_mov_b32 m0, s71
	s_nop 0
	global_load_lds_dwordx4 v186, s[72:73]
	s_add_i32 m0, s71, 0x2000
	s_nop 0
	global_load_lds_dwordx4 v190, s[72:73]
	s_mov_b32 m0, s49
	s_nop 0
	global_load_lds_dwordx4 v184, s[46:47]
	s_mov_b32 m0, s50
	s_nop 0
	global_load_lds_dwordx4 v188, s[46:47]
	s_waitcnt vmcnt(8)
	s_waitcnt lgkmcnt(0)
	s_barrier
	v_mfma_f32_16x16x32_bf16 v[60:63], v[96:99], v[160:163], v[60:63]
	v_mfma_f32_16x16x32_bf16 v[56:59], v[120:123], v[160:163], v[56:59]
	v_mfma_f32_16x16x32_bf16 v[44:47], v[96:99], v[168:171], v[44:47]
	v_mfma_f32_16x16x32_bf16 v[40:43], v[120:123], v[168:171], v[40:43]
	v_mfma_f32_16x16x32_bf16 v[28:31], v[96:99], v[176:179], v[28:31]
	v_mfma_f32_16x16x32_bf16 v[24:27], v[120:123], v[176:179], v[24:27]
	v_mfma_f32_16x16x32_bf16 v[12:15], v[96:99], v[202:205], v[12:15]
	v_mfma_f32_16x16x32_bf16 v[8:11], v[120:123], v[202:205], v[8:11]
	v_mfma_f32_16x16x32_bf16 v[60:63], v[108:111], v[164:167], v[60:63]
	v_mfma_f32_16x16x32_bf16 v[56:59], v[128:131], v[164:167], v[56:59]
	v_mfma_f32_16x16x32_bf16 v[44:47], v[108:111], v[172:175], v[44:47]
	v_mfma_f32_16x16x32_bf16 v[40:43], v[128:131], v[172:175], v[40:43]
	v_mfma_f32_16x16x32_bf16 v[28:31], v[108:111], v[180:183], v[28:31]
	v_mfma_f32_16x16x32_bf16 v[24:27], v[128:131], v[180:183], v[24:27]
	v_mfma_f32_16x16x32_bf16 v[12:15], v[108:111], v[206:209], v[12:15]
	v_mfma_f32_16x16x32_bf16 v[8:11], v[128:131], v[206:209], v[8:11]
	v_mfma_f32_16x16x32_bf16 v[52:55], v[144:147], v[160:163], v[52:55]
	v_mfma_f32_16x16x32_bf16 v[48:51], v[152:155], v[160:163], v[48:51]
	v_mfma_f32_16x16x32_bf16 v[36:39], v[144:147], v[168:171], v[36:39]
	v_mfma_f32_16x16x32_bf16 v[32:35], v[152:155], v[168:171], v[32:35]
	v_mfma_f32_16x16x32_bf16 v[20:23], v[144:147], v[176:179], v[20:23]
	v_mfma_f32_16x16x32_bf16 v[16:19], v[152:155], v[176:179], v[16:19]
	v_mfma_f32_16x16x32_bf16 v[4:7], v[144:147], v[202:205], v[4:7]
	v_mfma_f32_16x16x32_bf16 v[0:3], v[152:155], v[202:205], v[0:3]
	v_mfma_f32_16x16x32_bf16 v[52:55], v[148:151], v[164:167], v[52:55]
	v_mfma_f32_16x16x32_bf16 v[48:51], v[156:159], v[164:167], v[48:51]
	v_mfma_f32_16x16x32_bf16 v[36:39], v[148:151], v[172:175], v[36:39]
	v_mfma_f32_16x16x32_bf16 v[32:35], v[156:159], v[172:175], v[32:35]
	v_mfma_f32_16x16x32_bf16 v[20:23], v[148:151], v[180:183], v[20:23]
	v_mfma_f32_16x16x32_bf16 v[16:19], v[156:159], v[180:183], v[16:19]
	v_mfma_f32_16x16x32_bf16 v[4:7], v[148:151], v[206:209], v[4:7]
	v_mfma_f32_16x16x32_bf16 v[0:3], v[156:159], v[206:209], v[0:3]
	s_barrier
; #define PG8_STAGE(bufoff, gbase, voff) do { _Pragma("unroll") for (int _i = 0; _i < 2; ++_i) \
;         __builtin_amdgcn_global_load_lds((const unsigned*)((const char*)(gbase) + (voff)[_i]), (PG8_LAS unsigned*)(lds + (bufoff) + ldsw + _i * 8192), 16, 0, 0); } while (0)
; #define PG8_LDA(dst, b, h) do { _Pragma("unroll") for (int m = 0; m < 4; ++m) _Pragma("unroll") for (int k = 0; k < 2; ++k) dst[m][k] = *(const PG8_LAS bf16x8*)(lds + PG8_SA(b, h) + aoff + m * 2048 + k * 1024); } while (0)
; #define PG8_LDB(dst, b, h) do { _Pragma("unroll") for (int n = 0; n < 2; ++n) _Pragma("unroll") for (int k = 0; k < 2; ++k) dst[n][k] = *(const PG8_LAS bf16x8*)(lds + PG8_SB(b, h) + boff + n * 2048 + k * 1024); } while (0)
; #define PG8_MMA(ai, bj, At, Bt) do { __builtin_amdgcn_s_setprio(1); _Pragma("unroll") for (int m = 0; m < 4; ++m) _Pragma("unroll") for (int n = 0; n < 2; ++n) _Pragma("unroll") for (int k = 0; k < 2; ++k) \
;         acc[ai][bj][m][n] = __builtin_amdgcn_mfma_f32_16x16x32_bf16(Bt[n][k], At[m][k], acc[ai][bj][m][n], 0, 0, 0); __builtin_amdgcn_s_setprio(0); } while (0)
; #define PG8_WAIT_V(n) asm volatile("s_waitcnt vmcnt(" #n ")" ::: "memory")
; #define PG8_WAIT_L(n) asm volatile("s_waitcnt lgkmcnt(" #n ")" ::: "memory")
; #define PG8_BAR __builtin_amdgcn_s_barrier()
; #define PG8_SCHED __builtin_amdgcn_sched_barrier(0)
; template <class Epi, class Sched, bool ALIGN_EPI = false, bool SP2 = false>
; __device__ __forceinline__ void gemm_phase(PG8_LAS unsigned char* lds, const Gemm g, const Sched& S, const Epi& E) {
;     ...
;             PG8_LDB(B0, 1, 0); PG8_LDB(B1, 1, 1); PG8_SCHED; PG8_LDA(At, 1, 0); PG8_STAGE(PG8_SA(0, 1), a2 + hstep, voffA);
;             PG8_WAIT_V(8); PG8_WAIT_L(0); PG8_BAR; PG8_MMA(0, 0, At, B0); PG8_MMA(0, 1, At, B1); PG8_BAR; PG8_SCHED;
;             PG8_LDA(At, 1, 1); PG8_STAGE(PG8_SB(1, 0), b3, voffB); PG8_STAGE(PG8_SB(1, 1), b3 + hstep, voffB); PG8_STAGE(PG8_SA(1, 0), a3, voffA);
;             PG8_WAIT_V(8); PG8_WAIT_L(0); PG8_BAR; PG8_MMA(1, 0, At, B0); PG8_MMA(1, 1, At, B1); PG8_BAR; PG8_SCHED;
;     ...
;         if constexpr (ALIGN_EPI) { if (wr == 0) PG8_BAR; }
	s_add_i32 s71, 0, 0x18000
	s_add_i32 s72, 0, 0x1c000
	v_add_u32_e32 v128, s71, v197
	v_add_u32_e32 v156, s72, v197
	ds_read_b128 v[96:99], v128
	ds_read_b128 v[108:111], v128 offset:1024
	ds_read_b128 v[120:123], v128 offset:2048
	ds_read_b128 v[128:131], v128 offset:3072
	ds_read_b128 v[144:147], v156
	ds_read_b128 v[148:151], v156 offset:1024
	ds_read_b128 v[152:155], v156 offset:2048
	ds_read_b128 v[156:159], v156 offset:3072
	s_add_u32 s46, s46, 0xb0000
	s_addc_u32 s47, s47, 0
	s_mov_b32 m0, s51
	ds_read_b128 v[160:163], v224 offset:32768
	ds_read_b128 v[164:167], v224 offset:33792
	ds_read_b128 v[168:171], v224 offset:34816
	ds_read_b128 v[172:175], v224 offset:35840
	ds_read_b128 v[176:179], v224 offset:36864
	ds_read_b128 v[180:183], v224 offset:37888
	ds_read_b128 v[202:205], v224 offset:38912
	ds_read_b128 v[206:209], v224 offset:39936
	global_load_lds_dwordx4 v184, s[46:47]
	s_mov_b32 m0, s52
	s_nop 0
	global_load_lds_dwordx4 v188, s[46:47]
	s_waitcnt vmcnt(8)
	s_waitcnt lgkmcnt(0)
	s_barrier
	v_mfma_f32_16x16x32_bf16 v[140:143], v[96:99], v[160:163], v[140:143]
	v_mfma_f32_16x16x32_bf16 v[136:139], v[120:123], v[160:163], v[136:139]
	v_mfma_f32_16x16x32_bf16 v[116:119], v[96:99], v[168:171], v[116:119]
	v_mfma_f32_16x16x32_bf16 v[112:115], v[120:123], v[168:171], v[112:115]
	v_mfma_f32_16x16x32_bf16 v[92:95], v[96:99], v[176:179], v[92:95]
	v_mfma_f32_16x16x32_bf16 v[88:91], v[120:123], v[176:179], v[88:91]
	v_mfma_f32_16x16x32_bf16 v[76:79], v[96:99], v[202:205], v[76:79]
	v_mfma_f32_16x16x32_bf16 v[72:75], v[120:123], v[202:205], v[72:75]
	v_mfma_f32_16x16x32_bf16 v[140:143], v[108:111], v[164:167], v[140:143]
	v_mfma_f32_16x16x32_bf16 v[136:139], v[128:131], v[164:167], v[136:139]
	v_mfma_f32_16x16x32_bf16 v[116:119], v[108:111], v[172:175], v[116:119]
	v_mfma_f32_16x16x32_bf16 v[112:115], v[128:131], v[172:175], v[112:115]
	v_mfma_f32_16x16x32_bf16 v[92:95], v[108:111], v[180:183], v[92:95]
	v_mfma_f32_16x16x32_bf16 v[88:91], v[128:131], v[180:183], v[88:91]
	v_mfma_f32_16x16x32_bf16 v[76:79], v[108:111], v[206:209], v[76:79]
	v_mfma_f32_16x16x32_bf16 v[72:75], v[128:131], v[206:209], v[72:75]
	v_mfma_f32_16x16x32_bf16 v[132:135], v[144:147], v[160:163], v[132:135]
	v_mfma_f32_16x16x32_bf16 v[124:127], v[152:155], v[160:163], v[124:127]
	v_mfma_f32_16x16x32_bf16 v[104:107], v[144:147], v[168:171], v[104:107]
	v_mfma_f32_16x16x32_bf16 v[100:103], v[152:155], v[168:171], v[100:103]
	v_mfma_f32_16x16x32_bf16 v[84:87], v[144:147], v[176:179], v[84:87]
	v_mfma_f32_16x16x32_bf16 v[80:83], v[152:155], v[176:179], v[80:83]
	v_mfma_f32_16x16x32_bf16 v[68:71], v[144:147], v[202:205], v[68:71]
	v_mfma_f32_16x16x32_bf16 v[64:67], v[152:155], v[202:205], v[64:67]
	v_mfma_f32_16x16x32_bf16 v[132:135], v[148:151], v[164:167], v[132:135]
	v_mfma_f32_16x16x32_bf16 v[124:127], v[156:159], v[164:167], v[124:127]
	v_mfma_f32_16x16x32_bf16 v[104:107], v[148:151], v[172:175], v[104:107]
	v_mfma_f32_16x16x32_bf16 v[100:103], v[156:159], v[172:175], v[100:103]
	v_mfma_f32_16x16x32_bf16 v[84:87], v[148:151], v[180:183], v[84:87]
	v_mfma_f32_16x16x32_bf16 v[80:83], v[156:159], v[180:183], v[80:83]
	v_mfma_f32_16x16x32_bf16 v[68:71], v[148:151], v[206:209], v[68:71]
	v_mfma_f32_16x16x32_bf16 v[64:67], v[156:159], v[206:209], v[64:67]
	s_barrier
	s_add_i32 s46, s71, s48
	s_mov_b32 m0, s46
	ds_read_b128 v[160:163], v224 offset:49152
	ds_read_b128 v[164:167], v224 offset:50176
	ds_read_b128 v[168:171], v224 offset:51200
	ds_read_b128 v[172:175], v224 offset:52224
	ds_read_b128 v[176:179], v224 offset:53248
	ds_read_b128 v[180:183], v224 offset:54272
	ds_read_b128 v[202:205], v224 offset:55296
	ds_read_b128 v[206:209], v224 offset:56320
	global_load_lds_dwordx4 v186, s[98:99]
	s_add_i32 m0, s46, 0x2000
	s_add_u32 s34, s34, 0xb0080
	s_addc_u32 s35, s35, 0
	s_add_i32 s46, s72, s48
	global_load_lds_dwordx4 v190, s[98:99]
	s_mov_b32 m0, s46
	s_nop 0
	global_load_lds_dwordx4 v186, s[34:35]
	s_add_i32 m0, s46, 0x2000
	s_nop 0
	global_load_lds_dwordx4 v190, s[34:35]
	s_mov_b32 m0, s57
	s_nop 0
	global_load_lds_dwordx4 v184, s[100:101]
	s_mov_b32 m0, s58
	s_nop 0
	global_load_lds_dwordx4 v188, s[100:101]
	s_waitcnt vmcnt(8)
	s_waitcnt lgkmcnt(0)
	s_barrier
	v_mfma_f32_16x16x32_bf16 v[60:63], v[96:99], v[160:163], v[60:63]
	v_mfma_f32_16x16x32_bf16 v[56:59], v[120:123], v[160:163], v[56:59]
	v_mfma_f32_16x16x32_bf16 v[44:47], v[96:99], v[168:171], v[44:47]
	v_mfma_f32_16x16x32_bf16 v[40:43], v[120:123], v[168:171], v[40:43]
	v_mfma_f32_16x16x32_bf16 v[28:31], v[96:99], v[176:179], v[28:31]
	v_mfma_f32_16x16x32_bf16 v[24:27], v[120:123], v[176:179], v[24:27]
	v_mfma_f32_16x16x32_bf16 v[12:15], v[96:99], v[202:205], v[12:15]
	v_mfma_f32_16x16x32_bf16 v[8:11], v[120:123], v[202:205], v[8:11]
	v_mfma_f32_16x16x32_bf16 v[60:63], v[108:111], v[164:167], v[60:63]
	v_mfma_f32_16x16x32_bf16 v[56:59], v[128:131], v[164:167], v[56:59]
	v_mfma_f32_16x16x32_bf16 v[44:47], v[108:111], v[172:175], v[44:47]
	v_mfma_f32_16x16x32_bf16 v[40:43], v[128:131], v[172:175], v[40:43]
	v_mfma_f32_16x16x32_bf16 v[28:31], v[108:111], v[180:183], v[28:31]
	v_mfma_f32_16x16x32_bf16 v[24:27], v[128:131], v[180:183], v[24:27]
	v_mfma_f32_16x16x32_bf16 v[12:15], v[108:111], v[206:209], v[12:15]
	v_mfma_f32_16x16x32_bf16 v[8:11], v[128:131], v[206:209], v[8:11]
	v_mfma_f32_16x16x32_bf16 v[52:55], v[144:147], v[160:163], v[52:55]
	v_mfma_f32_16x16x32_bf16 v[48:51], v[152:155], v[160:163], v[48:51]
	v_mfma_f32_16x16x32_bf16 v[36:39], v[144:147], v[168:171], v[36:39]
	v_mfma_f32_16x16x32_bf16 v[32:35], v[152:155], v[168:171], v[32:35]
	v_mfma_f32_16x16x32_bf16 v[20:23], v[144:147], v[176:179], v[20:23]
	v_mfma_f32_16x16x32_bf16 v[16:19], v[152:155], v[176:179], v[16:19]
	v_mfma_f32_16x16x32_bf16 v[4:7], v[144:147], v[202:205], v[4:7]
	v_mfma_f32_16x16x32_bf16 v[0:3], v[152:155], v[202:205], v[0:3]
	v_mfma_f32_16x16x32_bf16 v[52:55], v[148:151], v[164:167], v[52:55]
	v_mfma_f32_16x16x32_bf16 v[48:51], v[156:159], v[164:167], v[48:51]
	v_mfma_f32_16x16x32_bf16 v[36:39], v[148:151], v[172:175], v[36:39]
	v_mfma_f32_16x16x32_bf16 v[32:35], v[156:159], v[172:175], v[32:35]
	v_mfma_f32_16x16x32_bf16 v[20:23], v[148:151], v[180:183], v[20:23]
	v_mfma_f32_16x16x32_bf16 v[16:19], v[156:159], v[180:183], v[16:19]
	v_mfma_f32_16x16x32_bf16 v[4:7], v[148:151], v[206:209], v[4:7]
	v_mfma_f32_16x16x32_bf16 v[0:3], v[156:159], v[206:209], v[0:3]
	s_barrier
	s_add_i32 s70, s70, 2
	s_add_u32 s20, s20, 0x100
	s_addc_u32 s21, s21, 0
	s_add_u32 s68, s68, 0x100
	s_addc_u32 s69, s69, 0
	s_cmp_gt_u32 s70, 41
	s_cbranch_scc0 .LBB0_1825
	s_and_b64 vcc, exec, s[14:15]
	s_cbranch_vccz .LBB0_1828
	s_barrier
